# peeled first k-iteration of GEMM loops (C=0 MFMAs, no acc zero-init movs), minor staging reorder
# speedup vs baseline: 1.0174x; 1.0077x over previous
; __device__ __forceinline__ const char* unitA(const Gemm& g, const Unit& u) { return (const char*)(g.A + (size_t)(u.z / g.zdiv) * g.sAhi + (size_t)(u.z % g.zdiv) * g.sAlo + (size_t)u.pm * BM * g.lda); }
; __device__ __forceinline__ const char* unitB(const Gemm& g, const Unit& u) { return (const char*)(g.Bt + (size_t)(u.z / g.zdiv) * g.sBhi + (size_t)(u.z % g.zdiv) * g.sBlo + (size_t)(u.pm / g.bdiv) * g.sBpm + (size_t)u.pn * BM * g.ldb); }
; #define PG8_STAGE(bufoff, gbase, voff) do { if constexpr (VAR != 1 && VAR != 3) { _Pragma("unroll") for (int _i = 0; _i < 2; ++_i) \
;         asm volatile("s_mov_b32 m0, %2\n\ts_nop 0\n\tglobal_load_lds_dwordx4 %0, %1" :: "v"((voff)[_i]), "s"((const char*)(gbase)), "s"(ldsbase + (unsigned)((bufoff) + _i * 8192)) : "memory", "m0"); } } while (0)
; #define PG8_LDA(dst, b, h) do { if constexpr (VAR < 2) _Pragma("unroll") for (int m = 0; m < 4; ++m) _Pragma("unroll") for (int k = 0; k < 2; ++k) dst[m][k] = *(const LAS bf16x8*)(lds + PG8_SA(b, h) + aoff + m * 2048 + k * 1024); } while (0)
; #define PG8_LDB(dst, b, h) do { if constexpr (VAR < 2) _Pragma("unroll") for (int n = 0; n < 2; ++n) _Pragma("unroll") for (int k = 0; k < 2; ++k) dst[n][k] = *(const LAS bf16x8*)(lds + PG8_SB(b, h) + boff + n * 2048 + k * 1024); } while (0)
; #define PG8_WAIT_V(n) asm volatile("s_waitcnt vmcnt(" #n ")" ::: "memory")
;     ...
;         const bool has_next = S.next(ui + 1, nxt);
;         const char* nA = has_next ? unitA(g, nxt) : cA; const char* nB = has_next ? unitB(g, nxt) : cB;
;         for (int t = 0; t < nt; t += 2) {
;             const bool last = (t == nt - 2);
;             const char* a1 = cA + (size_t)(t + 1) * kstep;
;             const char* a2 = last ? nA : cA + (size_t)(t + 2) * kstep; const char* b2 = last ? nB : cB + (size_t)(t + 2) * kstep;
;             const char* a3 = a2 + kstep; const char* b3 = b2 + kstep;
;             PG8_LDB(B0, 0, 0); PG8_LDB(B1, 0, 1); PG8_SCHED; PG8_LDA(At, 0, 0); PG8_STAGE(PG8_SA(1, 1), a1 + hstepA, voffA);
;             PG8_WAIT_V(8); PG8_WAIT_L(0); PG8_BAR; PG8_MMA(0, 0, At, B0); PG8_MMA(0, 1, At, B1); PG8_BAR; PG8_SCHED;
;             PG8_LDA(At, 0, 1); PG8_STAGE(PG8_SB(0, 0), b2, voffB); PG8_STAGE(PG8_SB(0, 1), b2 + hstepB, voffB); PG8_STAGE(PG8_SA(0, 0), a2, voffA);
;             PG8_WAIT_V(8); PG8_WAIT_L(0); PG8_BAR; PG8_MMA(1, 0, At, B0); PG8_MMA(1, 1, At, B1); PG8_BAR; PG8_SCHED;
.LBB0_345:
	s_ashr_i32 s65, s64, 31
	s_lshl_b64 s[6:7], s[64:65], 21
	s_add_u32 s70, s21, s6
	s_addc_u32 s71, s23, s7
	s_and_b64 s[6:7], s[2:3], exec
	s_cselect_b32 s14, s71, s93
	s_cselect_b32 s15, s70, s92
	s_ashr_i32 s69, s68, 31
	s_lshl_b64 s[6:7], s[68:69], 21
	s_add_u32 s88, s86, s6
	s_addc_u32 s89, s87, s7
	s_and_b64 s[6:7], s[2:3], exec
	s_cselect_b32 s63, s89, s91
	s_cselect_b32 s65, s88, s90
	s_add_u32 s66, s92, 0x100
	s_addc_u32 s67, s93, 0
	s_add_u32 s69, s90, 0x100
	s_addc_u32 vcc_lo, s91, 0
	s_add_u32 s90, s92, 0x100080
	s_addc_u32 s91, s93, 0
	s_mov_b32 vcc_hi, -2
	ds_read_b128 v[156:159], v151
	ds_read_b128 v[160:163], v151 offset:1024
	ds_read_b128 v[164:167], v151 offset:2048
	ds_read_b128 v[168:171], v151 offset:3072
	ds_read_b128 v[172:175], v152
	ds_read_b128 v[176:179], v152 offset:1024
	ds_read_b128 v[180:183], v152 offset:2048
	ds_read_b128 v[184:187], v152 offset:3072
	s_cmp_eq_u32 vcc_hi, 60
	s_cselect_b32 s96, s15, s66
	s_cselect_b32 s97, s14, s67
	s_cselect_b32 s94, s65, s69
	s_cselect_b32 s95, s63, vcc_lo
	s_add_u32 s92, s96, 0x80
	s_addc_u32 s93, s97, 0
	ds_read_b128 v[188:191], v153
	ds_read_b128 v[192:195], v153 offset:1024
	ds_read_b128 v[196:199], v153 offset:2048
	ds_read_b128 v[200:203], v153 offset:3072
	ds_read_b128 v[204:207], v153 offset:4096
	ds_read_b128 v[208:211], v153 offset:5120
	ds_read_b128 v[212:215], v153 offset:6144
	ds_read_b128 v[216:219], v153 offset:7168
	s_mov_b32 m0, s56
	s_nop 0
	global_load_lds_dwordx4 v1, s[90:91]
	s_mov_b32 m0, s57
	s_nop 0
	global_load_lds_dwordx4 v147, s[90:91]
	s_waitcnt vmcnt(8) lgkmcnt(0)
	s_barrier
	v_mfma_f32_16x16x32_bf16 v[126:129], v[156:159], v[188:191], 0
	v_mfma_f32_16x16x32_bf16 v[122:125], v[164:167], v[188:191], 0
	v_mfma_f32_16x16x32_bf16 v[118:121], v[156:159], v[196:199], 0
	v_mfma_f32_16x16x32_bf16 v[110:113], v[164:167], v[196:199], 0
	v_mfma_f32_16x16x32_bf16 v[102:105], v[156:159], v[204:207], 0
	v_mfma_f32_16x16x32_bf16 v[94:97], v[164:167], v[204:207], 0
	v_mfma_f32_16x16x32_bf16 v[86:89], v[156:159], v[212:215], 0
	v_mfma_f32_16x16x32_bf16 v[78:81], v[164:167], v[212:215], 0
	v_mfma_f32_16x16x32_bf16 v[126:129], v[160:163], v[192:195], v[126:129]
	v_mfma_f32_16x16x32_bf16 v[122:125], v[168:171], v[192:195], v[122:125]
	v_mfma_f32_16x16x32_bf16 v[118:121], v[160:163], v[200:203], v[118:121]
	v_mfma_f32_16x16x32_bf16 v[110:113], v[168:171], v[200:203], v[110:113]
	v_mfma_f32_16x16x32_bf16 v[102:105], v[160:163], v[208:211], v[102:105]
	v_mfma_f32_16x16x32_bf16 v[94:97], v[168:171], v[208:211], v[94:97]
	v_mfma_f32_16x16x32_bf16 v[86:89], v[160:163], v[216:219], v[86:89]
	v_mfma_f32_16x16x32_bf16 v[78:81], v[168:171], v[216:219], v[78:81]
	v_mfma_f32_16x16x32_bf16 v[114:117], v[172:175], v[188:191], 0
	v_mfma_f32_16x16x32_bf16 v[106:109], v[180:183], v[188:191], 0
	v_mfma_f32_16x16x32_bf16 v[98:101], v[172:175], v[196:199], 0
	v_mfma_f32_16x16x32_bf16 v[90:93], v[180:183], v[196:199], 0
	v_mfma_f32_16x16x32_bf16 v[82:85], v[172:175], v[204:207], 0
	v_mfma_f32_16x16x32_bf16 v[74:77], v[180:183], v[204:207], 0
	v_mfma_f32_16x16x32_bf16 v[70:73], v[172:175], v[212:215], 0
	v_mfma_f32_16x16x32_bf16 v[66:69], v[180:183], v[212:215], 0
	v_mfma_f32_16x16x32_bf16 v[114:117], v[176:179], v[192:195], v[114:117]
	v_mfma_f32_16x16x32_bf16 v[106:109], v[184:187], v[192:195], v[106:109]
	v_mfma_f32_16x16x32_bf16 v[98:101], v[176:179], v[200:203], v[98:101]
	v_mfma_f32_16x16x32_bf16 v[90:93], v[184:187], v[200:203], v[90:93]
	v_mfma_f32_16x16x32_bf16 v[82:85], v[176:179], v[208:211], v[82:85]
	v_mfma_f32_16x16x32_bf16 v[74:77], v[184:187], v[208:211], v[74:77]
	v_mfma_f32_16x16x32_bf16 v[70:73], v[176:179], v[216:219], v[70:73]
	v_mfma_f32_16x16x32_bf16 v[66:69], v[184:187], v[216:219], v[66:69]
	s_barrier
	ds_read_b128 v[188:191], v153 offset:16384
	ds_read_b128 v[192:195], v153 offset:17408
	ds_read_b128 v[196:199], v153 offset:18432
	ds_read_b128 v[200:203], v153 offset:19456
	ds_read_b128 v[204:207], v153 offset:20480
	ds_read_b128 v[208:211], v153 offset:21504
	ds_read_b128 v[212:215], v153 offset:22528
	ds_read_b128 v[216:219], v153 offset:23552
	s_mov_b32 m0, s25
	s_nop 0
	global_load_lds_dwordx4 v146, s[94:95]
	s_add_u32 s6, s94, 0x100000
	s_mov_b32 m0, s26
	s_nop 0
	global_load_lds_dwordx4 v148, s[94:95]
	s_addc_u32 s7, s95, 0
	s_mov_b32 m0, s27
	s_nop 0
	global_load_lds_dwordx4 v146, s[6:7]
	s_mov_b32 m0, s28
	s_nop 0
	global_load_lds_dwordx4 v148, s[6:7]
	s_mov_b32 m0, s19
	s_nop 0
	global_load_lds_dwordx4 v1, s[96:97]
	s_mov_b32 m0, s29
	s_nop 0
	global_load_lds_dwordx4 v147, s[96:97]
	s_waitcnt vmcnt(8) lgkmcnt(0)
	s_barrier
; #define PG8_STAGE(bufoff, gbase, voff) do { if constexpr (VAR != 1 && VAR != 3) { _Pragma("unroll") for (int _i = 0; _i < 2; ++_i) \
;         asm volatile("s_mov_b32 m0, %2\n\ts_nop 0\n\tglobal_load_lds_dwordx4 %0, %1" :: "v"((voff)[_i]), "s"((const char*)(gbase)), "s"(ldsbase + (unsigned)((bufoff) + _i * 8192)) : "memory", "m0"); } } while (0)
; #define PG8_LDA(dst, b, h) do { if constexpr (VAR < 2) _Pragma("unroll") for (int m = 0; m < 4; ++m) _Pragma("unroll") for (int k = 0; k < 2; ++k) dst[m][k] = *(const LAS bf16x8*)(lds + PG8_SA(b, h) + aoff + m * 2048 + k * 1024); } while (0)
; #define PG8_LDB(dst, b, h) do { if constexpr (VAR < 2) _Pragma("unroll") for (int n = 0; n < 2; ++n) _Pragma("unroll") for (int k = 0; k < 2; ++k) dst[n][k] = *(const LAS bf16x8*)(lds + PG8_SB(b, h) + boff + n * 2048 + k * 1024); } while (0)
; #define PG8_WAIT_V(n) asm volatile("s_waitcnt vmcnt(" #n ")" ::: "memory")
; #define PG8_WAIT_L(n) asm volatile("s_waitcnt lgkmcnt(" #n ")" ::: "memory")
; #define PG8_BAR do { if constexpr (VAR != 3) __builtin_amdgcn_s_barrier(); } while (0)
; #define PG8_SCHED __builtin_amdgcn_sched_barrier(0)
;     ...
;             PG8_WAIT_V(8); PG8_WAIT_L(0); PG8_BAR; PG8_MMA(1, 0, At, B0); PG8_MMA(1, 1, At, B1); PG8_BAR; PG8_SCHED;
;             PG8_LDB(B0, 1, 0); PG8_LDB(B1, 1, 1); PG8_SCHED; PG8_LDA(At, 1, 0); PG8_STAGE(PG8_SA(0, 1), a2 + hstepA, voffA);
;             PG8_WAIT_V(8); PG8_WAIT_L(0); PG8_BAR; PG8_MMA(0, 0, At, B0); PG8_MMA(0, 1, At, B1); PG8_BAR; PG8_SCHED;
	v_mfma_f32_16x16x32_bf16 v[62:65], v[156:159], v[188:191], 0
	v_mfma_f32_16x16x32_bf16 v[58:61], v[164:167], v[188:191], 0
	v_mfma_f32_16x16x32_bf16 v[54:57], v[156:159], v[196:199], 0
	v_mfma_f32_16x16x32_bf16 v[46:49], v[164:167], v[196:199], 0
	v_mfma_f32_16x16x32_bf16 v[38:41], v[156:159], v[204:207], 0
	v_mfma_f32_16x16x32_bf16 v[30:33], v[164:167], v[204:207], 0
	v_mfma_f32_16x16x32_bf16 v[22:25], v[156:159], v[212:215], 0
	v_mfma_f32_16x16x32_bf16 v[14:17], v[164:167], v[212:215], 0
	v_mfma_f32_16x16x32_bf16 v[62:65], v[160:163], v[192:195], v[62:65]
	v_mfma_f32_16x16x32_bf16 v[58:61], v[168:171], v[192:195], v[58:61]
	v_mfma_f32_16x16x32_bf16 v[54:57], v[160:163], v[200:203], v[54:57]
	v_mfma_f32_16x16x32_bf16 v[46:49], v[168:171], v[200:203], v[46:49]
	v_mfma_f32_16x16x32_bf16 v[38:41], v[160:163], v[208:211], v[38:41]
	v_mfma_f32_16x16x32_bf16 v[30:33], v[168:171], v[208:211], v[30:33]
	v_mfma_f32_16x16x32_bf16 v[22:25], v[160:163], v[216:219], v[22:25]
	v_mfma_f32_16x16x32_bf16 v[14:17], v[168:171], v[216:219], v[14:17]
	v_mfma_f32_16x16x32_bf16 v[50:53], v[172:175], v[188:191], 0
	v_mfma_f32_16x16x32_bf16 v[42:45], v[180:183], v[188:191], 0
	v_mfma_f32_16x16x32_bf16 v[34:37], v[172:175], v[196:199], 0
	v_mfma_f32_16x16x32_bf16 v[26:29], v[180:183], v[196:199], 0
	v_mfma_f32_16x16x32_bf16 v[18:21], v[172:175], v[204:207], 0
	v_mfma_f32_16x16x32_bf16 v[10:13], v[180:183], v[204:207], 0
	v_mfma_f32_16x16x32_bf16 v[6:9], v[172:175], v[212:215], 0
	v_mfma_f32_16x16x32_bf16 v[2:5], v[180:183], v[212:215], 0
	v_mfma_f32_16x16x32_bf16 v[50:53], v[176:179], v[192:195], v[50:53]
	v_mfma_f32_16x16x32_bf16 v[42:45], v[184:187], v[192:195], v[42:45]
	v_mfma_f32_16x16x32_bf16 v[34:37], v[176:179], v[200:203], v[34:37]
	v_mfma_f32_16x16x32_bf16 v[26:29], v[184:187], v[200:203], v[26:29]
	v_mfma_f32_16x16x32_bf16 v[18:21], v[176:179], v[208:211], v[18:21]
	v_mfma_f32_16x16x32_bf16 v[10:13], v[184:187], v[208:211], v[10:13]
	v_mfma_f32_16x16x32_bf16 v[6:9], v[176:179], v[216:219], v[6:9]
	v_mfma_f32_16x16x32_bf16 v[2:5], v[184:187], v[216:219], v[2:5]
	s_barrier
	ds_read_b128 v[156:159], v154
	ds_read_b128 v[160:163], v154 offset:1024
	ds_read_b128 v[164:167], v154 offset:2048
	ds_read_b128 v[168:171], v154 offset:3072
	ds_read_b128 v[172:175], v155
	ds_read_b128 v[176:179], v155 offset:1024
	ds_read_b128 v[180:183], v155 offset:2048
	ds_read_b128 v[184:187], v155 offset:3072
	ds_read_b128 v[188:191], v153 offset:32768
	ds_read_b128 v[192:195], v153 offset:33792
	ds_read_b128 v[196:199], v153 offset:34816
	ds_read_b128 v[200:203], v153 offset:35840
	ds_read_b128 v[204:207], v153 offset:36864
	ds_read_b128 v[208:211], v153 offset:37888
	ds_read_b128 v[212:215], v153 offset:38912
	ds_read_b128 v[216:219], v153 offset:39936
	s_add_u32 s6, s96, 0x100000
	s_addc_u32 s7, s97, 0
	s_mov_b32 m0, s30
	s_nop 0
	global_load_lds_dwordx4 v1, s[6:7]
	s_mov_b32 m0, s31
	s_nop 0
	global_load_lds_dwordx4 v147, s[6:7]
	s_waitcnt vmcnt(8) lgkmcnt(0)
	s_barrier
	v_mfma_f32_16x16x32_bf16 v[126:129], v[156:159], v[188:191], v[126:129]
	v_mfma_f32_16x16x32_bf16 v[122:125], v[164:167], v[188:191], v[122:125]
	v_mfma_f32_16x16x32_bf16 v[118:121], v[156:159], v[196:199], v[118:121]
	v_mfma_f32_16x16x32_bf16 v[110:113], v[164:167], v[196:199], v[110:113]
	v_mfma_f32_16x16x32_bf16 v[102:105], v[156:159], v[204:207], v[102:105]
	v_mfma_f32_16x16x32_bf16 v[94:97], v[164:167], v[204:207], v[94:97]
	v_mfma_f32_16x16x32_bf16 v[86:89], v[156:159], v[212:215], v[86:89]
	v_mfma_f32_16x16x32_bf16 v[78:81], v[164:167], v[212:215], v[78:81]
	v_mfma_f32_16x16x32_bf16 v[126:129], v[160:163], v[192:195], v[126:129]
	v_mfma_f32_16x16x32_bf16 v[122:125], v[168:171], v[192:195], v[122:125]
	v_mfma_f32_16x16x32_bf16 v[118:121], v[160:163], v[200:203], v[118:121]
	v_mfma_f32_16x16x32_bf16 v[110:113], v[168:171], v[200:203], v[110:113]
	v_mfma_f32_16x16x32_bf16 v[102:105], v[160:163], v[208:211], v[102:105]
	v_mfma_f32_16x16x32_bf16 v[94:97], v[168:171], v[208:211], v[94:97]
	v_mfma_f32_16x16x32_bf16 v[86:89], v[160:163], v[216:219], v[86:89]
	v_mfma_f32_16x16x32_bf16 v[78:81], v[168:171], v[216:219], v[78:81]
	v_mfma_f32_16x16x32_bf16 v[114:117], v[172:175], v[188:191], v[114:117]
	v_mfma_f32_16x16x32_bf16 v[106:109], v[180:183], v[188:191], v[106:109]
	v_mfma_f32_16x16x32_bf16 v[98:101], v[172:175], v[196:199], v[98:101]
	v_mfma_f32_16x16x32_bf16 v[90:93], v[180:183], v[196:199], v[90:93]
	v_mfma_f32_16x16x32_bf16 v[82:85], v[172:175], v[204:207], v[82:85]
	v_mfma_f32_16x16x32_bf16 v[74:77], v[180:183], v[204:207], v[74:77]
	v_mfma_f32_16x16x32_bf16 v[70:73], v[172:175], v[212:215], v[70:73]
	v_mfma_f32_16x16x32_bf16 v[66:69], v[180:183], v[212:215], v[66:69]
	v_mfma_f32_16x16x32_bf16 v[114:117], v[176:179], v[192:195], v[114:117]
	v_mfma_f32_16x16x32_bf16 v[106:109], v[184:187], v[192:195], v[106:109]
	v_mfma_f32_16x16x32_bf16 v[98:101], v[176:179], v[200:203], v[98:101]
	v_mfma_f32_16x16x32_bf16 v[90:93], v[184:187], v[200:203], v[90:93]
	v_mfma_f32_16x16x32_bf16 v[82:85], v[176:179], v[208:211], v[82:85]
	v_mfma_f32_16x16x32_bf16 v[74:77], v[184:187], v[208:211], v[74:77]
	v_mfma_f32_16x16x32_bf16 v[70:73], v[176:179], v[216:219], v[70:73]
	v_mfma_f32_16x16x32_bf16 v[66:69], v[184:187], v[216:219], v[66:69]
	s_barrier
; #define PG8_STAGE(bufoff, gbase, voff) do { if constexpr (VAR != 1 && VAR != 3) { _Pragma("unroll") for (int _i = 0; _i < 2; ++_i) \
;         asm volatile("s_mov_b32 m0, %2\n\ts_nop 0\n\tglobal_load_lds_dwordx4 %0, %1" :: "v"((voff)[_i]), "s"((const char*)(gbase)), "s"(ldsbase + (unsigned)((bufoff) + _i * 8192)) : "memory", "m0"); } } while (0)
; #define PG8_LDA(dst, b, h) do { if constexpr (VAR < 2) _Pragma("unroll") for (int m = 0; m < 4; ++m) _Pragma("unroll") for (int k = 0; k < 2; ++k) dst[m][k] = *(const LAS bf16x8*)(lds + PG8_SA(b, h) + aoff + m * 2048 + k * 1024); } while (0)
; #define PG8_LDB(dst, b, h) do { if constexpr (VAR < 2) _Pragma("unroll") for (int n = 0; n < 2; ++n) _Pragma("unroll") for (int k = 0; k < 2; ++k) dst[n][k] = *(const LAS bf16x8*)(lds + PG8_SB(b, h) + boff + n * 2048 + k * 1024); } while (0)
; #define PG8_WAIT_V(n) asm volatile("s_waitcnt vmcnt(" #n ")" ::: "memory")
; #define PG8_WAIT_L(n) asm volatile("s_waitcnt lgkmcnt(" #n ")" ::: "memory")
;     ...
;         for (int t = 0; t < nt; t += 2) {
;             const bool last = (t == nt - 2);
;             const char* a1 = cA + (size_t)(t + 1) * kstep;
;             const char* a2 = last ? nA : cA + (size_t)(t + 2) * kstep; const char* b2 = last ? nB : cB + (size_t)(t + 2) * kstep;
;             const char* a3 = a2 + kstep; const char* b3 = b2 + kstep;
;             PG8_LDB(B0, 0, 0); PG8_LDB(B1, 0, 1); PG8_SCHED; PG8_LDA(At, 0, 0); PG8_STAGE(PG8_SA(1, 1), a1 + hstepA, voffA);
;             PG8_WAIT_V(8); PG8_WAIT_L(0); PG8_BAR; PG8_MMA(0, 0, At, B0); PG8_MMA(0, 1, At, B1); PG8_BAR; PG8_SCHED;
;             PG8_LDA(At, 0, 1); PG8_STAGE(PG8_SB(0, 0), b2, voffB); PG8_STAGE(PG8_SB(0, 1), b2 + hstepB, voffB); PG8_STAGE(PG8_SA(0, 0), a2, voffA);
;             PG8_WAIT_V(8); PG8_WAIT_L(0); PG8_BAR; PG8_MMA(1, 0, At, B0); PG8_MMA(1, 1, At, B1); PG8_BAR; PG8_SCHED;
;             PG8_LDB(B0, 1, 0); PG8_LDB(B1, 1, 1); PG8_SCHED; PG8_LDA(At, 1, 0); PG8_STAGE(PG8_SA(0, 1), a2 + hstepA, voffA);
;             PG8_WAIT_V(8); PG8_WAIT_L(0); PG8_BAR; PG8_MMA(0, 0, At, B0); PG8_MMA(0, 1, At, B1); PG8_BAR; PG8_SCHED;
;             PG8_LDA(At, 1, 1); PG8_STAGE(PG8_SB(1, 0), b3, voffB); PG8_STAGE(PG8_SB(1, 1), b3 + hstepB, voffB); PG8_STAGE(PG8_SA(1, 0), a3, voffA);
;             PG8_WAIT_V(8); PG8_WAIT_L(0); PG8_BAR; PG8_MMA(1, 0, At, B0); PG8_MMA(1, 1, At, B1); PG8_BAR; PG8_SCHED;
	ds_read_b128 v[188:191], v153 offset:49152
	ds_read_b128 v[192:195], v153 offset:50176
	ds_read_b128 v[196:199], v153 offset:51200
	ds_read_b128 v[200:203], v153 offset:52224
	ds_read_b128 v[204:207], v153 offset:53248
	ds_read_b128 v[208:211], v153 offset:54272
	ds_read_b128 v[212:215], v153 offset:55296
	ds_read_b128 v[216:219], v153 offset:56320
	s_add_u32 s6, s94, 0x80
	s_addc_u32 s7, s95, 0
	s_mov_b32 m0, s33
	s_nop 0
	global_load_lds_dwordx4 v146, s[6:7]
	s_mov_b32 m0, s35
	s_nop 0
	global_load_lds_dwordx4 v148, s[6:7]
	s_add_u32 s6, s94, 0x100080
	s_addc_u32 s7, s95, 0
	s_mov_b32 m0, s54
	s_nop 0
	global_load_lds_dwordx4 v146, s[6:7]
	s_mov_b32 m0, s55
	s_nop 0
	global_load_lds_dwordx4 v148, s[6:7]
	s_mov_b32 m0, s52
	s_nop 0
	global_load_lds_dwordx4 v1, s[92:93]
	s_mov_b32 m0, s53
	s_nop 0
	global_load_lds_dwordx4 v147, s[92:93]
	s_waitcnt vmcnt(8) lgkmcnt(0)
	s_barrier
	v_mfma_f32_16x16x32_bf16 v[62:65], v[156:159], v[188:191], v[62:65]
	v_mfma_f32_16x16x32_bf16 v[58:61], v[164:167], v[188:191], v[58:61]
	v_mfma_f32_16x16x32_bf16 v[54:57], v[156:159], v[196:199], v[54:57]
	v_mfma_f32_16x16x32_bf16 v[46:49], v[164:167], v[196:199], v[46:49]
	v_mfma_f32_16x16x32_bf16 v[38:41], v[156:159], v[204:207], v[38:41]
	v_mfma_f32_16x16x32_bf16 v[30:33], v[164:167], v[204:207], v[30:33]
	v_mfma_f32_16x16x32_bf16 v[22:25], v[156:159], v[212:215], v[22:25]
	v_mfma_f32_16x16x32_bf16 v[14:17], v[164:167], v[212:215], v[14:17]
	v_mfma_f32_16x16x32_bf16 v[62:65], v[160:163], v[192:195], v[62:65]
	v_mfma_f32_16x16x32_bf16 v[58:61], v[168:171], v[192:195], v[58:61]
	v_mfma_f32_16x16x32_bf16 v[54:57], v[160:163], v[200:203], v[54:57]
	v_mfma_f32_16x16x32_bf16 v[46:49], v[168:171], v[200:203], v[46:49]
	v_mfma_f32_16x16x32_bf16 v[38:41], v[160:163], v[208:211], v[38:41]
	v_mfma_f32_16x16x32_bf16 v[30:33], v[168:171], v[208:211], v[30:33]
	v_mfma_f32_16x16x32_bf16 v[22:25], v[160:163], v[216:219], v[22:25]
	v_mfma_f32_16x16x32_bf16 v[14:17], v[168:171], v[216:219], v[14:17]
	v_mfma_f32_16x16x32_bf16 v[50:53], v[172:175], v[188:191], v[50:53]
	v_mfma_f32_16x16x32_bf16 v[42:45], v[180:183], v[188:191], v[42:45]
	v_mfma_f32_16x16x32_bf16 v[34:37], v[172:175], v[196:199], v[34:37]
	v_mfma_f32_16x16x32_bf16 v[26:29], v[180:183], v[196:199], v[26:29]
	v_mfma_f32_16x16x32_bf16 v[18:21], v[172:175], v[204:207], v[18:21]
	v_mfma_f32_16x16x32_bf16 v[10:13], v[180:183], v[204:207], v[10:13]
	v_mfma_f32_16x16x32_bf16 v[6:9], v[172:175], v[212:215], v[6:9]
	v_mfma_f32_16x16x32_bf16 v[2:5], v[180:183], v[212:215], v[2:5]
	v_mfma_f32_16x16x32_bf16 v[50:53], v[176:179], v[192:195], v[50:53]
	v_mfma_f32_16x16x32_bf16 v[42:45], v[184:187], v[192:195], v[42:45]
	v_mfma_f32_16x16x32_bf16 v[34:37], v[176:179], v[200:203], v[34:37]
	v_mfma_f32_16x16x32_bf16 v[26:29], v[184:187], v[200:203], v[26:29]
	v_mfma_f32_16x16x32_bf16 v[18:21], v[176:179], v[208:211], v[18:21]
	v_mfma_f32_16x16x32_bf16 v[10:13], v[184:187], v[208:211], v[10:13]
	v_mfma_f32_16x16x32_bf16 v[6:9], v[176:179], v[216:219], v[6:9]
	v_mfma_f32_16x16x32_bf16 v[2:5], v[184:187], v[216:219], v[2:5]
	s_barrier
	s_add_i32 vcc_hi, vcc_hi, 2
	s_add_u32 s66, s66, 0x100
	s_addc_u32 s67, s67, 0
	s_add_u32 s69, s69, 0x100
	s_addc_u32 vcc_lo, vcc_lo, 0
	s_add_u32 s90, s90, 0x100
	s_addc_u32 s91, s91, 0
	s_cmp_gt_u32 vcc_hi, 61
	s_cbranch_scc0 .LBB0_346
	s_branch .Lmy_kexit_0
.LBB0_346:
	ds_read_b128 v[156:159], v151
	ds_read_b128 v[160:163], v151 offset:1024
	ds_read_b128 v[164:167], v151 offset:2048
	ds_read_b128 v[168:171], v151 offset:3072
	ds_read_b128 v[172:175], v152
	ds_read_b128 v[176:179], v152 offset:1024
	ds_read_b128 v[180:183], v152 offset:2048
	ds_read_b128 v[184:187], v152 offset:3072
	s_cmp_eq_u32 vcc_hi, 60
	s_cselect_b32 s96, s15, s66
	s_cselect_b32 s97, s14, s67
	s_cselect_b32 s94, s65, s69
	s_cselect_b32 s95, s63, vcc_lo
	s_add_u32 s92, s96, 0x80
	s_addc_u32 s93, s97, 0
	ds_read_b128 v[188:191], v153
	ds_read_b128 v[192:195], v153 offset:1024
	ds_read_b128 v[196:199], v153 offset:2048
	ds_read_b128 v[200:203], v153 offset:3072
	ds_read_b128 v[204:207], v153 offset:4096
	ds_read_b128 v[208:211], v153 offset:5120
	ds_read_b128 v[212:215], v153 offset:6144
	ds_read_b128 v[216:219], v153 offset:7168
	s_mov_b32 m0, s56
	s_nop 0
	global_load_lds_dwordx4 v1, s[90:91]
	s_mov_b32 m0, s57
	s_nop 0
	global_load_lds_dwordx4 v147, s[90:91]
	s_waitcnt vmcnt(8) lgkmcnt(0)
	s_barrier
	v_mfma_f32_16x16x32_bf16 v[126:129], v[156:159], v[188:191], v[126:129]
	v_mfma_f32_16x16x32_bf16 v[122:125], v[164:167], v[188:191], v[122:125]
	v_mfma_f32_16x16x32_bf16 v[118:121], v[156:159], v[196:199], v[118:121]
	v_mfma_f32_16x16x32_bf16 v[110:113], v[164:167], v[196:199], v[110:113]
	v_mfma_f32_16x16x32_bf16 v[102:105], v[156:159], v[204:207], v[102:105]
	v_mfma_f32_16x16x32_bf16 v[94:97], v[164:167], v[204:207], v[94:97]
	v_mfma_f32_16x16x32_bf16 v[86:89], v[156:159], v[212:215], v[86:89]
	v_mfma_f32_16x16x32_bf16 v[78:81], v[164:167], v[212:215], v[78:81]
	v_mfma_f32_16x16x32_bf16 v[126:129], v[160:163], v[192:195], v[126:129]
	v_mfma_f32_16x16x32_bf16 v[122:125], v[168:171], v[192:195], v[122:125]
	v_mfma_f32_16x16x32_bf16 v[118:121], v[160:163], v[200:203], v[118:121]
	v_mfma_f32_16x16x32_bf16 v[110:113], v[168:171], v[200:203], v[110:113]
	v_mfma_f32_16x16x32_bf16 v[102:105], v[160:163], v[208:211], v[102:105]
	v_mfma_f32_16x16x32_bf16 v[94:97], v[168:171], v[208:211], v[94:97]
	v_mfma_f32_16x16x32_bf16 v[86:89], v[160:163], v[216:219], v[86:89]
	v_mfma_f32_16x16x32_bf16 v[78:81], v[168:171], v[216:219], v[78:81]
	v_mfma_f32_16x16x32_bf16 v[114:117], v[172:175], v[188:191], v[114:117]
	v_mfma_f32_16x16x32_bf16 v[106:109], v[180:183], v[188:191], v[106:109]
	v_mfma_f32_16x16x32_bf16 v[98:101], v[172:175], v[196:199], v[98:101]
	v_mfma_f32_16x16x32_bf16 v[90:93], v[180:183], v[196:199], v[90:93]
	v_mfma_f32_16x16x32_bf16 v[82:85], v[172:175], v[204:207], v[82:85]
	v_mfma_f32_16x16x32_bf16 v[74:77], v[180:183], v[204:207], v[74:77]
	v_mfma_f32_16x16x32_bf16 v[70:73], v[172:175], v[212:215], v[70:73]
	v_mfma_f32_16x16x32_bf16 v[66:69], v[180:183], v[212:215], v[66:69]
	v_mfma_f32_16x16x32_bf16 v[114:117], v[176:179], v[192:195], v[114:117]
	v_mfma_f32_16x16x32_bf16 v[106:109], v[184:187], v[192:195], v[106:109]
	v_mfma_f32_16x16x32_bf16 v[98:101], v[176:179], v[200:203], v[98:101]
	v_mfma_f32_16x16x32_bf16 v[90:93], v[184:187], v[200:203], v[90:93]
	v_mfma_f32_16x16x32_bf16 v[82:85], v[176:179], v[208:211], v[82:85]
	v_mfma_f32_16x16x32_bf16 v[74:77], v[184:187], v[208:211], v[74:77]
	v_mfma_f32_16x16x32_bf16 v[70:73], v[176:179], v[216:219], v[70:73]
	v_mfma_f32_16x16x32_bf16 v[66:69], v[184:187], v[216:219], v[66:69]
	s_barrier
; #define PG8_STAGE(bufoff, gbase, voff) do { if constexpr (VAR != 1 && VAR != 3) { _Pragma("unroll") for (int _i = 0; _i < 2; ++_i) \
;         asm volatile("s_mov_b32 m0, %2\n\ts_nop 0\n\tglobal_load_lds_dwordx4 %0, %1" :: "v"((voff)[_i]), "s"((const char*)(gbase)), "s"(ldsbase + (unsigned)((bufoff) + _i * 8192)) : "memory", "m0"); } } while (0)
; #define PG8_LDA(dst, b, h) do { if constexpr (VAR < 2) _Pragma("unroll") for (int m = 0; m < 4; ++m) _Pragma("unroll") for (int k = 0; k < 2; ++k) dst[m][k] = *(const LAS bf16x8*)(lds + PG8_SA(b, h) + aoff + m * 2048 + k * 1024); } while (0)
; #define PG8_LDB(dst, b, h) do { if constexpr (VAR < 2) _Pragma("unroll") for (int n = 0; n < 2; ++n) _Pragma("unroll") for (int k = 0; k < 2; ++k) dst[n][k] = *(const LAS bf16x8*)(lds + PG8_SB(b, h) + boff + n * 2048 + k * 1024); } while (0)
; #define PG8_WAIT_V(n) asm volatile("s_waitcnt vmcnt(" #n ")" ::: "memory")
; #define PG8_WAIT_L(n) asm volatile("s_waitcnt lgkmcnt(" #n ")" ::: "memory")
; #define PG8_BAR do { if constexpr (VAR != 3) __builtin_amdgcn_s_barrier(); } while (0)
; #define PG8_SCHED __builtin_amdgcn_sched_barrier(0)
;     ...
;             PG8_LDA(At, 0, 1); PG8_STAGE(PG8_SB(0, 0), b2, voffB); PG8_STAGE(PG8_SB(0, 1), b2 + hstepB, voffB); PG8_STAGE(PG8_SA(0, 0), a2, voffA);
;             PG8_WAIT_V(8); PG8_WAIT_L(0); PG8_BAR; PG8_MMA(1, 0, At, B0); PG8_MMA(1, 1, At, B1); PG8_BAR; PG8_SCHED;
;             PG8_LDB(B0, 1, 0); PG8_LDB(B1, 1, 1); PG8_SCHED; PG8_LDA(At, 1, 0); PG8_STAGE(PG8_SA(0, 1), a2 + hstepA, voffA);
;             PG8_WAIT_V(8); PG8_WAIT_L(0); PG8_BAR; PG8_MMA(0, 0, At, B0); PG8_MMA(0, 1, At, B1); PG8_BAR; PG8_SCHED;
	ds_read_b128 v[188:191], v153 offset:16384
	ds_read_b128 v[192:195], v153 offset:17408
	ds_read_b128 v[196:199], v153 offset:18432
	ds_read_b128 v[200:203], v153 offset:19456
	ds_read_b128 v[204:207], v153 offset:20480
	ds_read_b128 v[208:211], v153 offset:21504
	ds_read_b128 v[212:215], v153 offset:22528
	ds_read_b128 v[216:219], v153 offset:23552
	s_mov_b32 m0, s25
	s_nop 0
	global_load_lds_dwordx4 v146, s[94:95]
	s_add_u32 s6, s94, 0x100000
	s_mov_b32 m0, s26
	s_nop 0
	global_load_lds_dwordx4 v148, s[94:95]
	s_addc_u32 s7, s95, 0
	s_mov_b32 m0, s27
	s_nop 0
	global_load_lds_dwordx4 v146, s[6:7]
	s_mov_b32 m0, s28
	s_nop 0
	global_load_lds_dwordx4 v148, s[6:7]
	s_mov_b32 m0, s19
	s_nop 0
	global_load_lds_dwordx4 v1, s[96:97]
	s_mov_b32 m0, s29
	s_nop 0
	global_load_lds_dwordx4 v147, s[96:97]
	s_waitcnt vmcnt(8) lgkmcnt(0)
	s_barrier
	v_mfma_f32_16x16x32_bf16 v[62:65], v[156:159], v[188:191], v[62:65]
	v_mfma_f32_16x16x32_bf16 v[58:61], v[164:167], v[188:191], v[58:61]
	v_mfma_f32_16x16x32_bf16 v[54:57], v[156:159], v[196:199], v[54:57]
	v_mfma_f32_16x16x32_bf16 v[46:49], v[164:167], v[196:199], v[46:49]
	v_mfma_f32_16x16x32_bf16 v[38:41], v[156:159], v[204:207], v[38:41]
	v_mfma_f32_16x16x32_bf16 v[30:33], v[164:167], v[204:207], v[30:33]
	v_mfma_f32_16x16x32_bf16 v[22:25], v[156:159], v[212:215], v[22:25]
	v_mfma_f32_16x16x32_bf16 v[14:17], v[164:167], v[212:215], v[14:17]
	v_mfma_f32_16x16x32_bf16 v[62:65], v[160:163], v[192:195], v[62:65]
	v_mfma_f32_16x16x32_bf16 v[58:61], v[168:171], v[192:195], v[58:61]
	v_mfma_f32_16x16x32_bf16 v[54:57], v[160:163], v[200:203], v[54:57]
	v_mfma_f32_16x16x32_bf16 v[46:49], v[168:171], v[200:203], v[46:49]
	v_mfma_f32_16x16x32_bf16 v[38:41], v[160:163], v[208:211], v[38:41]
	v_mfma_f32_16x16x32_bf16 v[30:33], v[168:171], v[208:211], v[30:33]
	v_mfma_f32_16x16x32_bf16 v[22:25], v[160:163], v[216:219], v[22:25]
	v_mfma_f32_16x16x32_bf16 v[14:17], v[168:171], v[216:219], v[14:17]
	v_mfma_f32_16x16x32_bf16 v[50:53], v[172:175], v[188:191], v[50:53]
	v_mfma_f32_16x16x32_bf16 v[42:45], v[180:183], v[188:191], v[42:45]
	v_mfma_f32_16x16x32_bf16 v[34:37], v[172:175], v[196:199], v[34:37]
	v_mfma_f32_16x16x32_bf16 v[26:29], v[180:183], v[196:199], v[26:29]
	v_mfma_f32_16x16x32_bf16 v[18:21], v[172:175], v[204:207], v[18:21]
	v_mfma_f32_16x16x32_bf16 v[10:13], v[180:183], v[204:207], v[10:13]
	v_mfma_f32_16x16x32_bf16 v[6:9], v[172:175], v[212:215], v[6:9]
	v_mfma_f32_16x16x32_bf16 v[2:5], v[180:183], v[212:215], v[2:5]
	v_mfma_f32_16x16x32_bf16 v[50:53], v[176:179], v[192:195], v[50:53]
	v_mfma_f32_16x16x32_bf16 v[42:45], v[184:187], v[192:195], v[42:45]
	v_mfma_f32_16x16x32_bf16 v[34:37], v[176:179], v[200:203], v[34:37]
	v_mfma_f32_16x16x32_bf16 v[26:29], v[184:187], v[200:203], v[26:29]
	v_mfma_f32_16x16x32_bf16 v[18:21], v[176:179], v[208:211], v[18:21]
	v_mfma_f32_16x16x32_bf16 v[10:13], v[184:187], v[208:211], v[10:13]
	v_mfma_f32_16x16x32_bf16 v[6:9], v[176:179], v[216:219], v[6:9]
	v_mfma_f32_16x16x32_bf16 v[2:5], v[184:187], v[216:219], v[2:5]
	s_barrier
	ds_read_b128 v[156:159], v154
	ds_read_b128 v[160:163], v154 offset:1024
	ds_read_b128 v[164:167], v154 offset:2048
	ds_read_b128 v[168:171], v154 offset:3072
	ds_read_b128 v[172:175], v155
	ds_read_b128 v[176:179], v155 offset:1024
	ds_read_b128 v[180:183], v155 offset:2048
	ds_read_b128 v[184:187], v155 offset:3072
	ds_read_b128 v[188:191], v153 offset:32768
	ds_read_b128 v[192:195], v153 offset:33792
	ds_read_b128 v[196:199], v153 offset:34816
	ds_read_b128 v[200:203], v153 offset:35840
	ds_read_b128 v[204:207], v153 offset:36864
	ds_read_b128 v[208:211], v153 offset:37888
	ds_read_b128 v[212:215], v153 offset:38912
	ds_read_b128 v[216:219], v153 offset:39936
	s_add_u32 s6, s96, 0x100000
	s_addc_u32 s7, s97, 0
	s_mov_b32 m0, s30
	s_nop 0
	global_load_lds_dwordx4 v1, s[6:7]
	s_mov_b32 m0, s31
	s_nop 0
	global_load_lds_dwordx4 v147, s[6:7]
	s_waitcnt vmcnt(8) lgkmcnt(0)
	s_barrier
; #define PG8_STAGE(bufoff, gbase, voff) do { if constexpr (VAR != 1 && VAR != 3) { _Pragma("unroll") for (int _i = 0; _i < 2; ++_i) \
;         asm volatile("s_mov_b32 m0, %2\n\ts_nop 0\n\tglobal_load_lds_dwordx4 %0, %1" :: "v"((voff)[_i]), "s"((const char*)(gbase)), "s"(ldsbase + (unsigned)((bufoff) + _i * 8192)) : "memory", "m0"); } } while (0)
; #define PG8_LDA(dst, b, h) do { if constexpr (VAR < 2) _Pragma("unroll") for (int m = 0; m < 4; ++m) _Pragma("unroll") for (int k = 0; k < 2; ++k) dst[m][k] = *(const LAS bf16x8*)(lds + PG8_SA(b, h) + aoff + m * 2048 + k * 1024); } while (0)
; #define PG8_WAIT_V(n) asm volatile("s_waitcnt vmcnt(" #n ")" ::: "memory")
; #define PG8_WAIT_L(n) asm volatile("s_waitcnt lgkmcnt(" #n ")" ::: "memory")
; #define PG8_BAR do { if constexpr (VAR != 3) __builtin_amdgcn_s_barrier(); } while (0)
; #define PG8_SCHED __builtin_amdgcn_sched_barrier(0)
;     ...
;             PG8_WAIT_V(8); PG8_WAIT_L(0); PG8_BAR; PG8_MMA(0, 0, At, B0); PG8_MMA(0, 1, At, B1); PG8_BAR; PG8_SCHED;
;             PG8_LDA(At, 1, 1); PG8_STAGE(PG8_SB(1, 0), b3, voffB); PG8_STAGE(PG8_SB(1, 1), b3 + hstepB, voffB); PG8_STAGE(PG8_SA(1, 0), a3, voffA);
;             PG8_WAIT_V(8); PG8_WAIT_L(0); PG8_BAR; PG8_MMA(1, 0, At, B0); PG8_MMA(1, 1, At, B1); PG8_BAR; PG8_SCHED;
	v_mfma_f32_16x16x32_bf16 v[126:129], v[156:159], v[188:191], v[126:129]
	v_mfma_f32_16x16x32_bf16 v[122:125], v[164:167], v[188:191], v[122:125]
	v_mfma_f32_16x16x32_bf16 v[118:121], v[156:159], v[196:199], v[118:121]
	v_mfma_f32_16x16x32_bf16 v[110:113], v[164:167], v[196:199], v[110:113]
	v_mfma_f32_16x16x32_bf16 v[102:105], v[156:159], v[204:207], v[102:105]
	v_mfma_f32_16x16x32_bf16 v[94:97], v[164:167], v[204:207], v[94:97]
	v_mfma_f32_16x16x32_bf16 v[86:89], v[156:159], v[212:215], v[86:89]
	v_mfma_f32_16x16x32_bf16 v[78:81], v[164:167], v[212:215], v[78:81]
	v_mfma_f32_16x16x32_bf16 v[126:129], v[160:163], v[192:195], v[126:129]
	v_mfma_f32_16x16x32_bf16 v[122:125], v[168:171], v[192:195], v[122:125]
	v_mfma_f32_16x16x32_bf16 v[118:121], v[160:163], v[200:203], v[118:121]
	v_mfma_f32_16x16x32_bf16 v[110:113], v[168:171], v[200:203], v[110:113]
	v_mfma_f32_16x16x32_bf16 v[102:105], v[160:163], v[208:211], v[102:105]
	v_mfma_f32_16x16x32_bf16 v[94:97], v[168:171], v[208:211], v[94:97]
	v_mfma_f32_16x16x32_bf16 v[86:89], v[160:163], v[216:219], v[86:89]
	v_mfma_f32_16x16x32_bf16 v[78:81], v[168:171], v[216:219], v[78:81]
	v_mfma_f32_16x16x32_bf16 v[114:117], v[172:175], v[188:191], v[114:117]
	v_mfma_f32_16x16x32_bf16 v[106:109], v[180:183], v[188:191], v[106:109]
	v_mfma_f32_16x16x32_bf16 v[98:101], v[172:175], v[196:199], v[98:101]
	v_mfma_f32_16x16x32_bf16 v[90:93], v[180:183], v[196:199], v[90:93]
	v_mfma_f32_16x16x32_bf16 v[82:85], v[172:175], v[204:207], v[82:85]
	v_mfma_f32_16x16x32_bf16 v[74:77], v[180:183], v[204:207], v[74:77]
	v_mfma_f32_16x16x32_bf16 v[70:73], v[172:175], v[212:215], v[70:73]
	v_mfma_f32_16x16x32_bf16 v[66:69], v[180:183], v[212:215], v[66:69]
	v_mfma_f32_16x16x32_bf16 v[114:117], v[176:179], v[192:195], v[114:117]
	v_mfma_f32_16x16x32_bf16 v[106:109], v[184:187], v[192:195], v[106:109]
	v_mfma_f32_16x16x32_bf16 v[98:101], v[176:179], v[200:203], v[98:101]
	v_mfma_f32_16x16x32_bf16 v[90:93], v[184:187], v[200:203], v[90:93]
	v_mfma_f32_16x16x32_bf16 v[82:85], v[176:179], v[208:211], v[82:85]
	v_mfma_f32_16x16x32_bf16 v[74:77], v[184:187], v[208:211], v[74:77]
	v_mfma_f32_16x16x32_bf16 v[70:73], v[176:179], v[216:219], v[70:73]
	v_mfma_f32_16x16x32_bf16 v[66:69], v[184:187], v[216:219], v[66:69]
	s_barrier
	ds_read_b128 v[188:191], v153 offset:49152
	ds_read_b128 v[192:195], v153 offset:50176
	ds_read_b128 v[196:199], v153 offset:51200
	ds_read_b128 v[200:203], v153 offset:52224
	ds_read_b128 v[204:207], v153 offset:53248
	ds_read_b128 v[208:211], v153 offset:54272
	ds_read_b128 v[212:215], v153 offset:55296
	ds_read_b128 v[216:219], v153 offset:56320
	s_add_u32 s6, s94, 0x80
	s_addc_u32 s7, s95, 0
	s_mov_b32 m0, s33
	s_nop 0
	global_load_lds_dwordx4 v146, s[6:7]
	s_mov_b32 m0, s35
	s_nop 0
	global_load_lds_dwordx4 v148, s[6:7]
	s_add_u32 s6, s94, 0x100080
	s_addc_u32 s7, s95, 0
	s_mov_b32 m0, s54
	s_nop 0
	global_load_lds_dwordx4 v146, s[6:7]
	s_mov_b32 m0, s55
	s_nop 0
	global_load_lds_dwordx4 v148, s[6:7]
	s_mov_b32 m0, s52
	s_nop 0
	global_load_lds_dwordx4 v1, s[92:93]
	s_mov_b32 m0, s53
	s_nop 0
	global_load_lds_dwordx4 v147, s[92:93]
	s_waitcnt vmcnt(8) lgkmcnt(0)
	s_barrier
	v_mfma_f32_16x16x32_bf16 v[62:65], v[156:159], v[188:191], v[62:65]
	v_mfma_f32_16x16x32_bf16 v[58:61], v[164:167], v[188:191], v[58:61]
	v_mfma_f32_16x16x32_bf16 v[54:57], v[156:159], v[196:199], v[54:57]
	v_mfma_f32_16x16x32_bf16 v[46:49], v[164:167], v[196:199], v[46:49]
	v_mfma_f32_16x16x32_bf16 v[38:41], v[156:159], v[204:207], v[38:41]
	v_mfma_f32_16x16x32_bf16 v[30:33], v[164:167], v[204:207], v[30:33]
	v_mfma_f32_16x16x32_bf16 v[22:25], v[156:159], v[212:215], v[22:25]
	v_mfma_f32_16x16x32_bf16 v[14:17], v[164:167], v[212:215], v[14:17]
	v_mfma_f32_16x16x32_bf16 v[62:65], v[160:163], v[192:195], v[62:65]
	v_mfma_f32_16x16x32_bf16 v[58:61], v[168:171], v[192:195], v[58:61]
	v_mfma_f32_16x16x32_bf16 v[54:57], v[160:163], v[200:203], v[54:57]
	v_mfma_f32_16x16x32_bf16 v[46:49], v[168:171], v[200:203], v[46:49]
	v_mfma_f32_16x16x32_bf16 v[38:41], v[160:163], v[208:211], v[38:41]
	v_mfma_f32_16x16x32_bf16 v[30:33], v[168:171], v[208:211], v[30:33]
	v_mfma_f32_16x16x32_bf16 v[22:25], v[160:163], v[216:219], v[22:25]
	v_mfma_f32_16x16x32_bf16 v[14:17], v[168:171], v[216:219], v[14:17]
	v_mfma_f32_16x16x32_bf16 v[50:53], v[172:175], v[188:191], v[50:53]
	v_mfma_f32_16x16x32_bf16 v[42:45], v[180:183], v[188:191], v[42:45]
	v_mfma_f32_16x16x32_bf16 v[34:37], v[172:175], v[196:199], v[34:37]
	v_mfma_f32_16x16x32_bf16 v[26:29], v[180:183], v[196:199], v[26:29]
	v_mfma_f32_16x16x32_bf16 v[18:21], v[172:175], v[204:207], v[18:21]
	v_mfma_f32_16x16x32_bf16 v[10:13], v[180:183], v[204:207], v[10:13]
	v_mfma_f32_16x16x32_bf16 v[6:9], v[172:175], v[212:215], v[6:9]
	v_mfma_f32_16x16x32_bf16 v[2:5], v[180:183], v[212:215], v[2:5]
	v_mfma_f32_16x16x32_bf16 v[50:53], v[176:179], v[192:195], v[50:53]
	v_mfma_f32_16x16x32_bf16 v[42:45], v[184:187], v[192:195], v[42:45]
	v_mfma_f32_16x16x32_bf16 v[34:37], v[176:179], v[200:203], v[34:37]
	v_mfma_f32_16x16x32_bf16 v[26:29], v[184:187], v[200:203], v[26:29]
	v_mfma_f32_16x16x32_bf16 v[18:21], v[176:179], v[208:211], v[18:21]
	v_mfma_f32_16x16x32_bf16 v[10:13], v[184:187], v[208:211], v[10:13]
	v_mfma_f32_16x16x32_bf16 v[6:9], v[176:179], v[216:219], v[6:9]
	v_mfma_f32_16x16x32_bf16 v[2:5], v[184:187], v[216:219], v[2:5]
	s_barrier
	s_add_i32 vcc_hi, vcc_hi, 2
	s_add_u32 s66, s66, 0x100
	s_addc_u32 s67, s67, 0
	s_add_u32 s69, s69, 0x100
	s_addc_u32 vcc_lo, vcc_lo, 0
	s_add_u32 s90, s90, 0x100
	s_addc_u32 s91, s91, 0
	s_cmp_gt_u32 vcc_hi, 61
	s_cbranch_scc0 .LBB0_346

; __device__ __forceinline__ const char* unitA(const Gemm& g, const Unit& u) { return (const char*)(g.A + (size_t)(u.z / g.zdiv) * g.sAhi + (size_t)(u.z % g.zdiv) * g.sAlo + (size_t)u.pm * BM * g.lda); }
; __device__ __forceinline__ const char* unitB(const Gemm& g, const Unit& u) { return (const char*)(g.Bt + (size_t)(u.z / g.zdiv) * g.sBhi + (size_t)(u.z % g.zdiv) * g.sBlo + (size_t)(u.pm / g.bdiv) * g.sBpm + (size_t)u.pn * BM * g.ldb); }
; #define PG8_STAGE(bufoff, gbase, voff) do { if constexpr (VAR != 1 && VAR != 3) { _Pragma("unroll") for (int _i = 0; _i < 2; ++_i) \
;         asm volatile("s_mov_b32 m0, %2\n\ts_nop 0\n\tglobal_load_lds_dwordx4 %0, %1" :: "v"((voff)[_i]), "s"((const char*)(gbase)), "s"(ldsbase + (unsigned)((bufoff) + _i * 8192)) : "memory", "m0"); } } while (0)
; #define PG8_LDA(dst, b, h) do { if constexpr (VAR < 2) _Pragma("unroll") for (int m = 0; m < 4; ++m) _Pragma("unroll") for (int k = 0; k < 2; ++k) dst[m][k] = *(const LAS bf16x8*)(lds + PG8_SA(b, h) + aoff + m * 2048 + k * 1024); } while (0)
; #define PG8_LDB(dst, b, h) do { if constexpr (VAR < 2) _Pragma("unroll") for (int n = 0; n < 2; ++n) _Pragma("unroll") for (int k = 0; k < 2; ++k) dst[n][k] = *(const LAS bf16x8*)(lds + PG8_SB(b, h) + boff + n * 2048 + k * 1024); } while (0)
; #define PG8_WAIT_V(n) asm volatile("s_waitcnt vmcnt(" #n ")" ::: "memory")
;     ...
;         const bool has_next = S.next(ui + 1, nxt);
;         const char* nA = has_next ? unitA(g, nxt) : cA; const char* nB = has_next ? unitB(g, nxt) : cB;
;         for (int t = 0; t < nt; t += 2) {
;             const bool last = (t == nt - 2);
;             const char* a1 = cA + (size_t)(t + 1) * kstep;
;             const char* a2 = last ? nA : cA + (size_t)(t + 2) * kstep; const char* b2 = last ? nB : cB + (size_t)(t + 2) * kstep;
;             const char* a3 = a2 + kstep; const char* b3 = b2 + kstep;
;             PG8_LDB(B0, 0, 0); PG8_LDB(B1, 0, 1); PG8_SCHED; PG8_LDA(At, 0, 0); PG8_STAGE(PG8_SA(1, 1), a1 + hstepA, voffA);
;             PG8_WAIT_V(8); PG8_WAIT_L(0); PG8_BAR; PG8_MMA(0, 0, At, B0); PG8_MMA(0, 1, At, B1); PG8_BAR; PG8_SCHED;
;             PG8_LDA(At, 0, 1); PG8_STAGE(PG8_SB(0, 0), b2, voffB); PG8_STAGE(PG8_SB(0, 1), b2 + hstepB, voffB); PG8_STAGE(PG8_SA(0, 0), a2, voffA);
;             PG8_WAIT_V(8); PG8_WAIT_L(0); PG8_BAR; PG8_MMA(1, 0, At, B0); PG8_MMA(1, 1, At, B1); PG8_BAR; PG8_SCHED;
.LBB0_538:
	s_ashr_i32 s73, s72, 31
	s_lshl_b64 s[6:7], s[72:73], 20
	s_add_u32 s74, s27, s6
	s_addc_u32 s75, s28, s7
	s_and_b64 s[6:7], s[4:5], exec
	s_cselect_b32 s14, s75, s91
	s_cselect_b32 s15, s74, s90
	s_ashr_i32 s71, s70, 31
	s_lshl_b64 s[6:7], s[70:71], 20
	s_add_u32 s84, s0, s6
	s_addc_u32 s85, s1, s7
	s_and_b64 s[6:7], s[4:5], exec
	s_cselect_b32 s71, s85, s89
	s_cselect_b32 s73, s84, s88
	s_add_u32 vcc_lo, s90, 0x100
	s_addc_u32 vcc_hi, s91, 0
	s_add_u32 s54, s88, 0x100
	s_addc_u32 s55, s89, 0
	s_add_u32 s88, s90, 0x80080
	s_addc_u32 s89, s91, 0
	s_mov_b32 s6, -2
	s_waitcnt vmcnt(45)
	s_waitcnt vmcnt(41)
	s_waitcnt vmcnt(39)
	s_waitcnt vmcnt(38)
	s_waitcnt vmcnt(36)
	s_waitcnt vmcnt(35)
	s_waitcnt vmcnt(32)
	ds_read_b128 v[138:141], v159
	ds_read_b128 v[164:167], v159 offset:1024
	ds_read_b128 v[168:171], v159 offset:2048
	ds_read_b128 v[172:175], v159 offset:3072
	ds_read_b128 v[176:179], v160
	ds_read_b128 v[180:183], v160 offset:1024
	ds_read_b128 v[184:187], v160 offset:2048
	ds_read_b128 v[188:191], v160 offset:3072
	s_cmp_eq_u32 s6, 28
	s_cselect_b32 s94, s15, vcc_lo
	s_cselect_b32 s95, s14, vcc_hi
	s_cselect_b32 s92, s73, s54
	s_cselect_b32 s93, s71, s55
	s_add_u32 s90, s94, 0x80
	s_addc_u32 s91, s95, 0
	ds_read_b128 v[192:195], v161
	ds_read_b128 v[196:199], v161 offset:1024
	ds_read_b128 v[200:203], v161 offset:2048
	ds_read_b128 v[204:207], v161 offset:3072
	ds_read_b128 v[208:211], v161 offset:4096
	ds_read_b128 v[212:215], v161 offset:5120
	ds_read_b128 v[216:219], v161 offset:6144
	ds_read_b128 v[220:223], v161 offset:7168
	s_mov_b32 m0, s57
	s_nop 0
	global_load_lds_dwordx4 v151, s[88:89]
	s_mov_b32 m0, s24
	s_nop 0
	global_load_lds_dwordx4 v153, s[88:89]
	s_waitcnt vmcnt(8) lgkmcnt(0)
	s_barrier
	v_mfma_i32_16x16x64_i8 v[126:129], v[138:141], v[192:195], 0
	v_mfma_i32_16x16x64_i8 v[118:121], v[168:171], v[192:195], 0
	v_mfma_i32_16x16x64_i8 v[110:113], v[138:141], v[200:203], 0
	v_mfma_i32_16x16x64_i8 v[102:105], v[168:171], v[200:203], 0
	v_mfma_i32_16x16x64_i8 v[94:97], v[138:141], v[208:211], 0
	v_mfma_i32_16x16x64_i8 v[86:89], v[168:171], v[208:211], 0
	v_mfma_i32_16x16x64_i8 v[78:81], v[138:141], v[216:219], 0
	v_mfma_i32_16x16x64_i8 v[70:73], v[168:171], v[216:219], 0
	v_mfma_i32_16x16x64_i8 v[126:129], v[164:167], v[196:199], v[126:129]
	v_mfma_i32_16x16x64_i8 v[118:121], v[172:175], v[196:199], v[118:121]
	v_mfma_i32_16x16x64_i8 v[110:113], v[164:167], v[204:207], v[110:113]
	v_mfma_i32_16x16x64_i8 v[102:105], v[172:175], v[204:207], v[102:105]
	v_mfma_i32_16x16x64_i8 v[94:97], v[164:167], v[212:215], v[94:97]
	v_mfma_i32_16x16x64_i8 v[86:89], v[172:175], v[212:215], v[86:89]
	v_mfma_i32_16x16x64_i8 v[78:81], v[164:167], v[220:223], v[78:81]
	v_mfma_i32_16x16x64_i8 v[70:73], v[172:175], v[220:223], v[70:73]
	v_mfma_i32_16x16x64_i8 v[122:125], v[176:179], v[192:195], 0
	v_mfma_i32_16x16x64_i8 v[114:117], v[184:187], v[192:195], 0
	v_mfma_i32_16x16x64_i8 v[106:109], v[176:179], v[200:203], 0
	v_mfma_i32_16x16x64_i8 v[98:101], v[184:187], v[200:203], 0
	v_mfma_i32_16x16x64_i8 v[90:93], v[176:179], v[208:211], 0
	v_mfma_i32_16x16x64_i8 v[82:85], v[184:187], v[208:211], 0
	v_mfma_i32_16x16x64_i8 v[74:77], v[176:179], v[216:219], 0
	v_mfma_i32_16x16x64_i8 v[66:69], v[184:187], v[216:219], 0
	v_mfma_i32_16x16x64_i8 v[122:125], v[180:183], v[196:199], v[122:125]
	v_mfma_i32_16x16x64_i8 v[114:117], v[188:191], v[196:199], v[114:117]
	v_mfma_i32_16x16x64_i8 v[106:109], v[180:183], v[204:207], v[106:109]
	v_mfma_i32_16x16x64_i8 v[98:101], v[188:191], v[204:207], v[98:101]
	v_mfma_i32_16x16x64_i8 v[90:93], v[180:183], v[212:215], v[90:93]
	v_mfma_i32_16x16x64_i8 v[82:85], v[188:191], v[212:215], v[82:85]
	v_mfma_i32_16x16x64_i8 v[74:77], v[180:183], v[220:223], v[74:77]
	v_mfma_i32_16x16x64_i8 v[66:69], v[188:191], v[220:223], v[66:69]
	s_barrier
	ds_read_b128 v[192:195], v161 offset:16384
	ds_read_b128 v[196:199], v161 offset:17408
	ds_read_b128 v[200:203], v161 offset:18432
	ds_read_b128 v[204:207], v161 offset:19456
	ds_read_b128 v[208:211], v161 offset:20480
	ds_read_b128 v[212:215], v161 offset:21504
	ds_read_b128 v[216:219], v161 offset:22528
	ds_read_b128 v[220:223], v161 offset:23552
	s_mov_b32 m0, s29
	s_nop 0
	global_load_lds_dwordx4 v152, s[92:93]
	s_add_u32 s10, s92, 0x80000
	s_mov_b32 m0, s30
	s_nop 0
	global_load_lds_dwordx4 v154, s[92:93]
	s_addc_u32 s11, s93, 0
	s_mov_b32 m0, s31
	s_nop 0
	global_load_lds_dwordx4 v152, s[10:11]
	s_mov_b32 m0, s33
	s_nop 0
	global_load_lds_dwordx4 v154, s[10:11]
	s_mov_b32 m0, s26
	s_nop 0
	global_load_lds_dwordx4 v151, s[94:95]
	s_mov_b32 m0, s35
	s_nop 0
	global_load_lds_dwordx4 v153, s[94:95]
	s_waitcnt vmcnt(8) lgkmcnt(0)
	s_barrier
; #define PG8_STAGE(bufoff, gbase, voff) do { if constexpr (VAR != 1 && VAR != 3) { _Pragma("unroll") for (int _i = 0; _i < 2; ++_i) \
;         asm volatile("s_mov_b32 m0, %2\n\ts_nop 0\n\tglobal_load_lds_dwordx4 %0, %1" :: "v"((voff)[_i]), "s"((const char*)(gbase)), "s"(ldsbase + (unsigned)((bufoff) + _i * 8192)) : "memory", "m0"); } } while (0)
; #define PG8_LDA(dst, b, h) do { if constexpr (VAR < 2) _Pragma("unroll") for (int m = 0; m < 4; ++m) _Pragma("unroll") for (int k = 0; k < 2; ++k) dst[m][k] = *(const LAS bf16x8*)(lds + PG8_SA(b, h) + aoff + m * 2048 + k * 1024); } while (0)
; #define PG8_LDB(dst, b, h) do { if constexpr (VAR < 2) _Pragma("unroll") for (int n = 0; n < 2; ++n) _Pragma("unroll") for (int k = 0; k < 2; ++k) dst[n][k] = *(const LAS bf16x8*)(lds + PG8_SB(b, h) + boff + n * 2048 + k * 1024); } while (0)
; #define PG8_WAIT_V(n) asm volatile("s_waitcnt vmcnt(" #n ")" ::: "memory")
; #define PG8_WAIT_L(n) asm volatile("s_waitcnt lgkmcnt(" #n ")" ::: "memory")
; #define PG8_BAR do { if constexpr (VAR != 3) __builtin_amdgcn_s_barrier(); } while (0)
; #define PG8_SCHED __builtin_amdgcn_sched_barrier(0)
;     ...
;             PG8_WAIT_V(8); PG8_WAIT_L(0); PG8_BAR; PG8_MMA(1, 0, At, B0); PG8_MMA(1, 1, At, B1); PG8_BAR; PG8_SCHED;
;             PG8_LDB(B0, 1, 0); PG8_LDB(B1, 1, 1); PG8_SCHED; PG8_LDA(At, 1, 0); PG8_STAGE(PG8_SA(0, 1), a2 + hstepA, voffA);
;             PG8_WAIT_V(8); PG8_WAIT_L(0); PG8_BAR; PG8_MMA(0, 0, At, B0); PG8_MMA(0, 1, At, B1); PG8_BAR; PG8_SCHED;
;             PG8_LDA(At, 1, 1); PG8_STAGE(PG8_SB(1, 0), b3, voffB); PG8_STAGE(PG8_SB(1, 1), b3 + hstepB, voffB); PG8_STAGE(PG8_SA(1, 0), a3, voffA);
	v_mfma_i32_16x16x64_i8 v[62:65], v[138:141], v[192:195], 0
	v_mfma_i32_16x16x64_i8 v[54:57], v[168:171], v[192:195], 0
	v_mfma_i32_16x16x64_i8 v[46:49], v[138:141], v[200:203], 0
	v_mfma_i32_16x16x64_i8 v[38:41], v[168:171], v[200:203], 0
	v_mfma_i32_16x16x64_i8 v[30:33], v[138:141], v[208:211], 0
	v_mfma_i32_16x16x64_i8 v[22:25], v[168:171], v[208:211], 0
	v_mfma_i32_16x16x64_i8 v[14:17], v[138:141], v[216:219], 0
	v_mfma_i32_16x16x64_i8 v[6:9], v[168:171], v[216:219], 0
	v_mfma_i32_16x16x64_i8 v[62:65], v[164:167], v[196:199], v[62:65]
	v_mfma_i32_16x16x64_i8 v[54:57], v[172:175], v[196:199], v[54:57]
	v_mfma_i32_16x16x64_i8 v[46:49], v[164:167], v[204:207], v[46:49]
	v_mfma_i32_16x16x64_i8 v[38:41], v[172:175], v[204:207], v[38:41]
	v_mfma_i32_16x16x64_i8 v[30:33], v[164:167], v[212:215], v[30:33]
	v_mfma_i32_16x16x64_i8 v[22:25], v[172:175], v[212:215], v[22:25]
	v_mfma_i32_16x16x64_i8 v[14:17], v[164:167], v[220:223], v[14:17]
	v_mfma_i32_16x16x64_i8 v[6:9], v[172:175], v[220:223], v[6:9]
	v_mfma_i32_16x16x64_i8 v[58:61], v[176:179], v[192:195], 0
	v_mfma_i32_16x16x64_i8 v[50:53], v[184:187], v[192:195], 0
	v_mfma_i32_16x16x64_i8 v[42:45], v[176:179], v[200:203], 0
	v_mfma_i32_16x16x64_i8 v[34:37], v[184:187], v[200:203], 0
	v_mfma_i32_16x16x64_i8 v[26:29], v[176:179], v[208:211], 0
	v_mfma_i32_16x16x64_i8 v[18:21], v[184:187], v[208:211], 0
	v_mfma_i32_16x16x64_i8 v[10:13], v[176:179], v[216:219], 0
	v_mfma_i32_16x16x64_i8 v[2:5], v[184:187], v[216:219], 0
	v_mfma_i32_16x16x64_i8 v[58:61], v[180:183], v[196:199], v[58:61]
	v_mfma_i32_16x16x64_i8 v[50:53], v[188:191], v[196:199], v[50:53]
	v_mfma_i32_16x16x64_i8 v[42:45], v[180:183], v[204:207], v[42:45]
	v_mfma_i32_16x16x64_i8 v[34:37], v[188:191], v[204:207], v[34:37]
	v_mfma_i32_16x16x64_i8 v[26:29], v[180:183], v[212:215], v[26:29]
	v_mfma_i32_16x16x64_i8 v[18:21], v[188:191], v[212:215], v[18:21]
	v_mfma_i32_16x16x64_i8 v[10:13], v[180:183], v[220:223], v[10:13]
	v_mfma_i32_16x16x64_i8 v[2:5], v[188:191], v[220:223], v[2:5]
	s_barrier
	ds_read_b128 v[138:141], v162
	ds_read_b128 v[164:167], v162 offset:1024
	ds_read_b128 v[168:171], v162 offset:2048
	ds_read_b128 v[172:175], v162 offset:3072
	ds_read_b128 v[176:179], v163
	ds_read_b128 v[180:183], v163 offset:1024
	ds_read_b128 v[184:187], v163 offset:2048
	ds_read_b128 v[188:191], v163 offset:3072
	ds_read_b128 v[192:195], v161 offset:32768
	ds_read_b128 v[196:199], v161 offset:33792
	ds_read_b128 v[200:203], v161 offset:34816
	ds_read_b128 v[204:207], v161 offset:35840
	ds_read_b128 v[208:211], v161 offset:36864
	ds_read_b128 v[212:215], v161 offset:37888
	ds_read_b128 v[216:219], v161 offset:38912
	ds_read_b128 v[220:223], v161 offset:39936
	s_add_u32 s10, s94, 0x80000
	s_addc_u32 s11, s95, 0
	s_mov_b32 m0, s62
	s_nop 0
	global_load_lds_dwordx4 v151, s[10:11]
	s_mov_b32 m0, s63
	s_nop 0
	global_load_lds_dwordx4 v153, s[10:11]
	s_waitcnt vmcnt(8) lgkmcnt(0)
	s_barrier
	v_mfma_i32_16x16x64_i8 v[126:129], v[138:141], v[192:195], v[126:129]
	v_mfma_i32_16x16x64_i8 v[118:121], v[168:171], v[192:195], v[118:121]
	v_mfma_i32_16x16x64_i8 v[110:113], v[138:141], v[200:203], v[110:113]
	v_mfma_i32_16x16x64_i8 v[102:105], v[168:171], v[200:203], v[102:105]
	v_mfma_i32_16x16x64_i8 v[94:97], v[138:141], v[208:211], v[94:97]
	v_mfma_i32_16x16x64_i8 v[86:89], v[168:171], v[208:211], v[86:89]
	v_mfma_i32_16x16x64_i8 v[78:81], v[138:141], v[216:219], v[78:81]
	v_mfma_i32_16x16x64_i8 v[70:73], v[168:171], v[216:219], v[70:73]
	v_mfma_i32_16x16x64_i8 v[126:129], v[164:167], v[196:199], v[126:129]
	v_mfma_i32_16x16x64_i8 v[118:121], v[172:175], v[196:199], v[118:121]
	v_mfma_i32_16x16x64_i8 v[110:113], v[164:167], v[204:207], v[110:113]
	v_mfma_i32_16x16x64_i8 v[102:105], v[172:175], v[204:207], v[102:105]
	v_mfma_i32_16x16x64_i8 v[94:97], v[164:167], v[212:215], v[94:97]
	v_mfma_i32_16x16x64_i8 v[86:89], v[172:175], v[212:215], v[86:89]
	v_mfma_i32_16x16x64_i8 v[78:81], v[164:167], v[220:223], v[78:81]
	v_mfma_i32_16x16x64_i8 v[70:73], v[172:175], v[220:223], v[70:73]
	v_mfma_i32_16x16x64_i8 v[122:125], v[176:179], v[192:195], v[122:125]
	v_mfma_i32_16x16x64_i8 v[114:117], v[184:187], v[192:195], v[114:117]
	v_mfma_i32_16x16x64_i8 v[106:109], v[176:179], v[200:203], v[106:109]
	v_mfma_i32_16x16x64_i8 v[98:101], v[184:187], v[200:203], v[98:101]
	v_mfma_i32_16x16x64_i8 v[90:93], v[176:179], v[208:211], v[90:93]
	v_mfma_i32_16x16x64_i8 v[82:85], v[184:187], v[208:211], v[82:85]
	v_mfma_i32_16x16x64_i8 v[74:77], v[176:179], v[216:219], v[74:77]
	v_mfma_i32_16x16x64_i8 v[66:69], v[184:187], v[216:219], v[66:69]
	v_mfma_i32_16x16x64_i8 v[122:125], v[180:183], v[196:199], v[122:125]
	v_mfma_i32_16x16x64_i8 v[114:117], v[188:191], v[196:199], v[114:117]
	v_mfma_i32_16x16x64_i8 v[106:109], v[180:183], v[204:207], v[106:109]
	v_mfma_i32_16x16x64_i8 v[98:101], v[188:191], v[204:207], v[98:101]
	v_mfma_i32_16x16x64_i8 v[90:93], v[180:183], v[212:215], v[90:93]
	v_mfma_i32_16x16x64_i8 v[82:85], v[188:191], v[212:215], v[82:85]
	v_mfma_i32_16x16x64_i8 v[74:77], v[180:183], v[220:223], v[74:77]
	v_mfma_i32_16x16x64_i8 v[66:69], v[188:191], v[220:223], v[66:69]
	s_barrier
	ds_read_b128 v[192:195], v161 offset:49152
	ds_read_b128 v[196:199], v161 offset:50176
	ds_read_b128 v[200:203], v161 offset:51200
	ds_read_b128 v[204:207], v161 offset:52224
	ds_read_b128 v[208:211], v161 offset:53248
	ds_read_b128 v[212:215], v161 offset:54272
	ds_read_b128 v[216:219], v161 offset:55296
	ds_read_b128 v[220:223], v161 offset:56320
	s_add_u32 s10, s92, 0x80
	s_addc_u32 s11, s93, 0
	s_mov_b32 m0, s87
	s_nop 0
	global_load_lds_dwordx4 v152, s[10:11]
	s_mov_b32 m0, s96
	s_nop 0
	global_load_lds_dwordx4 v154, s[10:11]
	s_add_u32 s10, s92, 0x80080
	s_addc_u32 s11, s93, 0
	s_mov_b32 m0, s53
	s_nop 0
	global_load_lds_dwordx4 v152, s[10:11]
	s_mov_b32 m0, s56
	s_nop 0
	global_load_lds_dwordx4 v154, s[10:11]
	s_mov_b32 m0, s97
	s_nop 0
	global_load_lds_dwordx4 v151, s[90:91]
	s_mov_b32 m0, s52
	s_nop 0
	global_load_lds_dwordx4 v153, s[90:91]
	s_waitcnt vmcnt(8) lgkmcnt(0)
	s_barrier
; #define PG8_STAGE(bufoff, gbase, voff) do { if constexpr (VAR != 1 && VAR != 3) { _Pragma("unroll") for (int _i = 0; _i < 2; ++_i) \
;         asm volatile("s_mov_b32 m0, %2\n\ts_nop 0\n\tglobal_load_lds_dwordx4 %0, %1" :: "v"((voff)[_i]), "s"((const char*)(gbase)), "s"(ldsbase + (unsigned)((bufoff) + _i * 8192)) : "memory", "m0"); } } while (0)
; #define PG8_LDA(dst, b, h) do { if constexpr (VAR < 2) _Pragma("unroll") for (int m = 0; m < 4; ++m) _Pragma("unroll") for (int k = 0; k < 2; ++k) dst[m][k] = *(const LAS bf16x8*)(lds + PG8_SA(b, h) + aoff + m * 2048 + k * 1024); } while (0)
; #define PG8_LDB(dst, b, h) do { if constexpr (VAR < 2) _Pragma("unroll") for (int n = 0; n < 2; ++n) _Pragma("unroll") for (int k = 0; k < 2; ++k) dst[n][k] = *(const LAS bf16x8*)(lds + PG8_SB(b, h) + boff + n * 2048 + k * 1024); } while (0)
; #define PG8_WAIT_V(n) asm volatile("s_waitcnt vmcnt(" #n ")" ::: "memory")
; #define PG8_WAIT_L(n) asm volatile("s_waitcnt lgkmcnt(" #n ")" ::: "memory")
;     ...
;         for (int t = 0; t < nt; t += 2) {
;             const bool last = (t == nt - 2);
;             const char* a1 = cA + (size_t)(t + 1) * kstep;
;             const char* a2 = last ? nA : cA + (size_t)(t + 2) * kstep; const char* b2 = last ? nB : cB + (size_t)(t + 2) * kstep;
;             const char* a3 = a2 + kstep; const char* b3 = b2 + kstep;
;             PG8_LDB(B0, 0, 0); PG8_LDB(B1, 0, 1); PG8_SCHED; PG8_LDA(At, 0, 0); PG8_STAGE(PG8_SA(1, 1), a1 + hstepA, voffA);
;             PG8_WAIT_V(8); PG8_WAIT_L(0); PG8_BAR; PG8_MMA(0, 0, At, B0); PG8_MMA(0, 1, At, B1); PG8_BAR; PG8_SCHED;
;             PG8_LDA(At, 0, 1); PG8_STAGE(PG8_SB(0, 0), b2, voffB); PG8_STAGE(PG8_SB(0, 1), b2 + hstepB, voffB); PG8_STAGE(PG8_SA(0, 0), a2, voffA);
;             PG8_WAIT_V(8); PG8_WAIT_L(0); PG8_BAR; PG8_MMA(1, 0, At, B0); PG8_MMA(1, 1, At, B1); PG8_BAR; PG8_SCHED;
;             PG8_LDB(B0, 1, 0); PG8_LDB(B1, 1, 1); PG8_SCHED; PG8_LDA(At, 1, 0); PG8_STAGE(PG8_SA(0, 1), a2 + hstepA, voffA);
;             PG8_WAIT_V(8); PG8_WAIT_L(0); PG8_BAR; PG8_MMA(0, 0, At, B0); PG8_MMA(0, 1, At, B1); PG8_BAR; PG8_SCHED;
;             PG8_LDA(At, 1, 1); PG8_STAGE(PG8_SB(1, 0), b3, voffB); PG8_STAGE(PG8_SB(1, 1), b3 + hstepB, voffB); PG8_STAGE(PG8_SA(1, 0), a3, voffA);
;             PG8_WAIT_V(8); PG8_WAIT_L(0); PG8_BAR; PG8_MMA(1, 0, At, B0); PG8_MMA(1, 1, At, B1); PG8_BAR; PG8_SCHED;
	v_mfma_i32_16x16x64_i8 v[62:65], v[138:141], v[192:195], v[62:65]
	v_mfma_i32_16x16x64_i8 v[54:57], v[168:171], v[192:195], v[54:57]
	v_mfma_i32_16x16x64_i8 v[46:49], v[138:141], v[200:203], v[46:49]
	v_mfma_i32_16x16x64_i8 v[38:41], v[168:171], v[200:203], v[38:41]
	v_mfma_i32_16x16x64_i8 v[30:33], v[138:141], v[208:211], v[30:33]
	v_mfma_i32_16x16x64_i8 v[22:25], v[168:171], v[208:211], v[22:25]
	v_mfma_i32_16x16x64_i8 v[14:17], v[138:141], v[216:219], v[14:17]
	v_mfma_i32_16x16x64_i8 v[6:9], v[168:171], v[216:219], v[6:9]
	v_mfma_i32_16x16x64_i8 v[62:65], v[164:167], v[196:199], v[62:65]
	v_mfma_i32_16x16x64_i8 v[54:57], v[172:175], v[196:199], v[54:57]
	v_mfma_i32_16x16x64_i8 v[46:49], v[164:167], v[204:207], v[46:49]
	v_mfma_i32_16x16x64_i8 v[38:41], v[172:175], v[204:207], v[38:41]
	v_mfma_i32_16x16x64_i8 v[30:33], v[164:167], v[212:215], v[30:33]
	v_mfma_i32_16x16x64_i8 v[22:25], v[172:175], v[212:215], v[22:25]
	v_mfma_i32_16x16x64_i8 v[14:17], v[164:167], v[220:223], v[14:17]
	v_mfma_i32_16x16x64_i8 v[6:9], v[172:175], v[220:223], v[6:9]
	v_mfma_i32_16x16x64_i8 v[58:61], v[176:179], v[192:195], v[58:61]
	v_mfma_i32_16x16x64_i8 v[50:53], v[184:187], v[192:195], v[50:53]
	v_mfma_i32_16x16x64_i8 v[42:45], v[176:179], v[200:203], v[42:45]
	v_mfma_i32_16x16x64_i8 v[34:37], v[184:187], v[200:203], v[34:37]
	v_mfma_i32_16x16x64_i8 v[26:29], v[176:179], v[208:211], v[26:29]
	v_mfma_i32_16x16x64_i8 v[18:21], v[184:187], v[208:211], v[18:21]
	v_mfma_i32_16x16x64_i8 v[10:13], v[176:179], v[216:219], v[10:13]
	v_mfma_i32_16x16x64_i8 v[2:5], v[184:187], v[216:219], v[2:5]
	v_mfma_i32_16x16x64_i8 v[58:61], v[180:183], v[196:199], v[58:61]
	v_mfma_i32_16x16x64_i8 v[50:53], v[188:191], v[196:199], v[50:53]
	v_mfma_i32_16x16x64_i8 v[42:45], v[180:183], v[204:207], v[42:45]
	v_mfma_i32_16x16x64_i8 v[34:37], v[188:191], v[204:207], v[34:37]
	v_mfma_i32_16x16x64_i8 v[26:29], v[180:183], v[212:215], v[26:29]
	v_mfma_i32_16x16x64_i8 v[18:21], v[188:191], v[212:215], v[18:21]
	v_mfma_i32_16x16x64_i8 v[10:13], v[180:183], v[220:223], v[10:13]
	v_mfma_i32_16x16x64_i8 v[2:5], v[188:191], v[220:223], v[2:5]
	s_barrier
	s_add_i32 s6, s6, 2
	s_add_u32 vcc_lo, vcc_lo, 0x100
	s_addc_u32 vcc_hi, vcc_hi, 0
	s_add_u32 s54, s54, 0x100
	s_addc_u32 s55, s55, 0
	s_add_u32 s88, s88, 0x100
	s_addc_u32 s89, s89, 0
	s_cmp_gt_u32 s6, 29
	s_cbranch_scc0 .LBB0_539
	s_branch .Lmy_kexit_1
.LBB0_539:
	ds_read_b128 v[138:141], v159
	ds_read_b128 v[164:167], v159 offset:1024
	ds_read_b128 v[168:171], v159 offset:2048
	ds_read_b128 v[172:175], v159 offset:3072
	ds_read_b128 v[176:179], v160
	ds_read_b128 v[180:183], v160 offset:1024
	ds_read_b128 v[184:187], v160 offset:2048
	ds_read_b128 v[188:191], v160 offset:3072
	s_cmp_eq_u32 s6, 28
	s_cselect_b32 s94, s15, vcc_lo
	s_cselect_b32 s95, s14, vcc_hi
	s_cselect_b32 s92, s73, s54
	s_cselect_b32 s93, s71, s55
	s_add_u32 s90, s94, 0x80
	s_addc_u32 s91, s95, 0
	ds_read_b128 v[192:195], v161
	ds_read_b128 v[196:199], v161 offset:1024
	ds_read_b128 v[200:203], v161 offset:2048
	ds_read_b128 v[204:207], v161 offset:3072
	ds_read_b128 v[208:211], v161 offset:4096
	ds_read_b128 v[212:215], v161 offset:5120
	ds_read_b128 v[216:219], v161 offset:6144
	ds_read_b128 v[220:223], v161 offset:7168
	s_mov_b32 m0, s57
	s_nop 0
	global_load_lds_dwordx4 v151, s[88:89]
	s_mov_b32 m0, s24
	s_nop 0
	global_load_lds_dwordx4 v153, s[88:89]
	s_waitcnt vmcnt(8) lgkmcnt(0)
	s_barrier
	v_mfma_i32_16x16x64_i8 v[126:129], v[138:141], v[192:195], v[126:129]
	v_mfma_i32_16x16x64_i8 v[118:121], v[168:171], v[192:195], v[118:121]
	v_mfma_i32_16x16x64_i8 v[110:113], v[138:141], v[200:203], v[110:113]
	v_mfma_i32_16x16x64_i8 v[102:105], v[168:171], v[200:203], v[102:105]
	v_mfma_i32_16x16x64_i8 v[94:97], v[138:141], v[208:211], v[94:97]
	v_mfma_i32_16x16x64_i8 v[86:89], v[168:171], v[208:211], v[86:89]
	v_mfma_i32_16x16x64_i8 v[78:81], v[138:141], v[216:219], v[78:81]
	v_mfma_i32_16x16x64_i8 v[70:73], v[168:171], v[216:219], v[70:73]
	v_mfma_i32_16x16x64_i8 v[126:129], v[164:167], v[196:199], v[126:129]
	v_mfma_i32_16x16x64_i8 v[118:121], v[172:175], v[196:199], v[118:121]
	v_mfma_i32_16x16x64_i8 v[110:113], v[164:167], v[204:207], v[110:113]
	v_mfma_i32_16x16x64_i8 v[102:105], v[172:175], v[204:207], v[102:105]
	v_mfma_i32_16x16x64_i8 v[94:97], v[164:167], v[212:215], v[94:97]
	v_mfma_i32_16x16x64_i8 v[86:89], v[172:175], v[212:215], v[86:89]
	v_mfma_i32_16x16x64_i8 v[78:81], v[164:167], v[220:223], v[78:81]
	v_mfma_i32_16x16x64_i8 v[70:73], v[172:175], v[220:223], v[70:73]
	v_mfma_i32_16x16x64_i8 v[122:125], v[176:179], v[192:195], v[122:125]
	v_mfma_i32_16x16x64_i8 v[114:117], v[184:187], v[192:195], v[114:117]
	v_mfma_i32_16x16x64_i8 v[106:109], v[176:179], v[200:203], v[106:109]
	v_mfma_i32_16x16x64_i8 v[98:101], v[184:187], v[200:203], v[98:101]
	v_mfma_i32_16x16x64_i8 v[90:93], v[176:179], v[208:211], v[90:93]
	v_mfma_i32_16x16x64_i8 v[82:85], v[184:187], v[208:211], v[82:85]
	v_mfma_i32_16x16x64_i8 v[74:77], v[176:179], v[216:219], v[74:77]
	v_mfma_i32_16x16x64_i8 v[66:69], v[184:187], v[216:219], v[66:69]
	v_mfma_i32_16x16x64_i8 v[122:125], v[180:183], v[196:199], v[122:125]
	v_mfma_i32_16x16x64_i8 v[114:117], v[188:191], v[196:199], v[114:117]
	v_mfma_i32_16x16x64_i8 v[106:109], v[180:183], v[204:207], v[106:109]
	v_mfma_i32_16x16x64_i8 v[98:101], v[188:191], v[204:207], v[98:101]
	v_mfma_i32_16x16x64_i8 v[90:93], v[180:183], v[212:215], v[90:93]
	v_mfma_i32_16x16x64_i8 v[82:85], v[188:191], v[212:215], v[82:85]
	v_mfma_i32_16x16x64_i8 v[74:77], v[180:183], v[220:223], v[74:77]
	v_mfma_i32_16x16x64_i8 v[66:69], v[188:191], v[220:223], v[66:69]
	s_barrier
; #define PG8_STAGE(bufoff, gbase, voff) do { if constexpr (VAR != 1 && VAR != 3) { _Pragma("unroll") for (int _i = 0; _i < 2; ++_i) \
;         asm volatile("s_mov_b32 m0, %2\n\ts_nop 0\n\tglobal_load_lds_dwordx4 %0, %1" :: "v"((voff)[_i]), "s"((const char*)(gbase)), "s"(ldsbase + (unsigned)((bufoff) + _i * 8192)) : "memory", "m0"); } } while (0)
; #define PG8_LDA(dst, b, h) do { if constexpr (VAR < 2) _Pragma("unroll") for (int m = 0; m < 4; ++m) _Pragma("unroll") for (int k = 0; k < 2; ++k) dst[m][k] = *(const LAS bf16x8*)(lds + PG8_SA(b, h) + aoff + m * 2048 + k * 1024); } while (0)
; #define PG8_LDB(dst, b, h) do { if constexpr (VAR < 2) _Pragma("unroll") for (int n = 0; n < 2; ++n) _Pragma("unroll") for (int k = 0; k < 2; ++k) dst[n][k] = *(const LAS bf16x8*)(lds + PG8_SB(b, h) + boff + n * 2048 + k * 1024); } while (0)
; #define PG8_WAIT_V(n) asm volatile("s_waitcnt vmcnt(" #n ")" ::: "memory")
; #define PG8_WAIT_L(n) asm volatile("s_waitcnt lgkmcnt(" #n ")" ::: "memory")
; #define PG8_BAR do { if constexpr (VAR != 3) __builtin_amdgcn_s_barrier(); } while (0)
; #define PG8_SCHED __builtin_amdgcn_sched_barrier(0)
;     ...
;             PG8_LDA(At, 0, 1); PG8_STAGE(PG8_SB(0, 0), b2, voffB); PG8_STAGE(PG8_SB(0, 1), b2 + hstepB, voffB); PG8_STAGE(PG8_SA(0, 0), a2, voffA);
;             PG8_WAIT_V(8); PG8_WAIT_L(0); PG8_BAR; PG8_MMA(1, 0, At, B0); PG8_MMA(1, 1, At, B1); PG8_BAR; PG8_SCHED;
;             PG8_LDB(B0, 1, 0); PG8_LDB(B1, 1, 1); PG8_SCHED; PG8_LDA(At, 1, 0); PG8_STAGE(PG8_SA(0, 1), a2 + hstepA, voffA);
;             PG8_WAIT_V(8); PG8_WAIT_L(0); PG8_BAR; PG8_MMA(0, 0, At, B0); PG8_MMA(0, 1, At, B1); PG8_BAR; PG8_SCHED;
	ds_read_b128 v[192:195], v161 offset:16384
	ds_read_b128 v[196:199], v161 offset:17408
	ds_read_b128 v[200:203], v161 offset:18432
	ds_read_b128 v[204:207], v161 offset:19456
	ds_read_b128 v[208:211], v161 offset:20480
	ds_read_b128 v[212:215], v161 offset:21504
	ds_read_b128 v[216:219], v161 offset:22528
	ds_read_b128 v[220:223], v161 offset:23552
	s_mov_b32 m0, s29
	s_nop 0
	global_load_lds_dwordx4 v152, s[92:93]
	s_add_u32 s10, s92, 0x80000
	s_mov_b32 m0, s30
	s_nop 0
	global_load_lds_dwordx4 v154, s[92:93]
	s_addc_u32 s11, s93, 0
	s_mov_b32 m0, s31
	s_nop 0
	global_load_lds_dwordx4 v152, s[10:11]
	s_mov_b32 m0, s33
	s_nop 0
	global_load_lds_dwordx4 v154, s[10:11]
	s_mov_b32 m0, s26
	s_nop 0
	global_load_lds_dwordx4 v151, s[94:95]
	s_mov_b32 m0, s35
	s_nop 0
	global_load_lds_dwordx4 v153, s[94:95]
	s_waitcnt vmcnt(8) lgkmcnt(0)
	s_barrier
	v_mfma_i32_16x16x64_i8 v[62:65], v[138:141], v[192:195], v[62:65]
	v_mfma_i32_16x16x64_i8 v[54:57], v[168:171], v[192:195], v[54:57]
	v_mfma_i32_16x16x64_i8 v[46:49], v[138:141], v[200:203], v[46:49]
	v_mfma_i32_16x16x64_i8 v[38:41], v[168:171], v[200:203], v[38:41]
	v_mfma_i32_16x16x64_i8 v[30:33], v[138:141], v[208:211], v[30:33]
	v_mfma_i32_16x16x64_i8 v[22:25], v[168:171], v[208:211], v[22:25]
	v_mfma_i32_16x16x64_i8 v[14:17], v[138:141], v[216:219], v[14:17]
	v_mfma_i32_16x16x64_i8 v[6:9], v[168:171], v[216:219], v[6:9]
	v_mfma_i32_16x16x64_i8 v[62:65], v[164:167], v[196:199], v[62:65]
	v_mfma_i32_16x16x64_i8 v[54:57], v[172:175], v[196:199], v[54:57]
	v_mfma_i32_16x16x64_i8 v[46:49], v[164:167], v[204:207], v[46:49]
	v_mfma_i32_16x16x64_i8 v[38:41], v[172:175], v[204:207], v[38:41]
	v_mfma_i32_16x16x64_i8 v[30:33], v[164:167], v[212:215], v[30:33]
	v_mfma_i32_16x16x64_i8 v[22:25], v[172:175], v[212:215], v[22:25]
	v_mfma_i32_16x16x64_i8 v[14:17], v[164:167], v[220:223], v[14:17]
	v_mfma_i32_16x16x64_i8 v[6:9], v[172:175], v[220:223], v[6:9]
	v_mfma_i32_16x16x64_i8 v[58:61], v[176:179], v[192:195], v[58:61]
	v_mfma_i32_16x16x64_i8 v[50:53], v[184:187], v[192:195], v[50:53]
	v_mfma_i32_16x16x64_i8 v[42:45], v[176:179], v[200:203], v[42:45]
	v_mfma_i32_16x16x64_i8 v[34:37], v[184:187], v[200:203], v[34:37]
	v_mfma_i32_16x16x64_i8 v[26:29], v[176:179], v[208:211], v[26:29]
	v_mfma_i32_16x16x64_i8 v[18:21], v[184:187], v[208:211], v[18:21]
	v_mfma_i32_16x16x64_i8 v[10:13], v[176:179], v[216:219], v[10:13]
	v_mfma_i32_16x16x64_i8 v[2:5], v[184:187], v[216:219], v[2:5]
	v_mfma_i32_16x16x64_i8 v[58:61], v[180:183], v[196:199], v[58:61]
	v_mfma_i32_16x16x64_i8 v[50:53], v[188:191], v[196:199], v[50:53]
	v_mfma_i32_16x16x64_i8 v[42:45], v[180:183], v[204:207], v[42:45]
	v_mfma_i32_16x16x64_i8 v[34:37], v[188:191], v[204:207], v[34:37]
	v_mfma_i32_16x16x64_i8 v[26:29], v[180:183], v[212:215], v[26:29]
	v_mfma_i32_16x16x64_i8 v[18:21], v[188:191], v[212:215], v[18:21]
	v_mfma_i32_16x16x64_i8 v[10:13], v[180:183], v[220:223], v[10:13]
	v_mfma_i32_16x16x64_i8 v[2:5], v[188:191], v[220:223], v[2:5]
	s_barrier
	ds_read_b128 v[138:141], v162
	ds_read_b128 v[164:167], v162 offset:1024
	ds_read_b128 v[168:171], v162 offset:2048
	ds_read_b128 v[172:175], v162 offset:3072
	ds_read_b128 v[176:179], v163
	ds_read_b128 v[180:183], v163 offset:1024
	ds_read_b128 v[184:187], v163 offset:2048
	ds_read_b128 v[188:191], v163 offset:3072
	ds_read_b128 v[192:195], v161 offset:32768
	ds_read_b128 v[196:199], v161 offset:33792
	ds_read_b128 v[200:203], v161 offset:34816
	ds_read_b128 v[204:207], v161 offset:35840
	ds_read_b128 v[208:211], v161 offset:36864
	ds_read_b128 v[212:215], v161 offset:37888
	ds_read_b128 v[216:219], v161 offset:38912
	ds_read_b128 v[220:223], v161 offset:39936
	s_add_u32 s10, s94, 0x80000
	s_addc_u32 s11, s95, 0
	s_mov_b32 m0, s62
	s_nop 0
	global_load_lds_dwordx4 v151, s[10:11]
	s_mov_b32 m0, s63
	s_nop 0
	global_load_lds_dwordx4 v153, s[10:11]
	s_waitcnt vmcnt(8) lgkmcnt(0)
	s_barrier
; #define PG8_STAGE(bufoff, gbase, voff) do { if constexpr (VAR != 1 && VAR != 3) { _Pragma("unroll") for (int _i = 0; _i < 2; ++_i) \
;         asm volatile("s_mov_b32 m0, %2\n\ts_nop 0\n\tglobal_load_lds_dwordx4 %0, %1" :: "v"((voff)[_i]), "s"((const char*)(gbase)), "s"(ldsbase + (unsigned)((bufoff) + _i * 8192)) : "memory", "m0"); } } while (0)
; #define PG8_LDA(dst, b, h) do { if constexpr (VAR < 2) _Pragma("unroll") for (int m = 0; m < 4; ++m) _Pragma("unroll") for (int k = 0; k < 2; ++k) dst[m][k] = *(const LAS bf16x8*)(lds + PG8_SA(b, h) + aoff + m * 2048 + k * 1024); } while (0)
; #define PG8_WAIT_V(n) asm volatile("s_waitcnt vmcnt(" #n ")" ::: "memory")
; #define PG8_WAIT_L(n) asm volatile("s_waitcnt lgkmcnt(" #n ")" ::: "memory")
; #define PG8_BAR do { if constexpr (VAR != 3) __builtin_amdgcn_s_barrier(); } while (0)
; #define PG8_SCHED __builtin_amdgcn_sched_barrier(0)
;     ...
;             PG8_WAIT_V(8); PG8_WAIT_L(0); PG8_BAR; PG8_MMA(0, 0, At, B0); PG8_MMA(0, 1, At, B1); PG8_BAR; PG8_SCHED;
;             PG8_LDA(At, 1, 1); PG8_STAGE(PG8_SB(1, 0), b3, voffB); PG8_STAGE(PG8_SB(1, 1), b3 + hstepB, voffB); PG8_STAGE(PG8_SA(1, 0), a3, voffA);
;             PG8_WAIT_V(8); PG8_WAIT_L(0); PG8_BAR; PG8_MMA(1, 0, At, B0); PG8_MMA(1, 1, At, B1); PG8_BAR; PG8_SCHED;
	v_mfma_i32_16x16x64_i8 v[126:129], v[138:141], v[192:195], v[126:129]
	v_mfma_i32_16x16x64_i8 v[118:121], v[168:171], v[192:195], v[118:121]
	v_mfma_i32_16x16x64_i8 v[110:113], v[138:141], v[200:203], v[110:113]
	v_mfma_i32_16x16x64_i8 v[102:105], v[168:171], v[200:203], v[102:105]
	v_mfma_i32_16x16x64_i8 v[94:97], v[138:141], v[208:211], v[94:97]
	v_mfma_i32_16x16x64_i8 v[86:89], v[168:171], v[208:211], v[86:89]
	v_mfma_i32_16x16x64_i8 v[78:81], v[138:141], v[216:219], v[78:81]
	v_mfma_i32_16x16x64_i8 v[70:73], v[168:171], v[216:219], v[70:73]
	v_mfma_i32_16x16x64_i8 v[126:129], v[164:167], v[196:199], v[126:129]
	v_mfma_i32_16x16x64_i8 v[118:121], v[172:175], v[196:199], v[118:121]
	v_mfma_i32_16x16x64_i8 v[110:113], v[164:167], v[204:207], v[110:113]
	v_mfma_i32_16x16x64_i8 v[102:105], v[172:175], v[204:207], v[102:105]
	v_mfma_i32_16x16x64_i8 v[94:97], v[164:167], v[212:215], v[94:97]
	v_mfma_i32_16x16x64_i8 v[86:89], v[172:175], v[212:215], v[86:89]
	v_mfma_i32_16x16x64_i8 v[78:81], v[164:167], v[220:223], v[78:81]
	v_mfma_i32_16x16x64_i8 v[70:73], v[172:175], v[220:223], v[70:73]
	v_mfma_i32_16x16x64_i8 v[122:125], v[176:179], v[192:195], v[122:125]
	v_mfma_i32_16x16x64_i8 v[114:117], v[184:187], v[192:195], v[114:117]
	v_mfma_i32_16x16x64_i8 v[106:109], v[176:179], v[200:203], v[106:109]
	v_mfma_i32_16x16x64_i8 v[98:101], v[184:187], v[200:203], v[98:101]
	v_mfma_i32_16x16x64_i8 v[90:93], v[176:179], v[208:211], v[90:93]
	v_mfma_i32_16x16x64_i8 v[82:85], v[184:187], v[208:211], v[82:85]
	v_mfma_i32_16x16x64_i8 v[74:77], v[176:179], v[216:219], v[74:77]
	v_mfma_i32_16x16x64_i8 v[66:69], v[184:187], v[216:219], v[66:69]
	v_mfma_i32_16x16x64_i8 v[122:125], v[180:183], v[196:199], v[122:125]
	v_mfma_i32_16x16x64_i8 v[114:117], v[188:191], v[196:199], v[114:117]
	v_mfma_i32_16x16x64_i8 v[106:109], v[180:183], v[204:207], v[106:109]
	v_mfma_i32_16x16x64_i8 v[98:101], v[188:191], v[204:207], v[98:101]
	v_mfma_i32_16x16x64_i8 v[90:93], v[180:183], v[212:215], v[90:93]
	v_mfma_i32_16x16x64_i8 v[82:85], v[188:191], v[212:215], v[82:85]
	v_mfma_i32_16x16x64_i8 v[74:77], v[180:183], v[220:223], v[74:77]
	v_mfma_i32_16x16x64_i8 v[66:69], v[188:191], v[220:223], v[66:69]
	s_barrier
	ds_read_b128 v[192:195], v161 offset:49152
	ds_read_b128 v[196:199], v161 offset:50176
	ds_read_b128 v[200:203], v161 offset:51200
	ds_read_b128 v[204:207], v161 offset:52224
	ds_read_b128 v[208:211], v161 offset:53248
	ds_read_b128 v[212:215], v161 offset:54272
	ds_read_b128 v[216:219], v161 offset:55296
	ds_read_b128 v[220:223], v161 offset:56320
	s_add_u32 s10, s92, 0x80
	s_addc_u32 s11, s93, 0
	s_mov_b32 m0, s87
	s_nop 0
	global_load_lds_dwordx4 v152, s[10:11]
	s_mov_b32 m0, s96
	s_nop 0
	global_load_lds_dwordx4 v154, s[10:11]
	s_add_u32 s10, s92, 0x80080
	s_addc_u32 s11, s93, 0
	s_mov_b32 m0, s53
	s_nop 0
	global_load_lds_dwordx4 v152, s[10:11]
	s_mov_b32 m0, s56
	s_nop 0
	global_load_lds_dwordx4 v154, s[10:11]
	s_mov_b32 m0, s97
	s_nop 0
	global_load_lds_dwordx4 v151, s[90:91]
	s_mov_b32 m0, s52
	s_nop 0
	global_load_lds_dwordx4 v153, s[90:91]
	s_waitcnt vmcnt(8) lgkmcnt(0)
	s_barrier
	v_mfma_i32_16x16x64_i8 v[62:65], v[138:141], v[192:195], v[62:65]
	v_mfma_i32_16x16x64_i8 v[54:57], v[168:171], v[192:195], v[54:57]
	v_mfma_i32_16x16x64_i8 v[46:49], v[138:141], v[200:203], v[46:49]
	v_mfma_i32_16x16x64_i8 v[38:41], v[168:171], v[200:203], v[38:41]
	v_mfma_i32_16x16x64_i8 v[30:33], v[138:141], v[208:211], v[30:33]
	v_mfma_i32_16x16x64_i8 v[22:25], v[168:171], v[208:211], v[22:25]
	v_mfma_i32_16x16x64_i8 v[14:17], v[138:141], v[216:219], v[14:17]
	v_mfma_i32_16x16x64_i8 v[6:9], v[168:171], v[216:219], v[6:9]
	v_mfma_i32_16x16x64_i8 v[62:65], v[164:167], v[196:199], v[62:65]
	v_mfma_i32_16x16x64_i8 v[54:57], v[172:175], v[196:199], v[54:57]
	v_mfma_i32_16x16x64_i8 v[46:49], v[164:167], v[204:207], v[46:49]
	v_mfma_i32_16x16x64_i8 v[38:41], v[172:175], v[204:207], v[38:41]
	v_mfma_i32_16x16x64_i8 v[30:33], v[164:167], v[212:215], v[30:33]
	v_mfma_i32_16x16x64_i8 v[22:25], v[172:175], v[212:215], v[22:25]
	v_mfma_i32_16x16x64_i8 v[14:17], v[164:167], v[220:223], v[14:17]
	v_mfma_i32_16x16x64_i8 v[6:9], v[172:175], v[220:223], v[6:9]
	v_mfma_i32_16x16x64_i8 v[58:61], v[176:179], v[192:195], v[58:61]
	v_mfma_i32_16x16x64_i8 v[50:53], v[184:187], v[192:195], v[50:53]
	v_mfma_i32_16x16x64_i8 v[42:45], v[176:179], v[200:203], v[42:45]
	v_mfma_i32_16x16x64_i8 v[34:37], v[184:187], v[200:203], v[34:37]
	v_mfma_i32_16x16x64_i8 v[26:29], v[176:179], v[208:211], v[26:29]
	v_mfma_i32_16x16x64_i8 v[18:21], v[184:187], v[208:211], v[18:21]
	v_mfma_i32_16x16x64_i8 v[10:13], v[176:179], v[216:219], v[10:13]
	v_mfma_i32_16x16x64_i8 v[2:5], v[184:187], v[216:219], v[2:5]
	v_mfma_i32_16x16x64_i8 v[58:61], v[180:183], v[196:199], v[58:61]
	v_mfma_i32_16x16x64_i8 v[50:53], v[188:191], v[196:199], v[50:53]
	v_mfma_i32_16x16x64_i8 v[42:45], v[180:183], v[204:207], v[42:45]
	v_mfma_i32_16x16x64_i8 v[34:37], v[188:191], v[204:207], v[34:37]
	v_mfma_i32_16x16x64_i8 v[26:29], v[180:183], v[212:215], v[26:29]
	v_mfma_i32_16x16x64_i8 v[18:21], v[188:191], v[212:215], v[18:21]
	v_mfma_i32_16x16x64_i8 v[10:13], v[180:183], v[220:223], v[10:13]
	v_mfma_i32_16x16x64_i8 v[2:5], v[188:191], v[220:223], v[2:5]
	s_barrier
	s_add_i32 s6, s6, 2
	s_add_u32 vcc_lo, vcc_lo, 0x100
	s_addc_u32 vcc_hi, vcc_hi, 0
	s_add_u32 s54, s54, 0x100
	s_addc_u32 s55, s55, 0
	s_add_u32 s88, s88, 0x100
	s_addc_u32 s89, s89, 0
	s_cmp_gt_u32 s6, 29
	s_cbranch_scc0 .LBB0_539

; __device__ __forceinline__ const char* unitA(const Gemm& g, const Unit& u) { return (const char*)(g.A + (size_t)(u.z / g.zdiv) * g.sAhi + (size_t)(u.z % g.zdiv) * g.sAlo + (size_t)u.pm * BM * g.lda); }
; __device__ __forceinline__ const char* unitB(const Gemm& g, const Unit& u) { return (const char*)(g.Bt + (size_t)(u.z / g.zdiv) * g.sBhi + (size_t)(u.z % g.zdiv) * g.sBlo + (size_t)(u.pm / g.bdiv) * g.sBpm + (size_t)u.pn * BM * g.ldb); }
; #define PG8_STAGE(bufoff, gbase, voff) do { if constexpr (VAR != 1 && VAR != 3) { _Pragma("unroll") for (int _i = 0; _i < 2; ++_i) \
;         asm volatile("s_mov_b32 m0, %2\n\ts_nop 0\n\tglobal_load_lds_dwordx4 %0, %1" :: "v"((voff)[_i]), "s"((const char*)(gbase)), "s"(ldsbase + (unsigned)((bufoff) + _i * 8192)) : "memory", "m0"); } } while (0)
; #define PG8_LDA(dst, b, h) do { if constexpr (VAR < 2) _Pragma("unroll") for (int m = 0; m < 4; ++m) _Pragma("unroll") for (int k = 0; k < 2; ++k) dst[m][k] = *(const LAS bf16x8*)(lds + PG8_SA(b, h) + aoff + m * 2048 + k * 1024); } while (0)
; #define PG8_LDB(dst, b, h) do { if constexpr (VAR < 2) _Pragma("unroll") for (int n = 0; n < 2; ++n) _Pragma("unroll") for (int k = 0; k < 2; ++k) dst[n][k] = *(const LAS bf16x8*)(lds + PG8_SB(b, h) + boff + n * 2048 + k * 1024); } while (0)
; #define PG8_WAIT_V(n) asm volatile("s_waitcnt vmcnt(" #n ")" ::: "memory")
;     ...
;         const bool has_next = S.next(ui + 1, nxt);
;         const char* nA = has_next ? unitA(g, nxt) : cA; const char* nB = has_next ? unitB(g, nxt) : cB;
;         for (int t = 0; t < nt; t += 2) {
;             const bool last = (t == nt - 2);
;             const char* a1 = cA + (size_t)(t + 1) * kstep;
;             const char* a2 = last ? nA : cA + (size_t)(t + 2) * kstep; const char* b2 = last ? nB : cB + (size_t)(t + 2) * kstep;
;             const char* a3 = a2 + kstep; const char* b3 = b2 + kstep;
;             PG8_LDB(B0, 0, 0); PG8_LDB(B1, 0, 1); PG8_SCHED; PG8_LDA(At, 0, 0); PG8_STAGE(PG8_SA(1, 1), a1 + hstepA, voffA);
;             PG8_WAIT_V(8); PG8_WAIT_L(0); PG8_BAR; PG8_MMA(0, 0, At, B0); PG8_MMA(0, 1, At, B1); PG8_BAR; PG8_SCHED;
;             PG8_LDA(At, 0, 1); PG8_STAGE(PG8_SB(0, 0), b2, voffB); PG8_STAGE(PG8_SB(0, 1), b2 + hstepB, voffB); PG8_STAGE(PG8_SA(0, 0), a2, voffA);
;             PG8_WAIT_V(8); PG8_WAIT_L(0); PG8_BAR; PG8_MMA(1, 0, At, B0); PG8_MMA(1, 1, At, B1); PG8_BAR; PG8_SCHED;
.LBB0_560:
	s_ashr_i32 s65, s64, 31
	s_lshl_b64 s[6:7], s[64:65], 21
	s_add_u32 s66, s12, s6
	s_addc_u32 s67, s13, s7
	s_and_b64 s[6:7], s[2:3], exec
	s_cselect_b32 s1, s67, s73
	s_cselect_b32 s14, s66, s72
	s_ashr_i32 s61, s60, 31
	s_lshl_b64 s[6:7], s[60:61], 21
	s_add_u32 s68, s26, s6
	s_addc_u32 s69, s27, s7
	s_and_b64 s[6:7], s[2:3], exec
	s_cselect_b32 s15, s69, s71
	s_cselect_b32 s61, s68, s70
	s_add_u32 s65, s72, 0x100
	s_addc_u32 s92, s73, 0
	s_add_u32 s93, s70, 0x100
	s_addc_u32 s94, s71, 0
	s_add_u32 s70, s72, 0x100080
	s_addc_u32 s71, s73, 0
	s_mov_b32 s6, -2
	ds_read_b128 v[136:139], v152
	ds_read_b128 v[140:143], v152 offset:1024
	ds_read_b128 v[158:161], v152 offset:2048
	ds_read_b128 v[162:165], v152 offset:3072
	ds_read_b128 v[166:169], v153
	ds_read_b128 v[170:173], v153 offset:1024
	ds_read_b128 v[174:177], v153 offset:2048
	ds_read_b128 v[178:181], v153 offset:3072
	s_cmp_eq_u32 s6, 60
	s_cselect_b32 s84, s14, s65
	s_cselect_b32 s85, s1, s92
	s_cselect_b32 s74, s61, s93
	s_cselect_b32 s75, s15, s94
	s_add_u32 s72, s84, 0x80
	s_addc_u32 s73, s85, 0
	ds_read_b128 v[182:185], v154
	ds_read_b128 v[186:189], v154 offset:1024
	ds_read_b128 v[190:193], v154 offset:2048
	ds_read_b128 v[194:197], v154 offset:3072
	ds_read_b128 v[198:201], v154 offset:4096
	ds_read_b128 v[202:205], v154 offset:5120
	ds_read_b128 v[206:209], v154 offset:6144
	ds_read_b128 v[210:213], v154 offset:7168
	s_mov_b32 m0, s86
	s_nop 0
	global_load_lds_dwordx4 v1, s[70:71]
	s_mov_b32 m0, s87
	s_nop 0
	global_load_lds_dwordx4 v147, s[70:71]
	s_waitcnt vmcnt(8) lgkmcnt(0)
	s_barrier
	v_mfma_f32_16x16x32_bf16 v[126:129], v[136:139], v[182:185], 0
	v_mfma_f32_16x16x32_bf16 v[118:121], v[158:161], v[182:185], 0
	v_mfma_f32_16x16x32_bf16 v[110:113], v[136:139], v[190:193], 0
	v_mfma_f32_16x16x32_bf16 v[102:105], v[158:161], v[190:193], 0
	v_mfma_f32_16x16x32_bf16 v[94:97], v[136:139], v[198:201], 0
	v_mfma_f32_16x16x32_bf16 v[86:89], v[158:161], v[198:201], 0
	v_mfma_f32_16x16x32_bf16 v[78:81], v[136:139], v[206:209], 0
	v_mfma_f32_16x16x32_bf16 v[70:73], v[158:161], v[206:209], 0
	v_mfma_f32_16x16x32_bf16 v[126:129], v[140:143], v[186:189], v[126:129]
	v_mfma_f32_16x16x32_bf16 v[118:121], v[162:165], v[186:189], v[118:121]
	v_mfma_f32_16x16x32_bf16 v[110:113], v[140:143], v[194:197], v[110:113]
	v_mfma_f32_16x16x32_bf16 v[102:105], v[162:165], v[194:197], v[102:105]
	v_mfma_f32_16x16x32_bf16 v[94:97], v[140:143], v[202:205], v[94:97]
	v_mfma_f32_16x16x32_bf16 v[86:89], v[162:165], v[202:205], v[86:89]
	v_mfma_f32_16x16x32_bf16 v[78:81], v[140:143], v[210:213], v[78:81]
	v_mfma_f32_16x16x32_bf16 v[70:73], v[162:165], v[210:213], v[70:73]
	v_mfma_f32_16x16x32_bf16 v[122:125], v[166:169], v[182:185], 0
	v_mfma_f32_16x16x32_bf16 v[114:117], v[174:177], v[182:185], 0
	v_mfma_f32_16x16x32_bf16 v[106:109], v[166:169], v[190:193], 0
	v_mfma_f32_16x16x32_bf16 v[98:101], v[174:177], v[190:193], 0
	v_mfma_f32_16x16x32_bf16 v[90:93], v[166:169], v[198:201], 0
	v_mfma_f32_16x16x32_bf16 v[82:85], v[174:177], v[198:201], 0
	v_mfma_f32_16x16x32_bf16 v[74:77], v[166:169], v[206:209], 0
	v_mfma_f32_16x16x32_bf16 v[66:69], v[174:177], v[206:209], 0
	v_mfma_f32_16x16x32_bf16 v[122:125], v[170:173], v[186:189], v[122:125]
	v_mfma_f32_16x16x32_bf16 v[114:117], v[178:181], v[186:189], v[114:117]
	v_mfma_f32_16x16x32_bf16 v[106:109], v[170:173], v[194:197], v[106:109]
	v_mfma_f32_16x16x32_bf16 v[98:101], v[178:181], v[194:197], v[98:101]
	v_mfma_f32_16x16x32_bf16 v[90:93], v[170:173], v[202:205], v[90:93]
	v_mfma_f32_16x16x32_bf16 v[82:85], v[178:181], v[202:205], v[82:85]
	v_mfma_f32_16x16x32_bf16 v[74:77], v[170:173], v[210:213], v[74:77]
	v_mfma_f32_16x16x32_bf16 v[66:69], v[178:181], v[210:213], v[66:69]
	s_barrier
	ds_read_b128 v[182:185], v154 offset:16384
	ds_read_b128 v[186:189], v154 offset:17408
	ds_read_b128 v[190:193], v154 offset:18432
	ds_read_b128 v[194:197], v154 offset:19456
	ds_read_b128 v[198:201], v154 offset:20480
	ds_read_b128 v[202:205], v154 offset:21504
	ds_read_b128 v[206:209], v154 offset:22528
	ds_read_b128 v[210:213], v154 offset:23552
	s_mov_b32 m0, s21
	s_nop 0
	global_load_lds_dwordx4 v146, s[74:75]
	s_add_u32 s10, s74, 0x100000
	s_mov_b32 m0, s23
	s_nop 0
	global_load_lds_dwordx4 v148, s[74:75]
	s_addc_u32 s11, s75, 0
	s_mov_b32 m0, s29
	s_nop 0
	global_load_lds_dwordx4 v146, s[10:11]
	s_mov_b32 m0, s30
	s_nop 0
	global_load_lds_dwordx4 v148, s[10:11]
	s_mov_b32 m0, s25
	s_nop 0
	global_load_lds_dwordx4 v1, s[84:85]
	s_mov_b32 m0, s31
	s_nop 0
	global_load_lds_dwordx4 v147, s[84:85]
	s_waitcnt vmcnt(8) lgkmcnt(0)
	s_barrier
; #define PG8_STAGE(bufoff, gbase, voff) do { if constexpr (VAR != 1 && VAR != 3) { _Pragma("unroll") for (int _i = 0; _i < 2; ++_i) \
;         asm volatile("s_mov_b32 m0, %2\n\ts_nop 0\n\tglobal_load_lds_dwordx4 %0, %1" :: "v"((voff)[_i]), "s"((const char*)(gbase)), "s"(ldsbase + (unsigned)((bufoff) + _i * 8192)) : "memory", "m0"); } } while (0)
; #define PG8_LDA(dst, b, h) do { if constexpr (VAR < 2) _Pragma("unroll") for (int m = 0; m < 4; ++m) _Pragma("unroll") for (int k = 0; k < 2; ++k) dst[m][k] = *(const LAS bf16x8*)(lds + PG8_SA(b, h) + aoff + m * 2048 + k * 1024); } while (0)
; #define PG8_LDB(dst, b, h) do { if constexpr (VAR < 2) _Pragma("unroll") for (int n = 0; n < 2; ++n) _Pragma("unroll") for (int k = 0; k < 2; ++k) dst[n][k] = *(const LAS bf16x8*)(lds + PG8_SB(b, h) + boff + n * 2048 + k * 1024); } while (0)
; #define PG8_WAIT_V(n) asm volatile("s_waitcnt vmcnt(" #n ")" ::: "memory")
; #define PG8_WAIT_L(n) asm volatile("s_waitcnt lgkmcnt(" #n ")" ::: "memory")
; #define PG8_BAR do { if constexpr (VAR != 3) __builtin_amdgcn_s_barrier(); } while (0)
; #define PG8_SCHED __builtin_amdgcn_sched_barrier(0)
;     ...
;             PG8_WAIT_V(8); PG8_WAIT_L(0); PG8_BAR; PG8_MMA(1, 0, At, B0); PG8_MMA(1, 1, At, B1); PG8_BAR; PG8_SCHED;
;             PG8_LDB(B0, 1, 0); PG8_LDB(B1, 1, 1); PG8_SCHED; PG8_LDA(At, 1, 0); PG8_STAGE(PG8_SA(0, 1), a2 + hstepA, voffA);
;             PG8_WAIT_V(8); PG8_WAIT_L(0); PG8_BAR; PG8_MMA(0, 0, At, B0); PG8_MMA(0, 1, At, B1); PG8_BAR; PG8_SCHED;
	v_mfma_f32_16x16x32_bf16 v[62:65], v[136:139], v[182:185], 0
	v_mfma_f32_16x16x32_bf16 v[54:57], v[158:161], v[182:185], 0
	v_mfma_f32_16x16x32_bf16 v[46:49], v[136:139], v[190:193], 0
	v_mfma_f32_16x16x32_bf16 v[38:41], v[158:161], v[190:193], 0
	v_mfma_f32_16x16x32_bf16 v[30:33], v[136:139], v[198:201], 0
	v_mfma_f32_16x16x32_bf16 v[22:25], v[158:161], v[198:201], 0
	v_mfma_f32_16x16x32_bf16 v[14:17], v[136:139], v[206:209], 0
	v_mfma_f32_16x16x32_bf16 v[6:9], v[158:161], v[206:209], 0
	v_mfma_f32_16x16x32_bf16 v[62:65], v[140:143], v[186:189], v[62:65]
	v_mfma_f32_16x16x32_bf16 v[54:57], v[162:165], v[186:189], v[54:57]
	v_mfma_f32_16x16x32_bf16 v[46:49], v[140:143], v[194:197], v[46:49]
	v_mfma_f32_16x16x32_bf16 v[38:41], v[162:165], v[194:197], v[38:41]
	v_mfma_f32_16x16x32_bf16 v[30:33], v[140:143], v[202:205], v[30:33]
	v_mfma_f32_16x16x32_bf16 v[22:25], v[162:165], v[202:205], v[22:25]
	v_mfma_f32_16x16x32_bf16 v[14:17], v[140:143], v[210:213], v[14:17]
	v_mfma_f32_16x16x32_bf16 v[6:9], v[162:165], v[210:213], v[6:9]
	v_mfma_f32_16x16x32_bf16 v[58:61], v[166:169], v[182:185], 0
	v_mfma_f32_16x16x32_bf16 v[50:53], v[174:177], v[182:185], 0
	v_mfma_f32_16x16x32_bf16 v[42:45], v[166:169], v[190:193], 0
	v_mfma_f32_16x16x32_bf16 v[34:37], v[174:177], v[190:193], 0
	v_mfma_f32_16x16x32_bf16 v[26:29], v[166:169], v[198:201], 0
	v_mfma_f32_16x16x32_bf16 v[18:21], v[174:177], v[198:201], 0
	v_mfma_f32_16x16x32_bf16 v[10:13], v[166:169], v[206:209], 0
	v_mfma_f32_16x16x32_bf16 v[2:5], v[174:177], v[206:209], 0
	v_mfma_f32_16x16x32_bf16 v[58:61], v[170:173], v[186:189], v[58:61]
	v_mfma_f32_16x16x32_bf16 v[50:53], v[178:181], v[186:189], v[50:53]
	v_mfma_f32_16x16x32_bf16 v[42:45], v[170:173], v[194:197], v[42:45]
	v_mfma_f32_16x16x32_bf16 v[34:37], v[178:181], v[194:197], v[34:37]
	v_mfma_f32_16x16x32_bf16 v[26:29], v[170:173], v[202:205], v[26:29]
	v_mfma_f32_16x16x32_bf16 v[18:21], v[178:181], v[202:205], v[18:21]
	v_mfma_f32_16x16x32_bf16 v[10:13], v[170:173], v[210:213], v[10:13]
	v_mfma_f32_16x16x32_bf16 v[2:5], v[178:181], v[210:213], v[2:5]
	s_barrier
	ds_read_b128 v[136:139], v155
	ds_read_b128 v[140:143], v155 offset:1024
	ds_read_b128 v[158:161], v155 offset:2048
	ds_read_b128 v[162:165], v155 offset:3072
	ds_read_b128 v[166:169], v156
	ds_read_b128 v[170:173], v156 offset:1024
	ds_read_b128 v[174:177], v156 offset:2048
	ds_read_b128 v[178:181], v156 offset:3072
	ds_read_b128 v[182:185], v154 offset:32768
	ds_read_b128 v[186:189], v154 offset:33792
	ds_read_b128 v[190:193], v154 offset:34816
	ds_read_b128 v[194:197], v154 offset:35840
	ds_read_b128 v[198:201], v154 offset:36864
	ds_read_b128 v[202:205], v154 offset:37888
	ds_read_b128 v[206:209], v154 offset:38912
	ds_read_b128 v[210:213], v154 offset:39936
	s_add_u32 s10, s84, 0x100000
	s_addc_u32 s11, s85, 0
	s_mov_b32 m0, s33
	s_nop 0
	global_load_lds_dwordx4 v1, s[10:11]
	s_mov_b32 m0, s35
	s_nop 0
	global_load_lds_dwordx4 v147, s[10:11]
	s_waitcnt vmcnt(8) lgkmcnt(0)
	s_barrier
	v_mfma_f32_16x16x32_bf16 v[126:129], v[136:139], v[182:185], v[126:129]
	v_mfma_f32_16x16x32_bf16 v[118:121], v[158:161], v[182:185], v[118:121]
	v_mfma_f32_16x16x32_bf16 v[110:113], v[136:139], v[190:193], v[110:113]
	v_mfma_f32_16x16x32_bf16 v[102:105], v[158:161], v[190:193], v[102:105]
	v_mfma_f32_16x16x32_bf16 v[94:97], v[136:139], v[198:201], v[94:97]
	v_mfma_f32_16x16x32_bf16 v[86:89], v[158:161], v[198:201], v[86:89]
	v_mfma_f32_16x16x32_bf16 v[78:81], v[136:139], v[206:209], v[78:81]
	v_mfma_f32_16x16x32_bf16 v[70:73], v[158:161], v[206:209], v[70:73]
	v_mfma_f32_16x16x32_bf16 v[126:129], v[140:143], v[186:189], v[126:129]
	v_mfma_f32_16x16x32_bf16 v[118:121], v[162:165], v[186:189], v[118:121]
	v_mfma_f32_16x16x32_bf16 v[110:113], v[140:143], v[194:197], v[110:113]
	v_mfma_f32_16x16x32_bf16 v[102:105], v[162:165], v[194:197], v[102:105]
	v_mfma_f32_16x16x32_bf16 v[94:97], v[140:143], v[202:205], v[94:97]
	v_mfma_f32_16x16x32_bf16 v[86:89], v[162:165], v[202:205], v[86:89]
	v_mfma_f32_16x16x32_bf16 v[78:81], v[140:143], v[210:213], v[78:81]
	v_mfma_f32_16x16x32_bf16 v[70:73], v[162:165], v[210:213], v[70:73]
	v_mfma_f32_16x16x32_bf16 v[122:125], v[166:169], v[182:185], v[122:125]
	v_mfma_f32_16x16x32_bf16 v[114:117], v[174:177], v[182:185], v[114:117]
	v_mfma_f32_16x16x32_bf16 v[106:109], v[166:169], v[190:193], v[106:109]
	v_mfma_f32_16x16x32_bf16 v[98:101], v[174:177], v[190:193], v[98:101]
	v_mfma_f32_16x16x32_bf16 v[90:93], v[166:169], v[198:201], v[90:93]
	v_mfma_f32_16x16x32_bf16 v[82:85], v[174:177], v[198:201], v[82:85]
	v_mfma_f32_16x16x32_bf16 v[74:77], v[166:169], v[206:209], v[74:77]
	v_mfma_f32_16x16x32_bf16 v[66:69], v[174:177], v[206:209], v[66:69]
	v_mfma_f32_16x16x32_bf16 v[122:125], v[170:173], v[186:189], v[122:125]
	v_mfma_f32_16x16x32_bf16 v[114:117], v[178:181], v[186:189], v[114:117]
	v_mfma_f32_16x16x32_bf16 v[106:109], v[170:173], v[194:197], v[106:109]
	v_mfma_f32_16x16x32_bf16 v[98:101], v[178:181], v[194:197], v[98:101]
	v_mfma_f32_16x16x32_bf16 v[90:93], v[170:173], v[202:205], v[90:93]
	v_mfma_f32_16x16x32_bf16 v[82:85], v[178:181], v[202:205], v[82:85]
	v_mfma_f32_16x16x32_bf16 v[74:77], v[170:173], v[210:213], v[74:77]
	v_mfma_f32_16x16x32_bf16 v[66:69], v[178:181], v[210:213], v[66:69]
	s_barrier
; #define PG8_STAGE(bufoff, gbase, voff) do { if constexpr (VAR != 1 && VAR != 3) { _Pragma("unroll") for (int _i = 0; _i < 2; ++_i) \
;         asm volatile("s_mov_b32 m0, %2\n\ts_nop 0\n\tglobal_load_lds_dwordx4 %0, %1" :: "v"((voff)[_i]), "s"((const char*)(gbase)), "s"(ldsbase + (unsigned)((bufoff) + _i * 8192)) : "memory", "m0"); } } while (0)
; #define PG8_LDA(dst, b, h) do { if constexpr (VAR < 2) _Pragma("unroll") for (int m = 0; m < 4; ++m) _Pragma("unroll") for (int k = 0; k < 2; ++k) dst[m][k] = *(const LAS bf16x8*)(lds + PG8_SA(b, h) + aoff + m * 2048 + k * 1024); } while (0)
; #define PG8_LDB(dst, b, h) do { if constexpr (VAR < 2) _Pragma("unroll") for (int n = 0; n < 2; ++n) _Pragma("unroll") for (int k = 0; k < 2; ++k) dst[n][k] = *(const LAS bf16x8*)(lds + PG8_SB(b, h) + boff + n * 2048 + k * 1024); } while (0)
; #define PG8_WAIT_V(n) asm volatile("s_waitcnt vmcnt(" #n ")" ::: "memory")
; #define PG8_WAIT_L(n) asm volatile("s_waitcnt lgkmcnt(" #n ")" ::: "memory")
;     ...
;         for (int t = 0; t < nt; t += 2) {
;             const bool last = (t == nt - 2);
;             const char* a1 = cA + (size_t)(t + 1) * kstep;
;             const char* a2 = last ? nA : cA + (size_t)(t + 2) * kstep; const char* b2 = last ? nB : cB + (size_t)(t + 2) * kstep;
;             const char* a3 = a2 + kstep; const char* b3 = b2 + kstep;
;             PG8_LDB(B0, 0, 0); PG8_LDB(B1, 0, 1); PG8_SCHED; PG8_LDA(At, 0, 0); PG8_STAGE(PG8_SA(1, 1), a1 + hstepA, voffA);
;             PG8_WAIT_V(8); PG8_WAIT_L(0); PG8_BAR; PG8_MMA(0, 0, At, B0); PG8_MMA(0, 1, At, B1); PG8_BAR; PG8_SCHED;
;             PG8_LDA(At, 0, 1); PG8_STAGE(PG8_SB(0, 0), b2, voffB); PG8_STAGE(PG8_SB(0, 1), b2 + hstepB, voffB); PG8_STAGE(PG8_SA(0, 0), a2, voffA);
;             PG8_WAIT_V(8); PG8_WAIT_L(0); PG8_BAR; PG8_MMA(1, 0, At, B0); PG8_MMA(1, 1, At, B1); PG8_BAR; PG8_SCHED;
;             PG8_LDB(B0, 1, 0); PG8_LDB(B1, 1, 1); PG8_SCHED; PG8_LDA(At, 1, 0); PG8_STAGE(PG8_SA(0, 1), a2 + hstepA, voffA);
;             PG8_WAIT_V(8); PG8_WAIT_L(0); PG8_BAR; PG8_MMA(0, 0, At, B0); PG8_MMA(0, 1, At, B1); PG8_BAR; PG8_SCHED;
;             PG8_LDA(At, 1, 1); PG8_STAGE(PG8_SB(1, 0), b3, voffB); PG8_STAGE(PG8_SB(1, 1), b3 + hstepB, voffB); PG8_STAGE(PG8_SA(1, 0), a3, voffA);
;             PG8_WAIT_V(8); PG8_WAIT_L(0); PG8_BAR; PG8_MMA(1, 0, At, B0); PG8_MMA(1, 1, At, B1); PG8_BAR; PG8_SCHED;
	ds_read_b128 v[182:185], v154 offset:49152
	ds_read_b128 v[186:189], v154 offset:50176
	ds_read_b128 v[190:193], v154 offset:51200
	ds_read_b128 v[194:197], v154 offset:52224
	ds_read_b128 v[198:201], v154 offset:53248
	ds_read_b128 v[202:205], v154 offset:54272
	ds_read_b128 v[206:209], v154 offset:55296
	ds_read_b128 v[210:213], v154 offset:56320
	s_add_u32 s10, s74, 0x80
	s_addc_u32 s11, s75, 0
	s_mov_b32 m0, s52
	s_nop 0
	global_load_lds_dwordx4 v146, s[10:11]
	s_mov_b32 m0, s53
	s_nop 0
	global_load_lds_dwordx4 v148, s[10:11]
	s_add_u32 s10, s74, 0x100080
	s_addc_u32 s11, s75, 0
	s_mov_b32 m0, s62
	s_nop 0
	global_load_lds_dwordx4 v146, s[10:11]
	s_mov_b32 m0, s63
	s_nop 0
	global_load_lds_dwordx4 v148, s[10:11]
	s_mov_b32 m0, s56
	s_nop 0
	global_load_lds_dwordx4 v1, s[72:73]
	s_mov_b32 m0, s57
	s_nop 0
	global_load_lds_dwordx4 v147, s[72:73]
	s_waitcnt vmcnt(8) lgkmcnt(0)
	s_barrier
	v_mfma_f32_16x16x32_bf16 v[62:65], v[136:139], v[182:185], v[62:65]
	v_mfma_f32_16x16x32_bf16 v[54:57], v[158:161], v[182:185], v[54:57]
	v_mfma_f32_16x16x32_bf16 v[46:49], v[136:139], v[190:193], v[46:49]
	v_mfma_f32_16x16x32_bf16 v[38:41], v[158:161], v[190:193], v[38:41]
	v_mfma_f32_16x16x32_bf16 v[30:33], v[136:139], v[198:201], v[30:33]
	v_mfma_f32_16x16x32_bf16 v[22:25], v[158:161], v[198:201], v[22:25]
	v_mfma_f32_16x16x32_bf16 v[14:17], v[136:139], v[206:209], v[14:17]
	v_mfma_f32_16x16x32_bf16 v[6:9], v[158:161], v[206:209], v[6:9]
	v_mfma_f32_16x16x32_bf16 v[62:65], v[140:143], v[186:189], v[62:65]
	v_mfma_f32_16x16x32_bf16 v[54:57], v[162:165], v[186:189], v[54:57]
	v_mfma_f32_16x16x32_bf16 v[46:49], v[140:143], v[194:197], v[46:49]
	v_mfma_f32_16x16x32_bf16 v[38:41], v[162:165], v[194:197], v[38:41]
	v_mfma_f32_16x16x32_bf16 v[30:33], v[140:143], v[202:205], v[30:33]
	v_mfma_f32_16x16x32_bf16 v[22:25], v[162:165], v[202:205], v[22:25]
	v_mfma_f32_16x16x32_bf16 v[14:17], v[140:143], v[210:213], v[14:17]
	v_mfma_f32_16x16x32_bf16 v[6:9], v[162:165], v[210:213], v[6:9]
	v_mfma_f32_16x16x32_bf16 v[58:61], v[166:169], v[182:185], v[58:61]
	v_mfma_f32_16x16x32_bf16 v[50:53], v[174:177], v[182:185], v[50:53]
	v_mfma_f32_16x16x32_bf16 v[42:45], v[166:169], v[190:193], v[42:45]
	v_mfma_f32_16x16x32_bf16 v[34:37], v[174:177], v[190:193], v[34:37]
	v_mfma_f32_16x16x32_bf16 v[26:29], v[166:169], v[198:201], v[26:29]
	v_mfma_f32_16x16x32_bf16 v[18:21], v[174:177], v[198:201], v[18:21]
	v_mfma_f32_16x16x32_bf16 v[10:13], v[166:169], v[206:209], v[10:13]
	v_mfma_f32_16x16x32_bf16 v[2:5], v[174:177], v[206:209], v[2:5]
	v_mfma_f32_16x16x32_bf16 v[58:61], v[170:173], v[186:189], v[58:61]
	v_mfma_f32_16x16x32_bf16 v[50:53], v[178:181], v[186:189], v[50:53]
	v_mfma_f32_16x16x32_bf16 v[42:45], v[170:173], v[194:197], v[42:45]
	v_mfma_f32_16x16x32_bf16 v[34:37], v[178:181], v[194:197], v[34:37]
	v_mfma_f32_16x16x32_bf16 v[26:29], v[170:173], v[202:205], v[26:29]
	v_mfma_f32_16x16x32_bf16 v[18:21], v[178:181], v[202:205], v[18:21]
	v_mfma_f32_16x16x32_bf16 v[10:13], v[170:173], v[210:213], v[10:13]
	v_mfma_f32_16x16x32_bf16 v[2:5], v[178:181], v[210:213], v[2:5]
	s_barrier
	s_add_i32 s6, s6, 2
	s_add_u32 s65, s65, 0x100
	s_addc_u32 s92, s92, 0
	s_add_u32 s93, s93, 0x100
	s_addc_u32 s94, s94, 0
	s_add_u32 s70, s70, 0x100
	s_addc_u32 s71, s71, 0
	s_cmp_gt_u32 s6, 61
	s_cbranch_scc0 .LBB0_561
	s_branch .Lmy_kexit_2
.LBB0_561:
	ds_read_b128 v[136:139], v152
	ds_read_b128 v[140:143], v152 offset:1024
	ds_read_b128 v[158:161], v152 offset:2048
	ds_read_b128 v[162:165], v152 offset:3072
	ds_read_b128 v[166:169], v153
	ds_read_b128 v[170:173], v153 offset:1024
	ds_read_b128 v[174:177], v153 offset:2048
	ds_read_b128 v[178:181], v153 offset:3072
	s_cmp_eq_u32 s6, 60
	s_cselect_b32 s84, s14, s65
	s_cselect_b32 s85, s1, s92
	s_cselect_b32 s74, s61, s93
	s_cselect_b32 s75, s15, s94
	s_add_u32 s72, s84, 0x80
	s_addc_u32 s73, s85, 0
	ds_read_b128 v[182:185], v154
	ds_read_b128 v[186:189], v154 offset:1024
	ds_read_b128 v[190:193], v154 offset:2048
	ds_read_b128 v[194:197], v154 offset:3072
	ds_read_b128 v[198:201], v154 offset:4096
	ds_read_b128 v[202:205], v154 offset:5120
	ds_read_b128 v[206:209], v154 offset:6144
	ds_read_b128 v[210:213], v154 offset:7168
	s_mov_b32 m0, s86
	s_nop 0
	global_load_lds_dwordx4 v1, s[70:71]
	s_mov_b32 m0, s87
	s_nop 0
	global_load_lds_dwordx4 v147, s[70:71]
	s_waitcnt vmcnt(8) lgkmcnt(0)
	s_barrier
	v_mfma_f32_16x16x32_bf16 v[126:129], v[136:139], v[182:185], v[126:129]
	v_mfma_f32_16x16x32_bf16 v[118:121], v[158:161], v[182:185], v[118:121]
	v_mfma_f32_16x16x32_bf16 v[110:113], v[136:139], v[190:193], v[110:113]
	v_mfma_f32_16x16x32_bf16 v[102:105], v[158:161], v[190:193], v[102:105]
	v_mfma_f32_16x16x32_bf16 v[94:97], v[136:139], v[198:201], v[94:97]
	v_mfma_f32_16x16x32_bf16 v[86:89], v[158:161], v[198:201], v[86:89]
	v_mfma_f32_16x16x32_bf16 v[78:81], v[136:139], v[206:209], v[78:81]
	v_mfma_f32_16x16x32_bf16 v[70:73], v[158:161], v[206:209], v[70:73]
	v_mfma_f32_16x16x32_bf16 v[126:129], v[140:143], v[186:189], v[126:129]
	v_mfma_f32_16x16x32_bf16 v[118:121], v[162:165], v[186:189], v[118:121]
	v_mfma_f32_16x16x32_bf16 v[110:113], v[140:143], v[194:197], v[110:113]
	v_mfma_f32_16x16x32_bf16 v[102:105], v[162:165], v[194:197], v[102:105]
	v_mfma_f32_16x16x32_bf16 v[94:97], v[140:143], v[202:205], v[94:97]
	v_mfma_f32_16x16x32_bf16 v[86:89], v[162:165], v[202:205], v[86:89]
	v_mfma_f32_16x16x32_bf16 v[78:81], v[140:143], v[210:213], v[78:81]
	v_mfma_f32_16x16x32_bf16 v[70:73], v[162:165], v[210:213], v[70:73]
	v_mfma_f32_16x16x32_bf16 v[122:125], v[166:169], v[182:185], v[122:125]
	v_mfma_f32_16x16x32_bf16 v[114:117], v[174:177], v[182:185], v[114:117]
	v_mfma_f32_16x16x32_bf16 v[106:109], v[166:169], v[190:193], v[106:109]
	v_mfma_f32_16x16x32_bf16 v[98:101], v[174:177], v[190:193], v[98:101]
	v_mfma_f32_16x16x32_bf16 v[90:93], v[166:169], v[198:201], v[90:93]
	v_mfma_f32_16x16x32_bf16 v[82:85], v[174:177], v[198:201], v[82:85]
	v_mfma_f32_16x16x32_bf16 v[74:77], v[166:169], v[206:209], v[74:77]
	v_mfma_f32_16x16x32_bf16 v[66:69], v[174:177], v[206:209], v[66:69]
	v_mfma_f32_16x16x32_bf16 v[122:125], v[170:173], v[186:189], v[122:125]
	v_mfma_f32_16x16x32_bf16 v[114:117], v[178:181], v[186:189], v[114:117]
	v_mfma_f32_16x16x32_bf16 v[106:109], v[170:173], v[194:197], v[106:109]
	v_mfma_f32_16x16x32_bf16 v[98:101], v[178:181], v[194:197], v[98:101]
	v_mfma_f32_16x16x32_bf16 v[90:93], v[170:173], v[202:205], v[90:93]
	v_mfma_f32_16x16x32_bf16 v[82:85], v[178:181], v[202:205], v[82:85]
	v_mfma_f32_16x16x32_bf16 v[74:77], v[170:173], v[210:213], v[74:77]
	v_mfma_f32_16x16x32_bf16 v[66:69], v[178:181], v[210:213], v[66:69]
	s_barrier
; #define PG8_STAGE(bufoff, gbase, voff) do { if constexpr (VAR != 1 && VAR != 3) { _Pragma("unroll") for (int _i = 0; _i < 2; ++_i) \
;         asm volatile("s_mov_b32 m0, %2\n\ts_nop 0\n\tglobal_load_lds_dwordx4 %0, %1" :: "v"((voff)[_i]), "s"((const char*)(gbase)), "s"(ldsbase + (unsigned)((bufoff) + _i * 8192)) : "memory", "m0"); } } while (0)
; #define PG8_LDA(dst, b, h) do { if constexpr (VAR < 2) _Pragma("unroll") for (int m = 0; m < 4; ++m) _Pragma("unroll") for (int k = 0; k < 2; ++k) dst[m][k] = *(const LAS bf16x8*)(lds + PG8_SA(b, h) + aoff + m * 2048 + k * 1024); } while (0)
; #define PG8_LDB(dst, b, h) do { if constexpr (VAR < 2) _Pragma("unroll") for (int n = 0; n < 2; ++n) _Pragma("unroll") for (int k = 0; k < 2; ++k) dst[n][k] = *(const LAS bf16x8*)(lds + PG8_SB(b, h) + boff + n * 2048 + k * 1024); } while (0)
; #define PG8_WAIT_V(n) asm volatile("s_waitcnt vmcnt(" #n ")" ::: "memory")
; #define PG8_WAIT_L(n) asm volatile("s_waitcnt lgkmcnt(" #n ")" ::: "memory")
; #define PG8_BAR do { if constexpr (VAR != 3) __builtin_amdgcn_s_barrier(); } while (0)
; #define PG8_SCHED __builtin_amdgcn_sched_barrier(0)
;     ...
;             PG8_LDA(At, 0, 1); PG8_STAGE(PG8_SB(0, 0), b2, voffB); PG8_STAGE(PG8_SB(0, 1), b2 + hstepB, voffB); PG8_STAGE(PG8_SA(0, 0), a2, voffA);
;             PG8_WAIT_V(8); PG8_WAIT_L(0); PG8_BAR; PG8_MMA(1, 0, At, B0); PG8_MMA(1, 1, At, B1); PG8_BAR; PG8_SCHED;
;             PG8_LDB(B0, 1, 0); PG8_LDB(B1, 1, 1); PG8_SCHED; PG8_LDA(At, 1, 0); PG8_STAGE(PG8_SA(0, 1), a2 + hstepA, voffA);
;             PG8_WAIT_V(8); PG8_WAIT_L(0); PG8_BAR; PG8_MMA(0, 0, At, B0); PG8_MMA(0, 1, At, B1); PG8_BAR; PG8_SCHED;
	ds_read_b128 v[182:185], v154 offset:16384
	ds_read_b128 v[186:189], v154 offset:17408
	ds_read_b128 v[190:193], v154 offset:18432
	ds_read_b128 v[194:197], v154 offset:19456
	ds_read_b128 v[198:201], v154 offset:20480
	ds_read_b128 v[202:205], v154 offset:21504
	ds_read_b128 v[206:209], v154 offset:22528
	ds_read_b128 v[210:213], v154 offset:23552
	s_mov_b32 m0, s21
	s_nop 0
	global_load_lds_dwordx4 v146, s[74:75]
	s_add_u32 s10, s74, 0x100000
	s_mov_b32 m0, s23
	s_nop 0
	global_load_lds_dwordx4 v148, s[74:75]
	s_addc_u32 s11, s75, 0
	s_mov_b32 m0, s29
	s_nop 0
	global_load_lds_dwordx4 v146, s[10:11]
	s_mov_b32 m0, s30
	s_nop 0
	global_load_lds_dwordx4 v148, s[10:11]
	s_mov_b32 m0, s25
	s_nop 0
	global_load_lds_dwordx4 v1, s[84:85]
	s_mov_b32 m0, s31
	s_nop 0
	global_load_lds_dwordx4 v147, s[84:85]
	s_waitcnt vmcnt(8) lgkmcnt(0)
	s_barrier
	v_mfma_f32_16x16x32_bf16 v[62:65], v[136:139], v[182:185], v[62:65]
	v_mfma_f32_16x16x32_bf16 v[54:57], v[158:161], v[182:185], v[54:57]
	v_mfma_f32_16x16x32_bf16 v[46:49], v[136:139], v[190:193], v[46:49]
	v_mfma_f32_16x16x32_bf16 v[38:41], v[158:161], v[190:193], v[38:41]
	v_mfma_f32_16x16x32_bf16 v[30:33], v[136:139], v[198:201], v[30:33]
	v_mfma_f32_16x16x32_bf16 v[22:25], v[158:161], v[198:201], v[22:25]
	v_mfma_f32_16x16x32_bf16 v[14:17], v[136:139], v[206:209], v[14:17]
	v_mfma_f32_16x16x32_bf16 v[6:9], v[158:161], v[206:209], v[6:9]
	v_mfma_f32_16x16x32_bf16 v[62:65], v[140:143], v[186:189], v[62:65]
	v_mfma_f32_16x16x32_bf16 v[54:57], v[162:165], v[186:189], v[54:57]
	v_mfma_f32_16x16x32_bf16 v[46:49], v[140:143], v[194:197], v[46:49]
	v_mfma_f32_16x16x32_bf16 v[38:41], v[162:165], v[194:197], v[38:41]
	v_mfma_f32_16x16x32_bf16 v[30:33], v[140:143], v[202:205], v[30:33]
	v_mfma_f32_16x16x32_bf16 v[22:25], v[162:165], v[202:205], v[22:25]
	v_mfma_f32_16x16x32_bf16 v[14:17], v[140:143], v[210:213], v[14:17]
	v_mfma_f32_16x16x32_bf16 v[6:9], v[162:165], v[210:213], v[6:9]
	v_mfma_f32_16x16x32_bf16 v[58:61], v[166:169], v[182:185], v[58:61]
	v_mfma_f32_16x16x32_bf16 v[50:53], v[174:177], v[182:185], v[50:53]
	v_mfma_f32_16x16x32_bf16 v[42:45], v[166:169], v[190:193], v[42:45]
	v_mfma_f32_16x16x32_bf16 v[34:37], v[174:177], v[190:193], v[34:37]
	v_mfma_f32_16x16x32_bf16 v[26:29], v[166:169], v[198:201], v[26:29]
	v_mfma_f32_16x16x32_bf16 v[18:21], v[174:177], v[198:201], v[18:21]
	v_mfma_f32_16x16x32_bf16 v[10:13], v[166:169], v[206:209], v[10:13]
	v_mfma_f32_16x16x32_bf16 v[2:5], v[174:177], v[206:209], v[2:5]
	v_mfma_f32_16x16x32_bf16 v[58:61], v[170:173], v[186:189], v[58:61]
	v_mfma_f32_16x16x32_bf16 v[50:53], v[178:181], v[186:189], v[50:53]
	v_mfma_f32_16x16x32_bf16 v[42:45], v[170:173], v[194:197], v[42:45]
	v_mfma_f32_16x16x32_bf16 v[34:37], v[178:181], v[194:197], v[34:37]
	v_mfma_f32_16x16x32_bf16 v[26:29], v[170:173], v[202:205], v[26:29]
	v_mfma_f32_16x16x32_bf16 v[18:21], v[178:181], v[202:205], v[18:21]
	v_mfma_f32_16x16x32_bf16 v[10:13], v[170:173], v[210:213], v[10:13]
	v_mfma_f32_16x16x32_bf16 v[2:5], v[178:181], v[210:213], v[2:5]
	s_barrier
	ds_read_b128 v[136:139], v155
	ds_read_b128 v[140:143], v155 offset:1024
	ds_read_b128 v[158:161], v155 offset:2048
	ds_read_b128 v[162:165], v155 offset:3072
	ds_read_b128 v[166:169], v156
	ds_read_b128 v[170:173], v156 offset:1024
	ds_read_b128 v[174:177], v156 offset:2048
	ds_read_b128 v[178:181], v156 offset:3072
	ds_read_b128 v[182:185], v154 offset:32768
	ds_read_b128 v[186:189], v154 offset:33792
	ds_read_b128 v[190:193], v154 offset:34816
	ds_read_b128 v[194:197], v154 offset:35840
	ds_read_b128 v[198:201], v154 offset:36864
	ds_read_b128 v[202:205], v154 offset:37888
	ds_read_b128 v[206:209], v154 offset:38912
	ds_read_b128 v[210:213], v154 offset:39936
	s_add_u32 s10, s84, 0x100000
	s_addc_u32 s11, s85, 0
	s_mov_b32 m0, s33
	s_nop 0
	global_load_lds_dwordx4 v1, s[10:11]
	s_mov_b32 m0, s35
	s_nop 0
	global_load_lds_dwordx4 v147, s[10:11]
	s_waitcnt vmcnt(8) lgkmcnt(0)
	s_barrier
; #define PG8_STAGE(bufoff, gbase, voff) do { if constexpr (VAR != 1 && VAR != 3) { _Pragma("unroll") for (int _i = 0; _i < 2; ++_i) \
;         asm volatile("s_mov_b32 m0, %2\n\ts_nop 0\n\tglobal_load_lds_dwordx4 %0, %1" :: "v"((voff)[_i]), "s"((const char*)(gbase)), "s"(ldsbase + (unsigned)((bufoff) + _i * 8192)) : "memory", "m0"); } } while (0)
; #define PG8_LDA(dst, b, h) do { if constexpr (VAR < 2) _Pragma("unroll") for (int m = 0; m < 4; ++m) _Pragma("unroll") for (int k = 0; k < 2; ++k) dst[m][k] = *(const LAS bf16x8*)(lds + PG8_SA(b, h) + aoff + m * 2048 + k * 1024); } while (0)
; #define PG8_WAIT_V(n) asm volatile("s_waitcnt vmcnt(" #n ")" ::: "memory")
; #define PG8_WAIT_L(n) asm volatile("s_waitcnt lgkmcnt(" #n ")" ::: "memory")
; #define PG8_BAR do { if constexpr (VAR != 3) __builtin_amdgcn_s_barrier(); } while (0)
; #define PG8_SCHED __builtin_amdgcn_sched_barrier(0)
;     ...
;             PG8_WAIT_V(8); PG8_WAIT_L(0); PG8_BAR; PG8_MMA(0, 0, At, B0); PG8_MMA(0, 1, At, B1); PG8_BAR; PG8_SCHED;
;             PG8_LDA(At, 1, 1); PG8_STAGE(PG8_SB(1, 0), b3, voffB); PG8_STAGE(PG8_SB(1, 1), b3 + hstepB, voffB); PG8_STAGE(PG8_SA(1, 0), a3, voffA);
;             PG8_WAIT_V(8); PG8_WAIT_L(0); PG8_BAR; PG8_MMA(1, 0, At, B0); PG8_MMA(1, 1, At, B1); PG8_BAR; PG8_SCHED;
	v_mfma_f32_16x16x32_bf16 v[126:129], v[136:139], v[182:185], v[126:129]
	v_mfma_f32_16x16x32_bf16 v[118:121], v[158:161], v[182:185], v[118:121]
	v_mfma_f32_16x16x32_bf16 v[110:113], v[136:139], v[190:193], v[110:113]
	v_mfma_f32_16x16x32_bf16 v[102:105], v[158:161], v[190:193], v[102:105]
	v_mfma_f32_16x16x32_bf16 v[94:97], v[136:139], v[198:201], v[94:97]
	v_mfma_f32_16x16x32_bf16 v[86:89], v[158:161], v[198:201], v[86:89]
	v_mfma_f32_16x16x32_bf16 v[78:81], v[136:139], v[206:209], v[78:81]
	v_mfma_f32_16x16x32_bf16 v[70:73], v[158:161], v[206:209], v[70:73]
	v_mfma_f32_16x16x32_bf16 v[126:129], v[140:143], v[186:189], v[126:129]
	v_mfma_f32_16x16x32_bf16 v[118:121], v[162:165], v[186:189], v[118:121]
	v_mfma_f32_16x16x32_bf16 v[110:113], v[140:143], v[194:197], v[110:113]
	v_mfma_f32_16x16x32_bf16 v[102:105], v[162:165], v[194:197], v[102:105]
	v_mfma_f32_16x16x32_bf16 v[94:97], v[140:143], v[202:205], v[94:97]
	v_mfma_f32_16x16x32_bf16 v[86:89], v[162:165], v[202:205], v[86:89]
	v_mfma_f32_16x16x32_bf16 v[78:81], v[140:143], v[210:213], v[78:81]
	v_mfma_f32_16x16x32_bf16 v[70:73], v[162:165], v[210:213], v[70:73]
	v_mfma_f32_16x16x32_bf16 v[122:125], v[166:169], v[182:185], v[122:125]
	v_mfma_f32_16x16x32_bf16 v[114:117], v[174:177], v[182:185], v[114:117]
	v_mfma_f32_16x16x32_bf16 v[106:109], v[166:169], v[190:193], v[106:109]
	v_mfma_f32_16x16x32_bf16 v[98:101], v[174:177], v[190:193], v[98:101]
	v_mfma_f32_16x16x32_bf16 v[90:93], v[166:169], v[198:201], v[90:93]
	v_mfma_f32_16x16x32_bf16 v[82:85], v[174:177], v[198:201], v[82:85]
	v_mfma_f32_16x16x32_bf16 v[74:77], v[166:169], v[206:209], v[74:77]
	v_mfma_f32_16x16x32_bf16 v[66:69], v[174:177], v[206:209], v[66:69]
	v_mfma_f32_16x16x32_bf16 v[122:125], v[170:173], v[186:189], v[122:125]
	v_mfma_f32_16x16x32_bf16 v[114:117], v[178:181], v[186:189], v[114:117]
	v_mfma_f32_16x16x32_bf16 v[106:109], v[170:173], v[194:197], v[106:109]
	v_mfma_f32_16x16x32_bf16 v[98:101], v[178:181], v[194:197], v[98:101]
	v_mfma_f32_16x16x32_bf16 v[90:93], v[170:173], v[202:205], v[90:93]
	v_mfma_f32_16x16x32_bf16 v[82:85], v[178:181], v[202:205], v[82:85]
	v_mfma_f32_16x16x32_bf16 v[74:77], v[170:173], v[210:213], v[74:77]
	v_mfma_f32_16x16x32_bf16 v[66:69], v[178:181], v[210:213], v[66:69]
	s_barrier
	ds_read_b128 v[182:185], v154 offset:49152
	ds_read_b128 v[186:189], v154 offset:50176
	ds_read_b128 v[190:193], v154 offset:51200
	ds_read_b128 v[194:197], v154 offset:52224
	ds_read_b128 v[198:201], v154 offset:53248
	ds_read_b128 v[202:205], v154 offset:54272
	ds_read_b128 v[206:209], v154 offset:55296
	ds_read_b128 v[210:213], v154 offset:56320
	s_add_u32 s10, s74, 0x80
	s_addc_u32 s11, s75, 0
	s_mov_b32 m0, s52
	s_nop 0
	global_load_lds_dwordx4 v146, s[10:11]
	s_mov_b32 m0, s53
	s_nop 0
	global_load_lds_dwordx4 v148, s[10:11]
	s_add_u32 s10, s74, 0x100080
	s_addc_u32 s11, s75, 0
	s_mov_b32 m0, s62
	s_nop 0
	global_load_lds_dwordx4 v146, s[10:11]
	s_mov_b32 m0, s63
	s_nop 0
	global_load_lds_dwordx4 v148, s[10:11]
	s_mov_b32 m0, s56
	s_nop 0
	global_load_lds_dwordx4 v1, s[72:73]
	s_mov_b32 m0, s57
	s_nop 0
	global_load_lds_dwordx4 v147, s[72:73]
	s_waitcnt vmcnt(8) lgkmcnt(0)
	s_barrier
	v_mfma_f32_16x16x32_bf16 v[62:65], v[136:139], v[182:185], v[62:65]
	v_mfma_f32_16x16x32_bf16 v[54:57], v[158:161], v[182:185], v[54:57]
	v_mfma_f32_16x16x32_bf16 v[46:49], v[136:139], v[190:193], v[46:49]
	v_mfma_f32_16x16x32_bf16 v[38:41], v[158:161], v[190:193], v[38:41]
	v_mfma_f32_16x16x32_bf16 v[30:33], v[136:139], v[198:201], v[30:33]
	v_mfma_f32_16x16x32_bf16 v[22:25], v[158:161], v[198:201], v[22:25]
	v_mfma_f32_16x16x32_bf16 v[14:17], v[136:139], v[206:209], v[14:17]
	v_mfma_f32_16x16x32_bf16 v[6:9], v[158:161], v[206:209], v[6:9]
	v_mfma_f32_16x16x32_bf16 v[62:65], v[140:143], v[186:189], v[62:65]
	v_mfma_f32_16x16x32_bf16 v[54:57], v[162:165], v[186:189], v[54:57]
	v_mfma_f32_16x16x32_bf16 v[46:49], v[140:143], v[194:197], v[46:49]
	v_mfma_f32_16x16x32_bf16 v[38:41], v[162:165], v[194:197], v[38:41]
	v_mfma_f32_16x16x32_bf16 v[30:33], v[140:143], v[202:205], v[30:33]
	v_mfma_f32_16x16x32_bf16 v[22:25], v[162:165], v[202:205], v[22:25]
	v_mfma_f32_16x16x32_bf16 v[14:17], v[140:143], v[210:213], v[14:17]
	v_mfma_f32_16x16x32_bf16 v[6:9], v[162:165], v[210:213], v[6:9]
	v_mfma_f32_16x16x32_bf16 v[58:61], v[166:169], v[182:185], v[58:61]
	v_mfma_f32_16x16x32_bf16 v[50:53], v[174:177], v[182:185], v[50:53]
	v_mfma_f32_16x16x32_bf16 v[42:45], v[166:169], v[190:193], v[42:45]
	v_mfma_f32_16x16x32_bf16 v[34:37], v[174:177], v[190:193], v[34:37]
	v_mfma_f32_16x16x32_bf16 v[26:29], v[166:169], v[198:201], v[26:29]
	v_mfma_f32_16x16x32_bf16 v[18:21], v[174:177], v[198:201], v[18:21]
	v_mfma_f32_16x16x32_bf16 v[10:13], v[166:169], v[206:209], v[10:13]
	v_mfma_f32_16x16x32_bf16 v[2:5], v[174:177], v[206:209], v[2:5]
	v_mfma_f32_16x16x32_bf16 v[58:61], v[170:173], v[186:189], v[58:61]
	v_mfma_f32_16x16x32_bf16 v[50:53], v[178:181], v[186:189], v[50:53]
	v_mfma_f32_16x16x32_bf16 v[42:45], v[170:173], v[194:197], v[42:45]
	v_mfma_f32_16x16x32_bf16 v[34:37], v[178:181], v[194:197], v[34:37]
	v_mfma_f32_16x16x32_bf16 v[26:29], v[170:173], v[202:205], v[26:29]
	v_mfma_f32_16x16x32_bf16 v[18:21], v[178:181], v[202:205], v[18:21]
	v_mfma_f32_16x16x32_bf16 v[10:13], v[170:173], v[210:213], v[10:13]
	v_mfma_f32_16x16x32_bf16 v[2:5], v[178:181], v[210:213], v[2:5]
	s_barrier
	s_add_i32 s6, s6, 2
	s_add_u32 s65, s65, 0x100
	s_addc_u32 s92, s92, 0
	s_add_u32 s93, s93, 0x100
	s_addc_u32 s94, s94, 0
	s_add_u32 s70, s70, 0x100
	s_addc_u32 s71, s71, 0
	s_cmp_gt_u32 s6, 61
	s_cbranch_scc0 .LBB0_561

; __device__ __forceinline__ const char* unitA(const Gemm& g, const Unit& u) { return (const char*)(g.A + (size_t)(u.z / g.zdiv) * g.sAhi + (size_t)(u.z % g.zdiv) * g.sAlo + (size_t)u.pm * BM * g.lda); }
; __device__ __forceinline__ const char* unitB(const Gemm& g, const Unit& u) { return (const char*)(g.Bt + (size_t)(u.z / g.zdiv) * g.sBhi + (size_t)(u.z % g.zdiv) * g.sBlo + (size_t)(u.pm / g.bdiv) * g.sBpm + (size_t)u.pn * BM * g.ldb); }
; #define PG8_STAGE(bufoff, gbase, voff) do { if constexpr (VAR != 1 && VAR != 3) { _Pragma("unroll") for (int _i = 0; _i < 2; ++_i) \
;         asm volatile("s_mov_b32 m0, %2\n\ts_nop 0\n\tglobal_load_lds_dwordx4 %0, %1" :: "v"((voff)[_i]), "s"((const char*)(gbase)), "s"(ldsbase + (unsigned)((bufoff) + _i * 8192)) : "memory", "m0"); } } while (0)
; #define PG8_LDA(dst, b, h) do { if constexpr (VAR < 2) _Pragma("unroll") for (int m = 0; m < 4; ++m) _Pragma("unroll") for (int k = 0; k < 2; ++k) dst[m][k] = *(const LAS bf16x8*)(lds + PG8_SA(b, h) + aoff + m * 2048 + k * 1024); } while (0)
; #define PG8_LDB(dst, b, h) do { if constexpr (VAR < 2) _Pragma("unroll") for (int n = 0; n < 2; ++n) _Pragma("unroll") for (int k = 0; k < 2; ++k) dst[n][k] = *(const LAS bf16x8*)(lds + PG8_SB(b, h) + boff + n * 2048 + k * 1024); } while (0)
; #define PG8_WAIT_V(n) asm volatile("s_waitcnt vmcnt(" #n ")" ::: "memory")
;     ...
;         const bool has_next = S.next(ui + 1, nxt);
;         const char* nA = has_next ? unitA(g, nxt) : cA; const char* nB = has_next ? unitB(g, nxt) : cB;
;         for (int t = 0; t < nt; t += 2) {
;             const bool last = (t == nt - 2);
;             const char* a1 = cA + (size_t)(t + 1) * kstep;
;             const char* a2 = last ? nA : cA + (size_t)(t + 2) * kstep; const char* b2 = last ? nB : cB + (size_t)(t + 2) * kstep;
;             const char* a3 = a2 + kstep; const char* b3 = b2 + kstep;
;             PG8_LDB(B0, 0, 0); PG8_LDB(B1, 0, 1); PG8_SCHED; PG8_LDA(At, 0, 0); PG8_STAGE(PG8_SA(1, 1), a1 + hstepA, voffA);
;             PG8_WAIT_V(8); PG8_WAIT_L(0); PG8_BAR; PG8_MMA(0, 0, At, B0); PG8_MMA(0, 1, At, B1); PG8_BAR; PG8_SCHED;
;             PG8_LDA(At, 0, 1); PG8_STAGE(PG8_SB(0, 0), b2, voffB); PG8_STAGE(PG8_SB(0, 1), b2 + hstepB, voffB); PG8_STAGE(PG8_SA(0, 0), a2, voffA);
;             PG8_WAIT_V(8); PG8_WAIT_L(0); PG8_BAR; PG8_MMA(1, 0, At, B0); PG8_MMA(1, 1, At, B1); PG8_BAR; PG8_SCHED;
.LBB0_672:
	s_add_u32 s75, s78, 0x100
	s_addc_u32 s92, s79, 0
	s_add_u32 s93, s4, 0x100
	s_addc_u32 s94, s5, 0
	s_add_u32 s4, s78, 0x200080
	s_addc_u32 s5, s79, 0
	s_mov_b32 s6, -2
	s_waitcnt vmcnt(34)
	s_waitcnt vmcnt(32)
	ds_read_b128 v[150:153], v183
	ds_read_b128 v[154:157], v183 offset:1024
	ds_read_b128 v[158:161], v183 offset:2048
	ds_read_b128 v[162:165], v183 offset:3072
	ds_read_b128 v[166:169], v184
	ds_read_b128 v[188:191], v184 offset:1024
	ds_read_b128 v[192:195], v184 offset:2048
	ds_read_b128 v[196:199], v184 offset:3072
	s_cmp_eq_u32 s6, 12
	s_cselect_b32 s82, s0, s75
	s_cselect_b32 s83, s1, s92
	s_cselect_b32 s80, s76, s93
	s_cselect_b32 s81, s77, s94
	s_add_u32 s78, s82, 0x80
	s_addc_u32 s79, s83, 0
	ds_read_b128 v[200:203], v185
	ds_read_b128 v[204:207], v185 offset:1024
	ds_read_b128 v[208:211], v185 offset:2048
	ds_read_b128 v[212:215], v185 offset:3072
	ds_read_b128 v[216:219], v185 offset:4096
	ds_read_b128 v[220:223], v185 offset:5120
	ds_read_b128 v[224:227], v185 offset:6144
	ds_read_b128 v[228:231], v185 offset:7168
	s_mov_b32 m0, s85
	s_nop 0
	global_load_lds_dwordx4 v178, s[4:5]
	s_mov_b32 m0, s86
	s_nop 0
	global_load_lds_dwordx4 v180, s[4:5]
	s_waitcnt vmcnt(8) lgkmcnt(0)
	s_barrier
	v_mfma_f32_16x16x32_bf16 v[126:129], v[150:153], v[200:203], 0
	v_mfma_f32_16x16x32_bf16 v[122:125], v[158:161], v[200:203], 0
	v_mfma_f32_16x16x32_bf16 v[114:117], v[150:153], v[208:211], 0
	v_mfma_f32_16x16x32_bf16 v[106:109], v[158:161], v[208:211], 0
	v_mfma_f32_16x16x32_bf16 v[98:101], v[150:153], v[216:219], 0
	v_mfma_f32_16x16x32_bf16 v[90:93], v[158:161], v[216:219], 0
	v_mfma_f32_16x16x32_bf16 v[82:85], v[150:153], v[224:227], 0
	v_mfma_f32_16x16x32_bf16 v[74:77], v[158:161], v[224:227], 0
	v_mfma_f32_16x16x32_bf16 v[126:129], v[154:157], v[204:207], v[126:129]
	v_mfma_f32_16x16x32_bf16 v[122:125], v[162:165], v[204:207], v[122:125]
	v_mfma_f32_16x16x32_bf16 v[114:117], v[154:157], v[212:215], v[114:117]
	v_mfma_f32_16x16x32_bf16 v[106:109], v[162:165], v[212:215], v[106:109]
	v_mfma_f32_16x16x32_bf16 v[98:101], v[154:157], v[220:223], v[98:101]
	v_mfma_f32_16x16x32_bf16 v[90:93], v[162:165], v[220:223], v[90:93]
	v_mfma_f32_16x16x32_bf16 v[82:85], v[154:157], v[228:231], v[82:85]
	v_mfma_f32_16x16x32_bf16 v[74:77], v[162:165], v[228:231], v[74:77]
	v_mfma_f32_16x16x32_bf16 v[118:121], v[166:169], v[200:203], 0
	v_mfma_f32_16x16x32_bf16 v[110:113], v[192:195], v[200:203], 0
	v_mfma_f32_16x16x32_bf16 v[102:105], v[166:169], v[208:211], 0
	v_mfma_f32_16x16x32_bf16 v[94:97], v[192:195], v[208:211], 0
	v_mfma_f32_16x16x32_bf16 v[86:89], v[166:169], v[216:219], 0
	v_mfma_f32_16x16x32_bf16 v[78:81], v[192:195], v[216:219], 0
	v_mfma_f32_16x16x32_bf16 v[70:73], v[166:169], v[224:227], 0
	v_mfma_f32_16x16x32_bf16 v[66:69], v[192:195], v[224:227], 0
	v_mfma_f32_16x16x32_bf16 v[118:121], v[188:191], v[204:207], v[118:121]
	v_mfma_f32_16x16x32_bf16 v[110:113], v[196:199], v[204:207], v[110:113]
	v_mfma_f32_16x16x32_bf16 v[102:105], v[188:191], v[212:215], v[102:105]
	v_mfma_f32_16x16x32_bf16 v[94:97], v[196:199], v[212:215], v[94:97]
	v_mfma_f32_16x16x32_bf16 v[86:89], v[188:191], v[220:223], v[86:89]
	v_mfma_f32_16x16x32_bf16 v[78:81], v[196:199], v[220:223], v[78:81]
	v_mfma_f32_16x16x32_bf16 v[70:73], v[188:191], v[228:231], v[70:73]
	v_mfma_f32_16x16x32_bf16 v[66:69], v[196:199], v[228:231], v[66:69]
	s_barrier
	ds_read_b128 v[200:203], v185 offset:16384
	ds_read_b128 v[204:207], v185 offset:17408
	ds_read_b128 v[208:211], v185 offset:18432
	ds_read_b128 v[212:215], v185 offset:19456
	ds_read_b128 v[216:219], v185 offset:20480
	ds_read_b128 v[220:223], v185 offset:21504
	ds_read_b128 v[224:227], v185 offset:22528
	ds_read_b128 v[228:231], v185 offset:23552
	s_mov_b32 m0, s24
	s_nop 0
	global_load_lds_dwordx4 v179, s[80:81]
	s_add_u32 s96, s80, 0x100000
	s_mov_b32 m0, s25
	s_nop 0
	global_load_lds_dwordx4 v181, s[80:81]
	s_addc_u32 s97, s81, 0
	s_mov_b32 m0, s26
	s_nop 0
	global_load_lds_dwordx4 v179, s[96:97]
	s_mov_b32 m0, s27
	s_nop 0
	global_load_lds_dwordx4 v181, s[96:97]
	s_mov_b32 m0, s15
	s_nop 0
	global_load_lds_dwordx4 v178, s[82:83]
	s_mov_b32 m0, s28
	s_nop 0
	global_load_lds_dwordx4 v180, s[82:83]
	s_waitcnt vmcnt(8) lgkmcnt(0)
	s_barrier
	v_mfma_f32_16x16x32_bf16 v[62:65], v[150:153], v[200:203], 0
	v_mfma_f32_16x16x32_bf16 v[58:61], v[158:161], v[200:203], 0
	v_mfma_f32_16x16x32_bf16 v[50:53], v[150:153], v[208:211], 0
	v_mfma_f32_16x16x32_bf16 v[42:45], v[158:161], v[208:211], 0
	v_mfma_f32_16x16x32_bf16 v[34:37], v[150:153], v[216:219], 0
	v_mfma_f32_16x16x32_bf16 v[26:29], v[158:161], v[216:219], 0
	v_mfma_f32_16x16x32_bf16 v[18:21], v[150:153], v[224:227], 0
	v_mfma_f32_16x16x32_bf16 v[10:13], v[158:161], v[224:227], 0
	v_mfma_f32_16x16x32_bf16 v[62:65], v[154:157], v[204:207], v[62:65]
	v_mfma_f32_16x16x32_bf16 v[58:61], v[162:165], v[204:207], v[58:61]
	v_mfma_f32_16x16x32_bf16 v[50:53], v[154:157], v[212:215], v[50:53]
	v_mfma_f32_16x16x32_bf16 v[42:45], v[162:165], v[212:215], v[42:45]
	v_mfma_f32_16x16x32_bf16 v[34:37], v[154:157], v[220:223], v[34:37]
	v_mfma_f32_16x16x32_bf16 v[26:29], v[162:165], v[220:223], v[26:29]
	v_mfma_f32_16x16x32_bf16 v[18:21], v[154:157], v[228:231], v[18:21]
	v_mfma_f32_16x16x32_bf16 v[10:13], v[162:165], v[228:231], v[10:13]
	v_mfma_f32_16x16x32_bf16 v[54:57], v[166:169], v[200:203], 0
	v_mfma_f32_16x16x32_bf16 v[46:49], v[192:195], v[200:203], 0
	v_mfma_f32_16x16x32_bf16 v[38:41], v[166:169], v[208:211], 0
	v_mfma_f32_16x16x32_bf16 v[30:33], v[192:195], v[208:211], 0
	v_mfma_f32_16x16x32_bf16 v[22:25], v[166:169], v[216:219], 0
	v_mfma_f32_16x16x32_bf16 v[14:17], v[192:195], v[216:219], 0
	v_mfma_f32_16x16x32_bf16 v[6:9], v[166:169], v[224:227], 0
	v_mfma_f32_16x16x32_bf16 v[2:5], v[192:195], v[224:227], 0
	v_mfma_f32_16x16x32_bf16 v[54:57], v[188:191], v[204:207], v[54:57]
	v_mfma_f32_16x16x32_bf16 v[46:49], v[196:199], v[204:207], v[46:49]
	v_mfma_f32_16x16x32_bf16 v[38:41], v[188:191], v[212:215], v[38:41]
	v_mfma_f32_16x16x32_bf16 v[30:33], v[196:199], v[212:215], v[30:33]
	v_mfma_f32_16x16x32_bf16 v[22:25], v[188:191], v[220:223], v[22:25]
	v_mfma_f32_16x16x32_bf16 v[14:17], v[196:199], v[220:223], v[14:17]
	v_mfma_f32_16x16x32_bf16 v[6:9], v[188:191], v[228:231], v[6:9]
	v_mfma_f32_16x16x32_bf16 v[2:5], v[196:199], v[228:231], v[2:5]
	s_barrier
; #define PG8_STAGE(bufoff, gbase, voff) do { if constexpr (VAR != 1 && VAR != 3) { _Pragma("unroll") for (int _i = 0; _i < 2; ++_i) \
;         asm volatile("s_mov_b32 m0, %2\n\ts_nop 0\n\tglobal_load_lds_dwordx4 %0, %1" :: "v"((voff)[_i]), "s"((const char*)(gbase)), "s"(ldsbase + (unsigned)((bufoff) + _i * 8192)) : "memory", "m0"); } } while (0)
; #define PG8_LDA(dst, b, h) do { if constexpr (VAR < 2) _Pragma("unroll") for (int m = 0; m < 4; ++m) _Pragma("unroll") for (int k = 0; k < 2; ++k) dst[m][k] = *(const LAS bf16x8*)(lds + PG8_SA(b, h) + aoff + m * 2048 + k * 1024); } while (0)
; #define PG8_LDB(dst, b, h) do { if constexpr (VAR < 2) _Pragma("unroll") for (int n = 0; n < 2; ++n) _Pragma("unroll") for (int k = 0; k < 2; ++k) dst[n][k] = *(const LAS bf16x8*)(lds + PG8_SB(b, h) + boff + n * 2048 + k * 1024); } while (0)
; #define PG8_WAIT_V(n) asm volatile("s_waitcnt vmcnt(" #n ")" ::: "memory")
; #define PG8_WAIT_L(n) asm volatile("s_waitcnt lgkmcnt(" #n ")" ::: "memory")
; #define PG8_BAR do { if constexpr (VAR != 3) __builtin_amdgcn_s_barrier(); } while (0)
; #define PG8_SCHED __builtin_amdgcn_sched_barrier(0)
;     ...
;             PG8_LDB(B0, 1, 0); PG8_LDB(B1, 1, 1); PG8_SCHED; PG8_LDA(At, 1, 0); PG8_STAGE(PG8_SA(0, 1), a2 + hstepA, voffA);
;             PG8_WAIT_V(8); PG8_WAIT_L(0); PG8_BAR; PG8_MMA(0, 0, At, B0); PG8_MMA(0, 1, At, B1); PG8_BAR; PG8_SCHED;
;             PG8_LDA(At, 1, 1); PG8_STAGE(PG8_SB(1, 0), b3, voffB); PG8_STAGE(PG8_SB(1, 1), b3 + hstepB, voffB); PG8_STAGE(PG8_SA(1, 0), a3, voffA);
;             PG8_WAIT_V(8); PG8_WAIT_L(0); PG8_BAR; PG8_MMA(1, 0, At, B0); PG8_MMA(1, 1, At, B1); PG8_BAR; PG8_SCHED;
;         }
	ds_read_b128 v[150:153], v186
	ds_read_b128 v[154:157], v186 offset:1024
	ds_read_b128 v[158:161], v186 offset:2048
	ds_read_b128 v[162:165], v186 offset:3072
	ds_read_b128 v[166:169], v187
	ds_read_b128 v[188:191], v187 offset:1024
	ds_read_b128 v[192:195], v187 offset:2048
	ds_read_b128 v[196:199], v187 offset:3072
	ds_read_b128 v[200:203], v185 offset:32768
	ds_read_b128 v[204:207], v185 offset:33792
	ds_read_b128 v[208:211], v185 offset:34816
	ds_read_b128 v[212:215], v185 offset:35840
	ds_read_b128 v[216:219], v185 offset:36864
	ds_read_b128 v[220:223], v185 offset:37888
	ds_read_b128 v[224:227], v185 offset:38912
	ds_read_b128 v[228:231], v185 offset:39936
	s_add_u32 s82, s82, 0x200000
	s_addc_u32 s83, s83, 0
	s_mov_b32 m0, s29
	s_nop 0
	global_load_lds_dwordx4 v178, s[82:83]
	s_mov_b32 m0, s30
	s_nop 0
	global_load_lds_dwordx4 v180, s[82:83]
	s_waitcnt vmcnt(8) lgkmcnt(0)
	s_barrier
	v_mfma_f32_16x16x32_bf16 v[126:129], v[150:153], v[200:203], v[126:129]
	v_mfma_f32_16x16x32_bf16 v[122:125], v[158:161], v[200:203], v[122:125]
	v_mfma_f32_16x16x32_bf16 v[114:117], v[150:153], v[208:211], v[114:117]
	v_mfma_f32_16x16x32_bf16 v[106:109], v[158:161], v[208:211], v[106:109]
	v_mfma_f32_16x16x32_bf16 v[98:101], v[150:153], v[216:219], v[98:101]
	v_mfma_f32_16x16x32_bf16 v[90:93], v[158:161], v[216:219], v[90:93]
	v_mfma_f32_16x16x32_bf16 v[82:85], v[150:153], v[224:227], v[82:85]
	v_mfma_f32_16x16x32_bf16 v[74:77], v[158:161], v[224:227], v[74:77]
	v_mfma_f32_16x16x32_bf16 v[126:129], v[154:157], v[204:207], v[126:129]
	v_mfma_f32_16x16x32_bf16 v[122:125], v[162:165], v[204:207], v[122:125]
	v_mfma_f32_16x16x32_bf16 v[114:117], v[154:157], v[212:215], v[114:117]
	v_mfma_f32_16x16x32_bf16 v[106:109], v[162:165], v[212:215], v[106:109]
	v_mfma_f32_16x16x32_bf16 v[98:101], v[154:157], v[220:223], v[98:101]
	v_mfma_f32_16x16x32_bf16 v[90:93], v[162:165], v[220:223], v[90:93]
	v_mfma_f32_16x16x32_bf16 v[82:85], v[154:157], v[228:231], v[82:85]
	v_mfma_f32_16x16x32_bf16 v[74:77], v[162:165], v[228:231], v[74:77]
	v_mfma_f32_16x16x32_bf16 v[118:121], v[166:169], v[200:203], v[118:121]
	v_mfma_f32_16x16x32_bf16 v[110:113], v[192:195], v[200:203], v[110:113]
	v_mfma_f32_16x16x32_bf16 v[102:105], v[166:169], v[208:211], v[102:105]
	v_mfma_f32_16x16x32_bf16 v[94:97], v[192:195], v[208:211], v[94:97]
	v_mfma_f32_16x16x32_bf16 v[86:89], v[166:169], v[216:219], v[86:89]
	v_mfma_f32_16x16x32_bf16 v[78:81], v[192:195], v[216:219], v[78:81]
	v_mfma_f32_16x16x32_bf16 v[70:73], v[166:169], v[224:227], v[70:73]
	v_mfma_f32_16x16x32_bf16 v[66:69], v[192:195], v[224:227], v[66:69]
	v_mfma_f32_16x16x32_bf16 v[118:121], v[188:191], v[204:207], v[118:121]
	v_mfma_f32_16x16x32_bf16 v[110:113], v[196:199], v[204:207], v[110:113]
	v_mfma_f32_16x16x32_bf16 v[102:105], v[188:191], v[212:215], v[102:105]
	v_mfma_f32_16x16x32_bf16 v[94:97], v[196:199], v[212:215], v[94:97]
	v_mfma_f32_16x16x32_bf16 v[86:89], v[188:191], v[220:223], v[86:89]
	v_mfma_f32_16x16x32_bf16 v[78:81], v[196:199], v[220:223], v[78:81]
	v_mfma_f32_16x16x32_bf16 v[70:73], v[188:191], v[228:231], v[70:73]
	v_mfma_f32_16x16x32_bf16 v[66:69], v[196:199], v[228:231], v[66:69]
	s_barrier
	ds_read_b128 v[200:203], v185 offset:49152
	ds_read_b128 v[204:207], v185 offset:50176
	ds_read_b128 v[208:211], v185 offset:51200
	ds_read_b128 v[212:215], v185 offset:52224
	ds_read_b128 v[216:219], v185 offset:53248
	ds_read_b128 v[220:223], v185 offset:54272
	ds_read_b128 v[224:227], v185 offset:55296
	ds_read_b128 v[228:231], v185 offset:56320
	s_add_u32 s82, s80, 0x80
	s_addc_u32 s83, s81, 0
	s_mov_b32 m0, s31
	s_nop 0
	global_load_lds_dwordx4 v179, s[82:83]
	s_add_u32 s80, s80, 0x100080
	s_mov_b32 m0, s33
	s_nop 0
	global_load_lds_dwordx4 v181, s[82:83]
	s_addc_u32 s81, s81, 0
	s_mov_b32 m0, s73
	s_nop 0
	global_load_lds_dwordx4 v179, s[80:81]
	s_mov_b32 m0, s84
	s_nop 0
	global_load_lds_dwordx4 v181, s[80:81]
	s_mov_b32 m0, s56
	s_nop 0
	global_load_lds_dwordx4 v178, s[78:79]
	s_mov_b32 m0, s57
	s_nop 0
	global_load_lds_dwordx4 v180, s[78:79]
	s_waitcnt vmcnt(8) lgkmcnt(0)
	s_barrier
	v_mfma_f32_16x16x32_bf16 v[62:65], v[150:153], v[200:203], v[62:65]
	v_mfma_f32_16x16x32_bf16 v[58:61], v[158:161], v[200:203], v[58:61]
	v_mfma_f32_16x16x32_bf16 v[50:53], v[150:153], v[208:211], v[50:53]
	v_mfma_f32_16x16x32_bf16 v[42:45], v[158:161], v[208:211], v[42:45]
	v_mfma_f32_16x16x32_bf16 v[34:37], v[150:153], v[216:219], v[34:37]
	v_mfma_f32_16x16x32_bf16 v[26:29], v[158:161], v[216:219], v[26:29]
	v_mfma_f32_16x16x32_bf16 v[18:21], v[150:153], v[224:227], v[18:21]
	v_mfma_f32_16x16x32_bf16 v[10:13], v[158:161], v[224:227], v[10:13]
	v_mfma_f32_16x16x32_bf16 v[62:65], v[154:157], v[204:207], v[62:65]
	v_mfma_f32_16x16x32_bf16 v[58:61], v[162:165], v[204:207], v[58:61]
	v_mfma_f32_16x16x32_bf16 v[50:53], v[154:157], v[212:215], v[50:53]
	v_mfma_f32_16x16x32_bf16 v[42:45], v[162:165], v[212:215], v[42:45]
	v_mfma_f32_16x16x32_bf16 v[34:37], v[154:157], v[220:223], v[34:37]
	v_mfma_f32_16x16x32_bf16 v[26:29], v[162:165], v[220:223], v[26:29]
	v_mfma_f32_16x16x32_bf16 v[18:21], v[154:157], v[228:231], v[18:21]
	v_mfma_f32_16x16x32_bf16 v[10:13], v[162:165], v[228:231], v[10:13]
	v_mfma_f32_16x16x32_bf16 v[54:57], v[166:169], v[200:203], v[54:57]
	v_mfma_f32_16x16x32_bf16 v[46:49], v[192:195], v[200:203], v[46:49]
	v_mfma_f32_16x16x32_bf16 v[38:41], v[166:169], v[208:211], v[38:41]
	v_mfma_f32_16x16x32_bf16 v[30:33], v[192:195], v[208:211], v[30:33]
	v_mfma_f32_16x16x32_bf16 v[22:25], v[166:169], v[216:219], v[22:25]
	v_mfma_f32_16x16x32_bf16 v[14:17], v[192:195], v[216:219], v[14:17]
	v_mfma_f32_16x16x32_bf16 v[6:9], v[166:169], v[224:227], v[6:9]
	v_mfma_f32_16x16x32_bf16 v[2:5], v[192:195], v[224:227], v[2:5]
	v_mfma_f32_16x16x32_bf16 v[54:57], v[188:191], v[204:207], v[54:57]
	v_mfma_f32_16x16x32_bf16 v[46:49], v[196:199], v[204:207], v[46:49]
	v_mfma_f32_16x16x32_bf16 v[38:41], v[188:191], v[212:215], v[38:41]
	v_mfma_f32_16x16x32_bf16 v[30:33], v[196:199], v[212:215], v[30:33]
	v_mfma_f32_16x16x32_bf16 v[22:25], v[188:191], v[220:223], v[22:25]
	v_mfma_f32_16x16x32_bf16 v[14:17], v[196:199], v[220:223], v[14:17]
	v_mfma_f32_16x16x32_bf16 v[6:9], v[188:191], v[228:231], v[6:9]
	v_mfma_f32_16x16x32_bf16 v[2:5], v[196:199], v[228:231], v[2:5]
	s_barrier
	s_add_i32 s6, s6, 2
	s_add_u32 s75, s75, 0x100
	s_addc_u32 s92, s92, 0
	s_add_u32 s93, s93, 0x100
	s_addc_u32 s94, s94, 0
	s_add_u32 s4, s4, 0x100
	s_addc_u32 s5, s5, 0
	s_cmp_gt_u32 s6, 13
	s_cbranch_scc0 .LBB0_673
	s_branch .Lmy_kexit_3
; #define PG8_STAGE(bufoff, gbase, voff) do { if constexpr (VAR != 1 && VAR != 3) { _Pragma("unroll") for (int _i = 0; _i < 2; ++_i) \
;         asm volatile("s_mov_b32 m0, %2\n\ts_nop 0\n\tglobal_load_lds_dwordx4 %0, %1" :: "v"((voff)[_i]), "s"((const char*)(gbase)), "s"(ldsbase + (unsigned)((bufoff) + _i * 8192)) : "memory", "m0"); } } while (0)
; #define PG8_LDA(dst, b, h) do { if constexpr (VAR < 2) _Pragma("unroll") for (int m = 0; m < 4; ++m) _Pragma("unroll") for (int k = 0; k < 2; ++k) dst[m][k] = *(const LAS bf16x8*)(lds + PG8_SA(b, h) + aoff + m * 2048 + k * 1024); } while (0)
; #define PG8_LDB(dst, b, h) do { if constexpr (VAR < 2) _Pragma("unroll") for (int n = 0; n < 2; ++n) _Pragma("unroll") for (int k = 0; k < 2; ++k) dst[n][k] = *(const LAS bf16x8*)(lds + PG8_SB(b, h) + boff + n * 2048 + k * 1024); } while (0)
; #define PG8_WAIT_V(n) asm volatile("s_waitcnt vmcnt(" #n ")" ::: "memory")
; #define PG8_WAIT_L(n) asm volatile("s_waitcnt lgkmcnt(" #n ")" ::: "memory")
; #define PG8_BAR do { if constexpr (VAR != 3) __builtin_amdgcn_s_barrier(); } while (0)
; #define PG8_SCHED __builtin_amdgcn_sched_barrier(0)
;     ...
;         for (int t = 0; t < nt; t += 2) {
;             const bool last = (t == nt - 2);
;             const char* a1 = cA + (size_t)(t + 1) * kstep;
;             const char* a2 = last ? nA : cA + (size_t)(t + 2) * kstep; const char* b2 = last ? nB : cB + (size_t)(t + 2) * kstep;
;             const char* a3 = a2 + kstep; const char* b3 = b2 + kstep;
;             PG8_LDB(B0, 0, 0); PG8_LDB(B1, 0, 1); PG8_SCHED; PG8_LDA(At, 0, 0); PG8_STAGE(PG8_SA(1, 1), a1 + hstepA, voffA);
;             PG8_WAIT_V(8); PG8_WAIT_L(0); PG8_BAR; PG8_MMA(0, 0, At, B0); PG8_MMA(0, 1, At, B1); PG8_BAR; PG8_SCHED;
;             PG8_LDA(At, 0, 1); PG8_STAGE(PG8_SB(0, 0), b2, voffB); PG8_STAGE(PG8_SB(0, 1), b2 + hstepB, voffB); PG8_STAGE(PG8_SA(0, 0), a2, voffA);
;             PG8_WAIT_V(8); PG8_WAIT_L(0); PG8_BAR; PG8_MMA(1, 0, At, B0); PG8_MMA(1, 1, At, B1); PG8_BAR; PG8_SCHED;
.LBB0_673:
	ds_read_b128 v[150:153], v183
	ds_read_b128 v[154:157], v183 offset:1024
	ds_read_b128 v[158:161], v183 offset:2048
	ds_read_b128 v[162:165], v183 offset:3072
	ds_read_b128 v[166:169], v184
	ds_read_b128 v[188:191], v184 offset:1024
	ds_read_b128 v[192:195], v184 offset:2048
	ds_read_b128 v[196:199], v184 offset:3072
	s_cmp_eq_u32 s6, 12
	s_cselect_b32 s82, s0, s75
	s_cselect_b32 s83, s1, s92
	s_cselect_b32 s80, s76, s93
	s_cselect_b32 s81, s77, s94
	s_add_u32 s78, s82, 0x80
	s_addc_u32 s79, s83, 0
	ds_read_b128 v[200:203], v185
	ds_read_b128 v[204:207], v185 offset:1024
	ds_read_b128 v[208:211], v185 offset:2048
	ds_read_b128 v[212:215], v185 offset:3072
	ds_read_b128 v[216:219], v185 offset:4096
	ds_read_b128 v[220:223], v185 offset:5120
	ds_read_b128 v[224:227], v185 offset:6144
	ds_read_b128 v[228:231], v185 offset:7168
	s_mov_b32 m0, s85
	s_nop 0
	global_load_lds_dwordx4 v178, s[4:5]
	s_mov_b32 m0, s86
	s_nop 0
	global_load_lds_dwordx4 v180, s[4:5]
	s_waitcnt vmcnt(8) lgkmcnt(0)
	s_barrier
	v_mfma_f32_16x16x32_bf16 v[126:129], v[150:153], v[200:203], v[126:129]
	v_mfma_f32_16x16x32_bf16 v[122:125], v[158:161], v[200:203], v[122:125]
	v_mfma_f32_16x16x32_bf16 v[114:117], v[150:153], v[208:211], v[114:117]
	v_mfma_f32_16x16x32_bf16 v[106:109], v[158:161], v[208:211], v[106:109]
	v_mfma_f32_16x16x32_bf16 v[98:101], v[150:153], v[216:219], v[98:101]
	v_mfma_f32_16x16x32_bf16 v[90:93], v[158:161], v[216:219], v[90:93]
	v_mfma_f32_16x16x32_bf16 v[82:85], v[150:153], v[224:227], v[82:85]
	v_mfma_f32_16x16x32_bf16 v[74:77], v[158:161], v[224:227], v[74:77]
	v_mfma_f32_16x16x32_bf16 v[126:129], v[154:157], v[204:207], v[126:129]
	v_mfma_f32_16x16x32_bf16 v[122:125], v[162:165], v[204:207], v[122:125]
	v_mfma_f32_16x16x32_bf16 v[114:117], v[154:157], v[212:215], v[114:117]
	v_mfma_f32_16x16x32_bf16 v[106:109], v[162:165], v[212:215], v[106:109]
	v_mfma_f32_16x16x32_bf16 v[98:101], v[154:157], v[220:223], v[98:101]
	v_mfma_f32_16x16x32_bf16 v[90:93], v[162:165], v[220:223], v[90:93]
	v_mfma_f32_16x16x32_bf16 v[82:85], v[154:157], v[228:231], v[82:85]
	v_mfma_f32_16x16x32_bf16 v[74:77], v[162:165], v[228:231], v[74:77]
	v_mfma_f32_16x16x32_bf16 v[118:121], v[166:169], v[200:203], v[118:121]
	v_mfma_f32_16x16x32_bf16 v[110:113], v[192:195], v[200:203], v[110:113]
	v_mfma_f32_16x16x32_bf16 v[102:105], v[166:169], v[208:211], v[102:105]
	v_mfma_f32_16x16x32_bf16 v[94:97], v[192:195], v[208:211], v[94:97]
	v_mfma_f32_16x16x32_bf16 v[86:89], v[166:169], v[216:219], v[86:89]
	v_mfma_f32_16x16x32_bf16 v[78:81], v[192:195], v[216:219], v[78:81]
	v_mfma_f32_16x16x32_bf16 v[70:73], v[166:169], v[224:227], v[70:73]
	v_mfma_f32_16x16x32_bf16 v[66:69], v[192:195], v[224:227], v[66:69]
	v_mfma_f32_16x16x32_bf16 v[118:121], v[188:191], v[204:207], v[118:121]
	v_mfma_f32_16x16x32_bf16 v[110:113], v[196:199], v[204:207], v[110:113]
	v_mfma_f32_16x16x32_bf16 v[102:105], v[188:191], v[212:215], v[102:105]
	v_mfma_f32_16x16x32_bf16 v[94:97], v[196:199], v[212:215], v[94:97]
	v_mfma_f32_16x16x32_bf16 v[86:89], v[188:191], v[220:223], v[86:89]
	v_mfma_f32_16x16x32_bf16 v[78:81], v[196:199], v[220:223], v[78:81]
	v_mfma_f32_16x16x32_bf16 v[70:73], v[188:191], v[228:231], v[70:73]
	v_mfma_f32_16x16x32_bf16 v[66:69], v[196:199], v[228:231], v[66:69]
	s_barrier
	ds_read_b128 v[200:203], v185 offset:16384
	ds_read_b128 v[204:207], v185 offset:17408
	ds_read_b128 v[208:211], v185 offset:18432
	ds_read_b128 v[212:215], v185 offset:19456
	ds_read_b128 v[216:219], v185 offset:20480
	ds_read_b128 v[220:223], v185 offset:21504
	ds_read_b128 v[224:227], v185 offset:22528
	ds_read_b128 v[228:231], v185 offset:23552
	s_mov_b32 m0, s24
	s_nop 0
	global_load_lds_dwordx4 v179, s[80:81]
	s_add_u32 s96, s80, 0x100000
	s_mov_b32 m0, s25
	s_nop 0
	global_load_lds_dwordx4 v181, s[80:81]
	s_addc_u32 s97, s81, 0
	s_mov_b32 m0, s26
	s_nop 0
	global_load_lds_dwordx4 v179, s[96:97]
	s_mov_b32 m0, s27
	s_nop 0
	global_load_lds_dwordx4 v181, s[96:97]
	s_mov_b32 m0, s15
	s_nop 0
	global_load_lds_dwordx4 v178, s[82:83]
	s_mov_b32 m0, s28
	s_nop 0
	global_load_lds_dwordx4 v180, s[82:83]
	s_waitcnt vmcnt(8) lgkmcnt(0)
	s_barrier
	v_mfma_f32_16x16x32_bf16 v[62:65], v[150:153], v[200:203], v[62:65]
	v_mfma_f32_16x16x32_bf16 v[58:61], v[158:161], v[200:203], v[58:61]
	v_mfma_f32_16x16x32_bf16 v[50:53], v[150:153], v[208:211], v[50:53]
	v_mfma_f32_16x16x32_bf16 v[42:45], v[158:161], v[208:211], v[42:45]
	v_mfma_f32_16x16x32_bf16 v[34:37], v[150:153], v[216:219], v[34:37]
	v_mfma_f32_16x16x32_bf16 v[26:29], v[158:161], v[216:219], v[26:29]
	v_mfma_f32_16x16x32_bf16 v[18:21], v[150:153], v[224:227], v[18:21]
	v_mfma_f32_16x16x32_bf16 v[10:13], v[158:161], v[224:227], v[10:13]
	v_mfma_f32_16x16x32_bf16 v[62:65], v[154:157], v[204:207], v[62:65]
	v_mfma_f32_16x16x32_bf16 v[58:61], v[162:165], v[204:207], v[58:61]
	v_mfma_f32_16x16x32_bf16 v[50:53], v[154:157], v[212:215], v[50:53]
	v_mfma_f32_16x16x32_bf16 v[42:45], v[162:165], v[212:215], v[42:45]
	v_mfma_f32_16x16x32_bf16 v[34:37], v[154:157], v[220:223], v[34:37]
	v_mfma_f32_16x16x32_bf16 v[26:29], v[162:165], v[220:223], v[26:29]
	v_mfma_f32_16x16x32_bf16 v[18:21], v[154:157], v[228:231], v[18:21]
	v_mfma_f32_16x16x32_bf16 v[10:13], v[162:165], v[228:231], v[10:13]
	v_mfma_f32_16x16x32_bf16 v[54:57], v[166:169], v[200:203], v[54:57]
	v_mfma_f32_16x16x32_bf16 v[46:49], v[192:195], v[200:203], v[46:49]
	v_mfma_f32_16x16x32_bf16 v[38:41], v[166:169], v[208:211], v[38:41]
	v_mfma_f32_16x16x32_bf16 v[30:33], v[192:195], v[208:211], v[30:33]
	v_mfma_f32_16x16x32_bf16 v[22:25], v[166:169], v[216:219], v[22:25]
	v_mfma_f32_16x16x32_bf16 v[14:17], v[192:195], v[216:219], v[14:17]
	v_mfma_f32_16x16x32_bf16 v[6:9], v[166:169], v[224:227], v[6:9]
	v_mfma_f32_16x16x32_bf16 v[2:5], v[192:195], v[224:227], v[2:5]
	v_mfma_f32_16x16x32_bf16 v[54:57], v[188:191], v[204:207], v[54:57]
	v_mfma_f32_16x16x32_bf16 v[46:49], v[196:199], v[204:207], v[46:49]
	v_mfma_f32_16x16x32_bf16 v[38:41], v[188:191], v[212:215], v[38:41]
	v_mfma_f32_16x16x32_bf16 v[30:33], v[196:199], v[212:215], v[30:33]
	v_mfma_f32_16x16x32_bf16 v[22:25], v[188:191], v[220:223], v[22:25]
	v_mfma_f32_16x16x32_bf16 v[14:17], v[196:199], v[220:223], v[14:17]
	v_mfma_f32_16x16x32_bf16 v[6:9], v[188:191], v[228:231], v[6:9]
	v_mfma_f32_16x16x32_bf16 v[2:5], v[196:199], v[228:231], v[2:5]
	s_barrier
; #define PG8_STAGE(bufoff, gbase, voff) do { if constexpr (VAR != 1 && VAR != 3) { _Pragma("unroll") for (int _i = 0; _i < 2; ++_i) \
;         asm volatile("s_mov_b32 m0, %2\n\ts_nop 0\n\tglobal_load_lds_dwordx4 %0, %1" :: "v"((voff)[_i]), "s"((const char*)(gbase)), "s"(ldsbase + (unsigned)((bufoff) + _i * 8192)) : "memory", "m0"); } } while (0)
; #define PG8_LDA(dst, b, h) do { if constexpr (VAR < 2) _Pragma("unroll") for (int m = 0; m < 4; ++m) _Pragma("unroll") for (int k = 0; k < 2; ++k) dst[m][k] = *(const LAS bf16x8*)(lds + PG8_SA(b, h) + aoff + m * 2048 + k * 1024); } while (0)
; #define PG8_LDB(dst, b, h) do { if constexpr (VAR < 2) _Pragma("unroll") for (int n = 0; n < 2; ++n) _Pragma("unroll") for (int k = 0; k < 2; ++k) dst[n][k] = *(const LAS bf16x8*)(lds + PG8_SB(b, h) + boff + n * 2048 + k * 1024); } while (0)
; #define PG8_WAIT_V(n) asm volatile("s_waitcnt vmcnt(" #n ")" ::: "memory")
; #define PG8_WAIT_L(n) asm volatile("s_waitcnt lgkmcnt(" #n ")" ::: "memory")
; #define PG8_BAR do { if constexpr (VAR != 3) __builtin_amdgcn_s_barrier(); } while (0)
; #define PG8_SCHED __builtin_amdgcn_sched_barrier(0)
;     ...
;             PG8_LDB(B0, 1, 0); PG8_LDB(B1, 1, 1); PG8_SCHED; PG8_LDA(At, 1, 0); PG8_STAGE(PG8_SA(0, 1), a2 + hstepA, voffA);
;             PG8_WAIT_V(8); PG8_WAIT_L(0); PG8_BAR; PG8_MMA(0, 0, At, B0); PG8_MMA(0, 1, At, B1); PG8_BAR; PG8_SCHED;
;             PG8_LDA(At, 1, 1); PG8_STAGE(PG8_SB(1, 0), b3, voffB); PG8_STAGE(PG8_SB(1, 1), b3 + hstepB, voffB); PG8_STAGE(PG8_SA(1, 0), a3, voffA);
;             PG8_WAIT_V(8); PG8_WAIT_L(0); PG8_BAR; PG8_MMA(1, 0, At, B0); PG8_MMA(1, 1, At, B1); PG8_BAR; PG8_SCHED;
;         }
	ds_read_b128 v[150:153], v186
	ds_read_b128 v[154:157], v186 offset:1024
	ds_read_b128 v[158:161], v186 offset:2048
	ds_read_b128 v[162:165], v186 offset:3072
	ds_read_b128 v[166:169], v187
	ds_read_b128 v[188:191], v187 offset:1024
	ds_read_b128 v[192:195], v187 offset:2048
	ds_read_b128 v[196:199], v187 offset:3072
	ds_read_b128 v[200:203], v185 offset:32768
	ds_read_b128 v[204:207], v185 offset:33792
	ds_read_b128 v[208:211], v185 offset:34816
	ds_read_b128 v[212:215], v185 offset:35840
	ds_read_b128 v[216:219], v185 offset:36864
	ds_read_b128 v[220:223], v185 offset:37888
	ds_read_b128 v[224:227], v185 offset:38912
	ds_read_b128 v[228:231], v185 offset:39936
	s_add_u32 s82, s82, 0x200000
	s_addc_u32 s83, s83, 0
	s_mov_b32 m0, s29
	s_nop 0
	global_load_lds_dwordx4 v178, s[82:83]
	s_mov_b32 m0, s30
	s_nop 0
	global_load_lds_dwordx4 v180, s[82:83]
	s_waitcnt vmcnt(8) lgkmcnt(0)
	s_barrier
	v_mfma_f32_16x16x32_bf16 v[126:129], v[150:153], v[200:203], v[126:129]
	v_mfma_f32_16x16x32_bf16 v[122:125], v[158:161], v[200:203], v[122:125]
	v_mfma_f32_16x16x32_bf16 v[114:117], v[150:153], v[208:211], v[114:117]
	v_mfma_f32_16x16x32_bf16 v[106:109], v[158:161], v[208:211], v[106:109]
	v_mfma_f32_16x16x32_bf16 v[98:101], v[150:153], v[216:219], v[98:101]
	v_mfma_f32_16x16x32_bf16 v[90:93], v[158:161], v[216:219], v[90:93]
	v_mfma_f32_16x16x32_bf16 v[82:85], v[150:153], v[224:227], v[82:85]
	v_mfma_f32_16x16x32_bf16 v[74:77], v[158:161], v[224:227], v[74:77]
	v_mfma_f32_16x16x32_bf16 v[126:129], v[154:157], v[204:207], v[126:129]
	v_mfma_f32_16x16x32_bf16 v[122:125], v[162:165], v[204:207], v[122:125]
	v_mfma_f32_16x16x32_bf16 v[114:117], v[154:157], v[212:215], v[114:117]
	v_mfma_f32_16x16x32_bf16 v[106:109], v[162:165], v[212:215], v[106:109]
	v_mfma_f32_16x16x32_bf16 v[98:101], v[154:157], v[220:223], v[98:101]
	v_mfma_f32_16x16x32_bf16 v[90:93], v[162:165], v[220:223], v[90:93]
	v_mfma_f32_16x16x32_bf16 v[82:85], v[154:157], v[228:231], v[82:85]
	v_mfma_f32_16x16x32_bf16 v[74:77], v[162:165], v[228:231], v[74:77]
	v_mfma_f32_16x16x32_bf16 v[118:121], v[166:169], v[200:203], v[118:121]
	v_mfma_f32_16x16x32_bf16 v[110:113], v[192:195], v[200:203], v[110:113]
	v_mfma_f32_16x16x32_bf16 v[102:105], v[166:169], v[208:211], v[102:105]
	v_mfma_f32_16x16x32_bf16 v[94:97], v[192:195], v[208:211], v[94:97]
	v_mfma_f32_16x16x32_bf16 v[86:89], v[166:169], v[216:219], v[86:89]
	v_mfma_f32_16x16x32_bf16 v[78:81], v[192:195], v[216:219], v[78:81]
	v_mfma_f32_16x16x32_bf16 v[70:73], v[166:169], v[224:227], v[70:73]
	v_mfma_f32_16x16x32_bf16 v[66:69], v[192:195], v[224:227], v[66:69]
	v_mfma_f32_16x16x32_bf16 v[118:121], v[188:191], v[204:207], v[118:121]
	v_mfma_f32_16x16x32_bf16 v[110:113], v[196:199], v[204:207], v[110:113]
	v_mfma_f32_16x16x32_bf16 v[102:105], v[188:191], v[212:215], v[102:105]
	v_mfma_f32_16x16x32_bf16 v[94:97], v[196:199], v[212:215], v[94:97]
	v_mfma_f32_16x16x32_bf16 v[86:89], v[188:191], v[220:223], v[86:89]
	v_mfma_f32_16x16x32_bf16 v[78:81], v[196:199], v[220:223], v[78:81]
	v_mfma_f32_16x16x32_bf16 v[70:73], v[188:191], v[228:231], v[70:73]
	v_mfma_f32_16x16x32_bf16 v[66:69], v[196:199], v[228:231], v[66:69]
	s_barrier
	ds_read_b128 v[200:203], v185 offset:49152
	ds_read_b128 v[204:207], v185 offset:50176
	ds_read_b128 v[208:211], v185 offset:51200
	ds_read_b128 v[212:215], v185 offset:52224
	ds_read_b128 v[216:219], v185 offset:53248
	ds_read_b128 v[220:223], v185 offset:54272
	ds_read_b128 v[224:227], v185 offset:55296
	ds_read_b128 v[228:231], v185 offset:56320
	s_add_u32 s82, s80, 0x80
	s_addc_u32 s83, s81, 0
	s_mov_b32 m0, s31
	s_nop 0
	global_load_lds_dwordx4 v179, s[82:83]
	s_add_u32 s80, s80, 0x100080
	s_mov_b32 m0, s33
	s_nop 0
	global_load_lds_dwordx4 v181, s[82:83]
	s_addc_u32 s81, s81, 0
	s_mov_b32 m0, s73
	s_nop 0
	global_load_lds_dwordx4 v179, s[80:81]
	s_mov_b32 m0, s84
	s_nop 0
	global_load_lds_dwordx4 v181, s[80:81]
	s_mov_b32 m0, s56
	s_nop 0
	global_load_lds_dwordx4 v178, s[78:79]
	s_mov_b32 m0, s57
	s_nop 0
	global_load_lds_dwordx4 v180, s[78:79]
	s_waitcnt vmcnt(8) lgkmcnt(0)
	s_barrier
	v_mfma_f32_16x16x32_bf16 v[62:65], v[150:153], v[200:203], v[62:65]
	v_mfma_f32_16x16x32_bf16 v[58:61], v[158:161], v[200:203], v[58:61]
	v_mfma_f32_16x16x32_bf16 v[50:53], v[150:153], v[208:211], v[50:53]
	v_mfma_f32_16x16x32_bf16 v[42:45], v[158:161], v[208:211], v[42:45]
	v_mfma_f32_16x16x32_bf16 v[34:37], v[150:153], v[216:219], v[34:37]
	v_mfma_f32_16x16x32_bf16 v[26:29], v[158:161], v[216:219], v[26:29]
	v_mfma_f32_16x16x32_bf16 v[18:21], v[150:153], v[224:227], v[18:21]
	v_mfma_f32_16x16x32_bf16 v[10:13], v[158:161], v[224:227], v[10:13]
	v_mfma_f32_16x16x32_bf16 v[62:65], v[154:157], v[204:207], v[62:65]
	v_mfma_f32_16x16x32_bf16 v[58:61], v[162:165], v[204:207], v[58:61]
	v_mfma_f32_16x16x32_bf16 v[50:53], v[154:157], v[212:215], v[50:53]
	v_mfma_f32_16x16x32_bf16 v[42:45], v[162:165], v[212:215], v[42:45]
	v_mfma_f32_16x16x32_bf16 v[34:37], v[154:157], v[220:223], v[34:37]
	v_mfma_f32_16x16x32_bf16 v[26:29], v[162:165], v[220:223], v[26:29]
	v_mfma_f32_16x16x32_bf16 v[18:21], v[154:157], v[228:231], v[18:21]
	v_mfma_f32_16x16x32_bf16 v[10:13], v[162:165], v[228:231], v[10:13]
	v_mfma_f32_16x16x32_bf16 v[54:57], v[166:169], v[200:203], v[54:57]
	v_mfma_f32_16x16x32_bf16 v[46:49], v[192:195], v[200:203], v[46:49]
	v_mfma_f32_16x16x32_bf16 v[38:41], v[166:169], v[208:211], v[38:41]
	v_mfma_f32_16x16x32_bf16 v[30:33], v[192:195], v[208:211], v[30:33]
	v_mfma_f32_16x16x32_bf16 v[22:25], v[166:169], v[216:219], v[22:25]
	v_mfma_f32_16x16x32_bf16 v[14:17], v[192:195], v[216:219], v[14:17]
	v_mfma_f32_16x16x32_bf16 v[6:9], v[166:169], v[224:227], v[6:9]
	v_mfma_f32_16x16x32_bf16 v[2:5], v[192:195], v[224:227], v[2:5]
	v_mfma_f32_16x16x32_bf16 v[54:57], v[188:191], v[204:207], v[54:57]
	v_mfma_f32_16x16x32_bf16 v[46:49], v[196:199], v[204:207], v[46:49]
	v_mfma_f32_16x16x32_bf16 v[38:41], v[188:191], v[212:215], v[38:41]
	v_mfma_f32_16x16x32_bf16 v[30:33], v[196:199], v[212:215], v[30:33]
	v_mfma_f32_16x16x32_bf16 v[22:25], v[188:191], v[220:223], v[22:25]
	v_mfma_f32_16x16x32_bf16 v[14:17], v[196:199], v[220:223], v[14:17]
	v_mfma_f32_16x16x32_bf16 v[6:9], v[188:191], v[228:231], v[6:9]
	v_mfma_f32_16x16x32_bf16 v[2:5], v[196:199], v[228:231], v[2:5]
	s_barrier
	s_add_i32 s6, s6, 2
	s_add_u32 s75, s75, 0x100
	s_addc_u32 s92, s92, 0
	s_add_u32 s93, s93, 0x100
	s_addc_u32 s94, s94, 0
	s_add_u32 s4, s4, 0x100
	s_addc_u32 s5, s5, 0
	s_cmp_gt_u32 s6, 13
	s_cbranch_scc0 .LBB0_673

; __device__ __forceinline__ const char* unitA(const Gemm& g, const Unit& u) { return (const char*)(g.A + (size_t)(u.z / g.zdiv) * g.sAhi + (size_t)(u.z % g.zdiv) * g.sAlo + (size_t)u.pm * BM * g.lda); }
; __device__ __forceinline__ const char* unitB(const Gemm& g, const Unit& u) { return (const char*)(g.Bt + (size_t)(u.z / g.zdiv) * g.sBhi + (size_t)(u.z % g.zdiv) * g.sBlo + (size_t)(u.pm / g.bdiv) * g.sBpm + (size_t)u.pn * BM * g.ldb); }
; #define PG8_STAGE(bufoff, gbase, voff) do { if constexpr (VAR != 1 && VAR != 3) { _Pragma("unroll") for (int _i = 0; _i < 2; ++_i) \
;         asm volatile("s_mov_b32 m0, %2\n\ts_nop 0\n\tglobal_load_lds_dwordx4 %0, %1" :: "v"((voff)[_i]), "s"((const char*)(gbase)), "s"(ldsbase + (unsigned)((bufoff) + _i * 8192)) : "memory", "m0"); } } while (0)
; #define PG8_LDA(dst, b, h) do { if constexpr (VAR < 2) _Pragma("unroll") for (int m = 0; m < 4; ++m) _Pragma("unroll") for (int k = 0; k < 2; ++k) dst[m][k] = *(const LAS bf16x8*)(lds + PG8_SA(b, h) + aoff + m * 2048 + k * 1024); } while (0)
; #define PG8_LDB(dst, b, h) do { if constexpr (VAR < 2) _Pragma("unroll") for (int n = 0; n < 2; ++n) _Pragma("unroll") for (int k = 0; k < 2; ++k) dst[n][k] = *(const LAS bf16x8*)(lds + PG8_SB(b, h) + boff + n * 2048 + k * 1024); } while (0)
; #define PG8_WAIT_V(n) asm volatile("s_waitcnt vmcnt(" #n ")" ::: "memory")
;     ...
;         const bool has_next = S.next(ui + 1, nxt);
;         const char* nA = has_next ? unitA(g, nxt) : cA; const char* nB = has_next ? unitB(g, nxt) : cB;
;         for (int t = 0; t < nt; t += 2) {
;             const bool last = (t == nt - 2);
;             const char* a1 = cA + (size_t)(t + 1) * kstep;
;             const char* a2 = last ? nA : cA + (size_t)(t + 2) * kstep; const char* b2 = last ? nB : cB + (size_t)(t + 2) * kstep;
;             const char* a3 = a2 + kstep; const char* b3 = b2 + kstep;
;             PG8_LDB(B0, 0, 0); PG8_LDB(B1, 0, 1); PG8_SCHED; PG8_LDA(At, 0, 0); PG8_STAGE(PG8_SA(1, 1), a1 + hstepA, voffA);
;             PG8_WAIT_V(8); PG8_WAIT_L(0); PG8_BAR; PG8_MMA(0, 0, At, B0); PG8_MMA(0, 1, At, B1); PG8_BAR; PG8_SCHED;
;             PG8_LDA(At, 0, 1); PG8_STAGE(PG8_SB(0, 0), b2, voffB); PG8_STAGE(PG8_SB(0, 1), b2 + hstepB, voffB); PG8_STAGE(PG8_SA(0, 0), a2, voffA);
;             PG8_WAIT_V(8); PG8_WAIT_L(0); PG8_BAR; PG8_MMA(1, 0, At, B0); PG8_MMA(1, 1, At, B1); PG8_BAR; PG8_SCHED;
.LBB0_700:
	s_add_u32 s57, s66, 0x100
	s_addc_u32 s81, s67, 0
	s_add_u32 s82, s64, 0x100
	s_addc_u32 s83, s65, 0
	s_add_u32 s64, s66, 0x100080
	s_addc_u32 s65, s67, 0
	s_mov_b32 s6, -2
	ds_read_b128 v[148:151], v1
	ds_read_b128 v[152:155], v1 offset:1024
	ds_read_b128 v[156:159], v1 offset:2048
	ds_read_b128 v[160:163], v1 offset:3072
	ds_read_b128 v[164:167], v143
	ds_read_b128 v[168:171], v143 offset:1024
	ds_read_b128 v[172:175], v143 offset:2048
	ds_read_b128 v[176:179], v143 offset:3072
	s_cmp_eq_u32 s6, 12
	s_cselect_b32 s70, s0, s57
	s_cselect_b32 s71, s1, s81
	s_cselect_b32 s68, s62, s82
	s_cselect_b32 s69, s63, s83
	s_add_u32 s66, s70, 0x80
	s_addc_u32 s67, s71, 0
	ds_read_b128 v[180:183], v144
	ds_read_b128 v[184:187], v144 offset:1024
	ds_read_b128 v[188:191], v144 offset:2048
	ds_read_b128 v[192:195], v144 offset:3072
	ds_read_b128 v[196:199], v144 offset:4096
	ds_read_b128 v[200:203], v144 offset:5120
	ds_read_b128 v[204:207], v144 offset:6144
	ds_read_b128 v[208:211], v144 offset:7168
	s_mov_b32 m0, s76
	s_nop 0
	global_load_lds_dwordx4 v138, s[64:65]
	s_mov_b32 m0, s77
	s_nop 0
	global_load_lds_dwordx4 v140, s[64:65]
	s_waitcnt vmcnt(8) lgkmcnt(0)
	s_barrier
	v_mfma_f32_16x16x32_bf16 v[126:129], v[148:151], v[180:183], 0
	v_mfma_f32_16x16x32_bf16 v[122:125], v[156:159], v[180:183], 0
	v_mfma_f32_16x16x32_bf16 v[118:121], v[148:151], v[188:191], 0
	v_mfma_f32_16x16x32_bf16 v[110:113], v[156:159], v[188:191], 0
	v_mfma_f32_16x16x32_bf16 v[102:105], v[148:151], v[196:199], 0
	v_mfma_f32_16x16x32_bf16 v[94:97], v[156:159], v[196:199], 0
	v_mfma_f32_16x16x32_bf16 v[86:89], v[148:151], v[204:207], 0
	v_mfma_f32_16x16x32_bf16 v[78:81], v[156:159], v[204:207], 0
	v_mfma_f32_16x16x32_bf16 v[126:129], v[152:155], v[184:187], v[126:129]
	v_mfma_f32_16x16x32_bf16 v[122:125], v[160:163], v[184:187], v[122:125]
	v_mfma_f32_16x16x32_bf16 v[118:121], v[152:155], v[192:195], v[118:121]
	v_mfma_f32_16x16x32_bf16 v[110:113], v[160:163], v[192:195], v[110:113]
	v_mfma_f32_16x16x32_bf16 v[102:105], v[152:155], v[200:203], v[102:105]
	v_mfma_f32_16x16x32_bf16 v[94:97], v[160:163], v[200:203], v[94:97]
	v_mfma_f32_16x16x32_bf16 v[86:89], v[152:155], v[208:211], v[86:89]
	v_mfma_f32_16x16x32_bf16 v[78:81], v[160:163], v[208:211], v[78:81]
	v_mfma_f32_16x16x32_bf16 v[114:117], v[164:167], v[180:183], 0
	v_mfma_f32_16x16x32_bf16 v[106:109], v[172:175], v[180:183], 0
	v_mfma_f32_16x16x32_bf16 v[98:101], v[164:167], v[188:191], 0
	v_mfma_f32_16x16x32_bf16 v[90:93], v[172:175], v[188:191], 0
	v_mfma_f32_16x16x32_bf16 v[82:85], v[164:167], v[196:199], 0
	v_mfma_f32_16x16x32_bf16 v[74:77], v[172:175], v[196:199], 0
	v_mfma_f32_16x16x32_bf16 v[70:73], v[164:167], v[204:207], 0
	v_mfma_f32_16x16x32_bf16 v[66:69], v[172:175], v[204:207], 0
	v_mfma_f32_16x16x32_bf16 v[114:117], v[168:171], v[184:187], v[114:117]
	v_mfma_f32_16x16x32_bf16 v[106:109], v[176:179], v[184:187], v[106:109]
	v_mfma_f32_16x16x32_bf16 v[98:101], v[168:171], v[192:195], v[98:101]
	v_mfma_f32_16x16x32_bf16 v[90:93], v[176:179], v[192:195], v[90:93]
	v_mfma_f32_16x16x32_bf16 v[82:85], v[168:171], v[200:203], v[82:85]
	v_mfma_f32_16x16x32_bf16 v[74:77], v[176:179], v[200:203], v[74:77]
	v_mfma_f32_16x16x32_bf16 v[70:73], v[168:171], v[208:211], v[70:73]
	v_mfma_f32_16x16x32_bf16 v[66:69], v[176:179], v[208:211], v[66:69]
	s_barrier
	ds_read_b128 v[180:183], v144 offset:16384
	ds_read_b128 v[184:187], v144 offset:17408
	ds_read_b128 v[188:191], v144 offset:18432
	ds_read_b128 v[192:195], v144 offset:19456
	ds_read_b128 v[196:199], v144 offset:20480
	ds_read_b128 v[200:203], v144 offset:21504
	ds_read_b128 v[204:207], v144 offset:22528
	ds_read_b128 v[208:211], v144 offset:23552
	s_mov_b32 m0, s24
	s_nop 0
	global_load_lds_dwordx4 v139, s[68:69]
	s_add_u32 s84, s68, 0x200000
	s_mov_b32 m0, s25
	s_nop 0
	global_load_lds_dwordx4 v141, s[68:69]
	s_addc_u32 s85, s69, 0
	s_mov_b32 m0, s26
	s_nop 0
	global_load_lds_dwordx4 v139, s[84:85]
	s_mov_b32 m0, s27
	s_nop 0
	global_load_lds_dwordx4 v141, s[84:85]
	s_mov_b32 m0, s15
	s_nop 0
	global_load_lds_dwordx4 v138, s[70:71]
	s_mov_b32 m0, s28
	s_nop 0
	global_load_lds_dwordx4 v140, s[70:71]
	s_waitcnt vmcnt(8) lgkmcnt(0)
	s_barrier
	v_mfma_f32_16x16x32_bf16 v[62:65], v[148:151], v[180:183], 0
	v_mfma_f32_16x16x32_bf16 v[58:61], v[156:159], v[180:183], 0
	v_mfma_f32_16x16x32_bf16 v[54:57], v[148:151], v[188:191], 0
	v_mfma_f32_16x16x32_bf16 v[46:49], v[156:159], v[188:191], 0
	v_mfma_f32_16x16x32_bf16 v[38:41], v[148:151], v[196:199], 0
	v_mfma_f32_16x16x32_bf16 v[30:33], v[156:159], v[196:199], 0
	v_mfma_f32_16x16x32_bf16 v[22:25], v[148:151], v[204:207], 0
	v_mfma_f32_16x16x32_bf16 v[14:17], v[156:159], v[204:207], 0
	v_mfma_f32_16x16x32_bf16 v[62:65], v[152:155], v[184:187], v[62:65]
	v_mfma_f32_16x16x32_bf16 v[58:61], v[160:163], v[184:187], v[58:61]
	v_mfma_f32_16x16x32_bf16 v[54:57], v[152:155], v[192:195], v[54:57]
	v_mfma_f32_16x16x32_bf16 v[46:49], v[160:163], v[192:195], v[46:49]
	v_mfma_f32_16x16x32_bf16 v[38:41], v[152:155], v[200:203], v[38:41]
	v_mfma_f32_16x16x32_bf16 v[30:33], v[160:163], v[200:203], v[30:33]
	v_mfma_f32_16x16x32_bf16 v[22:25], v[152:155], v[208:211], v[22:25]
	v_mfma_f32_16x16x32_bf16 v[14:17], v[160:163], v[208:211], v[14:17]
	v_mfma_f32_16x16x32_bf16 v[50:53], v[164:167], v[180:183], 0
	v_mfma_f32_16x16x32_bf16 v[42:45], v[172:175], v[180:183], 0
	v_mfma_f32_16x16x32_bf16 v[34:37], v[164:167], v[188:191], 0
	v_mfma_f32_16x16x32_bf16 v[26:29], v[172:175], v[188:191], 0
	v_mfma_f32_16x16x32_bf16 v[18:21], v[164:167], v[196:199], 0
	v_mfma_f32_16x16x32_bf16 v[10:13], v[172:175], v[196:199], 0
	v_mfma_f32_16x16x32_bf16 v[6:9], v[164:167], v[204:207], 0
	v_mfma_f32_16x16x32_bf16 v[2:5], v[172:175], v[204:207], 0
	v_mfma_f32_16x16x32_bf16 v[50:53], v[168:171], v[184:187], v[50:53]
	v_mfma_f32_16x16x32_bf16 v[42:45], v[176:179], v[184:187], v[42:45]
	v_mfma_f32_16x16x32_bf16 v[34:37], v[168:171], v[192:195], v[34:37]
	v_mfma_f32_16x16x32_bf16 v[26:29], v[176:179], v[192:195], v[26:29]
	v_mfma_f32_16x16x32_bf16 v[18:21], v[168:171], v[200:203], v[18:21]
	v_mfma_f32_16x16x32_bf16 v[10:13], v[176:179], v[200:203], v[10:13]
	v_mfma_f32_16x16x32_bf16 v[6:9], v[168:171], v[208:211], v[6:9]
	v_mfma_f32_16x16x32_bf16 v[2:5], v[176:179], v[208:211], v[2:5]
	s_barrier
; #define PG8_STAGE(bufoff, gbase, voff) do { if constexpr (VAR != 1 && VAR != 3) { _Pragma("unroll") for (int _i = 0; _i < 2; ++_i) \
;         asm volatile("s_mov_b32 m0, %2\n\ts_nop 0\n\tglobal_load_lds_dwordx4 %0, %1" :: "v"((voff)[_i]), "s"((const char*)(gbase)), "s"(ldsbase + (unsigned)((bufoff) + _i * 8192)) : "memory", "m0"); } } while (0)
; #define PG8_LDA(dst, b, h) do { if constexpr (VAR < 2) _Pragma("unroll") for (int m = 0; m < 4; ++m) _Pragma("unroll") for (int k = 0; k < 2; ++k) dst[m][k] = *(const LAS bf16x8*)(lds + PG8_SA(b, h) + aoff + m * 2048 + k * 1024); } while (0)
; #define PG8_LDB(dst, b, h) do { if constexpr (VAR < 2) _Pragma("unroll") for (int n = 0; n < 2; ++n) _Pragma("unroll") for (int k = 0; k < 2; ++k) dst[n][k] = *(const LAS bf16x8*)(lds + PG8_SB(b, h) + boff + n * 2048 + k * 1024); } while (0)
; #define PG8_WAIT_V(n) asm volatile("s_waitcnt vmcnt(" #n ")" ::: "memory")
; #define PG8_WAIT_L(n) asm volatile("s_waitcnt lgkmcnt(" #n ")" ::: "memory")
; #define PG8_BAR do { if constexpr (VAR != 3) __builtin_amdgcn_s_barrier(); } while (0)
; #define PG8_SCHED __builtin_amdgcn_sched_barrier(0)
;     ...
;             PG8_LDB(B0, 1, 0); PG8_LDB(B1, 1, 1); PG8_SCHED; PG8_LDA(At, 1, 0); PG8_STAGE(PG8_SA(0, 1), a2 + hstepA, voffA);
;             PG8_WAIT_V(8); PG8_WAIT_L(0); PG8_BAR; PG8_MMA(0, 0, At, B0); PG8_MMA(0, 1, At, B1); PG8_BAR; PG8_SCHED;
;             PG8_LDA(At, 1, 1); PG8_STAGE(PG8_SB(1, 0), b3, voffB); PG8_STAGE(PG8_SB(1, 1), b3 + hstepB, voffB); PG8_STAGE(PG8_SA(1, 0), a3, voffA);
;             PG8_WAIT_V(8); PG8_WAIT_L(0); PG8_BAR; PG8_MMA(1, 0, At, B0); PG8_MMA(1, 1, At, B1); PG8_BAR; PG8_SCHED;
;         }
	ds_read_b128 v[148:151], v145
	ds_read_b128 v[152:155], v145 offset:1024
	ds_read_b128 v[156:159], v145 offset:2048
	ds_read_b128 v[160:163], v145 offset:3072
	ds_read_b128 v[164:167], v146
	ds_read_b128 v[168:171], v146 offset:1024
	ds_read_b128 v[172:175], v146 offset:2048
	ds_read_b128 v[176:179], v146 offset:3072
	ds_read_b128 v[180:183], v144 offset:32768
	ds_read_b128 v[184:187], v144 offset:33792
	ds_read_b128 v[188:191], v144 offset:34816
	ds_read_b128 v[192:195], v144 offset:35840
	ds_read_b128 v[196:199], v144 offset:36864
	ds_read_b128 v[200:203], v144 offset:37888
	ds_read_b128 v[204:207], v144 offset:38912
	ds_read_b128 v[208:211], v144 offset:39936
	s_add_u32 s70, s70, 0x100000
	s_addc_u32 s71, s71, 0
	s_mov_b32 m0, s29
	s_nop 0
	global_load_lds_dwordx4 v138, s[70:71]
	s_mov_b32 m0, s30
	s_nop 0
	global_load_lds_dwordx4 v140, s[70:71]
	s_waitcnt vmcnt(8) lgkmcnt(0)
	s_barrier
	v_mfma_f32_16x16x32_bf16 v[126:129], v[148:151], v[180:183], v[126:129]
	v_mfma_f32_16x16x32_bf16 v[122:125], v[156:159], v[180:183], v[122:125]
	v_mfma_f32_16x16x32_bf16 v[118:121], v[148:151], v[188:191], v[118:121]
	v_mfma_f32_16x16x32_bf16 v[110:113], v[156:159], v[188:191], v[110:113]
	v_mfma_f32_16x16x32_bf16 v[102:105], v[148:151], v[196:199], v[102:105]
	v_mfma_f32_16x16x32_bf16 v[94:97], v[156:159], v[196:199], v[94:97]
	v_mfma_f32_16x16x32_bf16 v[86:89], v[148:151], v[204:207], v[86:89]
	v_mfma_f32_16x16x32_bf16 v[78:81], v[156:159], v[204:207], v[78:81]
	v_mfma_f32_16x16x32_bf16 v[126:129], v[152:155], v[184:187], v[126:129]
	v_mfma_f32_16x16x32_bf16 v[122:125], v[160:163], v[184:187], v[122:125]
	v_mfma_f32_16x16x32_bf16 v[118:121], v[152:155], v[192:195], v[118:121]
	v_mfma_f32_16x16x32_bf16 v[110:113], v[160:163], v[192:195], v[110:113]
	v_mfma_f32_16x16x32_bf16 v[102:105], v[152:155], v[200:203], v[102:105]
	v_mfma_f32_16x16x32_bf16 v[94:97], v[160:163], v[200:203], v[94:97]
	v_mfma_f32_16x16x32_bf16 v[86:89], v[152:155], v[208:211], v[86:89]
	v_mfma_f32_16x16x32_bf16 v[78:81], v[160:163], v[208:211], v[78:81]
	v_mfma_f32_16x16x32_bf16 v[114:117], v[164:167], v[180:183], v[114:117]
	v_mfma_f32_16x16x32_bf16 v[106:109], v[172:175], v[180:183], v[106:109]
	v_mfma_f32_16x16x32_bf16 v[98:101], v[164:167], v[188:191], v[98:101]
	v_mfma_f32_16x16x32_bf16 v[90:93], v[172:175], v[188:191], v[90:93]
	v_mfma_f32_16x16x32_bf16 v[82:85], v[164:167], v[196:199], v[82:85]
	v_mfma_f32_16x16x32_bf16 v[74:77], v[172:175], v[196:199], v[74:77]
	v_mfma_f32_16x16x32_bf16 v[70:73], v[164:167], v[204:207], v[70:73]
	v_mfma_f32_16x16x32_bf16 v[66:69], v[172:175], v[204:207], v[66:69]
	v_mfma_f32_16x16x32_bf16 v[114:117], v[168:171], v[184:187], v[114:117]
	v_mfma_f32_16x16x32_bf16 v[106:109], v[176:179], v[184:187], v[106:109]
	v_mfma_f32_16x16x32_bf16 v[98:101], v[168:171], v[192:195], v[98:101]
	v_mfma_f32_16x16x32_bf16 v[90:93], v[176:179], v[192:195], v[90:93]
	v_mfma_f32_16x16x32_bf16 v[82:85], v[168:171], v[200:203], v[82:85]
	v_mfma_f32_16x16x32_bf16 v[74:77], v[176:179], v[200:203], v[74:77]
	v_mfma_f32_16x16x32_bf16 v[70:73], v[168:171], v[208:211], v[70:73]
	v_mfma_f32_16x16x32_bf16 v[66:69], v[176:179], v[208:211], v[66:69]
	s_barrier
	ds_read_b128 v[180:183], v144 offset:49152
	ds_read_b128 v[184:187], v144 offset:50176
	ds_read_b128 v[188:191], v144 offset:51200
	ds_read_b128 v[192:195], v144 offset:52224
	ds_read_b128 v[196:199], v144 offset:53248
	ds_read_b128 v[200:203], v144 offset:54272
	ds_read_b128 v[204:207], v144 offset:55296
	ds_read_b128 v[208:211], v144 offset:56320
	s_add_u32 s70, s68, 0x80
	s_addc_u32 s71, s69, 0
	s_mov_b32 m0, s31
	s_nop 0
	global_load_lds_dwordx4 v139, s[70:71]
	s_add_u32 s68, s68, 0x200080
	s_mov_b32 m0, s33
	s_nop 0
	global_load_lds_dwordx4 v141, s[70:71]
	s_addc_u32 s69, s69, 0
	s_mov_b32 m0, s74
	s_nop 0
	global_load_lds_dwordx4 v139, s[68:69]
	s_mov_b32 m0, s75
	s_nop 0
	global_load_lds_dwordx4 v141, s[68:69]
	s_mov_b32 m0, s72
	s_nop 0
	global_load_lds_dwordx4 v138, s[66:67]
	s_mov_b32 m0, s73
	s_nop 0
	global_load_lds_dwordx4 v140, s[66:67]
	s_waitcnt vmcnt(8) lgkmcnt(0)
	s_barrier
	v_mfma_f32_16x16x32_bf16 v[62:65], v[148:151], v[180:183], v[62:65]
	v_mfma_f32_16x16x32_bf16 v[58:61], v[156:159], v[180:183], v[58:61]
	v_mfma_f32_16x16x32_bf16 v[54:57], v[148:151], v[188:191], v[54:57]
	v_mfma_f32_16x16x32_bf16 v[46:49], v[156:159], v[188:191], v[46:49]
	v_mfma_f32_16x16x32_bf16 v[38:41], v[148:151], v[196:199], v[38:41]
	v_mfma_f32_16x16x32_bf16 v[30:33], v[156:159], v[196:199], v[30:33]
	v_mfma_f32_16x16x32_bf16 v[22:25], v[148:151], v[204:207], v[22:25]
	v_mfma_f32_16x16x32_bf16 v[14:17], v[156:159], v[204:207], v[14:17]
	v_mfma_f32_16x16x32_bf16 v[62:65], v[152:155], v[184:187], v[62:65]
	v_mfma_f32_16x16x32_bf16 v[58:61], v[160:163], v[184:187], v[58:61]
	v_mfma_f32_16x16x32_bf16 v[54:57], v[152:155], v[192:195], v[54:57]
	v_mfma_f32_16x16x32_bf16 v[46:49], v[160:163], v[192:195], v[46:49]
	v_mfma_f32_16x16x32_bf16 v[38:41], v[152:155], v[200:203], v[38:41]
	v_mfma_f32_16x16x32_bf16 v[30:33], v[160:163], v[200:203], v[30:33]
	v_mfma_f32_16x16x32_bf16 v[22:25], v[152:155], v[208:211], v[22:25]
	v_mfma_f32_16x16x32_bf16 v[14:17], v[160:163], v[208:211], v[14:17]
	v_mfma_f32_16x16x32_bf16 v[50:53], v[164:167], v[180:183], v[50:53]
	v_mfma_f32_16x16x32_bf16 v[42:45], v[172:175], v[180:183], v[42:45]
	v_mfma_f32_16x16x32_bf16 v[34:37], v[164:167], v[188:191], v[34:37]
	v_mfma_f32_16x16x32_bf16 v[26:29], v[172:175], v[188:191], v[26:29]
	v_mfma_f32_16x16x32_bf16 v[18:21], v[164:167], v[196:199], v[18:21]
	v_mfma_f32_16x16x32_bf16 v[10:13], v[172:175], v[196:199], v[10:13]
	v_mfma_f32_16x16x32_bf16 v[6:9], v[164:167], v[204:207], v[6:9]
	v_mfma_f32_16x16x32_bf16 v[2:5], v[172:175], v[204:207], v[2:5]
	v_mfma_f32_16x16x32_bf16 v[50:53], v[168:171], v[184:187], v[50:53]
	v_mfma_f32_16x16x32_bf16 v[42:45], v[176:179], v[184:187], v[42:45]
	v_mfma_f32_16x16x32_bf16 v[34:37], v[168:171], v[192:195], v[34:37]
	v_mfma_f32_16x16x32_bf16 v[26:29], v[176:179], v[192:195], v[26:29]
	v_mfma_f32_16x16x32_bf16 v[18:21], v[168:171], v[200:203], v[18:21]
	v_mfma_f32_16x16x32_bf16 v[10:13], v[176:179], v[200:203], v[10:13]
	v_mfma_f32_16x16x32_bf16 v[6:9], v[168:171], v[208:211], v[6:9]
	v_mfma_f32_16x16x32_bf16 v[2:5], v[176:179], v[208:211], v[2:5]
	s_barrier
	s_add_i32 s6, s6, 2
	s_add_u32 s57, s57, 0x100
	s_addc_u32 s81, s81, 0
	s_add_u32 s82, s82, 0x100
	s_addc_u32 s83, s83, 0
	s_add_u32 s64, s64, 0x100
	s_addc_u32 s65, s65, 0
	s_cmp_gt_u32 s6, 13
	s_cbranch_scc0 .LBB0_701
	s_branch .Lmy_kexit_4
; #define PG8_STAGE(bufoff, gbase, voff) do { if constexpr (VAR != 1 && VAR != 3) { _Pragma("unroll") for (int _i = 0; _i < 2; ++_i) \
;         asm volatile("s_mov_b32 m0, %2\n\ts_nop 0\n\tglobal_load_lds_dwordx4 %0, %1" :: "v"((voff)[_i]), "s"((const char*)(gbase)), "s"(ldsbase + (unsigned)((bufoff) + _i * 8192)) : "memory", "m0"); } } while (0)
; #define PG8_LDA(dst, b, h) do { if constexpr (VAR < 2) _Pragma("unroll") for (int m = 0; m < 4; ++m) _Pragma("unroll") for (int k = 0; k < 2; ++k) dst[m][k] = *(const LAS bf16x8*)(lds + PG8_SA(b, h) + aoff + m * 2048 + k * 1024); } while (0)
; #define PG8_LDB(dst, b, h) do { if constexpr (VAR < 2) _Pragma("unroll") for (int n = 0; n < 2; ++n) _Pragma("unroll") for (int k = 0; k < 2; ++k) dst[n][k] = *(const LAS bf16x8*)(lds + PG8_SB(b, h) + boff + n * 2048 + k * 1024); } while (0)
; #define PG8_WAIT_V(n) asm volatile("s_waitcnt vmcnt(" #n ")" ::: "memory")
; #define PG8_WAIT_L(n) asm volatile("s_waitcnt lgkmcnt(" #n ")" ::: "memory")
; #define PG8_BAR do { if constexpr (VAR != 3) __builtin_amdgcn_s_barrier(); } while (0)
; #define PG8_SCHED __builtin_amdgcn_sched_barrier(0)
;     ...
;         for (int t = 0; t < nt; t += 2) {
;             const bool last = (t == nt - 2);
;             const char* a1 = cA + (size_t)(t + 1) * kstep;
;             const char* a2 = last ? nA : cA + (size_t)(t + 2) * kstep; const char* b2 = last ? nB : cB + (size_t)(t + 2) * kstep;
;             const char* a3 = a2 + kstep; const char* b3 = b2 + kstep;
;             PG8_LDB(B0, 0, 0); PG8_LDB(B1, 0, 1); PG8_SCHED; PG8_LDA(At, 0, 0); PG8_STAGE(PG8_SA(1, 1), a1 + hstepA, voffA);
;             PG8_WAIT_V(8); PG8_WAIT_L(0); PG8_BAR; PG8_MMA(0, 0, At, B0); PG8_MMA(0, 1, At, B1); PG8_BAR; PG8_SCHED;
;             PG8_LDA(At, 0, 1); PG8_STAGE(PG8_SB(0, 0), b2, voffB); PG8_STAGE(PG8_SB(0, 1), b2 + hstepB, voffB); PG8_STAGE(PG8_SA(0, 0), a2, voffA);
;             PG8_WAIT_V(8); PG8_WAIT_L(0); PG8_BAR; PG8_MMA(1, 0, At, B0); PG8_MMA(1, 1, At, B1); PG8_BAR; PG8_SCHED;
.LBB0_701:
	ds_read_b128 v[148:151], v1
	ds_read_b128 v[152:155], v1 offset:1024
	ds_read_b128 v[156:159], v1 offset:2048
	ds_read_b128 v[160:163], v1 offset:3072
	ds_read_b128 v[164:167], v143
	ds_read_b128 v[168:171], v143 offset:1024
	ds_read_b128 v[172:175], v143 offset:2048
	ds_read_b128 v[176:179], v143 offset:3072
	s_cmp_eq_u32 s6, 12
	s_cselect_b32 s70, s0, s57
	s_cselect_b32 s71, s1, s81
	s_cselect_b32 s68, s62, s82
	s_cselect_b32 s69, s63, s83
	s_add_u32 s66, s70, 0x80
	s_addc_u32 s67, s71, 0
	ds_read_b128 v[180:183], v144
	ds_read_b128 v[184:187], v144 offset:1024
	ds_read_b128 v[188:191], v144 offset:2048
	ds_read_b128 v[192:195], v144 offset:3072
	ds_read_b128 v[196:199], v144 offset:4096
	ds_read_b128 v[200:203], v144 offset:5120
	ds_read_b128 v[204:207], v144 offset:6144
	ds_read_b128 v[208:211], v144 offset:7168
	s_mov_b32 m0, s76
	s_nop 0
	global_load_lds_dwordx4 v138, s[64:65]
	s_mov_b32 m0, s77
	s_nop 0
	global_load_lds_dwordx4 v140, s[64:65]
	s_waitcnt vmcnt(8) lgkmcnt(0)
	s_barrier
	v_mfma_f32_16x16x32_bf16 v[126:129], v[148:151], v[180:183], v[126:129]
	v_mfma_f32_16x16x32_bf16 v[122:125], v[156:159], v[180:183], v[122:125]
	v_mfma_f32_16x16x32_bf16 v[118:121], v[148:151], v[188:191], v[118:121]
	v_mfma_f32_16x16x32_bf16 v[110:113], v[156:159], v[188:191], v[110:113]
	v_mfma_f32_16x16x32_bf16 v[102:105], v[148:151], v[196:199], v[102:105]
	v_mfma_f32_16x16x32_bf16 v[94:97], v[156:159], v[196:199], v[94:97]
	v_mfma_f32_16x16x32_bf16 v[86:89], v[148:151], v[204:207], v[86:89]
	v_mfma_f32_16x16x32_bf16 v[78:81], v[156:159], v[204:207], v[78:81]
	v_mfma_f32_16x16x32_bf16 v[126:129], v[152:155], v[184:187], v[126:129]
	v_mfma_f32_16x16x32_bf16 v[122:125], v[160:163], v[184:187], v[122:125]
	v_mfma_f32_16x16x32_bf16 v[118:121], v[152:155], v[192:195], v[118:121]
	v_mfma_f32_16x16x32_bf16 v[110:113], v[160:163], v[192:195], v[110:113]
	v_mfma_f32_16x16x32_bf16 v[102:105], v[152:155], v[200:203], v[102:105]
	v_mfma_f32_16x16x32_bf16 v[94:97], v[160:163], v[200:203], v[94:97]
	v_mfma_f32_16x16x32_bf16 v[86:89], v[152:155], v[208:211], v[86:89]
	v_mfma_f32_16x16x32_bf16 v[78:81], v[160:163], v[208:211], v[78:81]
	v_mfma_f32_16x16x32_bf16 v[114:117], v[164:167], v[180:183], v[114:117]
	v_mfma_f32_16x16x32_bf16 v[106:109], v[172:175], v[180:183], v[106:109]
	v_mfma_f32_16x16x32_bf16 v[98:101], v[164:167], v[188:191], v[98:101]
	v_mfma_f32_16x16x32_bf16 v[90:93], v[172:175], v[188:191], v[90:93]
	v_mfma_f32_16x16x32_bf16 v[82:85], v[164:167], v[196:199], v[82:85]
	v_mfma_f32_16x16x32_bf16 v[74:77], v[172:175], v[196:199], v[74:77]
	v_mfma_f32_16x16x32_bf16 v[70:73], v[164:167], v[204:207], v[70:73]
	v_mfma_f32_16x16x32_bf16 v[66:69], v[172:175], v[204:207], v[66:69]
	v_mfma_f32_16x16x32_bf16 v[114:117], v[168:171], v[184:187], v[114:117]
	v_mfma_f32_16x16x32_bf16 v[106:109], v[176:179], v[184:187], v[106:109]
	v_mfma_f32_16x16x32_bf16 v[98:101], v[168:171], v[192:195], v[98:101]
	v_mfma_f32_16x16x32_bf16 v[90:93], v[176:179], v[192:195], v[90:93]
	v_mfma_f32_16x16x32_bf16 v[82:85], v[168:171], v[200:203], v[82:85]
	v_mfma_f32_16x16x32_bf16 v[74:77], v[176:179], v[200:203], v[74:77]
	v_mfma_f32_16x16x32_bf16 v[70:73], v[168:171], v[208:211], v[70:73]
	v_mfma_f32_16x16x32_bf16 v[66:69], v[176:179], v[208:211], v[66:69]
	s_barrier
	ds_read_b128 v[180:183], v144 offset:16384
	ds_read_b128 v[184:187], v144 offset:17408
	ds_read_b128 v[188:191], v144 offset:18432
	ds_read_b128 v[192:195], v144 offset:19456
	ds_read_b128 v[196:199], v144 offset:20480
	ds_read_b128 v[200:203], v144 offset:21504
	ds_read_b128 v[204:207], v144 offset:22528
	ds_read_b128 v[208:211], v144 offset:23552
	s_mov_b32 m0, s24
	s_nop 0
	global_load_lds_dwordx4 v139, s[68:69]
	s_add_u32 s84, s68, 0x200000
	s_mov_b32 m0, s25
	s_nop 0
	global_load_lds_dwordx4 v141, s[68:69]
	s_addc_u32 s85, s69, 0
	s_mov_b32 m0, s26
	s_nop 0
	global_load_lds_dwordx4 v139, s[84:85]
	s_mov_b32 m0, s27
	s_nop 0
	global_load_lds_dwordx4 v141, s[84:85]
	s_mov_b32 m0, s15
	s_nop 0
	global_load_lds_dwordx4 v138, s[70:71]
	s_mov_b32 m0, s28
	s_nop 0
	global_load_lds_dwordx4 v140, s[70:71]
	s_waitcnt vmcnt(8) lgkmcnt(0)
	s_barrier
	v_mfma_f32_16x16x32_bf16 v[62:65], v[148:151], v[180:183], v[62:65]
	v_mfma_f32_16x16x32_bf16 v[58:61], v[156:159], v[180:183], v[58:61]
	v_mfma_f32_16x16x32_bf16 v[54:57], v[148:151], v[188:191], v[54:57]
	v_mfma_f32_16x16x32_bf16 v[46:49], v[156:159], v[188:191], v[46:49]
	v_mfma_f32_16x16x32_bf16 v[38:41], v[148:151], v[196:199], v[38:41]
	v_mfma_f32_16x16x32_bf16 v[30:33], v[156:159], v[196:199], v[30:33]
	v_mfma_f32_16x16x32_bf16 v[22:25], v[148:151], v[204:207], v[22:25]
	v_mfma_f32_16x16x32_bf16 v[14:17], v[156:159], v[204:207], v[14:17]
	v_mfma_f32_16x16x32_bf16 v[62:65], v[152:155], v[184:187], v[62:65]
	v_mfma_f32_16x16x32_bf16 v[58:61], v[160:163], v[184:187], v[58:61]
	v_mfma_f32_16x16x32_bf16 v[54:57], v[152:155], v[192:195], v[54:57]
	v_mfma_f32_16x16x32_bf16 v[46:49], v[160:163], v[192:195], v[46:49]
	v_mfma_f32_16x16x32_bf16 v[38:41], v[152:155], v[200:203], v[38:41]
	v_mfma_f32_16x16x32_bf16 v[30:33], v[160:163], v[200:203], v[30:33]
	v_mfma_f32_16x16x32_bf16 v[22:25], v[152:155], v[208:211], v[22:25]
	v_mfma_f32_16x16x32_bf16 v[14:17], v[160:163], v[208:211], v[14:17]
	v_mfma_f32_16x16x32_bf16 v[50:53], v[164:167], v[180:183], v[50:53]
	v_mfma_f32_16x16x32_bf16 v[42:45], v[172:175], v[180:183], v[42:45]
	v_mfma_f32_16x16x32_bf16 v[34:37], v[164:167], v[188:191], v[34:37]
	v_mfma_f32_16x16x32_bf16 v[26:29], v[172:175], v[188:191], v[26:29]
	v_mfma_f32_16x16x32_bf16 v[18:21], v[164:167], v[196:199], v[18:21]
	v_mfma_f32_16x16x32_bf16 v[10:13], v[172:175], v[196:199], v[10:13]
	v_mfma_f32_16x16x32_bf16 v[6:9], v[164:167], v[204:207], v[6:9]
	v_mfma_f32_16x16x32_bf16 v[2:5], v[172:175], v[204:207], v[2:5]
	v_mfma_f32_16x16x32_bf16 v[50:53], v[168:171], v[184:187], v[50:53]
	v_mfma_f32_16x16x32_bf16 v[42:45], v[176:179], v[184:187], v[42:45]
	v_mfma_f32_16x16x32_bf16 v[34:37], v[168:171], v[192:195], v[34:37]
	v_mfma_f32_16x16x32_bf16 v[26:29], v[176:179], v[192:195], v[26:29]
	v_mfma_f32_16x16x32_bf16 v[18:21], v[168:171], v[200:203], v[18:21]
	v_mfma_f32_16x16x32_bf16 v[10:13], v[176:179], v[200:203], v[10:13]
	v_mfma_f32_16x16x32_bf16 v[6:9], v[168:171], v[208:211], v[6:9]
	v_mfma_f32_16x16x32_bf16 v[2:5], v[176:179], v[208:211], v[2:5]
	s_barrier
; #define PG8_STAGE(bufoff, gbase, voff) do { if constexpr (VAR != 1 && VAR != 3) { _Pragma("unroll") for (int _i = 0; _i < 2; ++_i) \
;         asm volatile("s_mov_b32 m0, %2\n\ts_nop 0\n\tglobal_load_lds_dwordx4 %0, %1" :: "v"((voff)[_i]), "s"((const char*)(gbase)), "s"(ldsbase + (unsigned)((bufoff) + _i * 8192)) : "memory", "m0"); } } while (0)
; #define PG8_LDA(dst, b, h) do { if constexpr (VAR < 2) _Pragma("unroll") for (int m = 0; m < 4; ++m) _Pragma("unroll") for (int k = 0; k < 2; ++k) dst[m][k] = *(const LAS bf16x8*)(lds + PG8_SA(b, h) + aoff + m * 2048 + k * 1024); } while (0)
; #define PG8_LDB(dst, b, h) do { if constexpr (VAR < 2) _Pragma("unroll") for (int n = 0; n < 2; ++n) _Pragma("unroll") for (int k = 0; k < 2; ++k) dst[n][k] = *(const LAS bf16x8*)(lds + PG8_SB(b, h) + boff + n * 2048 + k * 1024); } while (0)
; #define PG8_WAIT_V(n) asm volatile("s_waitcnt vmcnt(" #n ")" ::: "memory")
; #define PG8_WAIT_L(n) asm volatile("s_waitcnt lgkmcnt(" #n ")" ::: "memory")
; #define PG8_BAR do { if constexpr (VAR != 3) __builtin_amdgcn_s_barrier(); } while (0)
; #define PG8_SCHED __builtin_amdgcn_sched_barrier(0)
;     ...
;             PG8_LDB(B0, 1, 0); PG8_LDB(B1, 1, 1); PG8_SCHED; PG8_LDA(At, 1, 0); PG8_STAGE(PG8_SA(0, 1), a2 + hstepA, voffA);
;             PG8_WAIT_V(8); PG8_WAIT_L(0); PG8_BAR; PG8_MMA(0, 0, At, B0); PG8_MMA(0, 1, At, B1); PG8_BAR; PG8_SCHED;
;             PG8_LDA(At, 1, 1); PG8_STAGE(PG8_SB(1, 0), b3, voffB); PG8_STAGE(PG8_SB(1, 1), b3 + hstepB, voffB); PG8_STAGE(PG8_SA(1, 0), a3, voffA);
;             PG8_WAIT_V(8); PG8_WAIT_L(0); PG8_BAR; PG8_MMA(1, 0, At, B0); PG8_MMA(1, 1, At, B1); PG8_BAR; PG8_SCHED;
;         }
	ds_read_b128 v[148:151], v145
	ds_read_b128 v[152:155], v145 offset:1024
	ds_read_b128 v[156:159], v145 offset:2048
	ds_read_b128 v[160:163], v145 offset:3072
	ds_read_b128 v[164:167], v146
	ds_read_b128 v[168:171], v146 offset:1024
	ds_read_b128 v[172:175], v146 offset:2048
	ds_read_b128 v[176:179], v146 offset:3072
	ds_read_b128 v[180:183], v144 offset:32768
	ds_read_b128 v[184:187], v144 offset:33792
	ds_read_b128 v[188:191], v144 offset:34816
	ds_read_b128 v[192:195], v144 offset:35840
	ds_read_b128 v[196:199], v144 offset:36864
	ds_read_b128 v[200:203], v144 offset:37888
	ds_read_b128 v[204:207], v144 offset:38912
	ds_read_b128 v[208:211], v144 offset:39936
	s_add_u32 s70, s70, 0x100000
	s_addc_u32 s71, s71, 0
	s_mov_b32 m0, s29
	s_nop 0
	global_load_lds_dwordx4 v138, s[70:71]
	s_mov_b32 m0, s30
	s_nop 0
	global_load_lds_dwordx4 v140, s[70:71]
	s_waitcnt vmcnt(8) lgkmcnt(0)
	s_barrier
	v_mfma_f32_16x16x32_bf16 v[126:129], v[148:151], v[180:183], v[126:129]
	v_mfma_f32_16x16x32_bf16 v[122:125], v[156:159], v[180:183], v[122:125]
	v_mfma_f32_16x16x32_bf16 v[118:121], v[148:151], v[188:191], v[118:121]
	v_mfma_f32_16x16x32_bf16 v[110:113], v[156:159], v[188:191], v[110:113]
	v_mfma_f32_16x16x32_bf16 v[102:105], v[148:151], v[196:199], v[102:105]
	v_mfma_f32_16x16x32_bf16 v[94:97], v[156:159], v[196:199], v[94:97]
	v_mfma_f32_16x16x32_bf16 v[86:89], v[148:151], v[204:207], v[86:89]
	v_mfma_f32_16x16x32_bf16 v[78:81], v[156:159], v[204:207], v[78:81]
	v_mfma_f32_16x16x32_bf16 v[126:129], v[152:155], v[184:187], v[126:129]
	v_mfma_f32_16x16x32_bf16 v[122:125], v[160:163], v[184:187], v[122:125]
	v_mfma_f32_16x16x32_bf16 v[118:121], v[152:155], v[192:195], v[118:121]
	v_mfma_f32_16x16x32_bf16 v[110:113], v[160:163], v[192:195], v[110:113]
	v_mfma_f32_16x16x32_bf16 v[102:105], v[152:155], v[200:203], v[102:105]
	v_mfma_f32_16x16x32_bf16 v[94:97], v[160:163], v[200:203], v[94:97]
	v_mfma_f32_16x16x32_bf16 v[86:89], v[152:155], v[208:211], v[86:89]
	v_mfma_f32_16x16x32_bf16 v[78:81], v[160:163], v[208:211], v[78:81]
	v_mfma_f32_16x16x32_bf16 v[114:117], v[164:167], v[180:183], v[114:117]
	v_mfma_f32_16x16x32_bf16 v[106:109], v[172:175], v[180:183], v[106:109]
	v_mfma_f32_16x16x32_bf16 v[98:101], v[164:167], v[188:191], v[98:101]
	v_mfma_f32_16x16x32_bf16 v[90:93], v[172:175], v[188:191], v[90:93]
	v_mfma_f32_16x16x32_bf16 v[82:85], v[164:167], v[196:199], v[82:85]
	v_mfma_f32_16x16x32_bf16 v[74:77], v[172:175], v[196:199], v[74:77]
	v_mfma_f32_16x16x32_bf16 v[70:73], v[164:167], v[204:207], v[70:73]
	v_mfma_f32_16x16x32_bf16 v[66:69], v[172:175], v[204:207], v[66:69]
	v_mfma_f32_16x16x32_bf16 v[114:117], v[168:171], v[184:187], v[114:117]
	v_mfma_f32_16x16x32_bf16 v[106:109], v[176:179], v[184:187], v[106:109]
	v_mfma_f32_16x16x32_bf16 v[98:101], v[168:171], v[192:195], v[98:101]
	v_mfma_f32_16x16x32_bf16 v[90:93], v[176:179], v[192:195], v[90:93]
	v_mfma_f32_16x16x32_bf16 v[82:85], v[168:171], v[200:203], v[82:85]
	v_mfma_f32_16x16x32_bf16 v[74:77], v[176:179], v[200:203], v[74:77]
	v_mfma_f32_16x16x32_bf16 v[70:73], v[168:171], v[208:211], v[70:73]
	v_mfma_f32_16x16x32_bf16 v[66:69], v[176:179], v[208:211], v[66:69]
	s_barrier
	ds_read_b128 v[180:183], v144 offset:49152
	ds_read_b128 v[184:187], v144 offset:50176
	ds_read_b128 v[188:191], v144 offset:51200
	ds_read_b128 v[192:195], v144 offset:52224
	ds_read_b128 v[196:199], v144 offset:53248
	ds_read_b128 v[200:203], v144 offset:54272
	ds_read_b128 v[204:207], v144 offset:55296
	ds_read_b128 v[208:211], v144 offset:56320
	s_add_u32 s70, s68, 0x80
	s_addc_u32 s71, s69, 0
	s_mov_b32 m0, s31
	s_nop 0
	global_load_lds_dwordx4 v139, s[70:71]
	s_add_u32 s68, s68, 0x200080
	s_mov_b32 m0, s33
	s_nop 0
	global_load_lds_dwordx4 v141, s[70:71]
	s_addc_u32 s69, s69, 0
	s_mov_b32 m0, s74
	s_nop 0
	global_load_lds_dwordx4 v139, s[68:69]
	s_mov_b32 m0, s75
	s_nop 0
	global_load_lds_dwordx4 v141, s[68:69]
	s_mov_b32 m0, s72
	s_nop 0
	global_load_lds_dwordx4 v138, s[66:67]
	s_mov_b32 m0, s73
	s_nop 0
	global_load_lds_dwordx4 v140, s[66:67]
	s_waitcnt vmcnt(8) lgkmcnt(0)
	s_barrier
	v_mfma_f32_16x16x32_bf16 v[62:65], v[148:151], v[180:183], v[62:65]
	v_mfma_f32_16x16x32_bf16 v[58:61], v[156:159], v[180:183], v[58:61]
	v_mfma_f32_16x16x32_bf16 v[54:57], v[148:151], v[188:191], v[54:57]
	v_mfma_f32_16x16x32_bf16 v[46:49], v[156:159], v[188:191], v[46:49]
	v_mfma_f32_16x16x32_bf16 v[38:41], v[148:151], v[196:199], v[38:41]
	v_mfma_f32_16x16x32_bf16 v[30:33], v[156:159], v[196:199], v[30:33]
	v_mfma_f32_16x16x32_bf16 v[22:25], v[148:151], v[204:207], v[22:25]
	v_mfma_f32_16x16x32_bf16 v[14:17], v[156:159], v[204:207], v[14:17]
	v_mfma_f32_16x16x32_bf16 v[62:65], v[152:155], v[184:187], v[62:65]
	v_mfma_f32_16x16x32_bf16 v[58:61], v[160:163], v[184:187], v[58:61]
	v_mfma_f32_16x16x32_bf16 v[54:57], v[152:155], v[192:195], v[54:57]
	v_mfma_f32_16x16x32_bf16 v[46:49], v[160:163], v[192:195], v[46:49]
	v_mfma_f32_16x16x32_bf16 v[38:41], v[152:155], v[200:203], v[38:41]
	v_mfma_f32_16x16x32_bf16 v[30:33], v[160:163], v[200:203], v[30:33]
	v_mfma_f32_16x16x32_bf16 v[22:25], v[152:155], v[208:211], v[22:25]
	v_mfma_f32_16x16x32_bf16 v[14:17], v[160:163], v[208:211], v[14:17]
	v_mfma_f32_16x16x32_bf16 v[50:53], v[164:167], v[180:183], v[50:53]
	v_mfma_f32_16x16x32_bf16 v[42:45], v[172:175], v[180:183], v[42:45]
	v_mfma_f32_16x16x32_bf16 v[34:37], v[164:167], v[188:191], v[34:37]
	v_mfma_f32_16x16x32_bf16 v[26:29], v[172:175], v[188:191], v[26:29]
	v_mfma_f32_16x16x32_bf16 v[18:21], v[164:167], v[196:199], v[18:21]
	v_mfma_f32_16x16x32_bf16 v[10:13], v[172:175], v[196:199], v[10:13]
	v_mfma_f32_16x16x32_bf16 v[6:9], v[164:167], v[204:207], v[6:9]
	v_mfma_f32_16x16x32_bf16 v[2:5], v[172:175], v[204:207], v[2:5]
	v_mfma_f32_16x16x32_bf16 v[50:53], v[168:171], v[184:187], v[50:53]
	v_mfma_f32_16x16x32_bf16 v[42:45], v[176:179], v[184:187], v[42:45]
	v_mfma_f32_16x16x32_bf16 v[34:37], v[168:171], v[192:195], v[34:37]
	v_mfma_f32_16x16x32_bf16 v[26:29], v[176:179], v[192:195], v[26:29]
	v_mfma_f32_16x16x32_bf16 v[18:21], v[168:171], v[200:203], v[18:21]
	v_mfma_f32_16x16x32_bf16 v[10:13], v[176:179], v[200:203], v[10:13]
	v_mfma_f32_16x16x32_bf16 v[6:9], v[168:171], v[208:211], v[6:9]
	v_mfma_f32_16x16x32_bf16 v[2:5], v[176:179], v[208:211], v[2:5]
	s_barrier
	s_add_i32 s6, s6, 2
	s_add_u32 s57, s57, 0x100
	s_addc_u32 s81, s81, 0
	s_add_u32 s82, s82, 0x100
	s_addc_u32 s83, s83, 0
	s_add_u32 s64, s64, 0x100
	s_addc_u32 s65, s65, 0
	s_cmp_gt_u32 s6, 13
	s_cbranch_scc0 .LBB0_701

; __device__ __forceinline__ const char* unitA(const Gemm& g, const Unit& u) { return (const char*)(g.A + (size_t)(u.z / g.zdiv) * g.sAhi + (size_t)(u.z % g.zdiv) * g.sAlo + (size_t)u.pm * BM * g.lda); }
; __device__ __forceinline__ const char* unitB(const Gemm& g, const Unit& u) { return (const char*)(g.Bt + (size_t)(u.z / g.zdiv) * g.sBhi + (size_t)(u.z % g.zdiv) * g.sBlo + (size_t)(u.pm / g.bdiv) * g.sBpm + (size_t)u.pn * BM * g.ldb); }
; #define PG8_STAGE(bufoff, gbase, voff) do { if constexpr (VAR != 1 && VAR != 3) { _Pragma("unroll") for (int _i = 0; _i < 2; ++_i) \
;         asm volatile("s_mov_b32 m0, %2\n\ts_nop 0\n\tglobal_load_lds_dwordx4 %0, %1" :: "v"((voff)[_i]), "s"((const char*)(gbase)), "s"(ldsbase + (unsigned)((bufoff) + _i * 8192)) : "memory", "m0"); } } while (0)
; #define PG8_LDA(dst, b, h) do { if constexpr (VAR < 2) _Pragma("unroll") for (int m = 0; m < 4; ++m) _Pragma("unroll") for (int k = 0; k < 2; ++k) dst[m][k] = *(const LAS bf16x8*)(lds + PG8_SA(b, h) + aoff + m * 2048 + k * 1024); } while (0)
; #define PG8_LDB(dst, b, h) do { if constexpr (VAR < 2) _Pragma("unroll") for (int n = 0; n < 2; ++n) _Pragma("unroll") for (int k = 0; k < 2; ++k) dst[n][k] = *(const LAS bf16x8*)(lds + PG8_SB(b, h) + boff + n * 2048 + k * 1024); } while (0)
; #define PG8_WAIT_V(n) asm volatile("s_waitcnt vmcnt(" #n ")" ::: "memory")
; #define PG8_WAIT_L(n) asm volatile("s_waitcnt lgkmcnt(" #n ")" ::: "memory")
; #define PG8_BAR do { if constexpr (VAR != 3) __builtin_amdgcn_s_barrier(); } while (0)
; #define PG8_SCHED __builtin_amdgcn_sched_barrier(0)
;     ...
;         const bool has_next = S.next(ui + 1, nxt);
;         const char* nA = has_next ? unitA(g, nxt) : cA; const char* nB = has_next ? unitB(g, nxt) : cB;
;         for (int t = 0; t < nt; t += 2) {
;             const bool last = (t == nt - 2);
;             const char* a1 = cA + (size_t)(t + 1) * kstep;
;             const char* a2 = last ? nA : cA + (size_t)(t + 2) * kstep; const char* b2 = last ? nB : cB + (size_t)(t + 2) * kstep;
;             const char* a3 = a2 + kstep; const char* b3 = b2 + kstep;
;             PG8_LDB(B0, 0, 0); PG8_LDB(B1, 0, 1); PG8_SCHED; PG8_LDA(At, 0, 0); PG8_STAGE(PG8_SA(1, 1), a1 + hstepA, voffA);
;             PG8_WAIT_V(8); PG8_WAIT_L(0); PG8_BAR; PG8_MMA(0, 0, At, B0); PG8_MMA(0, 1, At, B1); PG8_BAR; PG8_SCHED;
.LBB0_788:
	s_ashr_i32 s73, s72, 31
	s_lshl_b64 s[14:15], s[72:73], 21
	s_add_u32 s74, s60, s14
	s_addc_u32 s75, s61, s15
	s_and_b64 s[14:15], s[10:11], exec
	s_cselect_b32 s14, s75, s83
	s_cselect_b32 s15, s74, s82
	s_ashr_i32 s71, s70, 31
	s_lshl_b64 s[26:27], s[70:71], 21
	s_add_u32 s76, s58, s26
	s_addc_u32 s77, s59, s27
	s_and_b64 s[26:27], s[10:11], exec
	s_cselect_b32 s25, s77, s81
	s_cselect_b32 s26, s76, s80
	s_add_u32 s27, s82, 0x100
	s_addc_u32 s71, s83, 0
	s_add_u32 s73, s80, 0x100
	s_addc_u32 vcc_lo, s81, 0
	s_add_u32 s80, s82, 0x100080
	s_addc_u32 s81, s83, 0
	s_mov_b32 vcc_hi, -2
	s_waitcnt vmcnt(41)
	s_waitcnt vmcnt(40)
	s_waitcnt vmcnt(38)
	s_waitcnt vmcnt(35)
	s_waitcnt vmcnt(34)
	s_waitcnt vmcnt(32)
	ds_read_b128 v[98:101], v191
	ds_read_b128 v[110:113], v191 offset:1024
	ds_read_b128 v[122:125], v191 offset:2048
	ds_read_b128 v[134:137], v191 offset:3072
	ds_read_b128 v[138:141], v192
	ds_read_b128 v[150:153], v192 offset:1024
	ds_read_b128 v[154:157], v192 offset:2048
	ds_read_b128 v[162:165], v192 offset:3072
	s_cmp_eq_u32 vcc_hi, 60
	s_cselect_b32 s86, s15, s27
	s_cselect_b32 s87, s14, s71
	s_cselect_b32 s84, s26, s73
	s_cselect_b32 s85, s25, vcc_lo
	s_add_u32 s82, s86, 0x80
	s_addc_u32 s83, s87, 0
	ds_read_b128 v[166:169], v193
	ds_read_b128 v[170:173], v193 offset:1024
	ds_read_b128 v[174:177], v193 offset:2048
	ds_read_b128 v[178:181], v193 offset:3072
	ds_read_b128 v[198:201], v193 offset:4096
	ds_read_b128 v[202:205], v193 offset:5120
	ds_read_b128 v[206:209], v193 offset:6144
	ds_read_b128 v[210:213], v193 offset:7168
	s_mov_b32 m0, s31
	s_nop 0
	global_load_lds_dwordx4 v184, s[80:81]
	s_mov_b32 m0, s19
	s_nop 0
	global_load_lds_dwordx4 v186, s[80:81]
	s_waitcnt vmcnt(8) lgkmcnt(0)
	s_barrier
	v_mfma_f32_16x16x32_bf16 v[146:149], v[98:101], v[166:169], 0
	v_mfma_f32_16x16x32_bf16 v[142:145], v[122:125], v[166:169], 0
	v_mfma_f32_16x16x32_bf16 v[118:121], v[98:101], v[174:177], 0
	v_mfma_f32_16x16x32_bf16 v[114:117], v[122:125], v[174:177], 0
	v_mfma_f32_16x16x32_bf16 v[94:97], v[98:101], v[198:201], 0
	v_mfma_f32_16x16x32_bf16 v[90:93], v[122:125], v[198:201], 0
	v_mfma_f32_16x16x32_bf16 v[78:81], v[98:101], v[206:209], 0
	v_mfma_f32_16x16x32_bf16 v[74:77], v[122:125], v[206:209], 0
	v_mfma_f32_16x16x32_bf16 v[146:149], v[110:113], v[170:173], v[146:149]
	v_mfma_f32_16x16x32_bf16 v[142:145], v[134:137], v[170:173], v[142:145]
	v_mfma_f32_16x16x32_bf16 v[118:121], v[110:113], v[178:181], v[118:121]
	v_mfma_f32_16x16x32_bf16 v[114:117], v[134:137], v[178:181], v[114:117]
	v_mfma_f32_16x16x32_bf16 v[94:97], v[110:113], v[202:205], v[94:97]
	v_mfma_f32_16x16x32_bf16 v[90:93], v[134:137], v[202:205], v[90:93]
	v_mfma_f32_16x16x32_bf16 v[78:81], v[110:113], v[210:213], v[78:81]
	v_mfma_f32_16x16x32_bf16 v[74:77], v[134:137], v[210:213], v[74:77]
	v_mfma_f32_16x16x32_bf16 v[130:133], v[138:141], v[166:169], 0
	v_mfma_f32_16x16x32_bf16 v[126:129], v[154:157], v[166:169], 0
	v_mfma_f32_16x16x32_bf16 v[106:109], v[138:141], v[174:177], 0
	v_mfma_f32_16x16x32_bf16 v[102:105], v[154:157], v[174:177], 0
	v_mfma_f32_16x16x32_bf16 v[86:89], v[138:141], v[198:201], 0
	v_mfma_f32_16x16x32_bf16 v[82:85], v[154:157], v[198:201], 0
	v_mfma_f32_16x16x32_bf16 v[70:73], v[138:141], v[206:209], 0
	v_mfma_f32_16x16x32_bf16 v[66:69], v[154:157], v[206:209], 0
	v_mfma_f32_16x16x32_bf16 v[130:133], v[150:153], v[170:173], v[130:133]
	v_mfma_f32_16x16x32_bf16 v[126:129], v[162:165], v[170:173], v[126:129]
	v_mfma_f32_16x16x32_bf16 v[106:109], v[150:153], v[178:181], v[106:109]
	v_mfma_f32_16x16x32_bf16 v[102:105], v[162:165], v[178:181], v[102:105]
	v_mfma_f32_16x16x32_bf16 v[86:89], v[150:153], v[202:205], v[86:89]
	v_mfma_f32_16x16x32_bf16 v[82:85], v[162:165], v[202:205], v[82:85]
	v_mfma_f32_16x16x32_bf16 v[70:73], v[150:153], v[210:213], v[70:73]
	v_mfma_f32_16x16x32_bf16 v[66:69], v[162:165], v[210:213], v[66:69]
	s_barrier
	ds_read_b128 v[166:169], v193 offset:16384
	ds_read_b128 v[170:173], v193 offset:17408
	ds_read_b128 v[174:177], v193 offset:18432
	ds_read_b128 v[178:181], v193 offset:19456
	ds_read_b128 v[198:201], v193 offset:20480
	ds_read_b128 v[202:205], v193 offset:21504
	ds_read_b128 v[206:209], v193 offset:22528
	ds_read_b128 v[210:213], v193 offset:23552
	s_mov_b32 m0, s91
	s_nop 0
	global_load_lds_dwordx4 v185, s[84:85]
	s_add_u32 s88, s84, 0x100000
	s_mov_b32 m0, s92
	s_nop 0
	global_load_lds_dwordx4 v187, s[84:85]
	s_addc_u32 s89, s85, 0
	s_mov_b32 m0, s93
	s_nop 0
	global_load_lds_dwordx4 v185, s[88:89]
	s_mov_b32 m0, s94
	s_nop 0
	global_load_lds_dwordx4 v187, s[88:89]
	s_mov_b32 m0, s35
	s_nop 0
	global_load_lds_dwordx4 v184, s[86:87]
	s_mov_b32 m0, s79
	s_nop 0
	global_load_lds_dwordx4 v186, s[86:87]
	s_waitcnt vmcnt(8) lgkmcnt(0)
	s_barrier
; #define PG8_STAGE(bufoff, gbase, voff) do { if constexpr (VAR != 1 && VAR != 3) { _Pragma("unroll") for (int _i = 0; _i < 2; ++_i) \
;         asm volatile("s_mov_b32 m0, %2\n\ts_nop 0\n\tglobal_load_lds_dwordx4 %0, %1" :: "v"((voff)[_i]), "s"((const char*)(gbase)), "s"(ldsbase + (unsigned)((bufoff) + _i * 8192)) : "memory", "m0"); } } while (0)
; #define PG8_LDA(dst, b, h) do { if constexpr (VAR < 2) _Pragma("unroll") for (int m = 0; m < 4; ++m) _Pragma("unroll") for (int k = 0; k < 2; ++k) dst[m][k] = *(const LAS bf16x8*)(lds + PG8_SA(b, h) + aoff + m * 2048 + k * 1024); } while (0)
; #define PG8_LDB(dst, b, h) do { if constexpr (VAR < 2) _Pragma("unroll") for (int n = 0; n < 2; ++n) _Pragma("unroll") for (int k = 0; k < 2; ++k) dst[n][k] = *(const LAS bf16x8*)(lds + PG8_SB(b, h) + boff + n * 2048 + k * 1024); } while (0)
; #define PG8_WAIT_V(n) asm volatile("s_waitcnt vmcnt(" #n ")" ::: "memory")
; #define PG8_WAIT_L(n) asm volatile("s_waitcnt lgkmcnt(" #n ")" ::: "memory")
; #define PG8_BAR do { if constexpr (VAR != 3) __builtin_amdgcn_s_barrier(); } while (0)
; #define PG8_SCHED __builtin_amdgcn_sched_barrier(0)
;     ...
;             PG8_WAIT_V(8); PG8_WAIT_L(0); PG8_BAR; PG8_MMA(0, 0, At, B0); PG8_MMA(0, 1, At, B1); PG8_BAR; PG8_SCHED;
;             PG8_LDA(At, 0, 1); PG8_STAGE(PG8_SB(0, 0), b2, voffB); PG8_STAGE(PG8_SB(0, 1), b2 + hstepB, voffB); PG8_STAGE(PG8_SA(0, 0), a2, voffA);
;             PG8_WAIT_V(8); PG8_WAIT_L(0); PG8_BAR; PG8_MMA(1, 0, At, B0); PG8_MMA(1, 1, At, B1); PG8_BAR; PG8_SCHED;
;             PG8_LDB(B0, 1, 0); PG8_LDB(B1, 1, 1); PG8_SCHED; PG8_LDA(At, 1, 0); PG8_STAGE(PG8_SA(0, 1), a2 + hstepA, voffA);
;             PG8_WAIT_V(8); PG8_WAIT_L(0); PG8_BAR; PG8_MMA(0, 0, At, B0); PG8_MMA(0, 1, At, B1); PG8_BAR; PG8_SCHED;
	v_mfma_f32_16x16x32_bf16 v[62:65], v[98:101], v[166:169], 0
	v_mfma_f32_16x16x32_bf16 v[58:61], v[122:125], v[166:169], 0
	v_mfma_f32_16x16x32_bf16 v[46:49], v[98:101], v[174:177], 0
	v_mfma_f32_16x16x32_bf16 v[42:45], v[122:125], v[174:177], 0
	v_mfma_f32_16x16x32_bf16 v[30:33], v[98:101], v[198:201], 0
	v_mfma_f32_16x16x32_bf16 v[26:29], v[122:125], v[198:201], 0
	v_mfma_f32_16x16x32_bf16 v[14:17], v[98:101], v[206:209], 0
	v_mfma_f32_16x16x32_bf16 v[10:13], v[122:125], v[206:209], 0
	v_mfma_f32_16x16x32_bf16 v[62:65], v[110:113], v[170:173], v[62:65]
	v_mfma_f32_16x16x32_bf16 v[58:61], v[134:137], v[170:173], v[58:61]
	v_mfma_f32_16x16x32_bf16 v[46:49], v[110:113], v[178:181], v[46:49]
	v_mfma_f32_16x16x32_bf16 v[42:45], v[134:137], v[178:181], v[42:45]
	v_mfma_f32_16x16x32_bf16 v[30:33], v[110:113], v[202:205], v[30:33]
	v_mfma_f32_16x16x32_bf16 v[26:29], v[134:137], v[202:205], v[26:29]
	v_mfma_f32_16x16x32_bf16 v[14:17], v[110:113], v[210:213], v[14:17]
	v_mfma_f32_16x16x32_bf16 v[10:13], v[134:137], v[210:213], v[10:13]
	v_mfma_f32_16x16x32_bf16 v[54:57], v[138:141], v[166:169], 0
	v_mfma_f32_16x16x32_bf16 v[50:53], v[154:157], v[166:169], 0
	v_mfma_f32_16x16x32_bf16 v[38:41], v[138:141], v[174:177], 0
	v_mfma_f32_16x16x32_bf16 v[34:37], v[154:157], v[174:177], 0
	v_mfma_f32_16x16x32_bf16 v[22:25], v[138:141], v[198:201], 0
	v_mfma_f32_16x16x32_bf16 v[18:21], v[154:157], v[198:201], 0
	v_mfma_f32_16x16x32_bf16 v[6:9], v[138:141], v[206:209], 0
	v_mfma_f32_16x16x32_bf16 v[2:5], v[154:157], v[206:209], 0
	v_mfma_f32_16x16x32_bf16 v[54:57], v[150:153], v[170:173], v[54:57]
	v_mfma_f32_16x16x32_bf16 v[50:53], v[162:165], v[170:173], v[50:53]
	v_mfma_f32_16x16x32_bf16 v[38:41], v[150:153], v[178:181], v[38:41]
	v_mfma_f32_16x16x32_bf16 v[34:37], v[162:165], v[178:181], v[34:37]
	v_mfma_f32_16x16x32_bf16 v[22:25], v[150:153], v[202:205], v[22:25]
	v_mfma_f32_16x16x32_bf16 v[18:21], v[162:165], v[202:205], v[18:21]
	v_mfma_f32_16x16x32_bf16 v[6:9], v[150:153], v[210:213], v[6:9]
	v_mfma_f32_16x16x32_bf16 v[2:5], v[162:165], v[210:213], v[2:5]
	s_barrier
	ds_read_b128 v[98:101], v194
	ds_read_b128 v[110:113], v194 offset:1024
	ds_read_b128 v[122:125], v194 offset:2048
	ds_read_b128 v[134:137], v194 offset:3072
	ds_read_b128 v[138:141], v195
	ds_read_b128 v[150:153], v195 offset:1024
	ds_read_b128 v[154:157], v195 offset:2048
	ds_read_b128 v[162:165], v195 offset:3072
	ds_read_b128 v[166:169], v193 offset:32768
	ds_read_b128 v[170:173], v193 offset:33792
	ds_read_b128 v[174:177], v193 offset:34816
	ds_read_b128 v[178:181], v193 offset:35840
	ds_read_b128 v[198:201], v193 offset:36864
	ds_read_b128 v[202:205], v193 offset:37888
	ds_read_b128 v[206:209], v193 offset:38912
	ds_read_b128 v[210:213], v193 offset:39936
	s_add_u32 s86, s86, 0x100000
	s_addc_u32 s87, s87, 0
	s_mov_b32 m0, s95
	s_nop 0
	global_load_lds_dwordx4 v184, s[86:87]
	s_mov_b32 m0, s96
	s_nop 0
	global_load_lds_dwordx4 v186, s[86:87]
	s_waitcnt vmcnt(8) lgkmcnt(0)
	s_barrier
	v_mfma_f32_16x16x32_bf16 v[146:149], v[98:101], v[166:169], v[146:149]
	v_mfma_f32_16x16x32_bf16 v[142:145], v[122:125], v[166:169], v[142:145]
	v_mfma_f32_16x16x32_bf16 v[118:121], v[98:101], v[174:177], v[118:121]
	v_mfma_f32_16x16x32_bf16 v[114:117], v[122:125], v[174:177], v[114:117]
	v_mfma_f32_16x16x32_bf16 v[94:97], v[98:101], v[198:201], v[94:97]
	v_mfma_f32_16x16x32_bf16 v[90:93], v[122:125], v[198:201], v[90:93]
	v_mfma_f32_16x16x32_bf16 v[78:81], v[98:101], v[206:209], v[78:81]
	v_mfma_f32_16x16x32_bf16 v[74:77], v[122:125], v[206:209], v[74:77]
	v_mfma_f32_16x16x32_bf16 v[146:149], v[110:113], v[170:173], v[146:149]
	v_mfma_f32_16x16x32_bf16 v[142:145], v[134:137], v[170:173], v[142:145]
	v_mfma_f32_16x16x32_bf16 v[118:121], v[110:113], v[178:181], v[118:121]
	v_mfma_f32_16x16x32_bf16 v[114:117], v[134:137], v[178:181], v[114:117]
	v_mfma_f32_16x16x32_bf16 v[94:97], v[110:113], v[202:205], v[94:97]
	v_mfma_f32_16x16x32_bf16 v[90:93], v[134:137], v[202:205], v[90:93]
	v_mfma_f32_16x16x32_bf16 v[78:81], v[110:113], v[210:213], v[78:81]
	v_mfma_f32_16x16x32_bf16 v[74:77], v[134:137], v[210:213], v[74:77]
	v_mfma_f32_16x16x32_bf16 v[130:133], v[138:141], v[166:169], v[130:133]
	v_mfma_f32_16x16x32_bf16 v[126:129], v[154:157], v[166:169], v[126:129]
	v_mfma_f32_16x16x32_bf16 v[106:109], v[138:141], v[174:177], v[106:109]
	v_mfma_f32_16x16x32_bf16 v[102:105], v[154:157], v[174:177], v[102:105]
	v_mfma_f32_16x16x32_bf16 v[86:89], v[138:141], v[198:201], v[86:89]
	v_mfma_f32_16x16x32_bf16 v[82:85], v[154:157], v[198:201], v[82:85]
	v_mfma_f32_16x16x32_bf16 v[70:73], v[138:141], v[206:209], v[70:73]
	v_mfma_f32_16x16x32_bf16 v[66:69], v[154:157], v[206:209], v[66:69]
	v_mfma_f32_16x16x32_bf16 v[130:133], v[150:153], v[170:173], v[130:133]
	v_mfma_f32_16x16x32_bf16 v[126:129], v[162:165], v[170:173], v[126:129]
	v_mfma_f32_16x16x32_bf16 v[106:109], v[150:153], v[178:181], v[106:109]
	v_mfma_f32_16x16x32_bf16 v[102:105], v[162:165], v[178:181], v[102:105]
	v_mfma_f32_16x16x32_bf16 v[86:89], v[150:153], v[202:205], v[86:89]
	v_mfma_f32_16x16x32_bf16 v[82:85], v[162:165], v[202:205], v[82:85]
	v_mfma_f32_16x16x32_bf16 v[70:73], v[150:153], v[210:213], v[70:73]
	v_mfma_f32_16x16x32_bf16 v[66:69], v[162:165], v[210:213], v[66:69]
	s_barrier
; #define PG8_STAGE(bufoff, gbase, voff) do { if constexpr (VAR != 1 && VAR != 3) { _Pragma("unroll") for (int _i = 0; _i < 2; ++_i) \
;         asm volatile("s_mov_b32 m0, %2\n\ts_nop 0\n\tglobal_load_lds_dwordx4 %0, %1" :: "v"((voff)[_i]), "s"((const char*)(gbase)), "s"(ldsbase + (unsigned)((bufoff) + _i * 8192)) : "memory", "m0"); } } while (0)
; #define PG8_LDA(dst, b, h) do { if constexpr (VAR < 2) _Pragma("unroll") for (int m = 0; m < 4; ++m) _Pragma("unroll") for (int k = 0; k < 2; ++k) dst[m][k] = *(const LAS bf16x8*)(lds + PG8_SA(b, h) + aoff + m * 2048 + k * 1024); } while (0)
; #define PG8_LDB(dst, b, h) do { if constexpr (VAR < 2) _Pragma("unroll") for (int n = 0; n < 2; ++n) _Pragma("unroll") for (int k = 0; k < 2; ++k) dst[n][k] = *(const LAS bf16x8*)(lds + PG8_SB(b, h) + boff + n * 2048 + k * 1024); } while (0)
; #define PG8_WAIT_V(n) asm volatile("s_waitcnt vmcnt(" #n ")" ::: "memory")
; #define PG8_WAIT_L(n) asm volatile("s_waitcnt lgkmcnt(" #n ")" ::: "memory")
; #define PG8_BAR do { if constexpr (VAR != 3) __builtin_amdgcn_s_barrier(); } while (0)
; #define PG8_SCHED __builtin_amdgcn_sched_barrier(0)
;     ...
;         for (int t = 0; t < nt; t += 2) {
;             const bool last = (t == nt - 2);
;             const char* a1 = cA + (size_t)(t + 1) * kstep;
;             const char* a2 = last ? nA : cA + (size_t)(t + 2) * kstep; const char* b2 = last ? nB : cB + (size_t)(t + 2) * kstep;
;             const char* a3 = a2 + kstep; const char* b3 = b2 + kstep;
;             PG8_LDB(B0, 0, 0); PG8_LDB(B1, 0, 1); PG8_SCHED; PG8_LDA(At, 0, 0); PG8_STAGE(PG8_SA(1, 1), a1 + hstepA, voffA);
;             PG8_WAIT_V(8); PG8_WAIT_L(0); PG8_BAR; PG8_MMA(0, 0, At, B0); PG8_MMA(0, 1, At, B1); PG8_BAR; PG8_SCHED;
;             PG8_LDA(At, 0, 1); PG8_STAGE(PG8_SB(0, 0), b2, voffB); PG8_STAGE(PG8_SB(0, 1), b2 + hstepB, voffB); PG8_STAGE(PG8_SA(0, 0), a2, voffA);
;             PG8_WAIT_V(8); PG8_WAIT_L(0); PG8_BAR; PG8_MMA(1, 0, At, B0); PG8_MMA(1, 1, At, B1); PG8_BAR; PG8_SCHED;
;     ...
;             PG8_LDA(At, 1, 1); PG8_STAGE(PG8_SB(1, 0), b3, voffB); PG8_STAGE(PG8_SB(1, 1), b3 + hstepB, voffB); PG8_STAGE(PG8_SA(1, 0), a3, voffA);
;             PG8_WAIT_V(8); PG8_WAIT_L(0); PG8_BAR; PG8_MMA(1, 0, At, B0); PG8_MMA(1, 1, At, B1); PG8_BAR; PG8_SCHED;
;         }
	ds_read_b128 v[166:169], v193 offset:49152
	ds_read_b128 v[170:173], v193 offset:50176
	ds_read_b128 v[174:177], v193 offset:51200
	ds_read_b128 v[178:181], v193 offset:52224
	ds_read_b128 v[198:201], v193 offset:53248
	ds_read_b128 v[202:205], v193 offset:54272
	ds_read_b128 v[206:209], v193 offset:55296
	ds_read_b128 v[210:213], v193 offset:56320
	s_add_u32 s86, s84, 0x80
	s_addc_u32 s87, s85, 0
	s_mov_b32 m0, s64
	s_nop 0
	global_load_lds_dwordx4 v185, s[86:87]
	s_add_u32 s84, s84, 0x100080
	s_mov_b32 m0, s65
	s_nop 0
	global_load_lds_dwordx4 v187, s[86:87]
	s_addc_u32 s85, s85, 0
	s_mov_b32 m0, s33
	s_nop 0
	global_load_lds_dwordx4 v185, s[84:85]
	s_mov_b32 m0, s30
	s_nop 0
	global_load_lds_dwordx4 v187, s[84:85]
	s_mov_b32 m0, s17
	s_nop 0
	global_load_lds_dwordx4 v184, s[82:83]
	s_mov_b32 m0, s28
	s_nop 0
	global_load_lds_dwordx4 v186, s[82:83]
	s_waitcnt vmcnt(8) lgkmcnt(0)
	s_barrier
	v_mfma_f32_16x16x32_bf16 v[62:65], v[98:101], v[166:169], v[62:65]
	v_mfma_f32_16x16x32_bf16 v[58:61], v[122:125], v[166:169], v[58:61]
	v_mfma_f32_16x16x32_bf16 v[46:49], v[98:101], v[174:177], v[46:49]
	v_mfma_f32_16x16x32_bf16 v[42:45], v[122:125], v[174:177], v[42:45]
	v_mfma_f32_16x16x32_bf16 v[30:33], v[98:101], v[198:201], v[30:33]
	v_mfma_f32_16x16x32_bf16 v[26:29], v[122:125], v[198:201], v[26:29]
	v_mfma_f32_16x16x32_bf16 v[14:17], v[98:101], v[206:209], v[14:17]
	v_mfma_f32_16x16x32_bf16 v[10:13], v[122:125], v[206:209], v[10:13]
	v_mfma_f32_16x16x32_bf16 v[62:65], v[110:113], v[170:173], v[62:65]
	v_mfma_f32_16x16x32_bf16 v[58:61], v[134:137], v[170:173], v[58:61]
	v_mfma_f32_16x16x32_bf16 v[46:49], v[110:113], v[178:181], v[46:49]
	v_mfma_f32_16x16x32_bf16 v[42:45], v[134:137], v[178:181], v[42:45]
	v_mfma_f32_16x16x32_bf16 v[30:33], v[110:113], v[202:205], v[30:33]
	v_mfma_f32_16x16x32_bf16 v[26:29], v[134:137], v[202:205], v[26:29]
	v_mfma_f32_16x16x32_bf16 v[14:17], v[110:113], v[210:213], v[14:17]
	v_mfma_f32_16x16x32_bf16 v[10:13], v[134:137], v[210:213], v[10:13]
	v_mfma_f32_16x16x32_bf16 v[54:57], v[138:141], v[166:169], v[54:57]
	v_mfma_f32_16x16x32_bf16 v[50:53], v[154:157], v[166:169], v[50:53]
	v_mfma_f32_16x16x32_bf16 v[38:41], v[138:141], v[174:177], v[38:41]
	v_mfma_f32_16x16x32_bf16 v[34:37], v[154:157], v[174:177], v[34:37]
	v_mfma_f32_16x16x32_bf16 v[22:25], v[138:141], v[198:201], v[22:25]
	v_mfma_f32_16x16x32_bf16 v[18:21], v[154:157], v[198:201], v[18:21]
	v_mfma_f32_16x16x32_bf16 v[6:9], v[138:141], v[206:209], v[6:9]
	v_mfma_f32_16x16x32_bf16 v[2:5], v[154:157], v[206:209], v[2:5]
	v_mfma_f32_16x16x32_bf16 v[54:57], v[150:153], v[170:173], v[54:57]
	v_mfma_f32_16x16x32_bf16 v[50:53], v[162:165], v[170:173], v[50:53]
	v_mfma_f32_16x16x32_bf16 v[38:41], v[150:153], v[178:181], v[38:41]
	v_mfma_f32_16x16x32_bf16 v[34:37], v[162:165], v[178:181], v[34:37]
	v_mfma_f32_16x16x32_bf16 v[22:25], v[150:153], v[202:205], v[22:25]
	v_mfma_f32_16x16x32_bf16 v[18:21], v[162:165], v[202:205], v[18:21]
	v_mfma_f32_16x16x32_bf16 v[6:9], v[150:153], v[210:213], v[6:9]
	v_mfma_f32_16x16x32_bf16 v[2:5], v[162:165], v[210:213], v[2:5]
	s_barrier
	s_add_i32 vcc_hi, vcc_hi, 2
	s_add_u32 s27, s27, 0x100
	s_addc_u32 s71, s71, 0
	s_add_u32 s73, s73, 0x100
	s_addc_u32 vcc_lo, vcc_lo, 0
	s_add_u32 s80, s80, 0x100
	s_addc_u32 s81, s81, 0
	s_cmp_gt_u32 vcc_hi, 61
	s_cbranch_scc0 .LBB0_789
	s_branch .Lmy_kexit_5
.LBB0_789:
	ds_read_b128 v[98:101], v191
	ds_read_b128 v[110:113], v191 offset:1024
	ds_read_b128 v[122:125], v191 offset:2048
	ds_read_b128 v[134:137], v191 offset:3072
	ds_read_b128 v[138:141], v192
	ds_read_b128 v[150:153], v192 offset:1024
	ds_read_b128 v[154:157], v192 offset:2048
	ds_read_b128 v[162:165], v192 offset:3072
	s_cmp_eq_u32 vcc_hi, 60
	s_cselect_b32 s86, s15, s27
	s_cselect_b32 s87, s14, s71
	s_cselect_b32 s84, s26, s73
	s_cselect_b32 s85, s25, vcc_lo
	s_add_u32 s82, s86, 0x80
	s_addc_u32 s83, s87, 0
	ds_read_b128 v[166:169], v193
	ds_read_b128 v[170:173], v193 offset:1024
	ds_read_b128 v[174:177], v193 offset:2048
	ds_read_b128 v[178:181], v193 offset:3072
	ds_read_b128 v[198:201], v193 offset:4096
	ds_read_b128 v[202:205], v193 offset:5120
	ds_read_b128 v[206:209], v193 offset:6144
	ds_read_b128 v[210:213], v193 offset:7168
	s_mov_b32 m0, s31
	s_nop 0
	global_load_lds_dwordx4 v184, s[80:81]
	s_mov_b32 m0, s19
	s_nop 0
	global_load_lds_dwordx4 v186, s[80:81]
	s_waitcnt vmcnt(8) lgkmcnt(0)
	s_barrier
	v_mfma_f32_16x16x32_bf16 v[146:149], v[98:101], v[166:169], v[146:149]
	v_mfma_f32_16x16x32_bf16 v[142:145], v[122:125], v[166:169], v[142:145]
	v_mfma_f32_16x16x32_bf16 v[118:121], v[98:101], v[174:177], v[118:121]
	v_mfma_f32_16x16x32_bf16 v[114:117], v[122:125], v[174:177], v[114:117]
	v_mfma_f32_16x16x32_bf16 v[94:97], v[98:101], v[198:201], v[94:97]
	v_mfma_f32_16x16x32_bf16 v[90:93], v[122:125], v[198:201], v[90:93]
	v_mfma_f32_16x16x32_bf16 v[78:81], v[98:101], v[206:209], v[78:81]
	v_mfma_f32_16x16x32_bf16 v[74:77], v[122:125], v[206:209], v[74:77]
	v_mfma_f32_16x16x32_bf16 v[146:149], v[110:113], v[170:173], v[146:149]
	v_mfma_f32_16x16x32_bf16 v[142:145], v[134:137], v[170:173], v[142:145]
	v_mfma_f32_16x16x32_bf16 v[118:121], v[110:113], v[178:181], v[118:121]
	v_mfma_f32_16x16x32_bf16 v[114:117], v[134:137], v[178:181], v[114:117]
	v_mfma_f32_16x16x32_bf16 v[94:97], v[110:113], v[202:205], v[94:97]
	v_mfma_f32_16x16x32_bf16 v[90:93], v[134:137], v[202:205], v[90:93]
	v_mfma_f32_16x16x32_bf16 v[78:81], v[110:113], v[210:213], v[78:81]
	v_mfma_f32_16x16x32_bf16 v[74:77], v[134:137], v[210:213], v[74:77]
	v_mfma_f32_16x16x32_bf16 v[130:133], v[138:141], v[166:169], v[130:133]
	v_mfma_f32_16x16x32_bf16 v[126:129], v[154:157], v[166:169], v[126:129]
	v_mfma_f32_16x16x32_bf16 v[106:109], v[138:141], v[174:177], v[106:109]
	v_mfma_f32_16x16x32_bf16 v[102:105], v[154:157], v[174:177], v[102:105]
	v_mfma_f32_16x16x32_bf16 v[86:89], v[138:141], v[198:201], v[86:89]
	v_mfma_f32_16x16x32_bf16 v[82:85], v[154:157], v[198:201], v[82:85]
	v_mfma_f32_16x16x32_bf16 v[70:73], v[138:141], v[206:209], v[70:73]
	v_mfma_f32_16x16x32_bf16 v[66:69], v[154:157], v[206:209], v[66:69]
	v_mfma_f32_16x16x32_bf16 v[130:133], v[150:153], v[170:173], v[130:133]
	v_mfma_f32_16x16x32_bf16 v[126:129], v[162:165], v[170:173], v[126:129]
	v_mfma_f32_16x16x32_bf16 v[106:109], v[150:153], v[178:181], v[106:109]
	v_mfma_f32_16x16x32_bf16 v[102:105], v[162:165], v[178:181], v[102:105]
	v_mfma_f32_16x16x32_bf16 v[86:89], v[150:153], v[202:205], v[86:89]
	v_mfma_f32_16x16x32_bf16 v[82:85], v[162:165], v[202:205], v[82:85]
	v_mfma_f32_16x16x32_bf16 v[70:73], v[150:153], v[210:213], v[70:73]
	v_mfma_f32_16x16x32_bf16 v[66:69], v[162:165], v[210:213], v[66:69]
	s_barrier
; #define PG8_STAGE(bufoff, gbase, voff) do { if constexpr (VAR != 1 && VAR != 3) { _Pragma("unroll") for (int _i = 0; _i < 2; ++_i) \
;         asm volatile("s_mov_b32 m0, %2\n\ts_nop 0\n\tglobal_load_lds_dwordx4 %0, %1" :: "v"((voff)[_i]), "s"((const char*)(gbase)), "s"(ldsbase + (unsigned)((bufoff) + _i * 8192)) : "memory", "m0"); } } while (0)
; #define PG8_LDA(dst, b, h) do { if constexpr (VAR < 2) _Pragma("unroll") for (int m = 0; m < 4; ++m) _Pragma("unroll") for (int k = 0; k < 2; ++k) dst[m][k] = *(const LAS bf16x8*)(lds + PG8_SA(b, h) + aoff + m * 2048 + k * 1024); } while (0)
; #define PG8_LDB(dst, b, h) do { if constexpr (VAR < 2) _Pragma("unroll") for (int n = 0; n < 2; ++n) _Pragma("unroll") for (int k = 0; k < 2; ++k) dst[n][k] = *(const LAS bf16x8*)(lds + PG8_SB(b, h) + boff + n * 2048 + k * 1024); } while (0)
; #define PG8_WAIT_V(n) asm volatile("s_waitcnt vmcnt(" #n ")" ::: "memory")
; #define PG8_WAIT_L(n) asm volatile("s_waitcnt lgkmcnt(" #n ")" ::: "memory")
; #define PG8_BAR do { if constexpr (VAR != 3) __builtin_amdgcn_s_barrier(); } while (0)
; #define PG8_SCHED __builtin_amdgcn_sched_barrier(0)
;     ...
;             PG8_LDA(At, 0, 1); PG8_STAGE(PG8_SB(0, 0), b2, voffB); PG8_STAGE(PG8_SB(0, 1), b2 + hstepB, voffB); PG8_STAGE(PG8_SA(0, 0), a2, voffA);
;             PG8_WAIT_V(8); PG8_WAIT_L(0); PG8_BAR; PG8_MMA(1, 0, At, B0); PG8_MMA(1, 1, At, B1); PG8_BAR; PG8_SCHED;
;             PG8_LDB(B0, 1, 0); PG8_LDB(B1, 1, 1); PG8_SCHED; PG8_LDA(At, 1, 0); PG8_STAGE(PG8_SA(0, 1), a2 + hstepA, voffA);
;             PG8_WAIT_V(8); PG8_WAIT_L(0); PG8_BAR; PG8_MMA(0, 0, At, B0); PG8_MMA(0, 1, At, B1); PG8_BAR; PG8_SCHED;
	ds_read_b128 v[166:169], v193 offset:16384
	ds_read_b128 v[170:173], v193 offset:17408
	ds_read_b128 v[174:177], v193 offset:18432
	ds_read_b128 v[178:181], v193 offset:19456
	ds_read_b128 v[198:201], v193 offset:20480
	ds_read_b128 v[202:205], v193 offset:21504
	ds_read_b128 v[206:209], v193 offset:22528
	ds_read_b128 v[210:213], v193 offset:23552
	s_mov_b32 m0, s91
	s_nop 0
	global_load_lds_dwordx4 v185, s[84:85]
	s_add_u32 s88, s84, 0x100000
	s_mov_b32 m0, s92
	s_nop 0
	global_load_lds_dwordx4 v187, s[84:85]
	s_addc_u32 s89, s85, 0
	s_mov_b32 m0, s93
	s_nop 0
	global_load_lds_dwordx4 v185, s[88:89]
	s_mov_b32 m0, s94
	s_nop 0
	global_load_lds_dwordx4 v187, s[88:89]
	s_mov_b32 m0, s35
	s_nop 0
	global_load_lds_dwordx4 v184, s[86:87]
	s_mov_b32 m0, s79
	s_nop 0
	global_load_lds_dwordx4 v186, s[86:87]
	s_waitcnt vmcnt(8) lgkmcnt(0)
	s_barrier
	v_mfma_f32_16x16x32_bf16 v[62:65], v[98:101], v[166:169], v[62:65]
	v_mfma_f32_16x16x32_bf16 v[58:61], v[122:125], v[166:169], v[58:61]
	v_mfma_f32_16x16x32_bf16 v[46:49], v[98:101], v[174:177], v[46:49]
	v_mfma_f32_16x16x32_bf16 v[42:45], v[122:125], v[174:177], v[42:45]
	v_mfma_f32_16x16x32_bf16 v[30:33], v[98:101], v[198:201], v[30:33]
	v_mfma_f32_16x16x32_bf16 v[26:29], v[122:125], v[198:201], v[26:29]
	v_mfma_f32_16x16x32_bf16 v[14:17], v[98:101], v[206:209], v[14:17]
	v_mfma_f32_16x16x32_bf16 v[10:13], v[122:125], v[206:209], v[10:13]
	v_mfma_f32_16x16x32_bf16 v[62:65], v[110:113], v[170:173], v[62:65]
	v_mfma_f32_16x16x32_bf16 v[58:61], v[134:137], v[170:173], v[58:61]
	v_mfma_f32_16x16x32_bf16 v[46:49], v[110:113], v[178:181], v[46:49]
	v_mfma_f32_16x16x32_bf16 v[42:45], v[134:137], v[178:181], v[42:45]
	v_mfma_f32_16x16x32_bf16 v[30:33], v[110:113], v[202:205], v[30:33]
	v_mfma_f32_16x16x32_bf16 v[26:29], v[134:137], v[202:205], v[26:29]
	v_mfma_f32_16x16x32_bf16 v[14:17], v[110:113], v[210:213], v[14:17]
	v_mfma_f32_16x16x32_bf16 v[10:13], v[134:137], v[210:213], v[10:13]
	v_mfma_f32_16x16x32_bf16 v[54:57], v[138:141], v[166:169], v[54:57]
	v_mfma_f32_16x16x32_bf16 v[50:53], v[154:157], v[166:169], v[50:53]
	v_mfma_f32_16x16x32_bf16 v[38:41], v[138:141], v[174:177], v[38:41]
	v_mfma_f32_16x16x32_bf16 v[34:37], v[154:157], v[174:177], v[34:37]
	v_mfma_f32_16x16x32_bf16 v[22:25], v[138:141], v[198:201], v[22:25]
	v_mfma_f32_16x16x32_bf16 v[18:21], v[154:157], v[198:201], v[18:21]
	v_mfma_f32_16x16x32_bf16 v[6:9], v[138:141], v[206:209], v[6:9]
	v_mfma_f32_16x16x32_bf16 v[2:5], v[154:157], v[206:209], v[2:5]
	v_mfma_f32_16x16x32_bf16 v[54:57], v[150:153], v[170:173], v[54:57]
	v_mfma_f32_16x16x32_bf16 v[50:53], v[162:165], v[170:173], v[50:53]
	v_mfma_f32_16x16x32_bf16 v[38:41], v[150:153], v[178:181], v[38:41]
	v_mfma_f32_16x16x32_bf16 v[34:37], v[162:165], v[178:181], v[34:37]
	v_mfma_f32_16x16x32_bf16 v[22:25], v[150:153], v[202:205], v[22:25]
	v_mfma_f32_16x16x32_bf16 v[18:21], v[162:165], v[202:205], v[18:21]
	v_mfma_f32_16x16x32_bf16 v[6:9], v[150:153], v[210:213], v[6:9]
	v_mfma_f32_16x16x32_bf16 v[2:5], v[162:165], v[210:213], v[2:5]
	s_barrier
	ds_read_b128 v[98:101], v194
	ds_read_b128 v[110:113], v194 offset:1024
	ds_read_b128 v[122:125], v194 offset:2048
	ds_read_b128 v[134:137], v194 offset:3072
	ds_read_b128 v[138:141], v195
	ds_read_b128 v[150:153], v195 offset:1024
	ds_read_b128 v[154:157], v195 offset:2048
	ds_read_b128 v[162:165], v195 offset:3072
	ds_read_b128 v[166:169], v193 offset:32768
	ds_read_b128 v[170:173], v193 offset:33792
	ds_read_b128 v[174:177], v193 offset:34816
	ds_read_b128 v[178:181], v193 offset:35840
	ds_read_b128 v[198:201], v193 offset:36864
	ds_read_b128 v[202:205], v193 offset:37888
	ds_read_b128 v[206:209], v193 offset:38912
	ds_read_b128 v[210:213], v193 offset:39936
	s_add_u32 s86, s86, 0x100000
	s_addc_u32 s87, s87, 0
	s_mov_b32 m0, s95
	s_nop 0
	global_load_lds_dwordx4 v184, s[86:87]
	s_mov_b32 m0, s96
	s_nop 0
	global_load_lds_dwordx4 v186, s[86:87]
	s_waitcnt vmcnt(8) lgkmcnt(0)
	s_barrier
; #define PG8_STAGE(bufoff, gbase, voff) do { if constexpr (VAR != 1 && VAR != 3) { _Pragma("unroll") for (int _i = 0; _i < 2; ++_i) \
;         asm volatile("s_mov_b32 m0, %2\n\ts_nop 0\n\tglobal_load_lds_dwordx4 %0, %1" :: "v"((voff)[_i]), "s"((const char*)(gbase)), "s"(ldsbase + (unsigned)((bufoff) + _i * 8192)) : "memory", "m0"); } } while (0)
; #define PG8_LDA(dst, b, h) do { if constexpr (VAR < 2) _Pragma("unroll") for (int m = 0; m < 4; ++m) _Pragma("unroll") for (int k = 0; k < 2; ++k) dst[m][k] = *(const LAS bf16x8*)(lds + PG8_SA(b, h) + aoff + m * 2048 + k * 1024); } while (0)
; #define PG8_WAIT_V(n) asm volatile("s_waitcnt vmcnt(" #n ")" ::: "memory")
; #define PG8_WAIT_L(n) asm volatile("s_waitcnt lgkmcnt(" #n ")" ::: "memory")
; #define PG8_BAR do { if constexpr (VAR != 3) __builtin_amdgcn_s_barrier(); } while (0)
; #define PG8_SCHED __builtin_amdgcn_sched_barrier(0)
;     ...
;             PG8_WAIT_V(8); PG8_WAIT_L(0); PG8_BAR; PG8_MMA(0, 0, At, B0); PG8_MMA(0, 1, At, B1); PG8_BAR; PG8_SCHED;
;             PG8_LDA(At, 1, 1); PG8_STAGE(PG8_SB(1, 0), b3, voffB); PG8_STAGE(PG8_SB(1, 1), b3 + hstepB, voffB); PG8_STAGE(PG8_SA(1, 0), a3, voffA);
;             PG8_WAIT_V(8); PG8_WAIT_L(0); PG8_BAR; PG8_MMA(1, 0, At, B0); PG8_MMA(1, 1, At, B1); PG8_BAR; PG8_SCHED;
;         }
	v_mfma_f32_16x16x32_bf16 v[146:149], v[98:101], v[166:169], v[146:149]
	v_mfma_f32_16x16x32_bf16 v[142:145], v[122:125], v[166:169], v[142:145]
	v_mfma_f32_16x16x32_bf16 v[118:121], v[98:101], v[174:177], v[118:121]
	v_mfma_f32_16x16x32_bf16 v[114:117], v[122:125], v[174:177], v[114:117]
	v_mfma_f32_16x16x32_bf16 v[94:97], v[98:101], v[198:201], v[94:97]
	v_mfma_f32_16x16x32_bf16 v[90:93], v[122:125], v[198:201], v[90:93]
	v_mfma_f32_16x16x32_bf16 v[78:81], v[98:101], v[206:209], v[78:81]
	v_mfma_f32_16x16x32_bf16 v[74:77], v[122:125], v[206:209], v[74:77]
	v_mfma_f32_16x16x32_bf16 v[146:149], v[110:113], v[170:173], v[146:149]
	v_mfma_f32_16x16x32_bf16 v[142:145], v[134:137], v[170:173], v[142:145]
	v_mfma_f32_16x16x32_bf16 v[118:121], v[110:113], v[178:181], v[118:121]
	v_mfma_f32_16x16x32_bf16 v[114:117], v[134:137], v[178:181], v[114:117]
	v_mfma_f32_16x16x32_bf16 v[94:97], v[110:113], v[202:205], v[94:97]
	v_mfma_f32_16x16x32_bf16 v[90:93], v[134:137], v[202:205], v[90:93]
	v_mfma_f32_16x16x32_bf16 v[78:81], v[110:113], v[210:213], v[78:81]
	v_mfma_f32_16x16x32_bf16 v[74:77], v[134:137], v[210:213], v[74:77]
	v_mfma_f32_16x16x32_bf16 v[130:133], v[138:141], v[166:169], v[130:133]
	v_mfma_f32_16x16x32_bf16 v[126:129], v[154:157], v[166:169], v[126:129]
	v_mfma_f32_16x16x32_bf16 v[106:109], v[138:141], v[174:177], v[106:109]
	v_mfma_f32_16x16x32_bf16 v[102:105], v[154:157], v[174:177], v[102:105]
	v_mfma_f32_16x16x32_bf16 v[86:89], v[138:141], v[198:201], v[86:89]
	v_mfma_f32_16x16x32_bf16 v[82:85], v[154:157], v[198:201], v[82:85]
	v_mfma_f32_16x16x32_bf16 v[70:73], v[138:141], v[206:209], v[70:73]
	v_mfma_f32_16x16x32_bf16 v[66:69], v[154:157], v[206:209], v[66:69]
	v_mfma_f32_16x16x32_bf16 v[130:133], v[150:153], v[170:173], v[130:133]
	v_mfma_f32_16x16x32_bf16 v[126:129], v[162:165], v[170:173], v[126:129]
	v_mfma_f32_16x16x32_bf16 v[106:109], v[150:153], v[178:181], v[106:109]
	v_mfma_f32_16x16x32_bf16 v[102:105], v[162:165], v[178:181], v[102:105]
	v_mfma_f32_16x16x32_bf16 v[86:89], v[150:153], v[202:205], v[86:89]
	v_mfma_f32_16x16x32_bf16 v[82:85], v[162:165], v[202:205], v[82:85]
	v_mfma_f32_16x16x32_bf16 v[70:73], v[150:153], v[210:213], v[70:73]
	v_mfma_f32_16x16x32_bf16 v[66:69], v[162:165], v[210:213], v[66:69]
	s_barrier
	ds_read_b128 v[166:169], v193 offset:49152
	ds_read_b128 v[170:173], v193 offset:50176
	ds_read_b128 v[174:177], v193 offset:51200
	ds_read_b128 v[178:181], v193 offset:52224
	ds_read_b128 v[198:201], v193 offset:53248
	ds_read_b128 v[202:205], v193 offset:54272
	ds_read_b128 v[206:209], v193 offset:55296
	ds_read_b128 v[210:213], v193 offset:56320
	s_add_u32 s86, s84, 0x80
	s_addc_u32 s87, s85, 0
	s_mov_b32 m0, s64
	s_nop 0
	global_load_lds_dwordx4 v185, s[86:87]
	s_add_u32 s84, s84, 0x100080
	s_mov_b32 m0, s65
	s_nop 0
	global_load_lds_dwordx4 v187, s[86:87]
	s_addc_u32 s85, s85, 0
	s_mov_b32 m0, s33
	s_nop 0
	global_load_lds_dwordx4 v185, s[84:85]
	s_mov_b32 m0, s30
	s_nop 0
	global_load_lds_dwordx4 v187, s[84:85]
	s_mov_b32 m0, s17
	s_nop 0
	global_load_lds_dwordx4 v184, s[82:83]
	s_mov_b32 m0, s28
	s_nop 0
	global_load_lds_dwordx4 v186, s[82:83]
	s_waitcnt vmcnt(8) lgkmcnt(0)
	s_barrier
	v_mfma_f32_16x16x32_bf16 v[62:65], v[98:101], v[166:169], v[62:65]
	v_mfma_f32_16x16x32_bf16 v[58:61], v[122:125], v[166:169], v[58:61]
	v_mfma_f32_16x16x32_bf16 v[46:49], v[98:101], v[174:177], v[46:49]
	v_mfma_f32_16x16x32_bf16 v[42:45], v[122:125], v[174:177], v[42:45]
	v_mfma_f32_16x16x32_bf16 v[30:33], v[98:101], v[198:201], v[30:33]
	v_mfma_f32_16x16x32_bf16 v[26:29], v[122:125], v[198:201], v[26:29]
	v_mfma_f32_16x16x32_bf16 v[14:17], v[98:101], v[206:209], v[14:17]
	v_mfma_f32_16x16x32_bf16 v[10:13], v[122:125], v[206:209], v[10:13]
	v_mfma_f32_16x16x32_bf16 v[62:65], v[110:113], v[170:173], v[62:65]
	v_mfma_f32_16x16x32_bf16 v[58:61], v[134:137], v[170:173], v[58:61]
	v_mfma_f32_16x16x32_bf16 v[46:49], v[110:113], v[178:181], v[46:49]
	v_mfma_f32_16x16x32_bf16 v[42:45], v[134:137], v[178:181], v[42:45]
	v_mfma_f32_16x16x32_bf16 v[30:33], v[110:113], v[202:205], v[30:33]
	v_mfma_f32_16x16x32_bf16 v[26:29], v[134:137], v[202:205], v[26:29]
	v_mfma_f32_16x16x32_bf16 v[14:17], v[110:113], v[210:213], v[14:17]
	v_mfma_f32_16x16x32_bf16 v[10:13], v[134:137], v[210:213], v[10:13]
	v_mfma_f32_16x16x32_bf16 v[54:57], v[138:141], v[166:169], v[54:57]
	v_mfma_f32_16x16x32_bf16 v[50:53], v[154:157], v[166:169], v[50:53]
	v_mfma_f32_16x16x32_bf16 v[38:41], v[138:141], v[174:177], v[38:41]
	v_mfma_f32_16x16x32_bf16 v[34:37], v[154:157], v[174:177], v[34:37]
	v_mfma_f32_16x16x32_bf16 v[22:25], v[138:141], v[198:201], v[22:25]
	v_mfma_f32_16x16x32_bf16 v[18:21], v[154:157], v[198:201], v[18:21]
	v_mfma_f32_16x16x32_bf16 v[6:9], v[138:141], v[206:209], v[6:9]
	v_mfma_f32_16x16x32_bf16 v[2:5], v[154:157], v[206:209], v[2:5]
	v_mfma_f32_16x16x32_bf16 v[54:57], v[150:153], v[170:173], v[54:57]
	v_mfma_f32_16x16x32_bf16 v[50:53], v[162:165], v[170:173], v[50:53]
	v_mfma_f32_16x16x32_bf16 v[38:41], v[150:153], v[178:181], v[38:41]
	v_mfma_f32_16x16x32_bf16 v[34:37], v[162:165], v[178:181], v[34:37]
	v_mfma_f32_16x16x32_bf16 v[22:25], v[150:153], v[202:205], v[22:25]
	v_mfma_f32_16x16x32_bf16 v[18:21], v[162:165], v[202:205], v[18:21]
	v_mfma_f32_16x16x32_bf16 v[6:9], v[150:153], v[210:213], v[6:9]
	v_mfma_f32_16x16x32_bf16 v[2:5], v[162:165], v[210:213], v[2:5]
	s_barrier
	s_add_i32 vcc_hi, vcc_hi, 2
	s_add_u32 s27, s27, 0x100
	s_addc_u32 s71, s71, 0
	s_add_u32 s73, s73, 0x100
	s_addc_u32 vcc_lo, vcc_lo, 0
	s_add_u32 s80, s80, 0x100
	s_addc_u32 s81, s81, 0
	s_cmp_gt_u32 vcc_hi, 61
	s_cbranch_scc0 .LBB0_789

; __device__ __forceinline__ const char* unitA(const Gemm& g, const Unit& u) { return (const char*)(g.A + (size_t)(u.z / g.zdiv) * g.sAhi + (size_t)(u.z % g.zdiv) * g.sAlo + (size_t)u.pm * BM * g.lda); }
; __device__ __forceinline__ const char* unitB(const Gemm& g, const Unit& u) { return (const char*)(g.Bt + (size_t)(u.z / g.zdiv) * g.sBhi + (size_t)(u.z % g.zdiv) * g.sBlo + (size_t)(u.pm / g.bdiv) * g.sBpm + (size_t)u.pn * BM * g.ldb); }
; #define PG8_STAGE(bufoff, gbase, voff) do { if constexpr (VAR != 1 && VAR != 3) { _Pragma("unroll") for (int _i = 0; _i < 2; ++_i) \
;         asm volatile("s_mov_b32 m0, %2\n\ts_nop 0\n\tglobal_load_lds_dwordx4 %0, %1" :: "v"((voff)[_i]), "s"((const char*)(gbase)), "s"(ldsbase + (unsigned)((bufoff) + _i * 8192)) : "memory", "m0"); } } while (0)
; #define PG8_LDA(dst, b, h) do { if constexpr (VAR < 2) _Pragma("unroll") for (int m = 0; m < 4; ++m) _Pragma("unroll") for (int k = 0; k < 2; ++k) dst[m][k] = *(const LAS bf16x8*)(lds + PG8_SA(b, h) + aoff + m * 2048 + k * 1024); } while (0)
; #define PG8_LDB(dst, b, h) do { if constexpr (VAR < 2) _Pragma("unroll") for (int n = 0; n < 2; ++n) _Pragma("unroll") for (int k = 0; k < 2; ++k) dst[n][k] = *(const LAS bf16x8*)(lds + PG8_SB(b, h) + boff + n * 2048 + k * 1024); } while (0)
; #define PG8_WAIT_V(n) asm volatile("s_waitcnt vmcnt(" #n ")" ::: "memory")
;     ...
;         const bool has_next = S.next(ui + 1, nxt);
;         const char* nA = has_next ? unitA(g, nxt) : cA; const char* nB = has_next ? unitB(g, nxt) : cB;
;         for (int t = 0; t < nt; t += 2) {
;             const bool last = (t == nt - 2);
;             const char* a1 = cA + (size_t)(t + 1) * kstep;
;             const char* a2 = last ? nA : cA + (size_t)(t + 2) * kstep; const char* b2 = last ? nB : cB + (size_t)(t + 2) * kstep;
;             const char* a3 = a2 + kstep; const char* b3 = b2 + kstep;
;             PG8_LDB(B0, 0, 0); PG8_LDB(B1, 0, 1); PG8_SCHED; PG8_LDA(At, 0, 0); PG8_STAGE(PG8_SA(1, 1), a1 + hstepA, voffA);
;             PG8_WAIT_V(8); PG8_WAIT_L(0); PG8_BAR; PG8_MMA(0, 0, At, B0); PG8_MMA(0, 1, At, B1); PG8_BAR; PG8_SCHED;
;             PG8_LDA(At, 0, 1); PG8_STAGE(PG8_SB(0, 0), b2, voffB); PG8_STAGE(PG8_SB(0, 1), b2 + hstepB, voffB); PG8_STAGE(PG8_SA(0, 0), a2, voffA);
;             PG8_WAIT_V(8); PG8_WAIT_L(0); PG8_BAR; PG8_MMA(1, 0, At, B0); PG8_MMA(1, 1, At, B1); PG8_BAR; PG8_SCHED;
.LBB0_891:
	s_ashr_i32 s59, s58, 31
	s_lshl_b64 s[24:25], s[58:59], 21
	s_add_u32 s64, s52, s24
	s_addc_u32 s65, s53, s25
	s_and_b64 s[6:7], s[6:7], exec
	s_cselect_b32 s1, s65, s71
	s_cselect_b32 s24, s64, s70
	s_add_u32 s25, s70, 0x100
	s_addc_u32 s39, s71, 0
	s_add_u32 s59, s68, 0x100
	s_addc_u32 s84, s69, 0
	s_add_u32 s6, s70, 0x100080
	s_addc_u32 s7, s71, 0
	s_mov_b32 s85, -2
	s_waitcnt vmcnt(41)
	s_waitcnt vmcnt(40)
	s_waitcnt vmcnt(38)
	s_waitcnt vmcnt(35)
	s_waitcnt vmcnt(34)
	s_waitcnt vmcnt(32)
	ds_read_b128 v[134:137], v201
	ds_read_b128 v[138:141], v201 offset:1024
	ds_read_b128 v[142:145], v201 offset:2048
	ds_read_b128 v[146:149], v201 offset:3072
	ds_read_b128 v[150:153], v202
	ds_read_b128 v[154:157], v202 offset:1024
	ds_read_b128 v[158:161], v202 offset:2048
	ds_read_b128 v[162:165], v202 offset:3072
	s_cmp_eq_u32 s85, 60
	s_cselect_b32 s72, s24, s25
	s_cselect_b32 s73, s1, s39
	s_cselect_b32 s70, s60, s59
	s_cselect_b32 s71, s61, s84
	s_add_u32 s68, s72, 0x80
	s_addc_u32 s69, s73, 0
	ds_read_b128 v[166:169], v203
	ds_read_b128 v[210:213], v203 offset:1024
	ds_read_b128 v[214:217], v203 offset:2048
	ds_read_b128 v[218:221], v203 offset:3072
	ds_read_b128 v[222:225], v203 offset:4096
	ds_read_b128 v[226:229], v203 offset:5120
	ds_read_b128 v[230:233], v203 offset:6144
	ds_read_b128 v[234:237], v203 offset:7168
	s_mov_b32 m0, s77
	s_nop 0
	global_load_lds_dwordx4 v1, s[6:7]
	s_mov_b32 m0, s79
	s_nop 0
	global_load_lds_dwordx4 v173, s[6:7]
	s_waitcnt vmcnt(8) lgkmcnt(0)
	s_barrier
	v_mfma_f32_16x16x32_bf16 v[126:129], v[134:137], v[166:169], 0
	v_mfma_f32_16x16x32_bf16 v[122:125], v[142:145], v[166:169], 0
	v_mfma_f32_16x16x32_bf16 v[110:113], v[134:137], v[214:217], 0
	v_mfma_f32_16x16x32_bf16 v[106:109], v[142:145], v[214:217], 0
	v_mfma_f32_16x16x32_bf16 v[94:97], v[134:137], v[222:225], 0
	v_mfma_f32_16x16x32_bf16 v[90:93], v[142:145], v[222:225], 0
	v_mfma_f32_16x16x32_bf16 v[78:81], v[134:137], v[230:233], 0
	v_mfma_f32_16x16x32_bf16 v[74:77], v[142:145], v[230:233], 0
	v_mfma_f32_16x16x32_bf16 v[126:129], v[138:141], v[210:213], v[126:129]
	v_mfma_f32_16x16x32_bf16 v[122:125], v[146:149], v[210:213], v[122:125]
	v_mfma_f32_16x16x32_bf16 v[110:113], v[138:141], v[218:221], v[110:113]
	v_mfma_f32_16x16x32_bf16 v[106:109], v[146:149], v[218:221], v[106:109]
	v_mfma_f32_16x16x32_bf16 v[94:97], v[138:141], v[226:229], v[94:97]
	v_mfma_f32_16x16x32_bf16 v[90:93], v[146:149], v[226:229], v[90:93]
	v_mfma_f32_16x16x32_bf16 v[78:81], v[138:141], v[234:237], v[78:81]
	v_mfma_f32_16x16x32_bf16 v[74:77], v[146:149], v[234:237], v[74:77]
	v_mfma_f32_16x16x32_bf16 v[118:121], v[150:153], v[166:169], 0
	v_mfma_f32_16x16x32_bf16 v[114:117], v[158:161], v[166:169], 0
	v_mfma_f32_16x16x32_bf16 v[102:105], v[150:153], v[214:217], 0
	v_mfma_f32_16x16x32_bf16 v[98:101], v[158:161], v[214:217], 0
	v_mfma_f32_16x16x32_bf16 v[86:89], v[150:153], v[222:225], 0
	v_mfma_f32_16x16x32_bf16 v[82:85], v[158:161], v[222:225], 0
	v_mfma_f32_16x16x32_bf16 v[70:73], v[150:153], v[230:233], 0
	v_mfma_f32_16x16x32_bf16 v[66:69], v[158:161], v[230:233], 0
	v_mfma_f32_16x16x32_bf16 v[118:121], v[154:157], v[210:213], v[118:121]
	v_mfma_f32_16x16x32_bf16 v[114:117], v[162:165], v[210:213], v[114:117]
	v_mfma_f32_16x16x32_bf16 v[102:105], v[154:157], v[218:221], v[102:105]
	v_mfma_f32_16x16x32_bf16 v[98:101], v[162:165], v[218:221], v[98:101]
	v_mfma_f32_16x16x32_bf16 v[86:89], v[154:157], v[226:229], v[86:89]
	v_mfma_f32_16x16x32_bf16 v[82:85], v[162:165], v[226:229], v[82:85]
	v_mfma_f32_16x16x32_bf16 v[70:73], v[154:157], v[234:237], v[70:73]
	v_mfma_f32_16x16x32_bf16 v[66:69], v[162:165], v[234:237], v[66:69]
	s_barrier
	ds_read_b128 v[166:169], v203 offset:16384
	ds_read_b128 v[210:213], v203 offset:17408
	ds_read_b128 v[214:217], v203 offset:18432
	ds_read_b128 v[218:221], v203 offset:19456
	ds_read_b128 v[222:225], v203 offset:20480
	ds_read_b128 v[226:229], v203 offset:21504
	ds_read_b128 v[230:233], v203 offset:22528
	ds_read_b128 v[234:237], v203 offset:23552
	s_mov_b32 m0, s17
	s_nop 0
	global_load_lds_dwordx4 v172, s[70:71]
	s_add_u32 s86, s70, 0x100000
	s_mov_b32 m0, s19
	s_nop 0
	global_load_lds_dwordx4 v174, s[70:71]
	s_addc_u32 s87, s71, 0
	s_mov_b32 m0, s23
	s_nop 0
	global_load_lds_dwordx4 v172, s[86:87]
	s_mov_b32 m0, s26
	s_nop 0
	global_load_lds_dwordx4 v174, s[86:87]
	s_mov_b32 m0, s15
	s_nop 0
	global_load_lds_dwordx4 v1, s[72:73]
	s_mov_b32 m0, s27
	s_nop 0
	global_load_lds_dwordx4 v173, s[72:73]
	s_waitcnt vmcnt(8) lgkmcnt(0)
	s_barrier
	v_mfma_f32_16x16x32_bf16 v[62:65], v[134:137], v[166:169], 0
	v_mfma_f32_16x16x32_bf16 v[58:61], v[142:145], v[166:169], 0
	v_mfma_f32_16x16x32_bf16 v[46:49], v[134:137], v[214:217], 0
	v_mfma_f32_16x16x32_bf16 v[42:45], v[142:145], v[214:217], 0
	v_mfma_f32_16x16x32_bf16 v[30:33], v[134:137], v[222:225], 0
	v_mfma_f32_16x16x32_bf16 v[26:29], v[142:145], v[222:225], 0
	v_mfma_f32_16x16x32_bf16 v[14:17], v[134:137], v[230:233], 0
	v_mfma_f32_16x16x32_bf16 v[10:13], v[142:145], v[230:233], 0
	v_mfma_f32_16x16x32_bf16 v[62:65], v[138:141], v[210:213], v[62:65]
	v_mfma_f32_16x16x32_bf16 v[58:61], v[146:149], v[210:213], v[58:61]
	v_mfma_f32_16x16x32_bf16 v[46:49], v[138:141], v[218:221], v[46:49]
	v_mfma_f32_16x16x32_bf16 v[42:45], v[146:149], v[218:221], v[42:45]
	v_mfma_f32_16x16x32_bf16 v[30:33], v[138:141], v[226:229], v[30:33]
	v_mfma_f32_16x16x32_bf16 v[26:29], v[146:149], v[226:229], v[26:29]
	v_mfma_f32_16x16x32_bf16 v[14:17], v[138:141], v[234:237], v[14:17]
	v_mfma_f32_16x16x32_bf16 v[10:13], v[146:149], v[234:237], v[10:13]
	v_mfma_f32_16x16x32_bf16 v[54:57], v[150:153], v[166:169], 0
	v_mfma_f32_16x16x32_bf16 v[50:53], v[158:161], v[166:169], 0
	v_mfma_f32_16x16x32_bf16 v[38:41], v[150:153], v[214:217], 0
	v_mfma_f32_16x16x32_bf16 v[34:37], v[158:161], v[214:217], 0
	v_mfma_f32_16x16x32_bf16 v[22:25], v[150:153], v[222:225], 0
	v_mfma_f32_16x16x32_bf16 v[18:21], v[158:161], v[222:225], 0
	v_mfma_f32_16x16x32_bf16 v[6:9], v[150:153], v[230:233], 0
	v_mfma_f32_16x16x32_bf16 v[2:5], v[158:161], v[230:233], 0
	v_mfma_f32_16x16x32_bf16 v[54:57], v[154:157], v[210:213], v[54:57]
	v_mfma_f32_16x16x32_bf16 v[50:53], v[162:165], v[210:213], v[50:53]
	v_mfma_f32_16x16x32_bf16 v[38:41], v[154:157], v[218:221], v[38:41]
	v_mfma_f32_16x16x32_bf16 v[34:37], v[162:165], v[218:221], v[34:37]
	v_mfma_f32_16x16x32_bf16 v[22:25], v[154:157], v[226:229], v[22:25]
	v_mfma_f32_16x16x32_bf16 v[18:21], v[162:165], v[226:229], v[18:21]
	v_mfma_f32_16x16x32_bf16 v[6:9], v[154:157], v[234:237], v[6:9]
	v_mfma_f32_16x16x32_bf16 v[2:5], v[162:165], v[234:237], v[2:5]
	s_barrier
; #define PG8_STAGE(bufoff, gbase, voff) do { if constexpr (VAR != 1 && VAR != 3) { _Pragma("unroll") for (int _i = 0; _i < 2; ++_i) \
;         asm volatile("s_mov_b32 m0, %2\n\ts_nop 0\n\tglobal_load_lds_dwordx4 %0, %1" :: "v"((voff)[_i]), "s"((const char*)(gbase)), "s"(ldsbase + (unsigned)((bufoff) + _i * 8192)) : "memory", "m0"); } } while (0)
; #define PG8_LDA(dst, b, h) do { if constexpr (VAR < 2) _Pragma("unroll") for (int m = 0; m < 4; ++m) _Pragma("unroll") for (int k = 0; k < 2; ++k) dst[m][k] = *(const LAS bf16x8*)(lds + PG8_SA(b, h) + aoff + m * 2048 + k * 1024); } while (0)
; #define PG8_LDB(dst, b, h) do { if constexpr (VAR < 2) _Pragma("unroll") for (int n = 0; n < 2; ++n) _Pragma("unroll") for (int k = 0; k < 2; ++k) dst[n][k] = *(const LAS bf16x8*)(lds + PG8_SB(b, h) + boff + n * 2048 + k * 1024); } while (0)
; #define PG8_WAIT_V(n) asm volatile("s_waitcnt vmcnt(" #n ")" ::: "memory")
; #define PG8_WAIT_L(n) asm volatile("s_waitcnt lgkmcnt(" #n ")" ::: "memory")
; #define PG8_BAR do { if constexpr (VAR != 3) __builtin_amdgcn_s_barrier(); } while (0)
; #define PG8_SCHED __builtin_amdgcn_sched_barrier(0)
;     ...
;             PG8_LDB(B0, 1, 0); PG8_LDB(B1, 1, 1); PG8_SCHED; PG8_LDA(At, 1, 0); PG8_STAGE(PG8_SA(0, 1), a2 + hstepA, voffA);
;             PG8_WAIT_V(8); PG8_WAIT_L(0); PG8_BAR; PG8_MMA(0, 0, At, B0); PG8_MMA(0, 1, At, B1); PG8_BAR; PG8_SCHED;
;             PG8_LDA(At, 1, 1); PG8_STAGE(PG8_SB(1, 0), b3, voffB); PG8_STAGE(PG8_SB(1, 1), b3 + hstepB, voffB); PG8_STAGE(PG8_SA(1, 0), a3, voffA);
;             PG8_WAIT_V(8); PG8_WAIT_L(0); PG8_BAR; PG8_MMA(1, 0, At, B0); PG8_MMA(1, 1, At, B1); PG8_BAR; PG8_SCHED;
;         }
	ds_read_b128 v[134:137], v204
	ds_read_b128 v[138:141], v204 offset:1024
	ds_read_b128 v[142:145], v204 offset:2048
	ds_read_b128 v[146:149], v204 offset:3072
	ds_read_b128 v[150:153], v205
	ds_read_b128 v[154:157], v205 offset:1024
	ds_read_b128 v[158:161], v205 offset:2048
	ds_read_b128 v[162:165], v205 offset:3072
	ds_read_b128 v[166:169], v203 offset:32768
	ds_read_b128 v[210:213], v203 offset:33792
	ds_read_b128 v[214:217], v203 offset:34816
	ds_read_b128 v[218:221], v203 offset:35840
	ds_read_b128 v[222:225], v203 offset:36864
	ds_read_b128 v[226:229], v203 offset:37888
	ds_read_b128 v[230:233], v203 offset:38912
	ds_read_b128 v[234:237], v203 offset:39936
	s_add_u32 s72, s72, 0x100000
	s_addc_u32 s73, s73, 0
	s_mov_b32 m0, s28
	s_nop 0
	global_load_lds_dwordx4 v1, s[72:73]
	s_mov_b32 m0, s29
	s_nop 0
	global_load_lds_dwordx4 v173, s[72:73]
	s_waitcnt vmcnt(8) lgkmcnt(0)
	s_barrier
	v_mfma_f32_16x16x32_bf16 v[126:129], v[134:137], v[166:169], v[126:129]
	v_mfma_f32_16x16x32_bf16 v[122:125], v[142:145], v[166:169], v[122:125]
	v_mfma_f32_16x16x32_bf16 v[110:113], v[134:137], v[214:217], v[110:113]
	v_mfma_f32_16x16x32_bf16 v[106:109], v[142:145], v[214:217], v[106:109]
	v_mfma_f32_16x16x32_bf16 v[94:97], v[134:137], v[222:225], v[94:97]
	v_mfma_f32_16x16x32_bf16 v[90:93], v[142:145], v[222:225], v[90:93]
	v_mfma_f32_16x16x32_bf16 v[78:81], v[134:137], v[230:233], v[78:81]
	v_mfma_f32_16x16x32_bf16 v[74:77], v[142:145], v[230:233], v[74:77]
	v_mfma_f32_16x16x32_bf16 v[126:129], v[138:141], v[210:213], v[126:129]
	v_mfma_f32_16x16x32_bf16 v[122:125], v[146:149], v[210:213], v[122:125]
	v_mfma_f32_16x16x32_bf16 v[110:113], v[138:141], v[218:221], v[110:113]
	v_mfma_f32_16x16x32_bf16 v[106:109], v[146:149], v[218:221], v[106:109]
	v_mfma_f32_16x16x32_bf16 v[94:97], v[138:141], v[226:229], v[94:97]
	v_mfma_f32_16x16x32_bf16 v[90:93], v[146:149], v[226:229], v[90:93]
	v_mfma_f32_16x16x32_bf16 v[78:81], v[138:141], v[234:237], v[78:81]
	v_mfma_f32_16x16x32_bf16 v[74:77], v[146:149], v[234:237], v[74:77]
	v_mfma_f32_16x16x32_bf16 v[118:121], v[150:153], v[166:169], v[118:121]
	v_mfma_f32_16x16x32_bf16 v[114:117], v[158:161], v[166:169], v[114:117]
	v_mfma_f32_16x16x32_bf16 v[102:105], v[150:153], v[214:217], v[102:105]
	v_mfma_f32_16x16x32_bf16 v[98:101], v[158:161], v[214:217], v[98:101]
	v_mfma_f32_16x16x32_bf16 v[86:89], v[150:153], v[222:225], v[86:89]
	v_mfma_f32_16x16x32_bf16 v[82:85], v[158:161], v[222:225], v[82:85]
	v_mfma_f32_16x16x32_bf16 v[70:73], v[150:153], v[230:233], v[70:73]
	v_mfma_f32_16x16x32_bf16 v[66:69], v[158:161], v[230:233], v[66:69]
	v_mfma_f32_16x16x32_bf16 v[118:121], v[154:157], v[210:213], v[118:121]
	v_mfma_f32_16x16x32_bf16 v[114:117], v[162:165], v[210:213], v[114:117]
	v_mfma_f32_16x16x32_bf16 v[102:105], v[154:157], v[218:221], v[102:105]
	v_mfma_f32_16x16x32_bf16 v[98:101], v[162:165], v[218:221], v[98:101]
	v_mfma_f32_16x16x32_bf16 v[86:89], v[154:157], v[226:229], v[86:89]
	v_mfma_f32_16x16x32_bf16 v[82:85], v[162:165], v[226:229], v[82:85]
	v_mfma_f32_16x16x32_bf16 v[70:73], v[154:157], v[234:237], v[70:73]
	v_mfma_f32_16x16x32_bf16 v[66:69], v[162:165], v[234:237], v[66:69]
	s_barrier
	ds_read_b128 v[166:169], v203 offset:49152
	ds_read_b128 v[210:213], v203 offset:50176
	ds_read_b128 v[214:217], v203 offset:51200
	ds_read_b128 v[218:221], v203 offset:52224
	ds_read_b128 v[222:225], v203 offset:53248
	ds_read_b128 v[226:229], v203 offset:54272
	ds_read_b128 v[230:233], v203 offset:55296
	ds_read_b128 v[234:237], v203 offset:56320
	s_add_u32 s72, s70, 0x80
	s_addc_u32 s73, s71, 0
	s_mov_b32 m0, s33
	s_nop 0
	global_load_lds_dwordx4 v172, s[72:73]
	s_add_u32 s70, s70, 0x100080
	s_mov_b32 m0, s35
	s_nop 0
	global_load_lds_dwordx4 v174, s[72:73]
	s_addc_u32 s71, s71, 0
	s_mov_b32 m0, s75
	s_nop 0
	global_load_lds_dwordx4 v172, s[70:71]
	s_mov_b32 m0, s76
	s_nop 0
	global_load_lds_dwordx4 v174, s[70:71]
	s_mov_b32 m0, s67
	s_nop 0
	global_load_lds_dwordx4 v1, s[68:69]
	s_mov_b32 m0, s74
	s_nop 0
	global_load_lds_dwordx4 v173, s[68:69]
	s_waitcnt vmcnt(8) lgkmcnt(0)
	s_barrier
	v_mfma_f32_16x16x32_bf16 v[62:65], v[134:137], v[166:169], v[62:65]
	v_mfma_f32_16x16x32_bf16 v[58:61], v[142:145], v[166:169], v[58:61]
	v_mfma_f32_16x16x32_bf16 v[46:49], v[134:137], v[214:217], v[46:49]
	v_mfma_f32_16x16x32_bf16 v[42:45], v[142:145], v[214:217], v[42:45]
	v_mfma_f32_16x16x32_bf16 v[30:33], v[134:137], v[222:225], v[30:33]
	v_mfma_f32_16x16x32_bf16 v[26:29], v[142:145], v[222:225], v[26:29]
	v_mfma_f32_16x16x32_bf16 v[14:17], v[134:137], v[230:233], v[14:17]
	v_mfma_f32_16x16x32_bf16 v[10:13], v[142:145], v[230:233], v[10:13]
	v_mfma_f32_16x16x32_bf16 v[62:65], v[138:141], v[210:213], v[62:65]
	v_mfma_f32_16x16x32_bf16 v[58:61], v[146:149], v[210:213], v[58:61]
	v_mfma_f32_16x16x32_bf16 v[46:49], v[138:141], v[218:221], v[46:49]
	v_mfma_f32_16x16x32_bf16 v[42:45], v[146:149], v[218:221], v[42:45]
	v_mfma_f32_16x16x32_bf16 v[30:33], v[138:141], v[226:229], v[30:33]
	v_mfma_f32_16x16x32_bf16 v[26:29], v[146:149], v[226:229], v[26:29]
	v_mfma_f32_16x16x32_bf16 v[14:17], v[138:141], v[234:237], v[14:17]
	v_mfma_f32_16x16x32_bf16 v[10:13], v[146:149], v[234:237], v[10:13]
	v_mfma_f32_16x16x32_bf16 v[54:57], v[150:153], v[166:169], v[54:57]
	v_mfma_f32_16x16x32_bf16 v[50:53], v[158:161], v[166:169], v[50:53]
	v_mfma_f32_16x16x32_bf16 v[38:41], v[150:153], v[214:217], v[38:41]
	v_mfma_f32_16x16x32_bf16 v[34:37], v[158:161], v[214:217], v[34:37]
	v_mfma_f32_16x16x32_bf16 v[22:25], v[150:153], v[222:225], v[22:25]
	v_mfma_f32_16x16x32_bf16 v[18:21], v[158:161], v[222:225], v[18:21]
	v_mfma_f32_16x16x32_bf16 v[6:9], v[150:153], v[230:233], v[6:9]
	v_mfma_f32_16x16x32_bf16 v[2:5], v[158:161], v[230:233], v[2:5]
	v_mfma_f32_16x16x32_bf16 v[54:57], v[154:157], v[210:213], v[54:57]
	v_mfma_f32_16x16x32_bf16 v[50:53], v[162:165], v[210:213], v[50:53]
	v_mfma_f32_16x16x32_bf16 v[38:41], v[154:157], v[218:221], v[38:41]
	v_mfma_f32_16x16x32_bf16 v[34:37], v[162:165], v[218:221], v[34:37]
	v_mfma_f32_16x16x32_bf16 v[22:25], v[154:157], v[226:229], v[22:25]
	v_mfma_f32_16x16x32_bf16 v[18:21], v[162:165], v[226:229], v[18:21]
	v_mfma_f32_16x16x32_bf16 v[6:9], v[154:157], v[234:237], v[6:9]
	v_mfma_f32_16x16x32_bf16 v[2:5], v[162:165], v[234:237], v[2:5]
	s_barrier
	s_add_i32 s85, s85, 2
	s_add_u32 s25, s25, 0x100
	s_addc_u32 s39, s39, 0
	s_add_u32 s59, s59, 0x100
	s_addc_u32 s84, s84, 0
	s_add_u32 s6, s6, 0x100
	s_addc_u32 s7, s7, 0
	s_cmp_gt_u32 s85, 61
	s_cbranch_scc0 .LBB0_892
	s_branch .Lmy_kexit_6
; #define PG8_STAGE(bufoff, gbase, voff) do { if constexpr (VAR != 1 && VAR != 3) { _Pragma("unroll") for (int _i = 0; _i < 2; ++_i) \
;         asm volatile("s_mov_b32 m0, %2\n\ts_nop 0\n\tglobal_load_lds_dwordx4 %0, %1" :: "v"((voff)[_i]), "s"((const char*)(gbase)), "s"(ldsbase + (unsigned)((bufoff) + _i * 8192)) : "memory", "m0"); } } while (0)
; #define PG8_LDA(dst, b, h) do { if constexpr (VAR < 2) _Pragma("unroll") for (int m = 0; m < 4; ++m) _Pragma("unroll") for (int k = 0; k < 2; ++k) dst[m][k] = *(const LAS bf16x8*)(lds + PG8_SA(b, h) + aoff + m * 2048 + k * 1024); } while (0)
; #define PG8_LDB(dst, b, h) do { if constexpr (VAR < 2) _Pragma("unroll") for (int n = 0; n < 2; ++n) _Pragma("unroll") for (int k = 0; k < 2; ++k) dst[n][k] = *(const LAS bf16x8*)(lds + PG8_SB(b, h) + boff + n * 2048 + k * 1024); } while (0)
; #define PG8_WAIT_V(n) asm volatile("s_waitcnt vmcnt(" #n ")" ::: "memory")
; #define PG8_WAIT_L(n) asm volatile("s_waitcnt lgkmcnt(" #n ")" ::: "memory")
; #define PG8_BAR do { if constexpr (VAR != 3) __builtin_amdgcn_s_barrier(); } while (0)
; #define PG8_SCHED __builtin_amdgcn_sched_barrier(0)
;     ...
;         for (int t = 0; t < nt; t += 2) {
;             const bool last = (t == nt - 2);
;             const char* a1 = cA + (size_t)(t + 1) * kstep;
;             const char* a2 = last ? nA : cA + (size_t)(t + 2) * kstep; const char* b2 = last ? nB : cB + (size_t)(t + 2) * kstep;
;             const char* a3 = a2 + kstep; const char* b3 = b2 + kstep;
;             PG8_LDB(B0, 0, 0); PG8_LDB(B1, 0, 1); PG8_SCHED; PG8_LDA(At, 0, 0); PG8_STAGE(PG8_SA(1, 1), a1 + hstepA, voffA);
;             PG8_WAIT_V(8); PG8_WAIT_L(0); PG8_BAR; PG8_MMA(0, 0, At, B0); PG8_MMA(0, 1, At, B1); PG8_BAR; PG8_SCHED;
;             PG8_LDA(At, 0, 1); PG8_STAGE(PG8_SB(0, 0), b2, voffB); PG8_STAGE(PG8_SB(0, 1), b2 + hstepB, voffB); PG8_STAGE(PG8_SA(0, 0), a2, voffA);
;             PG8_WAIT_V(8); PG8_WAIT_L(0); PG8_BAR; PG8_MMA(1, 0, At, B0); PG8_MMA(1, 1, At, B1); PG8_BAR; PG8_SCHED;
.LBB0_892:
	ds_read_b128 v[134:137], v201
	ds_read_b128 v[138:141], v201 offset:1024
	ds_read_b128 v[142:145], v201 offset:2048
	ds_read_b128 v[146:149], v201 offset:3072
	ds_read_b128 v[150:153], v202
	ds_read_b128 v[154:157], v202 offset:1024
	ds_read_b128 v[158:161], v202 offset:2048
	ds_read_b128 v[162:165], v202 offset:3072
	s_cmp_eq_u32 s85, 60
	s_cselect_b32 s72, s24, s25
	s_cselect_b32 s73, s1, s39
	s_cselect_b32 s70, s60, s59
	s_cselect_b32 s71, s61, s84
	s_add_u32 s68, s72, 0x80
	s_addc_u32 s69, s73, 0
	ds_read_b128 v[166:169], v203
	ds_read_b128 v[210:213], v203 offset:1024
	ds_read_b128 v[214:217], v203 offset:2048
	ds_read_b128 v[218:221], v203 offset:3072
	ds_read_b128 v[222:225], v203 offset:4096
	ds_read_b128 v[226:229], v203 offset:5120
	ds_read_b128 v[230:233], v203 offset:6144
	ds_read_b128 v[234:237], v203 offset:7168
	s_mov_b32 m0, s77
	s_nop 0
	global_load_lds_dwordx4 v1, s[6:7]
	s_mov_b32 m0, s79
	s_nop 0
	global_load_lds_dwordx4 v173, s[6:7]
	s_waitcnt vmcnt(8) lgkmcnt(0)
	s_barrier
	v_mfma_f32_16x16x32_bf16 v[126:129], v[134:137], v[166:169], v[126:129]
	v_mfma_f32_16x16x32_bf16 v[122:125], v[142:145], v[166:169], v[122:125]
	v_mfma_f32_16x16x32_bf16 v[110:113], v[134:137], v[214:217], v[110:113]
	v_mfma_f32_16x16x32_bf16 v[106:109], v[142:145], v[214:217], v[106:109]
	v_mfma_f32_16x16x32_bf16 v[94:97], v[134:137], v[222:225], v[94:97]
	v_mfma_f32_16x16x32_bf16 v[90:93], v[142:145], v[222:225], v[90:93]
	v_mfma_f32_16x16x32_bf16 v[78:81], v[134:137], v[230:233], v[78:81]
	v_mfma_f32_16x16x32_bf16 v[74:77], v[142:145], v[230:233], v[74:77]
	v_mfma_f32_16x16x32_bf16 v[126:129], v[138:141], v[210:213], v[126:129]
	v_mfma_f32_16x16x32_bf16 v[122:125], v[146:149], v[210:213], v[122:125]
	v_mfma_f32_16x16x32_bf16 v[110:113], v[138:141], v[218:221], v[110:113]
	v_mfma_f32_16x16x32_bf16 v[106:109], v[146:149], v[218:221], v[106:109]
	v_mfma_f32_16x16x32_bf16 v[94:97], v[138:141], v[226:229], v[94:97]
	v_mfma_f32_16x16x32_bf16 v[90:93], v[146:149], v[226:229], v[90:93]
	v_mfma_f32_16x16x32_bf16 v[78:81], v[138:141], v[234:237], v[78:81]
	v_mfma_f32_16x16x32_bf16 v[74:77], v[146:149], v[234:237], v[74:77]
	v_mfma_f32_16x16x32_bf16 v[118:121], v[150:153], v[166:169], v[118:121]
	v_mfma_f32_16x16x32_bf16 v[114:117], v[158:161], v[166:169], v[114:117]
	v_mfma_f32_16x16x32_bf16 v[102:105], v[150:153], v[214:217], v[102:105]
	v_mfma_f32_16x16x32_bf16 v[98:101], v[158:161], v[214:217], v[98:101]
	v_mfma_f32_16x16x32_bf16 v[86:89], v[150:153], v[222:225], v[86:89]
	v_mfma_f32_16x16x32_bf16 v[82:85], v[158:161], v[222:225], v[82:85]
	v_mfma_f32_16x16x32_bf16 v[70:73], v[150:153], v[230:233], v[70:73]
	v_mfma_f32_16x16x32_bf16 v[66:69], v[158:161], v[230:233], v[66:69]
	v_mfma_f32_16x16x32_bf16 v[118:121], v[154:157], v[210:213], v[118:121]
	v_mfma_f32_16x16x32_bf16 v[114:117], v[162:165], v[210:213], v[114:117]
	v_mfma_f32_16x16x32_bf16 v[102:105], v[154:157], v[218:221], v[102:105]
	v_mfma_f32_16x16x32_bf16 v[98:101], v[162:165], v[218:221], v[98:101]
	v_mfma_f32_16x16x32_bf16 v[86:89], v[154:157], v[226:229], v[86:89]
	v_mfma_f32_16x16x32_bf16 v[82:85], v[162:165], v[226:229], v[82:85]
	v_mfma_f32_16x16x32_bf16 v[70:73], v[154:157], v[234:237], v[70:73]
	v_mfma_f32_16x16x32_bf16 v[66:69], v[162:165], v[234:237], v[66:69]
	s_barrier
	ds_read_b128 v[166:169], v203 offset:16384
	ds_read_b128 v[210:213], v203 offset:17408
	ds_read_b128 v[214:217], v203 offset:18432
	ds_read_b128 v[218:221], v203 offset:19456
	ds_read_b128 v[222:225], v203 offset:20480
	ds_read_b128 v[226:229], v203 offset:21504
	ds_read_b128 v[230:233], v203 offset:22528
	ds_read_b128 v[234:237], v203 offset:23552
	s_mov_b32 m0, s17
	s_nop 0
	global_load_lds_dwordx4 v172, s[70:71]
	s_add_u32 s86, s70, 0x100000
	s_mov_b32 m0, s19
	s_nop 0
	global_load_lds_dwordx4 v174, s[70:71]
	s_addc_u32 s87, s71, 0
	s_mov_b32 m0, s23
	s_nop 0
	global_load_lds_dwordx4 v172, s[86:87]
	s_mov_b32 m0, s26
	s_nop 0
	global_load_lds_dwordx4 v174, s[86:87]
	s_mov_b32 m0, s15
	s_nop 0
	global_load_lds_dwordx4 v1, s[72:73]
	s_mov_b32 m0, s27
	s_nop 0
	global_load_lds_dwordx4 v173, s[72:73]
	s_waitcnt vmcnt(8) lgkmcnt(0)
	s_barrier
	v_mfma_f32_16x16x32_bf16 v[62:65], v[134:137], v[166:169], v[62:65]
	v_mfma_f32_16x16x32_bf16 v[58:61], v[142:145], v[166:169], v[58:61]
	v_mfma_f32_16x16x32_bf16 v[46:49], v[134:137], v[214:217], v[46:49]
	v_mfma_f32_16x16x32_bf16 v[42:45], v[142:145], v[214:217], v[42:45]
	v_mfma_f32_16x16x32_bf16 v[30:33], v[134:137], v[222:225], v[30:33]
	v_mfma_f32_16x16x32_bf16 v[26:29], v[142:145], v[222:225], v[26:29]
	v_mfma_f32_16x16x32_bf16 v[14:17], v[134:137], v[230:233], v[14:17]
	v_mfma_f32_16x16x32_bf16 v[10:13], v[142:145], v[230:233], v[10:13]
	v_mfma_f32_16x16x32_bf16 v[62:65], v[138:141], v[210:213], v[62:65]
	v_mfma_f32_16x16x32_bf16 v[58:61], v[146:149], v[210:213], v[58:61]
	v_mfma_f32_16x16x32_bf16 v[46:49], v[138:141], v[218:221], v[46:49]
	v_mfma_f32_16x16x32_bf16 v[42:45], v[146:149], v[218:221], v[42:45]
	v_mfma_f32_16x16x32_bf16 v[30:33], v[138:141], v[226:229], v[30:33]
	v_mfma_f32_16x16x32_bf16 v[26:29], v[146:149], v[226:229], v[26:29]
	v_mfma_f32_16x16x32_bf16 v[14:17], v[138:141], v[234:237], v[14:17]
	v_mfma_f32_16x16x32_bf16 v[10:13], v[146:149], v[234:237], v[10:13]
	v_mfma_f32_16x16x32_bf16 v[54:57], v[150:153], v[166:169], v[54:57]
	v_mfma_f32_16x16x32_bf16 v[50:53], v[158:161], v[166:169], v[50:53]
	v_mfma_f32_16x16x32_bf16 v[38:41], v[150:153], v[214:217], v[38:41]
	v_mfma_f32_16x16x32_bf16 v[34:37], v[158:161], v[214:217], v[34:37]
	v_mfma_f32_16x16x32_bf16 v[22:25], v[150:153], v[222:225], v[22:25]
	v_mfma_f32_16x16x32_bf16 v[18:21], v[158:161], v[222:225], v[18:21]
	v_mfma_f32_16x16x32_bf16 v[6:9], v[150:153], v[230:233], v[6:9]
	v_mfma_f32_16x16x32_bf16 v[2:5], v[158:161], v[230:233], v[2:5]
	v_mfma_f32_16x16x32_bf16 v[54:57], v[154:157], v[210:213], v[54:57]
	v_mfma_f32_16x16x32_bf16 v[50:53], v[162:165], v[210:213], v[50:53]
	v_mfma_f32_16x16x32_bf16 v[38:41], v[154:157], v[218:221], v[38:41]
	v_mfma_f32_16x16x32_bf16 v[34:37], v[162:165], v[218:221], v[34:37]
	v_mfma_f32_16x16x32_bf16 v[22:25], v[154:157], v[226:229], v[22:25]
	v_mfma_f32_16x16x32_bf16 v[18:21], v[162:165], v[226:229], v[18:21]
	v_mfma_f32_16x16x32_bf16 v[6:9], v[154:157], v[234:237], v[6:9]
	v_mfma_f32_16x16x32_bf16 v[2:5], v[162:165], v[234:237], v[2:5]
	s_barrier
; #define PG8_STAGE(bufoff, gbase, voff) do { if constexpr (VAR != 1 && VAR != 3) { _Pragma("unroll") for (int _i = 0; _i < 2; ++_i) \
;         asm volatile("s_mov_b32 m0, %2\n\ts_nop 0\n\tglobal_load_lds_dwordx4 %0, %1" :: "v"((voff)[_i]), "s"((const char*)(gbase)), "s"(ldsbase + (unsigned)((bufoff) + _i * 8192)) : "memory", "m0"); } } while (0)
; #define PG8_LDA(dst, b, h) do { if constexpr (VAR < 2) _Pragma("unroll") for (int m = 0; m < 4; ++m) _Pragma("unroll") for (int k = 0; k < 2; ++k) dst[m][k] = *(const LAS bf16x8*)(lds + PG8_SA(b, h) + aoff + m * 2048 + k * 1024); } while (0)
; #define PG8_LDB(dst, b, h) do { if constexpr (VAR < 2) _Pragma("unroll") for (int n = 0; n < 2; ++n) _Pragma("unroll") for (int k = 0; k < 2; ++k) dst[n][k] = *(const LAS bf16x8*)(lds + PG8_SB(b, h) + boff + n * 2048 + k * 1024); } while (0)
; #define PG8_WAIT_V(n) asm volatile("s_waitcnt vmcnt(" #n ")" ::: "memory")
; #define PG8_WAIT_L(n) asm volatile("s_waitcnt lgkmcnt(" #n ")" ::: "memory")
; #define PG8_BAR do { if constexpr (VAR != 3) __builtin_amdgcn_s_barrier(); } while (0)
; #define PG8_SCHED __builtin_amdgcn_sched_barrier(0)
;     ...
;             PG8_LDB(B0, 1, 0); PG8_LDB(B1, 1, 1); PG8_SCHED; PG8_LDA(At, 1, 0); PG8_STAGE(PG8_SA(0, 1), a2 + hstepA, voffA);
;             PG8_WAIT_V(8); PG8_WAIT_L(0); PG8_BAR; PG8_MMA(0, 0, At, B0); PG8_MMA(0, 1, At, B1); PG8_BAR; PG8_SCHED;
;             PG8_LDA(At, 1, 1); PG8_STAGE(PG8_SB(1, 0), b3, voffB); PG8_STAGE(PG8_SB(1, 1), b3 + hstepB, voffB); PG8_STAGE(PG8_SA(1, 0), a3, voffA);
;             PG8_WAIT_V(8); PG8_WAIT_L(0); PG8_BAR; PG8_MMA(1, 0, At, B0); PG8_MMA(1, 1, At, B1); PG8_BAR; PG8_SCHED;
;         }
	ds_read_b128 v[134:137], v204
	ds_read_b128 v[138:141], v204 offset:1024
	ds_read_b128 v[142:145], v204 offset:2048
	ds_read_b128 v[146:149], v204 offset:3072
	ds_read_b128 v[150:153], v205
	ds_read_b128 v[154:157], v205 offset:1024
	ds_read_b128 v[158:161], v205 offset:2048
	ds_read_b128 v[162:165], v205 offset:3072
	ds_read_b128 v[166:169], v203 offset:32768
	ds_read_b128 v[210:213], v203 offset:33792
	ds_read_b128 v[214:217], v203 offset:34816
	ds_read_b128 v[218:221], v203 offset:35840
	ds_read_b128 v[222:225], v203 offset:36864
	ds_read_b128 v[226:229], v203 offset:37888
	ds_read_b128 v[230:233], v203 offset:38912
	ds_read_b128 v[234:237], v203 offset:39936
	s_add_u32 s72, s72, 0x100000
	s_addc_u32 s73, s73, 0
	s_mov_b32 m0, s28
	s_nop 0
	global_load_lds_dwordx4 v1, s[72:73]
	s_mov_b32 m0, s29
	s_nop 0
	global_load_lds_dwordx4 v173, s[72:73]
	s_waitcnt vmcnt(8) lgkmcnt(0)
	s_barrier
	v_mfma_f32_16x16x32_bf16 v[126:129], v[134:137], v[166:169], v[126:129]
	v_mfma_f32_16x16x32_bf16 v[122:125], v[142:145], v[166:169], v[122:125]
	v_mfma_f32_16x16x32_bf16 v[110:113], v[134:137], v[214:217], v[110:113]
	v_mfma_f32_16x16x32_bf16 v[106:109], v[142:145], v[214:217], v[106:109]
	v_mfma_f32_16x16x32_bf16 v[94:97], v[134:137], v[222:225], v[94:97]
	v_mfma_f32_16x16x32_bf16 v[90:93], v[142:145], v[222:225], v[90:93]
	v_mfma_f32_16x16x32_bf16 v[78:81], v[134:137], v[230:233], v[78:81]
	v_mfma_f32_16x16x32_bf16 v[74:77], v[142:145], v[230:233], v[74:77]
	v_mfma_f32_16x16x32_bf16 v[126:129], v[138:141], v[210:213], v[126:129]
	v_mfma_f32_16x16x32_bf16 v[122:125], v[146:149], v[210:213], v[122:125]
	v_mfma_f32_16x16x32_bf16 v[110:113], v[138:141], v[218:221], v[110:113]
	v_mfma_f32_16x16x32_bf16 v[106:109], v[146:149], v[218:221], v[106:109]
	v_mfma_f32_16x16x32_bf16 v[94:97], v[138:141], v[226:229], v[94:97]
	v_mfma_f32_16x16x32_bf16 v[90:93], v[146:149], v[226:229], v[90:93]
	v_mfma_f32_16x16x32_bf16 v[78:81], v[138:141], v[234:237], v[78:81]
	v_mfma_f32_16x16x32_bf16 v[74:77], v[146:149], v[234:237], v[74:77]
	v_mfma_f32_16x16x32_bf16 v[118:121], v[150:153], v[166:169], v[118:121]
	v_mfma_f32_16x16x32_bf16 v[114:117], v[158:161], v[166:169], v[114:117]
	v_mfma_f32_16x16x32_bf16 v[102:105], v[150:153], v[214:217], v[102:105]
	v_mfma_f32_16x16x32_bf16 v[98:101], v[158:161], v[214:217], v[98:101]
	v_mfma_f32_16x16x32_bf16 v[86:89], v[150:153], v[222:225], v[86:89]
	v_mfma_f32_16x16x32_bf16 v[82:85], v[158:161], v[222:225], v[82:85]
	v_mfma_f32_16x16x32_bf16 v[70:73], v[150:153], v[230:233], v[70:73]
	v_mfma_f32_16x16x32_bf16 v[66:69], v[158:161], v[230:233], v[66:69]
	v_mfma_f32_16x16x32_bf16 v[118:121], v[154:157], v[210:213], v[118:121]
	v_mfma_f32_16x16x32_bf16 v[114:117], v[162:165], v[210:213], v[114:117]
	v_mfma_f32_16x16x32_bf16 v[102:105], v[154:157], v[218:221], v[102:105]
	v_mfma_f32_16x16x32_bf16 v[98:101], v[162:165], v[218:221], v[98:101]
	v_mfma_f32_16x16x32_bf16 v[86:89], v[154:157], v[226:229], v[86:89]
	v_mfma_f32_16x16x32_bf16 v[82:85], v[162:165], v[226:229], v[82:85]
	v_mfma_f32_16x16x32_bf16 v[70:73], v[154:157], v[234:237], v[70:73]
	v_mfma_f32_16x16x32_bf16 v[66:69], v[162:165], v[234:237], v[66:69]
	s_barrier
	ds_read_b128 v[166:169], v203 offset:49152
	ds_read_b128 v[210:213], v203 offset:50176
	ds_read_b128 v[214:217], v203 offset:51200
	ds_read_b128 v[218:221], v203 offset:52224
	ds_read_b128 v[222:225], v203 offset:53248
	ds_read_b128 v[226:229], v203 offset:54272
	ds_read_b128 v[230:233], v203 offset:55296
	ds_read_b128 v[234:237], v203 offset:56320
	s_add_u32 s72, s70, 0x80
	s_addc_u32 s73, s71, 0
	s_mov_b32 m0, s33
	s_nop 0
	global_load_lds_dwordx4 v172, s[72:73]
	s_add_u32 s70, s70, 0x100080
	s_mov_b32 m0, s35
	s_nop 0
	global_load_lds_dwordx4 v174, s[72:73]
	s_addc_u32 s71, s71, 0
	s_mov_b32 m0, s75
	s_nop 0
	global_load_lds_dwordx4 v172, s[70:71]
	s_mov_b32 m0, s76
	s_nop 0
	global_load_lds_dwordx4 v174, s[70:71]
	s_mov_b32 m0, s67
	s_nop 0
	global_load_lds_dwordx4 v1, s[68:69]
	s_mov_b32 m0, s74
	s_nop 0
	global_load_lds_dwordx4 v173, s[68:69]
	s_waitcnt vmcnt(8) lgkmcnt(0)
	s_barrier
	v_mfma_f32_16x16x32_bf16 v[62:65], v[134:137], v[166:169], v[62:65]
	v_mfma_f32_16x16x32_bf16 v[58:61], v[142:145], v[166:169], v[58:61]
	v_mfma_f32_16x16x32_bf16 v[46:49], v[134:137], v[214:217], v[46:49]
	v_mfma_f32_16x16x32_bf16 v[42:45], v[142:145], v[214:217], v[42:45]
	v_mfma_f32_16x16x32_bf16 v[30:33], v[134:137], v[222:225], v[30:33]
	v_mfma_f32_16x16x32_bf16 v[26:29], v[142:145], v[222:225], v[26:29]
	v_mfma_f32_16x16x32_bf16 v[14:17], v[134:137], v[230:233], v[14:17]
	v_mfma_f32_16x16x32_bf16 v[10:13], v[142:145], v[230:233], v[10:13]
	v_mfma_f32_16x16x32_bf16 v[62:65], v[138:141], v[210:213], v[62:65]
	v_mfma_f32_16x16x32_bf16 v[58:61], v[146:149], v[210:213], v[58:61]
	v_mfma_f32_16x16x32_bf16 v[46:49], v[138:141], v[218:221], v[46:49]
	v_mfma_f32_16x16x32_bf16 v[42:45], v[146:149], v[218:221], v[42:45]
	v_mfma_f32_16x16x32_bf16 v[30:33], v[138:141], v[226:229], v[30:33]
	v_mfma_f32_16x16x32_bf16 v[26:29], v[146:149], v[226:229], v[26:29]
	v_mfma_f32_16x16x32_bf16 v[14:17], v[138:141], v[234:237], v[14:17]
	v_mfma_f32_16x16x32_bf16 v[10:13], v[146:149], v[234:237], v[10:13]
	v_mfma_f32_16x16x32_bf16 v[54:57], v[150:153], v[166:169], v[54:57]
	v_mfma_f32_16x16x32_bf16 v[50:53], v[158:161], v[166:169], v[50:53]
	v_mfma_f32_16x16x32_bf16 v[38:41], v[150:153], v[214:217], v[38:41]
	v_mfma_f32_16x16x32_bf16 v[34:37], v[158:161], v[214:217], v[34:37]
	v_mfma_f32_16x16x32_bf16 v[22:25], v[150:153], v[222:225], v[22:25]
	v_mfma_f32_16x16x32_bf16 v[18:21], v[158:161], v[222:225], v[18:21]
	v_mfma_f32_16x16x32_bf16 v[6:9], v[150:153], v[230:233], v[6:9]
	v_mfma_f32_16x16x32_bf16 v[2:5], v[158:161], v[230:233], v[2:5]
	v_mfma_f32_16x16x32_bf16 v[54:57], v[154:157], v[210:213], v[54:57]
	v_mfma_f32_16x16x32_bf16 v[50:53], v[162:165], v[210:213], v[50:53]
	v_mfma_f32_16x16x32_bf16 v[38:41], v[154:157], v[218:221], v[38:41]
	v_mfma_f32_16x16x32_bf16 v[34:37], v[162:165], v[218:221], v[34:37]
	v_mfma_f32_16x16x32_bf16 v[22:25], v[154:157], v[226:229], v[22:25]
	v_mfma_f32_16x16x32_bf16 v[18:21], v[162:165], v[226:229], v[18:21]
	v_mfma_f32_16x16x32_bf16 v[6:9], v[154:157], v[234:237], v[6:9]
	v_mfma_f32_16x16x32_bf16 v[2:5], v[162:165], v[234:237], v[2:5]
	s_barrier
	s_add_i32 s85, s85, 2
	s_add_u32 s25, s25, 0x100
	s_addc_u32 s39, s39, 0
	s_add_u32 s59, s59, 0x100
	s_addc_u32 s84, s84, 0
	s_add_u32 s6, s6, 0x100
	s_addc_u32 s7, s7, 0
	s_cmp_gt_u32 s85, 61
	s_cbranch_scc0 .LBB0_892

; __device__ __forceinline__ const char* unitA(const Gemm& g, const Unit& u) { return (const char*)(g.A + (size_t)(u.z / g.zdiv) * g.sAhi + (size_t)(u.z % g.zdiv) * g.sAlo + (size_t)u.pm * BM * g.lda); }
; __device__ __forceinline__ const char* unitB(const Gemm& g, const Unit& u) { return (const char*)(g.Bt + (size_t)(u.z / g.zdiv) * g.sBhi + (size_t)(u.z % g.zdiv) * g.sBlo + (size_t)(u.pm / g.bdiv) * g.sBpm + (size_t)u.pn * BM * g.ldb); }
; #define PG8_STAGE(bufoff, gbase, voff) do { if constexpr (VAR != 1 && VAR != 3) { _Pragma("unroll") for (int _i = 0; _i < 2; ++_i) \
;         asm volatile("s_mov_b32 m0, %2\n\ts_nop 0\n\tglobal_load_lds_dwordx4 %0, %1" :: "v"((voff)[_i]), "s"((const char*)(gbase)), "s"(ldsbase + (unsigned)((bufoff) + _i * 8192)) : "memory", "m0"); } } while (0)
; #define PG8_LDA(dst, b, h) do { if constexpr (VAR < 2) _Pragma("unroll") for (int m = 0; m < 4; ++m) _Pragma("unroll") for (int k = 0; k < 2; ++k) dst[m][k] = *(const LAS bf16x8*)(lds + PG8_SA(b, h) + aoff + m * 2048 + k * 1024); } while (0)
; #define PG8_LDB(dst, b, h) do { if constexpr (VAR < 2) _Pragma("unroll") for (int n = 0; n < 2; ++n) _Pragma("unroll") for (int k = 0; k < 2; ++k) dst[n][k] = *(const LAS bf16x8*)(lds + PG8_SB(b, h) + boff + n * 2048 + k * 1024); } while (0)
; #define PG8_WAIT_V(n) asm volatile("s_waitcnt vmcnt(" #n ")" ::: "memory")
;     ...
;         const bool has_next = S.next(ui + 1, nxt);
;         const char* nA = has_next ? unitA(g, nxt) : cA; const char* nB = has_next ? unitB(g, nxt) : cB;
;         for (int t = 0; t < nt; t += 2) {
;             const bool last = (t == nt - 2);
;             const char* a1 = cA + (size_t)(t + 1) * kstep;
;             const char* a2 = last ? nA : cA + (size_t)(t + 2) * kstep; const char* b2 = last ? nB : cB + (size_t)(t + 2) * kstep;
;             const char* a3 = a2 + kstep; const char* b3 = b2 + kstep;
;             PG8_LDB(B0, 0, 0); PG8_LDB(B1, 0, 1); PG8_SCHED; PG8_LDA(At, 0, 0); PG8_STAGE(PG8_SA(1, 1), a1 + hstepA, voffA);
;             PG8_WAIT_V(8); PG8_WAIT_L(0); PG8_BAR; PG8_MMA(0, 0, At, B0); PG8_MMA(0, 1, At, B1); PG8_BAR; PG8_SCHED;
;             PG8_LDA(At, 0, 1); PG8_STAGE(PG8_SB(0, 0), b2, voffB); PG8_STAGE(PG8_SB(0, 1), b2 + hstepB, voffB); PG8_STAGE(PG8_SA(0, 0), a2, voffA);
;             PG8_WAIT_V(8); PG8_WAIT_L(0); PG8_BAR; PG8_MMA(1, 0, At, B0); PG8_MMA(1, 1, At, B1); PG8_BAR; PG8_SCHED;
.LBB0_1001:
	s_ashr_i32 s65, s64, 31
	s_lshl_b64 s[24:25], s[64:65], 19
	s_add_u32 s68, s40, s24
	s_addc_u32 s69, s41, s25
	s_and_b64 s[12:13], s[12:13], exec
	s_cselect_b32 s24, s69, s77
	s_cselect_b32 s25, s68, s76
	s_add_u32 s63, s76, 0x100
	s_addc_u32 s65, s77, 0
	s_add_u32 s84, s74, 0x100
	s_addc_u32 s85, s75, 0
	s_add_u32 s12, s76, 0x40080
	s_addc_u32 s13, s77, 0
	s_mov_b32 s86, -2
	s_waitcnt vmcnt(41)
	s_waitcnt vmcnt(40)
	s_waitcnt vmcnt(38)
	s_waitcnt vmcnt(35)
	s_waitcnt vmcnt(34)
	s_waitcnt vmcnt(32)
	ds_read_b128 v[130:133], v183
	ds_read_b128 v[134:137], v183 offset:1024
	ds_read_b128 v[138:141], v183 offset:2048
	ds_read_b128 v[142:145], v183 offset:3072
	ds_read_b128 v[146:149], v184
	ds_read_b128 v[150:153], v184 offset:1024
	ds_read_b128 v[154:157], v184 offset:2048
	ds_read_b128 v[162:165], v184 offset:3072
	s_cmp_eq_u32 s86, 12
	s_cselect_b32 s78, s25, s63
	s_cselect_b32 s79, s24, s65
	s_cselect_b32 s76, s66, s84
	s_cselect_b32 s77, s67, s85
	s_add_u32 s74, s78, 0x80
	s_addc_u32 s75, s79, 0
	ds_read_b128 v[166:169], v185
	ds_read_b128 v[170:173], v185 offset:1024
	ds_read_b128 v[190:193], v185 offset:2048
	ds_read_b128 v[194:197], v185 offset:3072
	ds_read_b128 v[198:201], v185 offset:4096
	ds_read_b128 v[202:205], v185 offset:5120
	ds_read_b128 v[206:209], v185 offset:6144
	ds_read_b128 v[210:213], v185 offset:7168
	s_mov_b32 m0, s82
	s_nop 0
	global_load_lds_dwordx4 v176, s[12:13]
	s_mov_b32 m0, s83
	s_nop 0
	global_load_lds_dwordx4 v178, s[12:13]
	s_waitcnt vmcnt(8) lgkmcnt(0)
	s_barrier
	v_mfma_f32_16x16x32_bf16 v[126:129], v[130:133], v[166:169], 0
	v_mfma_f32_16x16x32_bf16 v[122:125], v[138:141], v[166:169], 0
	v_mfma_f32_16x16x32_bf16 v[110:113], v[130:133], v[190:193], 0
	v_mfma_f32_16x16x32_bf16 v[106:109], v[138:141], v[190:193], 0
	v_mfma_f32_16x16x32_bf16 v[94:97], v[130:133], v[198:201], 0
	v_mfma_f32_16x16x32_bf16 v[90:93], v[138:141], v[198:201], 0
	v_mfma_f32_16x16x32_bf16 v[78:81], v[130:133], v[206:209], 0
	v_mfma_f32_16x16x32_bf16 v[74:77], v[138:141], v[206:209], 0
	v_mfma_f32_16x16x32_bf16 v[126:129], v[134:137], v[170:173], v[126:129]
	v_mfma_f32_16x16x32_bf16 v[122:125], v[142:145], v[170:173], v[122:125]
	v_mfma_f32_16x16x32_bf16 v[110:113], v[134:137], v[194:197], v[110:113]
	v_mfma_f32_16x16x32_bf16 v[106:109], v[142:145], v[194:197], v[106:109]
	v_mfma_f32_16x16x32_bf16 v[94:97], v[134:137], v[202:205], v[94:97]
	v_mfma_f32_16x16x32_bf16 v[90:93], v[142:145], v[202:205], v[90:93]
	v_mfma_f32_16x16x32_bf16 v[78:81], v[134:137], v[210:213], v[78:81]
	v_mfma_f32_16x16x32_bf16 v[74:77], v[142:145], v[210:213], v[74:77]
	v_mfma_f32_16x16x32_bf16 v[118:121], v[146:149], v[166:169], 0
	v_mfma_f32_16x16x32_bf16 v[114:117], v[154:157], v[166:169], 0
	v_mfma_f32_16x16x32_bf16 v[102:105], v[146:149], v[190:193], 0
	v_mfma_f32_16x16x32_bf16 v[98:101], v[154:157], v[190:193], 0
	v_mfma_f32_16x16x32_bf16 v[86:89], v[146:149], v[198:201], 0
	v_mfma_f32_16x16x32_bf16 v[82:85], v[154:157], v[198:201], 0
	v_mfma_f32_16x16x32_bf16 v[70:73], v[146:149], v[206:209], 0
	v_mfma_f32_16x16x32_bf16 v[66:69], v[154:157], v[206:209], 0
	v_mfma_f32_16x16x32_bf16 v[118:121], v[150:153], v[170:173], v[118:121]
	v_mfma_f32_16x16x32_bf16 v[114:117], v[162:165], v[170:173], v[114:117]
	v_mfma_f32_16x16x32_bf16 v[102:105], v[150:153], v[194:197], v[102:105]
	v_mfma_f32_16x16x32_bf16 v[98:101], v[162:165], v[194:197], v[98:101]
	v_mfma_f32_16x16x32_bf16 v[86:89], v[150:153], v[202:205], v[86:89]
	v_mfma_f32_16x16x32_bf16 v[82:85], v[162:165], v[202:205], v[82:85]
	v_mfma_f32_16x16x32_bf16 v[70:73], v[150:153], v[210:213], v[70:73]
	v_mfma_f32_16x16x32_bf16 v[66:69], v[162:165], v[210:213], v[66:69]
	s_barrier
	ds_read_b128 v[166:169], v185 offset:16384
	ds_read_b128 v[170:173], v185 offset:17408
	ds_read_b128 v[190:193], v185 offset:18432
	ds_read_b128 v[194:197], v185 offset:19456
	ds_read_b128 v[198:201], v185 offset:20480
	ds_read_b128 v[202:205], v185 offset:21504
	ds_read_b128 v[206:209], v185 offset:22528
	ds_read_b128 v[210:213], v185 offset:23552
	s_mov_b32 m0, s17
	s_nop 0
	global_load_lds_dwordx4 v177, s[76:77]
	s_add_u32 s88, s76, 0x40000
	s_mov_b32 m0, s19
	s_nop 0
	global_load_lds_dwordx4 v179, s[76:77]
	s_addc_u32 s89, s77, 0
	s_mov_b32 m0, s23
	s_nop 0
	global_load_lds_dwordx4 v177, s[88:89]
	s_mov_b32 m0, s26
	s_nop 0
	global_load_lds_dwordx4 v179, s[88:89]
	s_mov_b32 m0, s15
	s_nop 0
	global_load_lds_dwordx4 v176, s[78:79]
	s_mov_b32 m0, s27
	s_nop 0
	global_load_lds_dwordx4 v178, s[78:79]
	s_waitcnt vmcnt(8) lgkmcnt(0)
	s_barrier
	v_mfma_f32_16x16x32_bf16 v[62:65], v[130:133], v[166:169], 0
	v_mfma_f32_16x16x32_bf16 v[58:61], v[138:141], v[166:169], 0
	v_mfma_f32_16x16x32_bf16 v[46:49], v[130:133], v[190:193], 0
	v_mfma_f32_16x16x32_bf16 v[42:45], v[138:141], v[190:193], 0
	v_mfma_f32_16x16x32_bf16 v[30:33], v[130:133], v[198:201], 0
	v_mfma_f32_16x16x32_bf16 v[26:29], v[138:141], v[198:201], 0
	v_mfma_f32_16x16x32_bf16 v[14:17], v[130:133], v[206:209], 0
	v_mfma_f32_16x16x32_bf16 v[10:13], v[138:141], v[206:209], 0
	v_mfma_f32_16x16x32_bf16 v[62:65], v[134:137], v[170:173], v[62:65]
	v_mfma_f32_16x16x32_bf16 v[58:61], v[142:145], v[170:173], v[58:61]
	v_mfma_f32_16x16x32_bf16 v[46:49], v[134:137], v[194:197], v[46:49]
	v_mfma_f32_16x16x32_bf16 v[42:45], v[142:145], v[194:197], v[42:45]
	v_mfma_f32_16x16x32_bf16 v[30:33], v[134:137], v[202:205], v[30:33]
	v_mfma_f32_16x16x32_bf16 v[26:29], v[142:145], v[202:205], v[26:29]
	v_mfma_f32_16x16x32_bf16 v[14:17], v[134:137], v[210:213], v[14:17]
	v_mfma_f32_16x16x32_bf16 v[10:13], v[142:145], v[210:213], v[10:13]
	v_mfma_f32_16x16x32_bf16 v[54:57], v[146:149], v[166:169], 0
	v_mfma_f32_16x16x32_bf16 v[50:53], v[154:157], v[166:169], 0
	v_mfma_f32_16x16x32_bf16 v[38:41], v[146:149], v[190:193], 0
	v_mfma_f32_16x16x32_bf16 v[34:37], v[154:157], v[190:193], 0
	v_mfma_f32_16x16x32_bf16 v[22:25], v[146:149], v[198:201], 0
	v_mfma_f32_16x16x32_bf16 v[18:21], v[154:157], v[198:201], 0
	v_mfma_f32_16x16x32_bf16 v[6:9], v[146:149], v[206:209], 0
	v_mfma_f32_16x16x32_bf16 v[2:5], v[154:157], v[206:209], 0
	v_mfma_f32_16x16x32_bf16 v[54:57], v[150:153], v[170:173], v[54:57]
	v_mfma_f32_16x16x32_bf16 v[50:53], v[162:165], v[170:173], v[50:53]
	v_mfma_f32_16x16x32_bf16 v[38:41], v[150:153], v[194:197], v[38:41]
	v_mfma_f32_16x16x32_bf16 v[34:37], v[162:165], v[194:197], v[34:37]
	v_mfma_f32_16x16x32_bf16 v[22:25], v[150:153], v[202:205], v[22:25]
	v_mfma_f32_16x16x32_bf16 v[18:21], v[162:165], v[202:205], v[18:21]
	v_mfma_f32_16x16x32_bf16 v[6:9], v[150:153], v[210:213], v[6:9]
	v_mfma_f32_16x16x32_bf16 v[2:5], v[162:165], v[210:213], v[2:5]
	s_barrier
; #define PG8_STAGE(bufoff, gbase, voff) do { if constexpr (VAR != 1 && VAR != 3) { _Pragma("unroll") for (int _i = 0; _i < 2; ++_i) \
;         asm volatile("s_mov_b32 m0, %2\n\ts_nop 0\n\tglobal_load_lds_dwordx4 %0, %1" :: "v"((voff)[_i]), "s"((const char*)(gbase)), "s"(ldsbase + (unsigned)((bufoff) + _i * 8192)) : "memory", "m0"); } } while (0)
; #define PG8_LDA(dst, b, h) do { if constexpr (VAR < 2) _Pragma("unroll") for (int m = 0; m < 4; ++m) _Pragma("unroll") for (int k = 0; k < 2; ++k) dst[m][k] = *(const LAS bf16x8*)(lds + PG8_SA(b, h) + aoff + m * 2048 + k * 1024); } while (0)
; #define PG8_LDB(dst, b, h) do { if constexpr (VAR < 2) _Pragma("unroll") for (int n = 0; n < 2; ++n) _Pragma("unroll") for (int k = 0; k < 2; ++k) dst[n][k] = *(const LAS bf16x8*)(lds + PG8_SB(b, h) + boff + n * 2048 + k * 1024); } while (0)
; #define PG8_WAIT_V(n) asm volatile("s_waitcnt vmcnt(" #n ")" ::: "memory")
; #define PG8_WAIT_L(n) asm volatile("s_waitcnt lgkmcnt(" #n ")" ::: "memory")
; #define PG8_BAR do { if constexpr (VAR != 3) __builtin_amdgcn_s_barrier(); } while (0)
; #define PG8_SCHED __builtin_amdgcn_sched_barrier(0)
;     ...
;             PG8_LDB(B0, 1, 0); PG8_LDB(B1, 1, 1); PG8_SCHED; PG8_LDA(At, 1, 0); PG8_STAGE(PG8_SA(0, 1), a2 + hstepA, voffA);
;             PG8_WAIT_V(8); PG8_WAIT_L(0); PG8_BAR; PG8_MMA(0, 0, At, B0); PG8_MMA(0, 1, At, B1); PG8_BAR; PG8_SCHED;
;             PG8_LDA(At, 1, 1); PG8_STAGE(PG8_SB(1, 0), b3, voffB); PG8_STAGE(PG8_SB(1, 1), b3 + hstepB, voffB); PG8_STAGE(PG8_SA(1, 0), a3, voffA);
;             PG8_WAIT_V(8); PG8_WAIT_L(0); PG8_BAR; PG8_MMA(1, 0, At, B0); PG8_MMA(1, 1, At, B1); PG8_BAR; PG8_SCHED;
;         }
	ds_read_b128 v[130:133], v186
	ds_read_b128 v[134:137], v186 offset:1024
	ds_read_b128 v[138:141], v186 offset:2048
	ds_read_b128 v[142:145], v186 offset:3072
	ds_read_b128 v[146:149], v187
	ds_read_b128 v[150:153], v187 offset:1024
	ds_read_b128 v[154:157], v187 offset:2048
	ds_read_b128 v[162:165], v187 offset:3072
	ds_read_b128 v[166:169], v185 offset:32768
	ds_read_b128 v[170:173], v185 offset:33792
	ds_read_b128 v[190:193], v185 offset:34816
	ds_read_b128 v[194:197], v185 offset:35840
	ds_read_b128 v[198:201], v185 offset:36864
	ds_read_b128 v[202:205], v185 offset:37888
	ds_read_b128 v[206:209], v185 offset:38912
	ds_read_b128 v[210:213], v185 offset:39936
	s_add_u32 s78, s78, 0x40000
	s_addc_u32 s79, s79, 0
	s_mov_b32 m0, s28
	s_nop 0
	global_load_lds_dwordx4 v176, s[78:79]
	s_mov_b32 m0, s29
	s_nop 0
	global_load_lds_dwordx4 v178, s[78:79]
	s_waitcnt vmcnt(8) lgkmcnt(0)
	s_barrier
	v_mfma_f32_16x16x32_bf16 v[126:129], v[130:133], v[166:169], v[126:129]
	v_mfma_f32_16x16x32_bf16 v[122:125], v[138:141], v[166:169], v[122:125]
	v_mfma_f32_16x16x32_bf16 v[110:113], v[130:133], v[190:193], v[110:113]
	v_mfma_f32_16x16x32_bf16 v[106:109], v[138:141], v[190:193], v[106:109]
	v_mfma_f32_16x16x32_bf16 v[94:97], v[130:133], v[198:201], v[94:97]
	v_mfma_f32_16x16x32_bf16 v[90:93], v[138:141], v[198:201], v[90:93]
	v_mfma_f32_16x16x32_bf16 v[78:81], v[130:133], v[206:209], v[78:81]
	v_mfma_f32_16x16x32_bf16 v[74:77], v[138:141], v[206:209], v[74:77]
	v_mfma_f32_16x16x32_bf16 v[126:129], v[134:137], v[170:173], v[126:129]
	v_mfma_f32_16x16x32_bf16 v[122:125], v[142:145], v[170:173], v[122:125]
	v_mfma_f32_16x16x32_bf16 v[110:113], v[134:137], v[194:197], v[110:113]
	v_mfma_f32_16x16x32_bf16 v[106:109], v[142:145], v[194:197], v[106:109]
	v_mfma_f32_16x16x32_bf16 v[94:97], v[134:137], v[202:205], v[94:97]
	v_mfma_f32_16x16x32_bf16 v[90:93], v[142:145], v[202:205], v[90:93]
	v_mfma_f32_16x16x32_bf16 v[78:81], v[134:137], v[210:213], v[78:81]
	v_mfma_f32_16x16x32_bf16 v[74:77], v[142:145], v[210:213], v[74:77]
	v_mfma_f32_16x16x32_bf16 v[118:121], v[146:149], v[166:169], v[118:121]
	v_mfma_f32_16x16x32_bf16 v[114:117], v[154:157], v[166:169], v[114:117]
	v_mfma_f32_16x16x32_bf16 v[102:105], v[146:149], v[190:193], v[102:105]
	v_mfma_f32_16x16x32_bf16 v[98:101], v[154:157], v[190:193], v[98:101]
	v_mfma_f32_16x16x32_bf16 v[86:89], v[146:149], v[198:201], v[86:89]
	v_mfma_f32_16x16x32_bf16 v[82:85], v[154:157], v[198:201], v[82:85]
	v_mfma_f32_16x16x32_bf16 v[70:73], v[146:149], v[206:209], v[70:73]
	v_mfma_f32_16x16x32_bf16 v[66:69], v[154:157], v[206:209], v[66:69]
	v_mfma_f32_16x16x32_bf16 v[118:121], v[150:153], v[170:173], v[118:121]
	v_mfma_f32_16x16x32_bf16 v[114:117], v[162:165], v[170:173], v[114:117]
	v_mfma_f32_16x16x32_bf16 v[102:105], v[150:153], v[194:197], v[102:105]
	v_mfma_f32_16x16x32_bf16 v[98:101], v[162:165], v[194:197], v[98:101]
	v_mfma_f32_16x16x32_bf16 v[86:89], v[150:153], v[202:205], v[86:89]
	v_mfma_f32_16x16x32_bf16 v[82:85], v[162:165], v[202:205], v[82:85]
	v_mfma_f32_16x16x32_bf16 v[70:73], v[150:153], v[210:213], v[70:73]
	v_mfma_f32_16x16x32_bf16 v[66:69], v[162:165], v[210:213], v[66:69]
	s_barrier
	ds_read_b128 v[166:169], v185 offset:49152
	ds_read_b128 v[170:173], v185 offset:50176
	ds_read_b128 v[190:193], v185 offset:51200
	ds_read_b128 v[194:197], v185 offset:52224
	ds_read_b128 v[198:201], v185 offset:53248
	ds_read_b128 v[202:205], v185 offset:54272
	ds_read_b128 v[206:209], v185 offset:55296
	ds_read_b128 v[210:213], v185 offset:56320
	s_add_u32 s78, s76, 0x80
	s_addc_u32 s79, s77, 0
	s_mov_b32 m0, s33
	s_nop 0
	global_load_lds_dwordx4 v177, s[78:79]
	s_add_u32 s76, s76, 0x40080
	s_mov_b32 m0, s35
	s_nop 0
	global_load_lds_dwordx4 v179, s[78:79]
	s_addc_u32 s77, s77, 0
	s_mov_b32 m0, s80
	s_nop 0
	global_load_lds_dwordx4 v177, s[76:77]
	s_mov_b32 m0, s81
	s_nop 0
	global_load_lds_dwordx4 v179, s[76:77]
	s_mov_b32 m0, s71
	s_nop 0
	global_load_lds_dwordx4 v176, s[74:75]
	s_mov_b32 m0, s73
	s_nop 0
	global_load_lds_dwordx4 v178, s[74:75]
	s_waitcnt vmcnt(8) lgkmcnt(0)
	s_barrier
	v_mfma_f32_16x16x32_bf16 v[62:65], v[130:133], v[166:169], v[62:65]
	v_mfma_f32_16x16x32_bf16 v[58:61], v[138:141], v[166:169], v[58:61]
	v_mfma_f32_16x16x32_bf16 v[46:49], v[130:133], v[190:193], v[46:49]
	v_mfma_f32_16x16x32_bf16 v[42:45], v[138:141], v[190:193], v[42:45]
	v_mfma_f32_16x16x32_bf16 v[30:33], v[130:133], v[198:201], v[30:33]
	v_mfma_f32_16x16x32_bf16 v[26:29], v[138:141], v[198:201], v[26:29]
	v_mfma_f32_16x16x32_bf16 v[14:17], v[130:133], v[206:209], v[14:17]
	v_mfma_f32_16x16x32_bf16 v[10:13], v[138:141], v[206:209], v[10:13]
	v_mfma_f32_16x16x32_bf16 v[62:65], v[134:137], v[170:173], v[62:65]
	v_mfma_f32_16x16x32_bf16 v[58:61], v[142:145], v[170:173], v[58:61]
	v_mfma_f32_16x16x32_bf16 v[46:49], v[134:137], v[194:197], v[46:49]
	v_mfma_f32_16x16x32_bf16 v[42:45], v[142:145], v[194:197], v[42:45]
	v_mfma_f32_16x16x32_bf16 v[30:33], v[134:137], v[202:205], v[30:33]
	v_mfma_f32_16x16x32_bf16 v[26:29], v[142:145], v[202:205], v[26:29]
	v_mfma_f32_16x16x32_bf16 v[14:17], v[134:137], v[210:213], v[14:17]
	v_mfma_f32_16x16x32_bf16 v[10:13], v[142:145], v[210:213], v[10:13]
	v_mfma_f32_16x16x32_bf16 v[54:57], v[146:149], v[166:169], v[54:57]
	v_mfma_f32_16x16x32_bf16 v[50:53], v[154:157], v[166:169], v[50:53]
	v_mfma_f32_16x16x32_bf16 v[38:41], v[146:149], v[190:193], v[38:41]
	v_mfma_f32_16x16x32_bf16 v[34:37], v[154:157], v[190:193], v[34:37]
	v_mfma_f32_16x16x32_bf16 v[22:25], v[146:149], v[198:201], v[22:25]
	v_mfma_f32_16x16x32_bf16 v[18:21], v[154:157], v[198:201], v[18:21]
	v_mfma_f32_16x16x32_bf16 v[6:9], v[146:149], v[206:209], v[6:9]
	v_mfma_f32_16x16x32_bf16 v[2:5], v[154:157], v[206:209], v[2:5]
	v_mfma_f32_16x16x32_bf16 v[54:57], v[150:153], v[170:173], v[54:57]
	v_mfma_f32_16x16x32_bf16 v[50:53], v[162:165], v[170:173], v[50:53]
	v_mfma_f32_16x16x32_bf16 v[38:41], v[150:153], v[194:197], v[38:41]
	v_mfma_f32_16x16x32_bf16 v[34:37], v[162:165], v[194:197], v[34:37]
	v_mfma_f32_16x16x32_bf16 v[22:25], v[150:153], v[202:205], v[22:25]
	v_mfma_f32_16x16x32_bf16 v[18:21], v[162:165], v[202:205], v[18:21]
	v_mfma_f32_16x16x32_bf16 v[6:9], v[150:153], v[210:213], v[6:9]
	v_mfma_f32_16x16x32_bf16 v[2:5], v[162:165], v[210:213], v[2:5]
	s_barrier
	s_add_i32 s86, s86, 2
	s_add_u32 s63, s63, 0x100
	s_addc_u32 s65, s65, 0
	s_add_u32 s84, s84, 0x100
	s_addc_u32 s85, s85, 0
	s_add_u32 s12, s12, 0x100
	s_addc_u32 s13, s13, 0
	s_cmp_gt_u32 s86, 13
	s_cbranch_scc0 .LBB0_1002
	s_branch .Lmy_kexit_7
; #define PG8_STAGE(bufoff, gbase, voff) do { if constexpr (VAR != 1 && VAR != 3) { _Pragma("unroll") for (int _i = 0; _i < 2; ++_i) \
;         asm volatile("s_mov_b32 m0, %2\n\ts_nop 0\n\tglobal_load_lds_dwordx4 %0, %1" :: "v"((voff)[_i]), "s"((const char*)(gbase)), "s"(ldsbase + (unsigned)((bufoff) + _i * 8192)) : "memory", "m0"); } } while (0)
; #define PG8_LDA(dst, b, h) do { if constexpr (VAR < 2) _Pragma("unroll") for (int m = 0; m < 4; ++m) _Pragma("unroll") for (int k = 0; k < 2; ++k) dst[m][k] = *(const LAS bf16x8*)(lds + PG8_SA(b, h) + aoff + m * 2048 + k * 1024); } while (0)
; #define PG8_LDB(dst, b, h) do { if constexpr (VAR < 2) _Pragma("unroll") for (int n = 0; n < 2; ++n) _Pragma("unroll") for (int k = 0; k < 2; ++k) dst[n][k] = *(const LAS bf16x8*)(lds + PG8_SB(b, h) + boff + n * 2048 + k * 1024); } while (0)
; #define PG8_WAIT_V(n) asm volatile("s_waitcnt vmcnt(" #n ")" ::: "memory")
; #define PG8_WAIT_L(n) asm volatile("s_waitcnt lgkmcnt(" #n ")" ::: "memory")
; #define PG8_BAR do { if constexpr (VAR != 3) __builtin_amdgcn_s_barrier(); } while (0)
; #define PG8_SCHED __builtin_amdgcn_sched_barrier(0)
;     ...
;         for (int t = 0; t < nt; t += 2) {
;             const bool last = (t == nt - 2);
;             const char* a1 = cA + (size_t)(t + 1) * kstep;
;             const char* a2 = last ? nA : cA + (size_t)(t + 2) * kstep; const char* b2 = last ? nB : cB + (size_t)(t + 2) * kstep;
;             const char* a3 = a2 + kstep; const char* b3 = b2 + kstep;
;             PG8_LDB(B0, 0, 0); PG8_LDB(B1, 0, 1); PG8_SCHED; PG8_LDA(At, 0, 0); PG8_STAGE(PG8_SA(1, 1), a1 + hstepA, voffA);
;             PG8_WAIT_V(8); PG8_WAIT_L(0); PG8_BAR; PG8_MMA(0, 0, At, B0); PG8_MMA(0, 1, At, B1); PG8_BAR; PG8_SCHED;
;             PG8_LDA(At, 0, 1); PG8_STAGE(PG8_SB(0, 0), b2, voffB); PG8_STAGE(PG8_SB(0, 1), b2 + hstepB, voffB); PG8_STAGE(PG8_SA(0, 0), a2, voffA);
;             PG8_WAIT_V(8); PG8_WAIT_L(0); PG8_BAR; PG8_MMA(1, 0, At, B0); PG8_MMA(1, 1, At, B1); PG8_BAR; PG8_SCHED;
.LBB0_1002:
	ds_read_b128 v[130:133], v183
	ds_read_b128 v[134:137], v183 offset:1024
	ds_read_b128 v[138:141], v183 offset:2048
	ds_read_b128 v[142:145], v183 offset:3072
	ds_read_b128 v[146:149], v184
	ds_read_b128 v[150:153], v184 offset:1024
	ds_read_b128 v[154:157], v184 offset:2048
	ds_read_b128 v[162:165], v184 offset:3072
	s_cmp_eq_u32 s86, 12
	s_cselect_b32 s78, s25, s63
	s_cselect_b32 s79, s24, s65
	s_cselect_b32 s76, s66, s84
	s_cselect_b32 s77, s67, s85
	s_add_u32 s74, s78, 0x80
	s_addc_u32 s75, s79, 0
	ds_read_b128 v[166:169], v185
	ds_read_b128 v[170:173], v185 offset:1024
	ds_read_b128 v[190:193], v185 offset:2048
	ds_read_b128 v[194:197], v185 offset:3072
	ds_read_b128 v[198:201], v185 offset:4096
	ds_read_b128 v[202:205], v185 offset:5120
	ds_read_b128 v[206:209], v185 offset:6144
	ds_read_b128 v[210:213], v185 offset:7168
	s_mov_b32 m0, s82
	s_nop 0
	global_load_lds_dwordx4 v176, s[12:13]
	s_mov_b32 m0, s83
	s_nop 0
	global_load_lds_dwordx4 v178, s[12:13]
	s_waitcnt vmcnt(8) lgkmcnt(0)
	s_barrier
	v_mfma_f32_16x16x32_bf16 v[126:129], v[130:133], v[166:169], v[126:129]
	v_mfma_f32_16x16x32_bf16 v[122:125], v[138:141], v[166:169], v[122:125]
	v_mfma_f32_16x16x32_bf16 v[110:113], v[130:133], v[190:193], v[110:113]
	v_mfma_f32_16x16x32_bf16 v[106:109], v[138:141], v[190:193], v[106:109]
	v_mfma_f32_16x16x32_bf16 v[94:97], v[130:133], v[198:201], v[94:97]
	v_mfma_f32_16x16x32_bf16 v[90:93], v[138:141], v[198:201], v[90:93]
	v_mfma_f32_16x16x32_bf16 v[78:81], v[130:133], v[206:209], v[78:81]
	v_mfma_f32_16x16x32_bf16 v[74:77], v[138:141], v[206:209], v[74:77]
	v_mfma_f32_16x16x32_bf16 v[126:129], v[134:137], v[170:173], v[126:129]
	v_mfma_f32_16x16x32_bf16 v[122:125], v[142:145], v[170:173], v[122:125]
	v_mfma_f32_16x16x32_bf16 v[110:113], v[134:137], v[194:197], v[110:113]
	v_mfma_f32_16x16x32_bf16 v[106:109], v[142:145], v[194:197], v[106:109]
	v_mfma_f32_16x16x32_bf16 v[94:97], v[134:137], v[202:205], v[94:97]
	v_mfma_f32_16x16x32_bf16 v[90:93], v[142:145], v[202:205], v[90:93]
	v_mfma_f32_16x16x32_bf16 v[78:81], v[134:137], v[210:213], v[78:81]
	v_mfma_f32_16x16x32_bf16 v[74:77], v[142:145], v[210:213], v[74:77]
	v_mfma_f32_16x16x32_bf16 v[118:121], v[146:149], v[166:169], v[118:121]
	v_mfma_f32_16x16x32_bf16 v[114:117], v[154:157], v[166:169], v[114:117]
	v_mfma_f32_16x16x32_bf16 v[102:105], v[146:149], v[190:193], v[102:105]
	v_mfma_f32_16x16x32_bf16 v[98:101], v[154:157], v[190:193], v[98:101]
	v_mfma_f32_16x16x32_bf16 v[86:89], v[146:149], v[198:201], v[86:89]
	v_mfma_f32_16x16x32_bf16 v[82:85], v[154:157], v[198:201], v[82:85]
	v_mfma_f32_16x16x32_bf16 v[70:73], v[146:149], v[206:209], v[70:73]
	v_mfma_f32_16x16x32_bf16 v[66:69], v[154:157], v[206:209], v[66:69]
	v_mfma_f32_16x16x32_bf16 v[118:121], v[150:153], v[170:173], v[118:121]
	v_mfma_f32_16x16x32_bf16 v[114:117], v[162:165], v[170:173], v[114:117]
	v_mfma_f32_16x16x32_bf16 v[102:105], v[150:153], v[194:197], v[102:105]
	v_mfma_f32_16x16x32_bf16 v[98:101], v[162:165], v[194:197], v[98:101]
	v_mfma_f32_16x16x32_bf16 v[86:89], v[150:153], v[202:205], v[86:89]
	v_mfma_f32_16x16x32_bf16 v[82:85], v[162:165], v[202:205], v[82:85]
	v_mfma_f32_16x16x32_bf16 v[70:73], v[150:153], v[210:213], v[70:73]
	v_mfma_f32_16x16x32_bf16 v[66:69], v[162:165], v[210:213], v[66:69]
	s_barrier
	ds_read_b128 v[166:169], v185 offset:16384
	ds_read_b128 v[170:173], v185 offset:17408
	ds_read_b128 v[190:193], v185 offset:18432
	ds_read_b128 v[194:197], v185 offset:19456
	ds_read_b128 v[198:201], v185 offset:20480
	ds_read_b128 v[202:205], v185 offset:21504
	ds_read_b128 v[206:209], v185 offset:22528
	ds_read_b128 v[210:213], v185 offset:23552
	s_mov_b32 m0, s17
	s_nop 0
	global_load_lds_dwordx4 v177, s[76:77]
	s_add_u32 s88, s76, 0x40000
	s_mov_b32 m0, s19
	s_nop 0
	global_load_lds_dwordx4 v179, s[76:77]
	s_addc_u32 s89, s77, 0
	s_mov_b32 m0, s23
	s_nop 0
	global_load_lds_dwordx4 v177, s[88:89]
	s_mov_b32 m0, s26
	s_nop 0
	global_load_lds_dwordx4 v179, s[88:89]
	s_mov_b32 m0, s15
	s_nop 0
	global_load_lds_dwordx4 v176, s[78:79]
	s_mov_b32 m0, s27
	s_nop 0
	global_load_lds_dwordx4 v178, s[78:79]
	s_waitcnt vmcnt(8) lgkmcnt(0)
	s_barrier
	v_mfma_f32_16x16x32_bf16 v[62:65], v[130:133], v[166:169], v[62:65]
	v_mfma_f32_16x16x32_bf16 v[58:61], v[138:141], v[166:169], v[58:61]
	v_mfma_f32_16x16x32_bf16 v[46:49], v[130:133], v[190:193], v[46:49]
	v_mfma_f32_16x16x32_bf16 v[42:45], v[138:141], v[190:193], v[42:45]
	v_mfma_f32_16x16x32_bf16 v[30:33], v[130:133], v[198:201], v[30:33]
	v_mfma_f32_16x16x32_bf16 v[26:29], v[138:141], v[198:201], v[26:29]
	v_mfma_f32_16x16x32_bf16 v[14:17], v[130:133], v[206:209], v[14:17]
	v_mfma_f32_16x16x32_bf16 v[10:13], v[138:141], v[206:209], v[10:13]
	v_mfma_f32_16x16x32_bf16 v[62:65], v[134:137], v[170:173], v[62:65]
	v_mfma_f32_16x16x32_bf16 v[58:61], v[142:145], v[170:173], v[58:61]
	v_mfma_f32_16x16x32_bf16 v[46:49], v[134:137], v[194:197], v[46:49]
	v_mfma_f32_16x16x32_bf16 v[42:45], v[142:145], v[194:197], v[42:45]
	v_mfma_f32_16x16x32_bf16 v[30:33], v[134:137], v[202:205], v[30:33]
	v_mfma_f32_16x16x32_bf16 v[26:29], v[142:145], v[202:205], v[26:29]
	v_mfma_f32_16x16x32_bf16 v[14:17], v[134:137], v[210:213], v[14:17]
	v_mfma_f32_16x16x32_bf16 v[10:13], v[142:145], v[210:213], v[10:13]
	v_mfma_f32_16x16x32_bf16 v[54:57], v[146:149], v[166:169], v[54:57]
	v_mfma_f32_16x16x32_bf16 v[50:53], v[154:157], v[166:169], v[50:53]
	v_mfma_f32_16x16x32_bf16 v[38:41], v[146:149], v[190:193], v[38:41]
	v_mfma_f32_16x16x32_bf16 v[34:37], v[154:157], v[190:193], v[34:37]
	v_mfma_f32_16x16x32_bf16 v[22:25], v[146:149], v[198:201], v[22:25]
	v_mfma_f32_16x16x32_bf16 v[18:21], v[154:157], v[198:201], v[18:21]
	v_mfma_f32_16x16x32_bf16 v[6:9], v[146:149], v[206:209], v[6:9]
	v_mfma_f32_16x16x32_bf16 v[2:5], v[154:157], v[206:209], v[2:5]
	v_mfma_f32_16x16x32_bf16 v[54:57], v[150:153], v[170:173], v[54:57]
	v_mfma_f32_16x16x32_bf16 v[50:53], v[162:165], v[170:173], v[50:53]
	v_mfma_f32_16x16x32_bf16 v[38:41], v[150:153], v[194:197], v[38:41]
	v_mfma_f32_16x16x32_bf16 v[34:37], v[162:165], v[194:197], v[34:37]
	v_mfma_f32_16x16x32_bf16 v[22:25], v[150:153], v[202:205], v[22:25]
	v_mfma_f32_16x16x32_bf16 v[18:21], v[162:165], v[202:205], v[18:21]
	v_mfma_f32_16x16x32_bf16 v[6:9], v[150:153], v[210:213], v[6:9]
	v_mfma_f32_16x16x32_bf16 v[2:5], v[162:165], v[210:213], v[2:5]
	s_barrier
; #define PG8_STAGE(bufoff, gbase, voff) do { if constexpr (VAR != 1 && VAR != 3) { _Pragma("unroll") for (int _i = 0; _i < 2; ++_i) \
;         asm volatile("s_mov_b32 m0, %2\n\ts_nop 0\n\tglobal_load_lds_dwordx4 %0, %1" :: "v"((voff)[_i]), "s"((const char*)(gbase)), "s"(ldsbase + (unsigned)((bufoff) + _i * 8192)) : "memory", "m0"); } } while (0)
; #define PG8_LDA(dst, b, h) do { if constexpr (VAR < 2) _Pragma("unroll") for (int m = 0; m < 4; ++m) _Pragma("unroll") for (int k = 0; k < 2; ++k) dst[m][k] = *(const LAS bf16x8*)(lds + PG8_SA(b, h) + aoff + m * 2048 + k * 1024); } while (0)
; #define PG8_LDB(dst, b, h) do { if constexpr (VAR < 2) _Pragma("unroll") for (int n = 0; n < 2; ++n) _Pragma("unroll") for (int k = 0; k < 2; ++k) dst[n][k] = *(const LAS bf16x8*)(lds + PG8_SB(b, h) + boff + n * 2048 + k * 1024); } while (0)
; #define PG8_WAIT_V(n) asm volatile("s_waitcnt vmcnt(" #n ")" ::: "memory")
; #define PG8_WAIT_L(n) asm volatile("s_waitcnt lgkmcnt(" #n ")" ::: "memory")
; #define PG8_BAR do { if constexpr (VAR != 3) __builtin_amdgcn_s_barrier(); } while (0)
; #define PG8_SCHED __builtin_amdgcn_sched_barrier(0)
;     ...
;             PG8_LDB(B0, 1, 0); PG8_LDB(B1, 1, 1); PG8_SCHED; PG8_LDA(At, 1, 0); PG8_STAGE(PG8_SA(0, 1), a2 + hstepA, voffA);
;             PG8_WAIT_V(8); PG8_WAIT_L(0); PG8_BAR; PG8_MMA(0, 0, At, B0); PG8_MMA(0, 1, At, B1); PG8_BAR; PG8_SCHED;
;             PG8_LDA(At, 1, 1); PG8_STAGE(PG8_SB(1, 0), b3, voffB); PG8_STAGE(PG8_SB(1, 1), b3 + hstepB, voffB); PG8_STAGE(PG8_SA(1, 0), a3, voffA);
;             PG8_WAIT_V(8); PG8_WAIT_L(0); PG8_BAR; PG8_MMA(1, 0, At, B0); PG8_MMA(1, 1, At, B1); PG8_BAR; PG8_SCHED;
;         }
	ds_read_b128 v[130:133], v186
	ds_read_b128 v[134:137], v186 offset:1024
	ds_read_b128 v[138:141], v186 offset:2048
	ds_read_b128 v[142:145], v186 offset:3072
	ds_read_b128 v[146:149], v187
	ds_read_b128 v[150:153], v187 offset:1024
	ds_read_b128 v[154:157], v187 offset:2048
	ds_read_b128 v[162:165], v187 offset:3072
	ds_read_b128 v[166:169], v185 offset:32768
	ds_read_b128 v[170:173], v185 offset:33792
	ds_read_b128 v[190:193], v185 offset:34816
	ds_read_b128 v[194:197], v185 offset:35840
	ds_read_b128 v[198:201], v185 offset:36864
	ds_read_b128 v[202:205], v185 offset:37888
	ds_read_b128 v[206:209], v185 offset:38912
	ds_read_b128 v[210:213], v185 offset:39936
	s_add_u32 s78, s78, 0x40000
	s_addc_u32 s79, s79, 0
	s_mov_b32 m0, s28
	s_nop 0
	global_load_lds_dwordx4 v176, s[78:79]
	s_mov_b32 m0, s29
	s_nop 0
	global_load_lds_dwordx4 v178, s[78:79]
	s_waitcnt vmcnt(8) lgkmcnt(0)
	s_barrier
	v_mfma_f32_16x16x32_bf16 v[126:129], v[130:133], v[166:169], v[126:129]
	v_mfma_f32_16x16x32_bf16 v[122:125], v[138:141], v[166:169], v[122:125]
	v_mfma_f32_16x16x32_bf16 v[110:113], v[130:133], v[190:193], v[110:113]
	v_mfma_f32_16x16x32_bf16 v[106:109], v[138:141], v[190:193], v[106:109]
	v_mfma_f32_16x16x32_bf16 v[94:97], v[130:133], v[198:201], v[94:97]
	v_mfma_f32_16x16x32_bf16 v[90:93], v[138:141], v[198:201], v[90:93]
	v_mfma_f32_16x16x32_bf16 v[78:81], v[130:133], v[206:209], v[78:81]
	v_mfma_f32_16x16x32_bf16 v[74:77], v[138:141], v[206:209], v[74:77]
	v_mfma_f32_16x16x32_bf16 v[126:129], v[134:137], v[170:173], v[126:129]
	v_mfma_f32_16x16x32_bf16 v[122:125], v[142:145], v[170:173], v[122:125]
	v_mfma_f32_16x16x32_bf16 v[110:113], v[134:137], v[194:197], v[110:113]
	v_mfma_f32_16x16x32_bf16 v[106:109], v[142:145], v[194:197], v[106:109]
	v_mfma_f32_16x16x32_bf16 v[94:97], v[134:137], v[202:205], v[94:97]
	v_mfma_f32_16x16x32_bf16 v[90:93], v[142:145], v[202:205], v[90:93]
	v_mfma_f32_16x16x32_bf16 v[78:81], v[134:137], v[210:213], v[78:81]
	v_mfma_f32_16x16x32_bf16 v[74:77], v[142:145], v[210:213], v[74:77]
	v_mfma_f32_16x16x32_bf16 v[118:121], v[146:149], v[166:169], v[118:121]
	v_mfma_f32_16x16x32_bf16 v[114:117], v[154:157], v[166:169], v[114:117]
	v_mfma_f32_16x16x32_bf16 v[102:105], v[146:149], v[190:193], v[102:105]
	v_mfma_f32_16x16x32_bf16 v[98:101], v[154:157], v[190:193], v[98:101]
	v_mfma_f32_16x16x32_bf16 v[86:89], v[146:149], v[198:201], v[86:89]
	v_mfma_f32_16x16x32_bf16 v[82:85], v[154:157], v[198:201], v[82:85]
	v_mfma_f32_16x16x32_bf16 v[70:73], v[146:149], v[206:209], v[70:73]
	v_mfma_f32_16x16x32_bf16 v[66:69], v[154:157], v[206:209], v[66:69]
	v_mfma_f32_16x16x32_bf16 v[118:121], v[150:153], v[170:173], v[118:121]
	v_mfma_f32_16x16x32_bf16 v[114:117], v[162:165], v[170:173], v[114:117]
	v_mfma_f32_16x16x32_bf16 v[102:105], v[150:153], v[194:197], v[102:105]
	v_mfma_f32_16x16x32_bf16 v[98:101], v[162:165], v[194:197], v[98:101]
	v_mfma_f32_16x16x32_bf16 v[86:89], v[150:153], v[202:205], v[86:89]
	v_mfma_f32_16x16x32_bf16 v[82:85], v[162:165], v[202:205], v[82:85]
	v_mfma_f32_16x16x32_bf16 v[70:73], v[150:153], v[210:213], v[70:73]
	v_mfma_f32_16x16x32_bf16 v[66:69], v[162:165], v[210:213], v[66:69]
	s_barrier
	ds_read_b128 v[166:169], v185 offset:49152
	ds_read_b128 v[170:173], v185 offset:50176
	ds_read_b128 v[190:193], v185 offset:51200
	ds_read_b128 v[194:197], v185 offset:52224
	ds_read_b128 v[198:201], v185 offset:53248
	ds_read_b128 v[202:205], v185 offset:54272
	ds_read_b128 v[206:209], v185 offset:55296
	ds_read_b128 v[210:213], v185 offset:56320
	s_add_u32 s78, s76, 0x80
	s_addc_u32 s79, s77, 0
	s_mov_b32 m0, s33
	s_nop 0
	global_load_lds_dwordx4 v177, s[78:79]
	s_add_u32 s76, s76, 0x40080
	s_mov_b32 m0, s35
	s_nop 0
	global_load_lds_dwordx4 v179, s[78:79]
	s_addc_u32 s77, s77, 0
	s_mov_b32 m0, s80
	s_nop 0
	global_load_lds_dwordx4 v177, s[76:77]
	s_mov_b32 m0, s81
	s_nop 0
	global_load_lds_dwordx4 v179, s[76:77]
	s_mov_b32 m0, s71
	s_nop 0
	global_load_lds_dwordx4 v176, s[74:75]
	s_mov_b32 m0, s73
	s_nop 0
	global_load_lds_dwordx4 v178, s[74:75]
	s_waitcnt vmcnt(8) lgkmcnt(0)
	s_barrier
	v_mfma_f32_16x16x32_bf16 v[62:65], v[130:133], v[166:169], v[62:65]
	v_mfma_f32_16x16x32_bf16 v[58:61], v[138:141], v[166:169], v[58:61]
	v_mfma_f32_16x16x32_bf16 v[46:49], v[130:133], v[190:193], v[46:49]
	v_mfma_f32_16x16x32_bf16 v[42:45], v[138:141], v[190:193], v[42:45]
	v_mfma_f32_16x16x32_bf16 v[30:33], v[130:133], v[198:201], v[30:33]
	v_mfma_f32_16x16x32_bf16 v[26:29], v[138:141], v[198:201], v[26:29]
	v_mfma_f32_16x16x32_bf16 v[14:17], v[130:133], v[206:209], v[14:17]
	v_mfma_f32_16x16x32_bf16 v[10:13], v[138:141], v[206:209], v[10:13]
	v_mfma_f32_16x16x32_bf16 v[62:65], v[134:137], v[170:173], v[62:65]
	v_mfma_f32_16x16x32_bf16 v[58:61], v[142:145], v[170:173], v[58:61]
	v_mfma_f32_16x16x32_bf16 v[46:49], v[134:137], v[194:197], v[46:49]
	v_mfma_f32_16x16x32_bf16 v[42:45], v[142:145], v[194:197], v[42:45]
	v_mfma_f32_16x16x32_bf16 v[30:33], v[134:137], v[202:205], v[30:33]
	v_mfma_f32_16x16x32_bf16 v[26:29], v[142:145], v[202:205], v[26:29]
	v_mfma_f32_16x16x32_bf16 v[14:17], v[134:137], v[210:213], v[14:17]
	v_mfma_f32_16x16x32_bf16 v[10:13], v[142:145], v[210:213], v[10:13]
	v_mfma_f32_16x16x32_bf16 v[54:57], v[146:149], v[166:169], v[54:57]
	v_mfma_f32_16x16x32_bf16 v[50:53], v[154:157], v[166:169], v[50:53]
	v_mfma_f32_16x16x32_bf16 v[38:41], v[146:149], v[190:193], v[38:41]
	v_mfma_f32_16x16x32_bf16 v[34:37], v[154:157], v[190:193], v[34:37]
	v_mfma_f32_16x16x32_bf16 v[22:25], v[146:149], v[198:201], v[22:25]
	v_mfma_f32_16x16x32_bf16 v[18:21], v[154:157], v[198:201], v[18:21]
	v_mfma_f32_16x16x32_bf16 v[6:9], v[146:149], v[206:209], v[6:9]
	v_mfma_f32_16x16x32_bf16 v[2:5], v[154:157], v[206:209], v[2:5]
	v_mfma_f32_16x16x32_bf16 v[54:57], v[150:153], v[170:173], v[54:57]
	v_mfma_f32_16x16x32_bf16 v[50:53], v[162:165], v[170:173], v[50:53]
	v_mfma_f32_16x16x32_bf16 v[38:41], v[150:153], v[194:197], v[38:41]
	v_mfma_f32_16x16x32_bf16 v[34:37], v[162:165], v[194:197], v[34:37]
	v_mfma_f32_16x16x32_bf16 v[22:25], v[150:153], v[202:205], v[22:25]
	v_mfma_f32_16x16x32_bf16 v[18:21], v[162:165], v[202:205], v[18:21]
	v_mfma_f32_16x16x32_bf16 v[6:9], v[150:153], v[210:213], v[6:9]
	v_mfma_f32_16x16x32_bf16 v[2:5], v[162:165], v[210:213], v[2:5]
	s_barrier
	s_add_i32 s86, s86, 2
	s_add_u32 s63, s63, 0x100
	s_addc_u32 s65, s65, 0
	s_add_u32 s84, s84, 0x100
	s_addc_u32 s85, s85, 0
	s_add_u32 s12, s12, 0x100
	s_addc_u32 s13, s13, 0
	s_cmp_gt_u32 s86, 13
	s_cbranch_scc0 .LBB0_1002

; #define PG8_STAGE(bufoff, gbase, voff) do { if constexpr (VAR != 1 && VAR != 3) { _Pragma("unroll") for (int _i = 0; _i < 2; ++_i) \
;         asm volatile("s_mov_b32 m0, %2\n\ts_nop 0\n\tglobal_load_lds_dwordx4 %0, %1" :: "v"((voff)[_i]), "s"((const char*)(gbase)), "s"(ldsbase + (unsigned)((bufoff) + _i * 8192)) : "memory", "m0"); } } while (0)
; #define PG8_LDA(dst, b, h) do { if constexpr (VAR < 2) _Pragma("unroll") for (int m = 0; m < 4; ++m) _Pragma("unroll") for (int k = 0; k < 2; ++k) dst[m][k] = *(const LAS bf16x8*)(lds + PG8_SA(b, h) + aoff + m * 2048 + k * 1024); } while (0)
; #define PG8_LDB(dst, b, h) do { if constexpr (VAR < 2) _Pragma("unroll") for (int n = 0; n < 2; ++n) _Pragma("unroll") for (int k = 0; k < 2; ++k) dst[n][k] = *(const LAS bf16x8*)(lds + PG8_SB(b, h) + boff + n * 2048 + k * 1024); } while (0)
; #define PG8_WAIT_V(n) asm volatile("s_waitcnt vmcnt(" #n ")" ::: "memory")
; #define PG8_WAIT_L(n) asm volatile("s_waitcnt lgkmcnt(" #n ")" ::: "memory")
; #define PG8_BAR do { if constexpr (VAR != 3) __builtin_amdgcn_s_barrier(); } while (0)
; #define PG8_SCHED __builtin_amdgcn_sched_barrier(0)
;     ...
;             PG8_LDB(B0, 0, 0); PG8_LDB(B1, 0, 1); PG8_SCHED; PG8_LDA(At, 0, 0); PG8_STAGE(PG8_SA(1, 1), a1 + hstepA, voffA);
;             PG8_WAIT_V(8); PG8_WAIT_L(0); PG8_BAR; PG8_MMA(0, 0, At, B0); PG8_MMA(0, 1, At, B1); PG8_BAR; PG8_SCHED;
;             PG8_LDA(At, 0, 1); PG8_STAGE(PG8_SB(0, 0), b2, voffB); PG8_STAGE(PG8_SB(0, 1), b2 + hstepB, voffB); PG8_STAGE(PG8_SA(0, 0), a2, voffA);
;             PG8_WAIT_V(8); PG8_WAIT_L(0); PG8_BAR; PG8_MMA(1, 0, At, B0); PG8_MMA(1, 1, At, B1); PG8_BAR; PG8_SCHED;
.LBB0_1190:
	s_ashr_i32 s69, s68, 31
	s_lshl_b64 s[0:1], s[68:69], 20
	v_readlane_b32 s24, v244, 49
	v_readlane_b32 s25, v244, 50
	s_add_u32 s74, s24, s0
	s_addc_u32 s75, s25, s1
	s_and_b64 s[0:1], s[8:9], exec
	s_cselect_b32 s11, s75, s79
	s_cselect_b32 s24, s74, s78
	s_add_u32 s25, s80, 0x100
	s_addc_u32 s26, s81, 0
	s_add_u32 s27, s78, 0x100
	s_addc_u32 s69, s79, 0
	s_add_u32 s0, s80, 0x80080
	s_waitcnt vmcnt(38)
	s_addc_u32 s1, s81, 0
	s_mov_b32 s71, -2
	s_waitcnt vmcnt(36)
	s_waitcnt vmcnt(34)
	s_waitcnt vmcnt(33)
	s_waitcnt vmcnt(32)
	ds_read_b128 v[2:5], v231
	ds_read_b128 v[6:9], v231 offset:1024
	ds_read_b128 v[10:13], v231 offset:2048
	ds_read_b128 v[14:17], v231 offset:3072
	ds_read_b128 v[18:21], v232
	ds_read_b128 v[26:29], v232 offset:1024
	ds_read_b128 v[154:157], v232 offset:2048
	ds_read_b128 v[158:161], v232 offset:3072
	s_cmp_eq_u32 s71, 28
	s_cselect_b32 s82, s72, s25
	s_cselect_b32 s83, s73, s26
	s_cselect_b32 s80, s24, s27
	s_cselect_b32 s81, s11, s69
	s_add_u32 s78, s82, 0x80
	s_addc_u32 s79, s83, 0
	ds_read_b128 v[162:165], v233
	ds_read_b128 v[166:169], v233 offset:1024
	ds_read_b128 v[178:181], v233 offset:2048
	ds_read_b128 v[182:185], v233 offset:3072
	ds_read_b128 v[186:189], v233 offset:4096
	ds_read_b128 v[190:193], v233 offset:5120
	ds_read_b128 v[194:197], v233 offset:6144
	ds_read_b128 v[198:201], v233 offset:7168
	s_mov_b32 m0, s90
	s_nop 0
	global_load_lds_dwordx4 v208, s[0:1]
	s_mov_b32 m0, s91
	s_nop 0
	global_load_lds_dwordx4 v210, s[0:1]
	s_waitcnt vmcnt(8) lgkmcnt(0)
	s_barrier
	v_mfma_i32_16x16x64_i8 v[150:153], v[2:5], v[162:165], 0
	v_mfma_i32_16x16x64_i8 v[142:145], v[10:13], v[162:165], 0
	v_mfma_i32_16x16x64_i8 v[126:129], v[2:5], v[178:181], 0
	v_mfma_i32_16x16x64_i8 v[122:125], v[10:13], v[178:181], 0
	v_mfma_i32_16x16x64_i8 v[114:117], v[2:5], v[186:189], 0
	v_mfma_i32_16x16x64_i8 v[106:109], v[10:13], v[186:189], 0
	v_mfma_i32_16x16x64_i8 v[146:149], v[2:5], v[194:197], 0
	v_mfma_i32_16x16x64_i8 v[138:141], v[10:13], v[194:197], 0
	v_mfma_i32_16x16x64_i8 v[150:153], v[6:9], v[166:169], v[150:153]
	v_mfma_i32_16x16x64_i8 v[142:145], v[14:17], v[166:169], v[142:145]
	v_mfma_i32_16x16x64_i8 v[126:129], v[6:9], v[182:185], v[126:129]
	v_mfma_i32_16x16x64_i8 v[122:125], v[14:17], v[182:185], v[122:125]
	v_mfma_i32_16x16x64_i8 v[114:117], v[6:9], v[190:193], v[114:117]
	v_mfma_i32_16x16x64_i8 v[106:109], v[14:17], v[190:193], v[106:109]
	v_mfma_i32_16x16x64_i8 v[146:149], v[6:9], v[198:201], v[146:149]
	v_mfma_i32_16x16x64_i8 v[138:141], v[14:17], v[198:201], v[138:141]
	v_mfma_i32_16x16x64_i8 v[134:137], v[18:21], v[162:165], 0
	v_mfma_i32_16x16x64_i8 v[130:133], v[154:157], v[162:165], 0
	v_mfma_i32_16x16x64_i8 v[118:121], v[18:21], v[178:181], 0
	v_mfma_i32_16x16x64_i8 v[110:113], v[154:157], v[178:181], 0
	v_mfma_i32_16x16x64_i8 v[102:105], v[18:21], v[186:189], 0
	v_mfma_i32_16x16x64_i8 v[98:101], v[154:157], v[186:189], 0
	v_mfma_i32_16x16x64_i8 v[94:97], v[18:21], v[194:197], 0
	v_mfma_i32_16x16x64_i8 v[90:93], v[154:157], v[194:197], 0
	v_mfma_i32_16x16x64_i8 v[134:137], v[26:29], v[166:169], v[134:137]
	v_mfma_i32_16x16x64_i8 v[130:133], v[158:161], v[166:169], v[130:133]
	v_mfma_i32_16x16x64_i8 v[118:121], v[26:29], v[182:185], v[118:121]
	v_mfma_i32_16x16x64_i8 v[110:113], v[158:161], v[182:185], v[110:113]
	v_mfma_i32_16x16x64_i8 v[102:105], v[26:29], v[190:193], v[102:105]
	v_mfma_i32_16x16x64_i8 v[98:101], v[158:161], v[190:193], v[98:101]
	v_mfma_i32_16x16x64_i8 v[94:97], v[26:29], v[198:201], v[94:97]
	v_mfma_i32_16x16x64_i8 v[90:93], v[158:161], v[198:201], v[90:93]
	s_barrier
	ds_read_b128 v[162:165], v233 offset:16384
	ds_read_b128 v[166:169], v233 offset:17408
	ds_read_b128 v[178:181], v233 offset:18432
	ds_read_b128 v[182:185], v233 offset:19456
	ds_read_b128 v[186:189], v233 offset:20480
	ds_read_b128 v[190:193], v233 offset:21504
	ds_read_b128 v[194:197], v233 offset:22528
	ds_read_b128 v[198:201], v233 offset:23552
	s_mov_b32 m0, s21
	s_nop 0
	global_load_lds_dwordx4 v209, s[80:81]
	s_add_u32 s96, s80, 0x80000
	s_mov_b32 m0, s23
	s_nop 0
	global_load_lds_dwordx4 v211, s[80:81]
	s_addc_u32 s97, s81, 0
	s_mov_b32 m0, s28
	s_nop 0
	global_load_lds_dwordx4 v209, s[96:97]
	s_mov_b32 m0, s29
	s_nop 0
	global_load_lds_dwordx4 v211, s[96:97]
	s_mov_b32 m0, s15
	s_nop 0
	global_load_lds_dwordx4 v208, s[82:83]
	s_mov_b32 m0, s30
	s_nop 0
	global_load_lds_dwordx4 v210, s[82:83]
	s_waitcnt vmcnt(8) lgkmcnt(0)
	s_barrier
	v_mfma_i32_16x16x64_i8 v[86:89], v[2:5], v[162:165], 0
	v_mfma_i32_16x16x64_i8 v[82:85], v[10:13], v[162:165], 0
	v_mfma_i32_16x16x64_i8 v[74:77], v[2:5], v[178:181], 0
	v_mfma_i32_16x16x64_i8 v[66:69], v[10:13], v[178:181], 0
	v_mfma_i32_16x16x64_i8 v[58:61], v[2:5], v[186:189], 0
	v_mfma_i32_16x16x64_i8 v[50:53], v[10:13], v[186:189], 0
	v_mfma_i32_16x16x64_i8 v[2:5], v[2:5], v[194:197], 0
	v_mfma_i32_16x16x64_i8 v[86:89], v[6:9], v[166:169], v[86:89]
	v_mfma_i32_16x16x64_i8 v[82:85], v[14:17], v[166:169], v[82:85]
	v_mfma_i32_16x16x64_i8 v[74:77], v[6:9], v[182:185], v[74:77]
	v_mfma_i32_16x16x64_i8 v[66:69], v[14:17], v[182:185], v[66:69]
	v_mfma_i32_16x16x64_i8 v[58:61], v[6:9], v[190:193], v[58:61]
	v_mfma_i32_16x16x64_i8 v[50:53], v[14:17], v[190:193], v[50:53]
	v_mfma_i32_16x16x64_i8 v[2:5], v[6:9], v[198:201], v[2:5]
	v_mfma_i32_16x16x64_i8 v[6:9], v[10:13], v[194:197], 0
	v_mfma_i32_16x16x64_i8 v[6:9], v[14:17], v[198:201], v[6:9]
	v_mfma_i32_16x16x64_i8 v[22:25], v[18:21], v[178:181], 0
	v_mfma_i32_16x16x64_i8 v[62:65], v[26:29], v[182:185], v[22:25]
	v_mfma_i32_16x16x64_i8 v[22:25], v[154:157], v[178:181], 0
	v_mfma_i32_16x16x64_i8 v[54:57], v[158:161], v[182:185], v[22:25]
	v_mfma_i32_16x16x64_i8 v[22:25], v[18:21], v[186:189], 0
	v_mfma_i32_16x16x64_i8 v[46:49], v[26:29], v[190:193], v[22:25]
	v_mfma_i32_16x16x64_i8 v[22:25], v[154:157], v[186:189], 0
	v_mfma_i32_16x16x64_i8 v[10:13], v[18:21], v[162:165], 0
	v_mfma_i32_16x16x64_i8 v[14:17], v[154:157], v[162:165], 0
	v_mfma_i32_16x16x64_i8 v[42:45], v[158:161], v[190:193], v[22:25]
	v_mfma_i32_16x16x64_i8 v[18:21], v[18:21], v[194:197], 0
	v_mfma_i32_16x16x64_i8 v[22:25], v[154:157], v[194:197], 0
	v_mfma_i32_16x16x64_i8 v[10:13], v[26:29], v[166:169], v[10:13]
	v_mfma_i32_16x16x64_i8 v[14:17], v[158:161], v[166:169], v[14:17]
	v_mfma_i32_16x16x64_i8 v[18:21], v[26:29], v[198:201], v[18:21]
	v_mfma_i32_16x16x64_i8 v[26:29], v[158:161], v[198:201], v[22:25]
	s_barrier
; #define PG8_STAGE(bufoff, gbase, voff) do { if constexpr (VAR != 1 && VAR != 3) { _Pragma("unroll") for (int _i = 0; _i < 2; ++_i) \
;         asm volatile("s_mov_b32 m0, %2\n\ts_nop 0\n\tglobal_load_lds_dwordx4 %0, %1" :: "v"((voff)[_i]), "s"((const char*)(gbase)), "s"(ldsbase + (unsigned)((bufoff) + _i * 8192)) : "memory", "m0"); } } while (0)
; #define PG8_LDA(dst, b, h) do { if constexpr (VAR < 2) _Pragma("unroll") for (int m = 0; m < 4; ++m) _Pragma("unroll") for (int k = 0; k < 2; ++k) dst[m][k] = *(const LAS bf16x8*)(lds + PG8_SA(b, h) + aoff + m * 2048 + k * 1024); } while (0)
; #define PG8_LDB(dst, b, h) do { if constexpr (VAR < 2) _Pragma("unroll") for (int n = 0; n < 2; ++n) _Pragma("unroll") for (int k = 0; k < 2; ++k) dst[n][k] = *(const LAS bf16x8*)(lds + PG8_SB(b, h) + boff + n * 2048 + k * 1024); } while (0)
; #define PG8_WAIT_V(n) asm volatile("s_waitcnt vmcnt(" #n ")" ::: "memory")
; #define PG8_WAIT_L(n) asm volatile("s_waitcnt lgkmcnt(" #n ")" ::: "memory")
; #define PG8_BAR do { if constexpr (VAR != 3) __builtin_amdgcn_s_barrier(); } while (0)
; #define PG8_SCHED __builtin_amdgcn_sched_barrier(0)
;     ...
;             PG8_LDB(B0, 1, 0); PG8_LDB(B1, 1, 1); PG8_SCHED; PG8_LDA(At, 1, 0); PG8_STAGE(PG8_SA(0, 1), a2 + hstepA, voffA);
;             PG8_WAIT_V(8); PG8_WAIT_L(0); PG8_BAR; PG8_MMA(0, 0, At, B0); PG8_MMA(0, 1, At, B1); PG8_BAR; PG8_SCHED;
;             PG8_LDA(At, 1, 1); PG8_STAGE(PG8_SB(1, 0), b3, voffB); PG8_STAGE(PG8_SB(1, 1), b3 + hstepB, voffB); PG8_STAGE(PG8_SA(1, 0), a3, voffA);
;             PG8_WAIT_V(8); PG8_WAIT_L(0); PG8_BAR; PG8_MMA(1, 0, At, B0); PG8_MMA(1, 1, At, B1); PG8_BAR; PG8_SCHED;
;         }
	s_nop 1
	ds_read_b128 v[22:25], v234
	ds_read_b128 v[30:33], v234 offset:1024
	ds_read_b128 v[34:37], v234 offset:2048
	ds_read_b128 v[38:41], v234 offset:3072
	ds_read_b128 v[154:157], v235
	ds_read_b128 v[158:161], v235 offset:1024
	ds_read_b128 v[162:165], v235 offset:2048
	ds_read_b128 v[166:169], v235 offset:3072
	ds_read_b128 v[70:73], v233 offset:32768
	ds_read_b128 v[78:81], v233 offset:33792
	ds_read_b128 v[178:181], v233 offset:34816
	ds_read_b128 v[182:185], v233 offset:35840
	ds_read_b128 v[186:189], v233 offset:36864
	ds_read_b128 v[190:193], v233 offset:37888
	ds_read_b128 v[194:197], v233 offset:38912
	ds_read_b128 v[198:201], v233 offset:39936
	s_add_u32 s82, s82, 0x80000
	s_addc_u32 s83, s83, 0
	s_mov_b32 m0, s31
	s_nop 0
	global_load_lds_dwordx4 v208, s[82:83]
	s_mov_b32 m0, s33
	s_nop 0
	global_load_lds_dwordx4 v210, s[82:83]
	s_waitcnt vmcnt(8) lgkmcnt(0)
	s_barrier
	v_mfma_i32_16x16x64_i8 v[150:153], v[22:25], v[70:73], v[150:153]
	v_mfma_i32_16x16x64_i8 v[142:145], v[34:37], v[70:73], v[142:145]
	v_mfma_i32_16x16x64_i8 v[126:129], v[22:25], v[178:181], v[126:129]
	v_mfma_i32_16x16x64_i8 v[122:125], v[34:37], v[178:181], v[122:125]
	v_mfma_i32_16x16x64_i8 v[114:117], v[22:25], v[186:189], v[114:117]
	v_mfma_i32_16x16x64_i8 v[106:109], v[34:37], v[186:189], v[106:109]
	v_mfma_i32_16x16x64_i8 v[146:149], v[22:25], v[194:197], v[146:149]
	v_mfma_i32_16x16x64_i8 v[138:141], v[34:37], v[194:197], v[138:141]
	v_mfma_i32_16x16x64_i8 v[150:153], v[30:33], v[78:81], v[150:153]
	v_mfma_i32_16x16x64_i8 v[142:145], v[38:41], v[78:81], v[142:145]
	v_mfma_i32_16x16x64_i8 v[126:129], v[30:33], v[182:185], v[126:129]
	v_mfma_i32_16x16x64_i8 v[122:125], v[38:41], v[182:185], v[122:125]
	v_mfma_i32_16x16x64_i8 v[114:117], v[30:33], v[190:193], v[114:117]
	v_mfma_i32_16x16x64_i8 v[106:109], v[38:41], v[190:193], v[106:109]
	v_mfma_i32_16x16x64_i8 v[146:149], v[30:33], v[198:201], v[146:149]
	v_mfma_i32_16x16x64_i8 v[138:141], v[38:41], v[198:201], v[138:141]
	v_mfma_i32_16x16x64_i8 v[134:137], v[154:157], v[70:73], v[134:137]
	v_mfma_i32_16x16x64_i8 v[70:73], v[162:165], v[70:73], v[130:133]
	v_mfma_i32_16x16x64_i8 v[130:133], v[166:169], v[78:81], v[70:73]
	v_mfma_i32_16x16x64_i8 v[70:73], v[154:157], v[178:181], v[118:121]
	v_mfma_i32_16x16x64_i8 v[118:121], v[158:161], v[182:185], v[70:73]
	v_mfma_i32_16x16x64_i8 v[70:73], v[162:165], v[178:181], v[110:113]
	v_mfma_i32_16x16x64_i8 v[110:113], v[166:169], v[182:185], v[70:73]
	v_mfma_i32_16x16x64_i8 v[70:73], v[154:157], v[186:189], v[102:105]
	v_mfma_i32_16x16x64_i8 v[102:105], v[158:161], v[190:193], v[70:73]
	v_mfma_i32_16x16x64_i8 v[70:73], v[162:165], v[186:189], v[98:101]
	v_mfma_i32_16x16x64_i8 v[98:101], v[166:169], v[190:193], v[70:73]
	v_mfma_i32_16x16x64_i8 v[70:73], v[154:157], v[194:197], v[94:97]
	v_mfma_i32_16x16x64_i8 v[94:97], v[158:161], v[198:201], v[70:73]
	v_mfma_i32_16x16x64_i8 v[70:73], v[162:165], v[194:197], v[90:93]
	v_mfma_i32_16x16x64_i8 v[134:137], v[158:161], v[78:81], v[134:137]
	v_mfma_i32_16x16x64_i8 v[90:93], v[166:169], v[198:201], v[70:73]
	s_barrier
	s_nop 3
	ds_read_b128 v[70:73], v233 offset:49152
	ds_read_b128 v[178:181], v233 offset:50176
	ds_read_b128 v[182:185], v233 offset:51200
	ds_read_b128 v[186:189], v233 offset:52224
	ds_read_b128 v[190:193], v233 offset:53248
	ds_read_b128 v[194:197], v233 offset:54272
	ds_read_b128 v[198:201], v233 offset:55296
	ds_read_b128 v[202:205], v233 offset:56320
	s_add_u32 s82, s80, 0x80
	s_addc_u32 s83, s81, 0
	s_mov_b32 m0, s84
	s_nop 0
	global_load_lds_dwordx4 v209, s[82:83]
	s_add_u32 s80, s80, 0x80080
	s_mov_b32 m0, s85
	s_nop 0
	global_load_lds_dwordx4 v211, s[82:83]
	s_addc_u32 s81, s81, 0
	s_mov_b32 m0, s88
	s_nop 0
	global_load_lds_dwordx4 v209, s[80:81]
	s_mov_b32 m0, s89
	s_nop 0
	global_load_lds_dwordx4 v211, s[80:81]
	s_mov_b32 m0, s86
	s_nop 0
	global_load_lds_dwordx4 v208, s[78:79]
	s_mov_b32 m0, s87
	s_nop 0
	global_load_lds_dwordx4 v210, s[78:79]
	s_waitcnt vmcnt(8) lgkmcnt(0)
	s_barrier
	v_mfma_i32_16x16x64_i8 v[78:81], v[22:25], v[70:73], v[86:89]
	v_mfma_i32_16x16x64_i8 v[74:77], v[22:25], v[182:185], v[74:77]
	v_mfma_i32_16x16x64_i8 v[58:61], v[22:25], v[190:193], v[58:61]
	v_mfma_i32_16x16x64_i8 v[2:5], v[22:25], v[198:201], v[2:5]
	v_mfma_i32_16x16x64_i8 v[86:89], v[30:33], v[178:181], v[78:81]
	v_mfma_i32_16x16x64_i8 v[78:81], v[34:37], v[70:73], v[82:85]
	v_mfma_i32_16x16x64_i8 v[74:77], v[30:33], v[186:189], v[74:77]
	v_mfma_i32_16x16x64_i8 v[66:69], v[34:37], v[182:185], v[66:69]
	v_mfma_i32_16x16x64_i8 v[58:61], v[30:33], v[194:197], v[58:61]
	v_mfma_i32_16x16x64_i8 v[50:53], v[34:37], v[190:193], v[50:53]
	v_mfma_i32_16x16x64_i8 v[30:33], v[30:33], v[202:205], v[2:5]
	v_mfma_i32_16x16x64_i8 v[2:5], v[34:37], v[198:201], v[6:9]
	v_mfma_i32_16x16x64_i8 v[82:85], v[38:41], v[178:181], v[78:81]
	v_mfma_i32_16x16x64_i8 v[66:69], v[38:41], v[186:189], v[66:69]
	v_mfma_i32_16x16x64_i8 v[50:53], v[38:41], v[194:197], v[50:53]
	v_mfma_i32_16x16x64_i8 v[22:25], v[38:41], v[202:205], v[2:5]
	v_mfma_i32_16x16x64_i8 v[2:5], v[154:157], v[70:73], v[10:13]
	v_mfma_i32_16x16x64_i8 v[78:81], v[158:161], v[178:181], v[2:5]
	v_mfma_i32_16x16x64_i8 v[2:5], v[162:165], v[70:73], v[14:17]
	v_mfma_i32_16x16x64_i8 v[70:73], v[166:169], v[178:181], v[2:5]
	v_mfma_i32_16x16x64_i8 v[2:5], v[154:157], v[182:185], v[62:65]
	v_mfma_i32_16x16x64_i8 v[62:65], v[158:161], v[186:189], v[2:5]
	v_mfma_i32_16x16x64_i8 v[2:5], v[162:165], v[182:185], v[54:57]
	v_mfma_i32_16x16x64_i8 v[54:57], v[166:169], v[186:189], v[2:5]
	v_mfma_i32_16x16x64_i8 v[2:5], v[154:157], v[190:193], v[46:49]
	v_mfma_i32_16x16x64_i8 v[46:49], v[158:161], v[194:197], v[2:5]
	v_mfma_i32_16x16x64_i8 v[2:5], v[162:165], v[190:193], v[42:45]
	v_mfma_i32_16x16x64_i8 v[42:45], v[166:169], v[194:197], v[2:5]
	v_mfma_i32_16x16x64_i8 v[2:5], v[154:157], v[198:201], v[18:21]
	v_mfma_i32_16x16x64_i8 v[38:41], v[158:161], v[202:205], v[2:5]
	v_mfma_i32_16x16x64_i8 v[2:5], v[162:165], v[198:201], v[26:29]
	v_mfma_i32_16x16x64_i8 v[34:37], v[166:169], v[202:205], v[2:5]
	s_barrier
	s_add_i32 s71, s71, 2
	s_add_u32 s25, s25, 0x100
	s_addc_u32 s26, s26, 0
	s_add_u32 s27, s27, 0x100
	s_addc_u32 s69, s69, 0
	s_add_u32 s0, s0, 0x100
	s_addc_u32 s1, s1, 0
	s_cmp_gt_u32 s71, 29
	s_cbranch_scc0 .LBB0_1191
	s_branch .Lmy_kexit_8
; #define PG8_STAGE(bufoff, gbase, voff) do { if constexpr (VAR != 1 && VAR != 3) { _Pragma("unroll") for (int _i = 0; _i < 2; ++_i) \
;         asm volatile("s_mov_b32 m0, %2\n\ts_nop 0\n\tglobal_load_lds_dwordx4 %0, %1" :: "v"((voff)[_i]), "s"((const char*)(gbase)), "s"(ldsbase + (unsigned)((bufoff) + _i * 8192)) : "memory", "m0"); } } while (0)
; #define PG8_LDA(dst, b, h) do { if constexpr (VAR < 2) _Pragma("unroll") for (int m = 0; m < 4; ++m) _Pragma("unroll") for (int k = 0; k < 2; ++k) dst[m][k] = *(const LAS bf16x8*)(lds + PG8_SA(b, h) + aoff + m * 2048 + k * 1024); } while (0)
; #define PG8_LDB(dst, b, h) do { if constexpr (VAR < 2) _Pragma("unroll") for (int n = 0; n < 2; ++n) _Pragma("unroll") for (int k = 0; k < 2; ++k) dst[n][k] = *(const LAS bf16x8*)(lds + PG8_SB(b, h) + boff + n * 2048 + k * 1024); } while (0)
; #define PG8_WAIT_V(n) asm volatile("s_waitcnt vmcnt(" #n ")" ::: "memory")
; #define PG8_WAIT_L(n) asm volatile("s_waitcnt lgkmcnt(" #n ")" ::: "memory")
; #define PG8_BAR do { if constexpr (VAR != 3) __builtin_amdgcn_s_barrier(); } while (0)
; #define PG8_SCHED __builtin_amdgcn_sched_barrier(0)
;     ...
;         for (int t = 0; t < nt; t += 2) {
;             const bool last = (t == nt - 2);
;             const char* a1 = cA + (size_t)(t + 1) * kstep;
;             const char* a2 = last ? nA : cA + (size_t)(t + 2) * kstep; const char* b2 = last ? nB : cB + (size_t)(t + 2) * kstep;
;             const char* a3 = a2 + kstep; const char* b3 = b2 + kstep;
;             PG8_LDB(B0, 0, 0); PG8_LDB(B1, 0, 1); PG8_SCHED; PG8_LDA(At, 0, 0); PG8_STAGE(PG8_SA(1, 1), a1 + hstepA, voffA);
;             PG8_WAIT_V(8); PG8_WAIT_L(0); PG8_BAR; PG8_MMA(0, 0, At, B0); PG8_MMA(0, 1, At, B1); PG8_BAR; PG8_SCHED;
;             PG8_LDA(At, 0, 1); PG8_STAGE(PG8_SB(0, 0), b2, voffB); PG8_STAGE(PG8_SB(0, 1), b2 + hstepB, voffB); PG8_STAGE(PG8_SA(0, 0), a2, voffA);
;             PG8_WAIT_V(8); PG8_WAIT_L(0); PG8_BAR; PG8_MMA(1, 0, At, B0); PG8_MMA(1, 1, At, B1); PG8_BAR; PG8_SCHED;
.LBB0_1191:
	ds_read_b128 v[2:5], v231
	ds_read_b128 v[6:9], v231 offset:1024
	ds_read_b128 v[10:13], v231 offset:2048
	ds_read_b128 v[14:17], v231 offset:3072
	ds_read_b128 v[18:21], v232
	ds_read_b128 v[26:29], v232 offset:1024
	ds_read_b128 v[154:157], v232 offset:2048
	ds_read_b128 v[158:161], v232 offset:3072
	s_cmp_eq_u32 s71, 28
	s_cselect_b32 s82, s72, s25
	s_cselect_b32 s83, s73, s26
	s_cselect_b32 s80, s24, s27
	s_cselect_b32 s81, s11, s69
	s_add_u32 s78, s82, 0x80
	s_addc_u32 s79, s83, 0
	ds_read_b128 v[162:165], v233
	ds_read_b128 v[166:169], v233 offset:1024
	ds_read_b128 v[178:181], v233 offset:2048
	ds_read_b128 v[182:185], v233 offset:3072
	ds_read_b128 v[186:189], v233 offset:4096
	ds_read_b128 v[190:193], v233 offset:5120
	ds_read_b128 v[194:197], v233 offset:6144
	ds_read_b128 v[198:201], v233 offset:7168
	s_mov_b32 m0, s90
	s_nop 0
	global_load_lds_dwordx4 v208, s[0:1]
	s_mov_b32 m0, s91
	s_nop 0
	global_load_lds_dwordx4 v210, s[0:1]
	s_waitcnt vmcnt(8) lgkmcnt(0)
	s_barrier
	v_mfma_i32_16x16x64_i8 v[150:153], v[2:5], v[162:165], v[150:153]
	v_mfma_i32_16x16x64_i8 v[142:145], v[10:13], v[162:165], v[142:145]
	v_mfma_i32_16x16x64_i8 v[126:129], v[2:5], v[178:181], v[126:129]
	v_mfma_i32_16x16x64_i8 v[122:125], v[10:13], v[178:181], v[122:125]
	v_mfma_i32_16x16x64_i8 v[114:117], v[2:5], v[186:189], v[114:117]
	v_mfma_i32_16x16x64_i8 v[106:109], v[10:13], v[186:189], v[106:109]
	v_mfma_i32_16x16x64_i8 v[146:149], v[2:5], v[194:197], v[146:149]
	v_mfma_i32_16x16x64_i8 v[138:141], v[10:13], v[194:197], v[138:141]
	v_mfma_i32_16x16x64_i8 v[150:153], v[6:9], v[166:169], v[150:153]
	v_mfma_i32_16x16x64_i8 v[142:145], v[14:17], v[166:169], v[142:145]
	v_mfma_i32_16x16x64_i8 v[126:129], v[6:9], v[182:185], v[126:129]
	v_mfma_i32_16x16x64_i8 v[122:125], v[14:17], v[182:185], v[122:125]
	v_mfma_i32_16x16x64_i8 v[114:117], v[6:9], v[190:193], v[114:117]
	v_mfma_i32_16x16x64_i8 v[106:109], v[14:17], v[190:193], v[106:109]
	v_mfma_i32_16x16x64_i8 v[146:149], v[6:9], v[198:201], v[146:149]
	v_mfma_i32_16x16x64_i8 v[138:141], v[14:17], v[198:201], v[138:141]
	v_mfma_i32_16x16x64_i8 v[134:137], v[18:21], v[162:165], v[134:137]
	v_mfma_i32_16x16x64_i8 v[130:133], v[154:157], v[162:165], v[130:133]
	v_mfma_i32_16x16x64_i8 v[118:121], v[18:21], v[178:181], v[118:121]
	v_mfma_i32_16x16x64_i8 v[110:113], v[154:157], v[178:181], v[110:113]
	v_mfma_i32_16x16x64_i8 v[102:105], v[18:21], v[186:189], v[102:105]
	v_mfma_i32_16x16x64_i8 v[98:101], v[154:157], v[186:189], v[98:101]
	v_mfma_i32_16x16x64_i8 v[94:97], v[18:21], v[194:197], v[94:97]
	v_mfma_i32_16x16x64_i8 v[90:93], v[154:157], v[194:197], v[90:93]
	v_mfma_i32_16x16x64_i8 v[134:137], v[26:29], v[166:169], v[134:137]
	v_mfma_i32_16x16x64_i8 v[130:133], v[158:161], v[166:169], v[130:133]
	v_mfma_i32_16x16x64_i8 v[118:121], v[26:29], v[182:185], v[118:121]
	v_mfma_i32_16x16x64_i8 v[110:113], v[158:161], v[182:185], v[110:113]
	v_mfma_i32_16x16x64_i8 v[102:105], v[26:29], v[190:193], v[102:105]
	v_mfma_i32_16x16x64_i8 v[98:101], v[158:161], v[190:193], v[98:101]
	v_mfma_i32_16x16x64_i8 v[94:97], v[26:29], v[198:201], v[94:97]
	v_mfma_i32_16x16x64_i8 v[90:93], v[158:161], v[198:201], v[90:93]
	s_barrier
	ds_read_b128 v[162:165], v233 offset:16384
	ds_read_b128 v[166:169], v233 offset:17408
	ds_read_b128 v[178:181], v233 offset:18432
	ds_read_b128 v[182:185], v233 offset:19456
	ds_read_b128 v[186:189], v233 offset:20480
	ds_read_b128 v[190:193], v233 offset:21504
	ds_read_b128 v[194:197], v233 offset:22528
	ds_read_b128 v[198:201], v233 offset:23552
	s_mov_b32 m0, s21
	s_nop 0
	global_load_lds_dwordx4 v209, s[80:81]
	s_add_u32 s96, s80, 0x80000
	s_mov_b32 m0, s23
	s_nop 0
	global_load_lds_dwordx4 v211, s[80:81]
	s_addc_u32 s97, s81, 0
	s_mov_b32 m0, s28
	s_nop 0
	global_load_lds_dwordx4 v209, s[96:97]
	s_mov_b32 m0, s29
	s_nop 0
	global_load_lds_dwordx4 v211, s[96:97]
	s_mov_b32 m0, s15
	s_nop 0
	global_load_lds_dwordx4 v208, s[82:83]
	s_mov_b32 m0, s30
	s_nop 0
	global_load_lds_dwordx4 v210, s[82:83]
	s_waitcnt vmcnt(8) lgkmcnt(0)
	s_barrier
	v_mfma_i32_16x16x64_i8 v[86:89], v[2:5], v[162:165], v[86:89]
	v_mfma_i32_16x16x64_i8 v[82:85], v[10:13], v[162:165], v[82:85]
	v_mfma_i32_16x16x64_i8 v[74:77], v[2:5], v[178:181], v[74:77]
	v_mfma_i32_16x16x64_i8 v[66:69], v[10:13], v[178:181], v[66:69]
	v_mfma_i32_16x16x64_i8 v[58:61], v[2:5], v[186:189], v[58:61]
	v_mfma_i32_16x16x64_i8 v[50:53], v[10:13], v[186:189], v[50:53]
	v_mfma_i32_16x16x64_i8 v[2:5], v[2:5], v[194:197], v[30:33]
	v_mfma_i32_16x16x64_i8 v[86:89], v[6:9], v[166:169], v[86:89]
	v_mfma_i32_16x16x64_i8 v[82:85], v[14:17], v[166:169], v[82:85]
	v_mfma_i32_16x16x64_i8 v[74:77], v[6:9], v[182:185], v[74:77]
	v_mfma_i32_16x16x64_i8 v[66:69], v[14:17], v[182:185], v[66:69]
	v_mfma_i32_16x16x64_i8 v[58:61], v[6:9], v[190:193], v[58:61]
	v_mfma_i32_16x16x64_i8 v[50:53], v[14:17], v[190:193], v[50:53]
	v_mfma_i32_16x16x64_i8 v[2:5], v[6:9], v[198:201], v[2:5]
	v_mfma_i32_16x16x64_i8 v[6:9], v[10:13], v[194:197], v[22:25]
	v_mfma_i32_16x16x64_i8 v[6:9], v[14:17], v[198:201], v[6:9]
	v_mfma_i32_16x16x64_i8 v[22:25], v[18:21], v[178:181], v[62:65]
	v_mfma_i32_16x16x64_i8 v[62:65], v[26:29], v[182:185], v[22:25]
	v_mfma_i32_16x16x64_i8 v[22:25], v[154:157], v[178:181], v[54:57]
	v_mfma_i32_16x16x64_i8 v[54:57], v[158:161], v[182:185], v[22:25]
	v_mfma_i32_16x16x64_i8 v[22:25], v[18:21], v[186:189], v[46:49]
	v_mfma_i32_16x16x64_i8 v[46:49], v[26:29], v[190:193], v[22:25]
	v_mfma_i32_16x16x64_i8 v[22:25], v[154:157], v[186:189], v[42:45]
	v_mfma_i32_16x16x64_i8 v[10:13], v[18:21], v[162:165], v[78:81]
	v_mfma_i32_16x16x64_i8 v[14:17], v[154:157], v[162:165], v[70:73]
	v_mfma_i32_16x16x64_i8 v[42:45], v[158:161], v[190:193], v[22:25]
	v_mfma_i32_16x16x64_i8 v[18:21], v[18:21], v[194:197], v[38:41]
	v_mfma_i32_16x16x64_i8 v[22:25], v[154:157], v[194:197], v[34:37]
	v_mfma_i32_16x16x64_i8 v[10:13], v[26:29], v[166:169], v[10:13]
	v_mfma_i32_16x16x64_i8 v[14:17], v[158:161], v[166:169], v[14:17]
	v_mfma_i32_16x16x64_i8 v[18:21], v[26:29], v[198:201], v[18:21]
	v_mfma_i32_16x16x64_i8 v[26:29], v[158:161], v[198:201], v[22:25]
	s_barrier
; #define PG8_STAGE(bufoff, gbase, voff) do { if constexpr (VAR != 1 && VAR != 3) { _Pragma("unroll") for (int _i = 0; _i < 2; ++_i) \
;         asm volatile("s_mov_b32 m0, %2\n\ts_nop 0\n\tglobal_load_lds_dwordx4 %0, %1" :: "v"((voff)[_i]), "s"((const char*)(gbase)), "s"(ldsbase + (unsigned)((bufoff) + _i * 8192)) : "memory", "m0"); } } while (0)
; #define PG8_LDA(dst, b, h) do { if constexpr (VAR < 2) _Pragma("unroll") for (int m = 0; m < 4; ++m) _Pragma("unroll") for (int k = 0; k < 2; ++k) dst[m][k] = *(const LAS bf16x8*)(lds + PG8_SA(b, h) + aoff + m * 2048 + k * 1024); } while (0)
; #define PG8_LDB(dst, b, h) do { if constexpr (VAR < 2) _Pragma("unroll") for (int n = 0; n < 2; ++n) _Pragma("unroll") for (int k = 0; k < 2; ++k) dst[n][k] = *(const LAS bf16x8*)(lds + PG8_SB(b, h) + boff + n * 2048 + k * 1024); } while (0)
; #define PG8_WAIT_V(n) asm volatile("s_waitcnt vmcnt(" #n ")" ::: "memory")
; #define PG8_WAIT_L(n) asm volatile("s_waitcnt lgkmcnt(" #n ")" ::: "memory")
; #define PG8_BAR do { if constexpr (VAR != 3) __builtin_amdgcn_s_barrier(); } while (0)
; #define PG8_SCHED __builtin_amdgcn_sched_barrier(0)
;     ...
;             PG8_LDB(B0, 1, 0); PG8_LDB(B1, 1, 1); PG8_SCHED; PG8_LDA(At, 1, 0); PG8_STAGE(PG8_SA(0, 1), a2 + hstepA, voffA);
;             PG8_WAIT_V(8); PG8_WAIT_L(0); PG8_BAR; PG8_MMA(0, 0, At, B0); PG8_MMA(0, 1, At, B1); PG8_BAR; PG8_SCHED;
;             PG8_LDA(At, 1, 1); PG8_STAGE(PG8_SB(1, 0), b3, voffB); PG8_STAGE(PG8_SB(1, 1), b3 + hstepB, voffB); PG8_STAGE(PG8_SA(1, 0), a3, voffA);
;             PG8_WAIT_V(8); PG8_WAIT_L(0); PG8_BAR; PG8_MMA(1, 0, At, B0); PG8_MMA(1, 1, At, B1); PG8_BAR; PG8_SCHED;
;         }
	s_nop 1
	ds_read_b128 v[22:25], v234
	ds_read_b128 v[30:33], v234 offset:1024
	ds_read_b128 v[34:37], v234 offset:2048
	ds_read_b128 v[38:41], v234 offset:3072
	ds_read_b128 v[154:157], v235
	ds_read_b128 v[158:161], v235 offset:1024
	ds_read_b128 v[162:165], v235 offset:2048
	ds_read_b128 v[166:169], v235 offset:3072
	ds_read_b128 v[70:73], v233 offset:32768
	ds_read_b128 v[78:81], v233 offset:33792
	ds_read_b128 v[178:181], v233 offset:34816
	ds_read_b128 v[182:185], v233 offset:35840
	ds_read_b128 v[186:189], v233 offset:36864
	ds_read_b128 v[190:193], v233 offset:37888
	ds_read_b128 v[194:197], v233 offset:38912
	ds_read_b128 v[198:201], v233 offset:39936
	s_add_u32 s82, s82, 0x80000
	s_addc_u32 s83, s83, 0
	s_mov_b32 m0, s31
	s_nop 0
	global_load_lds_dwordx4 v208, s[82:83]
	s_mov_b32 m0, s33
	s_nop 0
	global_load_lds_dwordx4 v210, s[82:83]
	s_waitcnt vmcnt(8) lgkmcnt(0)
	s_barrier
	v_mfma_i32_16x16x64_i8 v[150:153], v[22:25], v[70:73], v[150:153]
	v_mfma_i32_16x16x64_i8 v[142:145], v[34:37], v[70:73], v[142:145]
	v_mfma_i32_16x16x64_i8 v[126:129], v[22:25], v[178:181], v[126:129]
	v_mfma_i32_16x16x64_i8 v[122:125], v[34:37], v[178:181], v[122:125]
	v_mfma_i32_16x16x64_i8 v[114:117], v[22:25], v[186:189], v[114:117]
	v_mfma_i32_16x16x64_i8 v[106:109], v[34:37], v[186:189], v[106:109]
	v_mfma_i32_16x16x64_i8 v[146:149], v[22:25], v[194:197], v[146:149]
	v_mfma_i32_16x16x64_i8 v[138:141], v[34:37], v[194:197], v[138:141]
	v_mfma_i32_16x16x64_i8 v[150:153], v[30:33], v[78:81], v[150:153]
	v_mfma_i32_16x16x64_i8 v[142:145], v[38:41], v[78:81], v[142:145]
	v_mfma_i32_16x16x64_i8 v[126:129], v[30:33], v[182:185], v[126:129]
	v_mfma_i32_16x16x64_i8 v[122:125], v[38:41], v[182:185], v[122:125]
	v_mfma_i32_16x16x64_i8 v[114:117], v[30:33], v[190:193], v[114:117]
	v_mfma_i32_16x16x64_i8 v[106:109], v[38:41], v[190:193], v[106:109]
	v_mfma_i32_16x16x64_i8 v[146:149], v[30:33], v[198:201], v[146:149]
	v_mfma_i32_16x16x64_i8 v[138:141], v[38:41], v[198:201], v[138:141]
	v_mfma_i32_16x16x64_i8 v[134:137], v[154:157], v[70:73], v[134:137]
	v_mfma_i32_16x16x64_i8 v[70:73], v[162:165], v[70:73], v[130:133]
	v_mfma_i32_16x16x64_i8 v[130:133], v[166:169], v[78:81], v[70:73]
	v_mfma_i32_16x16x64_i8 v[70:73], v[154:157], v[178:181], v[118:121]
	v_mfma_i32_16x16x64_i8 v[118:121], v[158:161], v[182:185], v[70:73]
	v_mfma_i32_16x16x64_i8 v[70:73], v[162:165], v[178:181], v[110:113]
	v_mfma_i32_16x16x64_i8 v[110:113], v[166:169], v[182:185], v[70:73]
	v_mfma_i32_16x16x64_i8 v[70:73], v[154:157], v[186:189], v[102:105]
	v_mfma_i32_16x16x64_i8 v[102:105], v[158:161], v[190:193], v[70:73]
	v_mfma_i32_16x16x64_i8 v[70:73], v[162:165], v[186:189], v[98:101]
	v_mfma_i32_16x16x64_i8 v[98:101], v[166:169], v[190:193], v[70:73]
	v_mfma_i32_16x16x64_i8 v[70:73], v[154:157], v[194:197], v[94:97]
	v_mfma_i32_16x16x64_i8 v[94:97], v[158:161], v[198:201], v[70:73]
	v_mfma_i32_16x16x64_i8 v[70:73], v[162:165], v[194:197], v[90:93]
	v_mfma_i32_16x16x64_i8 v[134:137], v[158:161], v[78:81], v[134:137]
	v_mfma_i32_16x16x64_i8 v[90:93], v[166:169], v[198:201], v[70:73]
	s_barrier
	s_nop 3
	ds_read_b128 v[70:73], v233 offset:49152
	ds_read_b128 v[178:181], v233 offset:50176
	ds_read_b128 v[182:185], v233 offset:51200
	ds_read_b128 v[186:189], v233 offset:52224
	ds_read_b128 v[190:193], v233 offset:53248
	ds_read_b128 v[194:197], v233 offset:54272
	ds_read_b128 v[198:201], v233 offset:55296
	ds_read_b128 v[202:205], v233 offset:56320
	s_add_u32 s82, s80, 0x80
	s_addc_u32 s83, s81, 0
	s_mov_b32 m0, s84
	s_nop 0
	global_load_lds_dwordx4 v209, s[82:83]
	s_add_u32 s80, s80, 0x80080
	s_mov_b32 m0, s85
	s_nop 0
	global_load_lds_dwordx4 v211, s[82:83]
	s_addc_u32 s81, s81, 0
	s_mov_b32 m0, s88
	s_nop 0
	global_load_lds_dwordx4 v209, s[80:81]
	s_mov_b32 m0, s89
	s_nop 0
	global_load_lds_dwordx4 v211, s[80:81]
	s_mov_b32 m0, s86
	s_nop 0
	global_load_lds_dwordx4 v208, s[78:79]
	s_mov_b32 m0, s87
	s_nop 0
	global_load_lds_dwordx4 v210, s[78:79]
	s_waitcnt vmcnt(8) lgkmcnt(0)
	s_barrier
	v_mfma_i32_16x16x64_i8 v[78:81], v[22:25], v[70:73], v[86:89]
	v_mfma_i32_16x16x64_i8 v[74:77], v[22:25], v[182:185], v[74:77]
	v_mfma_i32_16x16x64_i8 v[58:61], v[22:25], v[190:193], v[58:61]
	v_mfma_i32_16x16x64_i8 v[2:5], v[22:25], v[198:201], v[2:5]
	v_mfma_i32_16x16x64_i8 v[86:89], v[30:33], v[178:181], v[78:81]
	v_mfma_i32_16x16x64_i8 v[78:81], v[34:37], v[70:73], v[82:85]
	v_mfma_i32_16x16x64_i8 v[74:77], v[30:33], v[186:189], v[74:77]
	v_mfma_i32_16x16x64_i8 v[66:69], v[34:37], v[182:185], v[66:69]
	v_mfma_i32_16x16x64_i8 v[58:61], v[30:33], v[194:197], v[58:61]
	v_mfma_i32_16x16x64_i8 v[50:53], v[34:37], v[190:193], v[50:53]
	v_mfma_i32_16x16x64_i8 v[30:33], v[30:33], v[202:205], v[2:5]
	v_mfma_i32_16x16x64_i8 v[2:5], v[34:37], v[198:201], v[6:9]
	v_mfma_i32_16x16x64_i8 v[82:85], v[38:41], v[178:181], v[78:81]
	v_mfma_i32_16x16x64_i8 v[66:69], v[38:41], v[186:189], v[66:69]
	v_mfma_i32_16x16x64_i8 v[50:53], v[38:41], v[194:197], v[50:53]
	v_mfma_i32_16x16x64_i8 v[22:25], v[38:41], v[202:205], v[2:5]
	v_mfma_i32_16x16x64_i8 v[2:5], v[154:157], v[70:73], v[10:13]
	v_mfma_i32_16x16x64_i8 v[78:81], v[158:161], v[178:181], v[2:5]
	v_mfma_i32_16x16x64_i8 v[2:5], v[162:165], v[70:73], v[14:17]
	v_mfma_i32_16x16x64_i8 v[70:73], v[166:169], v[178:181], v[2:5]
	v_mfma_i32_16x16x64_i8 v[2:5], v[154:157], v[182:185], v[62:65]
	v_mfma_i32_16x16x64_i8 v[62:65], v[158:161], v[186:189], v[2:5]
	v_mfma_i32_16x16x64_i8 v[2:5], v[162:165], v[182:185], v[54:57]
	v_mfma_i32_16x16x64_i8 v[54:57], v[166:169], v[186:189], v[2:5]
	v_mfma_i32_16x16x64_i8 v[2:5], v[154:157], v[190:193], v[46:49]
	v_mfma_i32_16x16x64_i8 v[46:49], v[158:161], v[194:197], v[2:5]
	v_mfma_i32_16x16x64_i8 v[2:5], v[162:165], v[190:193], v[42:45]
	v_mfma_i32_16x16x64_i8 v[42:45], v[166:169], v[194:197], v[2:5]
	v_mfma_i32_16x16x64_i8 v[2:5], v[154:157], v[198:201], v[18:21]
	v_mfma_i32_16x16x64_i8 v[38:41], v[158:161], v[202:205], v[2:5]
	v_mfma_i32_16x16x64_i8 v[2:5], v[162:165], v[198:201], v[26:29]
	v_mfma_i32_16x16x64_i8 v[34:37], v[166:169], v[202:205], v[2:5]
	s_barrier
	s_add_i32 s71, s71, 2
	s_add_u32 s25, s25, 0x100
	s_addc_u32 s26, s26, 0
	s_add_u32 s27, s27, 0x100
	s_addc_u32 s69, s69, 0
	s_add_u32 s0, s0, 0x100
	s_addc_u32 s1, s1, 0
	s_cmp_gt_u32 s71, 29
	s_cbranch_scc0 .LBB0_1191

; #define PG8_STAGE(bufoff, gbase, voff) do { if constexpr (VAR != 1 && VAR != 3) { _Pragma("unroll") for (int _i = 0; _i < 2; ++_i) \
;         asm volatile("s_mov_b32 m0, %2\n\ts_nop 0\n\tglobal_load_lds_dwordx4 %0, %1" :: "v"((voff)[_i]), "s"((const char*)(gbase)), "s"(ldsbase + (unsigned)((bufoff) + _i * 8192)) : "memory", "m0"); } } while (0)
; #define PG8_LDA(dst, b, h) do { if constexpr (VAR < 2) _Pragma("unroll") for (int m = 0; m < 4; ++m) _Pragma("unroll") for (int k = 0; k < 2; ++k) dst[m][k] = *(const LAS bf16x8*)(lds + PG8_SA(b, h) + aoff + m * 2048 + k * 1024); } while (0)
; #define PG8_LDB(dst, b, h) do { if constexpr (VAR < 2) _Pragma("unroll") for (int n = 0; n < 2; ++n) _Pragma("unroll") for (int k = 0; k < 2; ++k) dst[n][k] = *(const LAS bf16x8*)(lds + PG8_SB(b, h) + boff + n * 2048 + k * 1024); } while (0)
; #define PG8_WAIT_V(n) asm volatile("s_waitcnt vmcnt(" #n ")" ::: "memory")
; #define PG8_WAIT_L(n) asm volatile("s_waitcnt lgkmcnt(" #n ")" ::: "memory")
; #define PG8_BAR do { if constexpr (VAR != 3) __builtin_amdgcn_s_barrier(); } while (0)
; #define PG8_SCHED __builtin_amdgcn_sched_barrier(0)
;     ...
;             PG8_LDB(B0, 0, 0); PG8_LDB(B1, 0, 1); PG8_SCHED; PG8_LDA(At, 0, 0); PG8_STAGE(PG8_SA(1, 1), a1 + hstepA, voffA);
;             PG8_WAIT_V(8); PG8_WAIT_L(0); PG8_BAR; PG8_MMA(0, 0, At, B0); PG8_MMA(0, 1, At, B1); PG8_BAR; PG8_SCHED;
;             PG8_LDA(At, 0, 1); PG8_STAGE(PG8_SB(0, 0), b2, voffB); PG8_STAGE(PG8_SB(0, 1), b2 + hstepB, voffB); PG8_STAGE(PG8_SA(0, 0), a2, voffA);
;             PG8_WAIT_V(8); PG8_WAIT_L(0); PG8_BAR; PG8_MMA(1, 0, At, B0); PG8_MMA(1, 1, At, B1); PG8_BAR; PG8_SCHED;
.LBB0_1360:
	s_add_u32 s74, s60, 0x100
	s_addc_u32 s75, s61, 0
	s_add_u32 s76, s58, 0x100
	s_addc_u32 s77, s59, 0
	s_add_u32 s58, s60, 0x2b0080
	s_addc_u32 s59, s61, 0
	s_mov_b32 s78, -2
	s_waitcnt vmcnt(41)
	s_waitcnt vmcnt(40)
	s_waitcnt vmcnt(38)
	s_waitcnt vmcnt(35)
	s_waitcnt vmcnt(34)
	s_waitcnt vmcnt(32)
	ds_read_b128 v[130:133], v160
	ds_read_b128 v[134:137], v160 offset:1024
	ds_read_b128 v[142:145], v160 offset:2048
	ds_read_b128 v[146:149], v160 offset:3072
	ds_read_b128 v[150:153], v161
	ds_read_b128 v[166:169], v161 offset:1024
	ds_read_b128 v[170:173], v161 offset:2048
	ds_read_b128 v[174:177], v161 offset:3072
	s_cmpk_eq_i32 s78, 0xa8
	s_cselect_b32 s64, s12, s74
	s_cselect_b32 s65, s13, s75
	s_cselect_b32 s62, s56, s76
	s_cselect_b32 s63, s57, s77
	s_add_u32 s60, s64, 0x80
	s_addc_u32 s61, s65, 0
	ds_read_b128 v[178:181], v162
	ds_read_b128 v[182:185], v162 offset:1024
	ds_read_b128 v[186:189], v162 offset:2048
	ds_read_b128 v[190:193], v162 offset:3072
	ds_read_b128 v[194:197], v162 offset:4096
	ds_read_b128 v[198:201], v162 offset:5120
	ds_read_b128 v[202:205], v162 offset:6144
	ds_read_b128 v[206:209], v162 offset:7168
	s_mov_b32 m0, s69
	s_nop 0
	global_load_lds_dwordx4 v1, s[58:59]
	s_mov_b32 m0, s70
	s_nop 0
	global_load_lds_dwordx4 v155, s[58:59]
	s_waitcnt vmcnt(8) lgkmcnt(0)
	s_barrier
	v_mfma_f32_16x16x32_bf16 v[126:129], v[130:133], v[178:181], 0
	v_mfma_f32_16x16x32_bf16 v[122:125], v[142:145], v[178:181], 0
	v_mfma_f32_16x16x32_bf16 v[110:113], v[130:133], v[186:189], 0
	v_mfma_f32_16x16x32_bf16 v[106:109], v[142:145], v[186:189], 0
	v_mfma_f32_16x16x32_bf16 v[94:97], v[130:133], v[194:197], 0
	v_mfma_f32_16x16x32_bf16 v[90:93], v[142:145], v[194:197], 0
	v_mfma_f32_16x16x32_bf16 v[78:81], v[130:133], v[202:205], 0
	v_mfma_f32_16x16x32_bf16 v[74:77], v[142:145], v[202:205], 0
	v_mfma_f32_16x16x32_bf16 v[126:129], v[134:137], v[182:185], v[126:129]
	v_mfma_f32_16x16x32_bf16 v[122:125], v[146:149], v[182:185], v[122:125]
	v_mfma_f32_16x16x32_bf16 v[110:113], v[134:137], v[190:193], v[110:113]
	v_mfma_f32_16x16x32_bf16 v[106:109], v[146:149], v[190:193], v[106:109]
	v_mfma_f32_16x16x32_bf16 v[94:97], v[134:137], v[198:201], v[94:97]
	v_mfma_f32_16x16x32_bf16 v[90:93], v[146:149], v[198:201], v[90:93]
	v_mfma_f32_16x16x32_bf16 v[78:81], v[134:137], v[206:209], v[78:81]
	v_mfma_f32_16x16x32_bf16 v[74:77], v[146:149], v[206:209], v[74:77]
	v_mfma_f32_16x16x32_bf16 v[118:121], v[150:153], v[178:181], 0
	v_mfma_f32_16x16x32_bf16 v[114:117], v[170:173], v[178:181], 0
	v_mfma_f32_16x16x32_bf16 v[102:105], v[150:153], v[186:189], 0
	v_mfma_f32_16x16x32_bf16 v[98:101], v[170:173], v[186:189], 0
	v_mfma_f32_16x16x32_bf16 v[86:89], v[150:153], v[194:197], 0
	v_mfma_f32_16x16x32_bf16 v[82:85], v[170:173], v[194:197], 0
	v_mfma_f32_16x16x32_bf16 v[70:73], v[150:153], v[202:205], 0
	v_mfma_f32_16x16x32_bf16 v[66:69], v[170:173], v[202:205], 0
	v_mfma_f32_16x16x32_bf16 v[118:121], v[166:169], v[182:185], v[118:121]
	v_mfma_f32_16x16x32_bf16 v[114:117], v[174:177], v[182:185], v[114:117]
	v_mfma_f32_16x16x32_bf16 v[102:105], v[166:169], v[190:193], v[102:105]
	v_mfma_f32_16x16x32_bf16 v[98:101], v[174:177], v[190:193], v[98:101]
	v_mfma_f32_16x16x32_bf16 v[86:89], v[166:169], v[198:201], v[86:89]
	v_mfma_f32_16x16x32_bf16 v[82:85], v[174:177], v[198:201], v[82:85]
	v_mfma_f32_16x16x32_bf16 v[70:73], v[166:169], v[206:209], v[70:73]
	v_mfma_f32_16x16x32_bf16 v[66:69], v[174:177], v[206:209], v[66:69]
	s_barrier
	ds_read_b128 v[178:181], v162 offset:16384
	ds_read_b128 v[182:185], v162 offset:17408
	ds_read_b128 v[186:189], v162 offset:18432
	ds_read_b128 v[190:193], v162 offset:19456
	ds_read_b128 v[194:197], v162 offset:20480
	ds_read_b128 v[198:201], v162 offset:21504
	ds_read_b128 v[202:205], v162 offset:22528
	ds_read_b128 v[206:209], v162 offset:23552
	s_mov_b32 m0, s19
	s_nop 0
	global_load_lds_dwordx4 v154, s[62:63]
	s_add_u32 s80, s62, 0x2b0000
	s_mov_b32 m0, s21
	s_nop 0
	global_load_lds_dwordx4 v156, s[62:63]
	s_addc_u32 s81, s63, 0
	s_mov_b32 m0, s23
	s_nop 0
	global_load_lds_dwordx4 v154, s[80:81]
	s_mov_b32 m0, s26
	s_nop 0
	global_load_lds_dwordx4 v156, s[80:81]
	s_mov_b32 m0, s17
	s_nop 0
	global_load_lds_dwordx4 v1, s[64:65]
	s_mov_b32 m0, s27
	s_nop 0
	global_load_lds_dwordx4 v155, s[64:65]
	s_waitcnt vmcnt(8) lgkmcnt(0)
	s_barrier
	v_mfma_f32_16x16x32_bf16 v[62:65], v[130:133], v[178:181], 0
	v_mfma_f32_16x16x32_bf16 v[58:61], v[142:145], v[178:181], 0
	v_mfma_f32_16x16x32_bf16 v[46:49], v[130:133], v[186:189], 0
	v_mfma_f32_16x16x32_bf16 v[42:45], v[142:145], v[186:189], 0
	v_mfma_f32_16x16x32_bf16 v[30:33], v[130:133], v[194:197], 0
	v_mfma_f32_16x16x32_bf16 v[26:29], v[142:145], v[194:197], 0
	v_mfma_f32_16x16x32_bf16 v[14:17], v[130:133], v[202:205], 0
	v_mfma_f32_16x16x32_bf16 v[10:13], v[142:145], v[202:205], 0
	v_mfma_f32_16x16x32_bf16 v[62:65], v[134:137], v[182:185], v[62:65]
	v_mfma_f32_16x16x32_bf16 v[58:61], v[146:149], v[182:185], v[58:61]
	v_mfma_f32_16x16x32_bf16 v[46:49], v[134:137], v[190:193], v[46:49]
	v_mfma_f32_16x16x32_bf16 v[42:45], v[146:149], v[190:193], v[42:45]
	v_mfma_f32_16x16x32_bf16 v[30:33], v[134:137], v[198:201], v[30:33]
	v_mfma_f32_16x16x32_bf16 v[26:29], v[146:149], v[198:201], v[26:29]
	v_mfma_f32_16x16x32_bf16 v[14:17], v[134:137], v[206:209], v[14:17]
	v_mfma_f32_16x16x32_bf16 v[10:13], v[146:149], v[206:209], v[10:13]
	v_mfma_f32_16x16x32_bf16 v[54:57], v[150:153], v[178:181], 0
	v_mfma_f32_16x16x32_bf16 v[50:53], v[170:173], v[178:181], 0
	v_mfma_f32_16x16x32_bf16 v[38:41], v[150:153], v[186:189], 0
	v_mfma_f32_16x16x32_bf16 v[34:37], v[170:173], v[186:189], 0
	v_mfma_f32_16x16x32_bf16 v[22:25], v[150:153], v[194:197], 0
	v_mfma_f32_16x16x32_bf16 v[18:21], v[170:173], v[194:197], 0
	v_mfma_f32_16x16x32_bf16 v[6:9], v[150:153], v[202:205], 0
	v_mfma_f32_16x16x32_bf16 v[2:5], v[170:173], v[202:205], 0
	v_mfma_f32_16x16x32_bf16 v[54:57], v[166:169], v[182:185], v[54:57]
	v_mfma_f32_16x16x32_bf16 v[50:53], v[174:177], v[182:185], v[50:53]
	v_mfma_f32_16x16x32_bf16 v[38:41], v[166:169], v[190:193], v[38:41]
	v_mfma_f32_16x16x32_bf16 v[34:37], v[174:177], v[190:193], v[34:37]
	v_mfma_f32_16x16x32_bf16 v[22:25], v[166:169], v[198:201], v[22:25]
	v_mfma_f32_16x16x32_bf16 v[18:21], v[174:177], v[198:201], v[18:21]
	v_mfma_f32_16x16x32_bf16 v[6:9], v[166:169], v[206:209], v[6:9]
	v_mfma_f32_16x16x32_bf16 v[2:5], v[174:177], v[206:209], v[2:5]
	s_barrier
; #define PG8_STAGE(bufoff, gbase, voff) do { if constexpr (VAR != 1 && VAR != 3) { _Pragma("unroll") for (int _i = 0; _i < 2; ++_i) \
;         asm volatile("s_mov_b32 m0, %2\n\ts_nop 0\n\tglobal_load_lds_dwordx4 %0, %1" :: "v"((voff)[_i]), "s"((const char*)(gbase)), "s"(ldsbase + (unsigned)((bufoff) + _i * 8192)) : "memory", "m0"); } } while (0)
; #define PG8_LDA(dst, b, h) do { if constexpr (VAR < 2) _Pragma("unroll") for (int m = 0; m < 4; ++m) _Pragma("unroll") for (int k = 0; k < 2; ++k) dst[m][k] = *(const LAS bf16x8*)(lds + PG8_SA(b, h) + aoff + m * 2048 + k * 1024); } while (0)
; #define PG8_LDB(dst, b, h) do { if constexpr (VAR < 2) _Pragma("unroll") for (int n = 0; n < 2; ++n) _Pragma("unroll") for (int k = 0; k < 2; ++k) dst[n][k] = *(const LAS bf16x8*)(lds + PG8_SB(b, h) + boff + n * 2048 + k * 1024); } while (0)
; #define PG8_WAIT_V(n) asm volatile("s_waitcnt vmcnt(" #n ")" ::: "memory")
; #define PG8_WAIT_L(n) asm volatile("s_waitcnt lgkmcnt(" #n ")" ::: "memory")
; #define PG8_BAR do { if constexpr (VAR != 3) __builtin_amdgcn_s_barrier(); } while (0)
; #define PG8_SCHED __builtin_amdgcn_sched_barrier(0)
;     ...
;             PG8_LDB(B0, 1, 0); PG8_LDB(B1, 1, 1); PG8_SCHED; PG8_LDA(At, 1, 0); PG8_STAGE(PG8_SA(0, 1), a2 + hstepA, voffA);
;             PG8_WAIT_V(8); PG8_WAIT_L(0); PG8_BAR; PG8_MMA(0, 0, At, B0); PG8_MMA(0, 1, At, B1); PG8_BAR; PG8_SCHED;
;             PG8_LDA(At, 1, 1); PG8_STAGE(PG8_SB(1, 0), b3, voffB); PG8_STAGE(PG8_SB(1, 1), b3 + hstepB, voffB); PG8_STAGE(PG8_SA(1, 0), a3, voffA);
;             PG8_WAIT_V(8); PG8_WAIT_L(0); PG8_BAR; PG8_MMA(1, 0, At, B0); PG8_MMA(1, 1, At, B1); PG8_BAR; PG8_SCHED;
;         }
	ds_read_b128 v[130:133], v163
	ds_read_b128 v[134:137], v163 offset:1024
	ds_read_b128 v[142:145], v163 offset:2048
	ds_read_b128 v[146:149], v163 offset:3072
	ds_read_b128 v[150:153], v164
	ds_read_b128 v[166:169], v164 offset:1024
	ds_read_b128 v[170:173], v164 offset:2048
	ds_read_b128 v[174:177], v164 offset:3072
	ds_read_b128 v[178:181], v162 offset:32768
	ds_read_b128 v[182:185], v162 offset:33792
	ds_read_b128 v[186:189], v162 offset:34816
	ds_read_b128 v[190:193], v162 offset:35840
	ds_read_b128 v[194:197], v162 offset:36864
	ds_read_b128 v[198:201], v162 offset:37888
	ds_read_b128 v[202:205], v162 offset:38912
	ds_read_b128 v[206:209], v162 offset:39936
	s_add_u32 s64, s64, 0x2b0000
	s_addc_u32 s65, s65, 0
	s_mov_b32 m0, s28
	s_nop 0
	global_load_lds_dwordx4 v1, s[64:65]
	s_mov_b32 m0, s29
	s_nop 0
	global_load_lds_dwordx4 v155, s[64:65]
	s_waitcnt vmcnt(8) lgkmcnt(0)
	s_barrier
	v_mfma_f32_16x16x32_bf16 v[126:129], v[130:133], v[178:181], v[126:129]
	v_mfma_f32_16x16x32_bf16 v[122:125], v[142:145], v[178:181], v[122:125]
	v_mfma_f32_16x16x32_bf16 v[110:113], v[130:133], v[186:189], v[110:113]
	v_mfma_f32_16x16x32_bf16 v[106:109], v[142:145], v[186:189], v[106:109]
	v_mfma_f32_16x16x32_bf16 v[94:97], v[130:133], v[194:197], v[94:97]
	v_mfma_f32_16x16x32_bf16 v[90:93], v[142:145], v[194:197], v[90:93]
	v_mfma_f32_16x16x32_bf16 v[78:81], v[130:133], v[202:205], v[78:81]
	v_mfma_f32_16x16x32_bf16 v[74:77], v[142:145], v[202:205], v[74:77]
	v_mfma_f32_16x16x32_bf16 v[126:129], v[134:137], v[182:185], v[126:129]
	v_mfma_f32_16x16x32_bf16 v[122:125], v[146:149], v[182:185], v[122:125]
	v_mfma_f32_16x16x32_bf16 v[110:113], v[134:137], v[190:193], v[110:113]
	v_mfma_f32_16x16x32_bf16 v[106:109], v[146:149], v[190:193], v[106:109]
	v_mfma_f32_16x16x32_bf16 v[94:97], v[134:137], v[198:201], v[94:97]
	v_mfma_f32_16x16x32_bf16 v[90:93], v[146:149], v[198:201], v[90:93]
	v_mfma_f32_16x16x32_bf16 v[78:81], v[134:137], v[206:209], v[78:81]
	v_mfma_f32_16x16x32_bf16 v[74:77], v[146:149], v[206:209], v[74:77]
	v_mfma_f32_16x16x32_bf16 v[118:121], v[150:153], v[178:181], v[118:121]
	v_mfma_f32_16x16x32_bf16 v[114:117], v[170:173], v[178:181], v[114:117]
	v_mfma_f32_16x16x32_bf16 v[102:105], v[150:153], v[186:189], v[102:105]
	v_mfma_f32_16x16x32_bf16 v[98:101], v[170:173], v[186:189], v[98:101]
	v_mfma_f32_16x16x32_bf16 v[86:89], v[150:153], v[194:197], v[86:89]
	v_mfma_f32_16x16x32_bf16 v[82:85], v[170:173], v[194:197], v[82:85]
	v_mfma_f32_16x16x32_bf16 v[70:73], v[150:153], v[202:205], v[70:73]
	v_mfma_f32_16x16x32_bf16 v[66:69], v[170:173], v[202:205], v[66:69]
	v_mfma_f32_16x16x32_bf16 v[118:121], v[166:169], v[182:185], v[118:121]
	v_mfma_f32_16x16x32_bf16 v[114:117], v[174:177], v[182:185], v[114:117]
	v_mfma_f32_16x16x32_bf16 v[102:105], v[166:169], v[190:193], v[102:105]
	v_mfma_f32_16x16x32_bf16 v[98:101], v[174:177], v[190:193], v[98:101]
	v_mfma_f32_16x16x32_bf16 v[86:89], v[166:169], v[198:201], v[86:89]
	v_mfma_f32_16x16x32_bf16 v[82:85], v[174:177], v[198:201], v[82:85]
	v_mfma_f32_16x16x32_bf16 v[70:73], v[166:169], v[206:209], v[70:73]
	v_mfma_f32_16x16x32_bf16 v[66:69], v[174:177], v[206:209], v[66:69]
	s_barrier
	ds_read_b128 v[178:181], v162 offset:49152
	ds_read_b128 v[182:185], v162 offset:50176
	ds_read_b128 v[186:189], v162 offset:51200
	ds_read_b128 v[190:193], v162 offset:52224
	ds_read_b128 v[194:197], v162 offset:53248
	ds_read_b128 v[198:201], v162 offset:54272
	ds_read_b128 v[202:205], v162 offset:55296
	ds_read_b128 v[206:209], v162 offset:56320
	s_add_u32 s64, s62, 0x80
	s_addc_u32 s65, s63, 0
	s_mov_b32 m0, s30
	s_nop 0
	global_load_lds_dwordx4 v154, s[64:65]
	s_add_u32 s62, s62, 0x2b0080
	s_mov_b32 m0, s31
	s_nop 0
	global_load_lds_dwordx4 v156, s[64:65]
	s_addc_u32 s63, s63, 0
	s_mov_b32 m0, s67
	s_nop 0
	global_load_lds_dwordx4 v154, s[62:63]
	s_mov_b32 m0, s68
	s_nop 0
	global_load_lds_dwordx4 v156, s[62:63]
	s_mov_b32 m0, s33
	s_nop 0
	global_load_lds_dwordx4 v1, s[60:61]
	s_mov_b32 m0, s66
	s_nop 0
	global_load_lds_dwordx4 v155, s[60:61]
	s_waitcnt vmcnt(8) lgkmcnt(0)
	s_barrier
	v_mfma_f32_16x16x32_bf16 v[62:65], v[130:133], v[178:181], v[62:65]
	v_mfma_f32_16x16x32_bf16 v[58:61], v[142:145], v[178:181], v[58:61]
	v_mfma_f32_16x16x32_bf16 v[46:49], v[130:133], v[186:189], v[46:49]
	v_mfma_f32_16x16x32_bf16 v[42:45], v[142:145], v[186:189], v[42:45]
	v_mfma_f32_16x16x32_bf16 v[30:33], v[130:133], v[194:197], v[30:33]
	v_mfma_f32_16x16x32_bf16 v[26:29], v[142:145], v[194:197], v[26:29]
	v_mfma_f32_16x16x32_bf16 v[14:17], v[130:133], v[202:205], v[14:17]
	v_mfma_f32_16x16x32_bf16 v[10:13], v[142:145], v[202:205], v[10:13]
	v_mfma_f32_16x16x32_bf16 v[62:65], v[134:137], v[182:185], v[62:65]
	v_mfma_f32_16x16x32_bf16 v[58:61], v[146:149], v[182:185], v[58:61]
	v_mfma_f32_16x16x32_bf16 v[46:49], v[134:137], v[190:193], v[46:49]
	v_mfma_f32_16x16x32_bf16 v[42:45], v[146:149], v[190:193], v[42:45]
	v_mfma_f32_16x16x32_bf16 v[30:33], v[134:137], v[198:201], v[30:33]
	v_mfma_f32_16x16x32_bf16 v[26:29], v[146:149], v[198:201], v[26:29]
	v_mfma_f32_16x16x32_bf16 v[14:17], v[134:137], v[206:209], v[14:17]
	v_mfma_f32_16x16x32_bf16 v[10:13], v[146:149], v[206:209], v[10:13]
	v_mfma_f32_16x16x32_bf16 v[54:57], v[150:153], v[178:181], v[54:57]
	v_mfma_f32_16x16x32_bf16 v[50:53], v[170:173], v[178:181], v[50:53]
	v_mfma_f32_16x16x32_bf16 v[38:41], v[150:153], v[186:189], v[38:41]
	v_mfma_f32_16x16x32_bf16 v[34:37], v[170:173], v[186:189], v[34:37]
	v_mfma_f32_16x16x32_bf16 v[22:25], v[150:153], v[194:197], v[22:25]
	v_mfma_f32_16x16x32_bf16 v[18:21], v[170:173], v[194:197], v[18:21]
	v_mfma_f32_16x16x32_bf16 v[6:9], v[150:153], v[202:205], v[6:9]
	v_mfma_f32_16x16x32_bf16 v[2:5], v[170:173], v[202:205], v[2:5]
	v_mfma_f32_16x16x32_bf16 v[54:57], v[166:169], v[182:185], v[54:57]
	v_mfma_f32_16x16x32_bf16 v[50:53], v[174:177], v[182:185], v[50:53]
	v_mfma_f32_16x16x32_bf16 v[38:41], v[166:169], v[190:193], v[38:41]
	v_mfma_f32_16x16x32_bf16 v[34:37], v[174:177], v[190:193], v[34:37]
	v_mfma_f32_16x16x32_bf16 v[22:25], v[166:169], v[198:201], v[22:25]
	v_mfma_f32_16x16x32_bf16 v[18:21], v[174:177], v[198:201], v[18:21]
	v_mfma_f32_16x16x32_bf16 v[6:9], v[166:169], v[206:209], v[6:9]
	v_mfma_f32_16x16x32_bf16 v[2:5], v[174:177], v[206:209], v[2:5]
	s_barrier
	s_add_i32 s78, s78, 2
	s_add_u32 s74, s74, 0x100
	s_addc_u32 s75, s75, 0
	s_add_u32 s76, s76, 0x100
	s_addc_u32 s77, s77, 0
	s_add_u32 s58, s58, 0x100
	s_addc_u32 s59, s59, 0
	s_cmpk_gt_u32 s78, 0xa9
	s_cbranch_scc0 .LBB0_1361
	s_branch .Lmy_kexit_9
; #define PG8_STAGE(bufoff, gbase, voff) do { if constexpr (VAR != 1 && VAR != 3) { _Pragma("unroll") for (int _i = 0; _i < 2; ++_i) \
;         asm volatile("s_mov_b32 m0, %2\n\ts_nop 0\n\tglobal_load_lds_dwordx4 %0, %1" :: "v"((voff)[_i]), "s"((const char*)(gbase)), "s"(ldsbase + (unsigned)((bufoff) + _i * 8192)) : "memory", "m0"); } } while (0)
; #define PG8_LDA(dst, b, h) do { if constexpr (VAR < 2) _Pragma("unroll") for (int m = 0; m < 4; ++m) _Pragma("unroll") for (int k = 0; k < 2; ++k) dst[m][k] = *(const LAS bf16x8*)(lds + PG8_SA(b, h) + aoff + m * 2048 + k * 1024); } while (0)
; #define PG8_LDB(dst, b, h) do { if constexpr (VAR < 2) _Pragma("unroll") for (int n = 0; n < 2; ++n) _Pragma("unroll") for (int k = 0; k < 2; ++k) dst[n][k] = *(const LAS bf16x8*)(lds + PG8_SB(b, h) + boff + n * 2048 + k * 1024); } while (0)
; #define PG8_WAIT_V(n) asm volatile("s_waitcnt vmcnt(" #n ")" ::: "memory")
; #define PG8_WAIT_L(n) asm volatile("s_waitcnt lgkmcnt(" #n ")" ::: "memory")
; #define PG8_BAR do { if constexpr (VAR != 3) __builtin_amdgcn_s_barrier(); } while (0)
; #define PG8_SCHED __builtin_amdgcn_sched_barrier(0)
;     ...
;         for (int t = 0; t < nt; t += 2) {
;             const bool last = (t == nt - 2);
;             const char* a1 = cA + (size_t)(t + 1) * kstep;
;             const char* a2 = last ? nA : cA + (size_t)(t + 2) * kstep; const char* b2 = last ? nB : cB + (size_t)(t + 2) * kstep;
;             const char* a3 = a2 + kstep; const char* b3 = b2 + kstep;
;             PG8_LDB(B0, 0, 0); PG8_LDB(B1, 0, 1); PG8_SCHED; PG8_LDA(At, 0, 0); PG8_STAGE(PG8_SA(1, 1), a1 + hstepA, voffA);
;             PG8_WAIT_V(8); PG8_WAIT_L(0); PG8_BAR; PG8_MMA(0, 0, At, B0); PG8_MMA(0, 1, At, B1); PG8_BAR; PG8_SCHED;
;             PG8_LDA(At, 0, 1); PG8_STAGE(PG8_SB(0, 0), b2, voffB); PG8_STAGE(PG8_SB(0, 1), b2 + hstepB, voffB); PG8_STAGE(PG8_SA(0, 0), a2, voffA);
;             PG8_WAIT_V(8); PG8_WAIT_L(0); PG8_BAR; PG8_MMA(1, 0, At, B0); PG8_MMA(1, 1, At, B1); PG8_BAR; PG8_SCHED;
.LBB0_1361:
	ds_read_b128 v[130:133], v160
	ds_read_b128 v[134:137], v160 offset:1024
	ds_read_b128 v[142:145], v160 offset:2048
	ds_read_b128 v[146:149], v160 offset:3072
	ds_read_b128 v[150:153], v161
	ds_read_b128 v[166:169], v161 offset:1024
	ds_read_b128 v[170:173], v161 offset:2048
	ds_read_b128 v[174:177], v161 offset:3072
	s_cmpk_eq_i32 s78, 0xa8
	s_cselect_b32 s64, s12, s74
	s_cselect_b32 s65, s13, s75
	s_cselect_b32 s62, s56, s76
	s_cselect_b32 s63, s57, s77
	s_add_u32 s60, s64, 0x80
	s_addc_u32 s61, s65, 0
	ds_read_b128 v[178:181], v162
	ds_read_b128 v[182:185], v162 offset:1024
	ds_read_b128 v[186:189], v162 offset:2048
	ds_read_b128 v[190:193], v162 offset:3072
	ds_read_b128 v[194:197], v162 offset:4096
	ds_read_b128 v[198:201], v162 offset:5120
	ds_read_b128 v[202:205], v162 offset:6144
	ds_read_b128 v[206:209], v162 offset:7168
	s_mov_b32 m0, s69
	s_nop 0
	global_load_lds_dwordx4 v1, s[58:59]
	s_mov_b32 m0, s70
	s_nop 0
	global_load_lds_dwordx4 v155, s[58:59]
	s_waitcnt vmcnt(8) lgkmcnt(0)
	s_barrier
	v_mfma_f32_16x16x32_bf16 v[126:129], v[130:133], v[178:181], v[126:129]
	v_mfma_f32_16x16x32_bf16 v[122:125], v[142:145], v[178:181], v[122:125]
	v_mfma_f32_16x16x32_bf16 v[110:113], v[130:133], v[186:189], v[110:113]
	v_mfma_f32_16x16x32_bf16 v[106:109], v[142:145], v[186:189], v[106:109]
	v_mfma_f32_16x16x32_bf16 v[94:97], v[130:133], v[194:197], v[94:97]
	v_mfma_f32_16x16x32_bf16 v[90:93], v[142:145], v[194:197], v[90:93]
	v_mfma_f32_16x16x32_bf16 v[78:81], v[130:133], v[202:205], v[78:81]
	v_mfma_f32_16x16x32_bf16 v[74:77], v[142:145], v[202:205], v[74:77]
	v_mfma_f32_16x16x32_bf16 v[126:129], v[134:137], v[182:185], v[126:129]
	v_mfma_f32_16x16x32_bf16 v[122:125], v[146:149], v[182:185], v[122:125]
	v_mfma_f32_16x16x32_bf16 v[110:113], v[134:137], v[190:193], v[110:113]
	v_mfma_f32_16x16x32_bf16 v[106:109], v[146:149], v[190:193], v[106:109]
	v_mfma_f32_16x16x32_bf16 v[94:97], v[134:137], v[198:201], v[94:97]
	v_mfma_f32_16x16x32_bf16 v[90:93], v[146:149], v[198:201], v[90:93]
	v_mfma_f32_16x16x32_bf16 v[78:81], v[134:137], v[206:209], v[78:81]
	v_mfma_f32_16x16x32_bf16 v[74:77], v[146:149], v[206:209], v[74:77]
	v_mfma_f32_16x16x32_bf16 v[118:121], v[150:153], v[178:181], v[118:121]
	v_mfma_f32_16x16x32_bf16 v[114:117], v[170:173], v[178:181], v[114:117]
	v_mfma_f32_16x16x32_bf16 v[102:105], v[150:153], v[186:189], v[102:105]
	v_mfma_f32_16x16x32_bf16 v[98:101], v[170:173], v[186:189], v[98:101]
	v_mfma_f32_16x16x32_bf16 v[86:89], v[150:153], v[194:197], v[86:89]
	v_mfma_f32_16x16x32_bf16 v[82:85], v[170:173], v[194:197], v[82:85]
	v_mfma_f32_16x16x32_bf16 v[70:73], v[150:153], v[202:205], v[70:73]
	v_mfma_f32_16x16x32_bf16 v[66:69], v[170:173], v[202:205], v[66:69]
	v_mfma_f32_16x16x32_bf16 v[118:121], v[166:169], v[182:185], v[118:121]
	v_mfma_f32_16x16x32_bf16 v[114:117], v[174:177], v[182:185], v[114:117]
	v_mfma_f32_16x16x32_bf16 v[102:105], v[166:169], v[190:193], v[102:105]
	v_mfma_f32_16x16x32_bf16 v[98:101], v[174:177], v[190:193], v[98:101]
	v_mfma_f32_16x16x32_bf16 v[86:89], v[166:169], v[198:201], v[86:89]
	v_mfma_f32_16x16x32_bf16 v[82:85], v[174:177], v[198:201], v[82:85]
	v_mfma_f32_16x16x32_bf16 v[70:73], v[166:169], v[206:209], v[70:73]
	v_mfma_f32_16x16x32_bf16 v[66:69], v[174:177], v[206:209], v[66:69]
	s_barrier
	ds_read_b128 v[178:181], v162 offset:16384
	ds_read_b128 v[182:185], v162 offset:17408
	ds_read_b128 v[186:189], v162 offset:18432
	ds_read_b128 v[190:193], v162 offset:19456
	ds_read_b128 v[194:197], v162 offset:20480
	ds_read_b128 v[198:201], v162 offset:21504
	ds_read_b128 v[202:205], v162 offset:22528
	ds_read_b128 v[206:209], v162 offset:23552
	s_mov_b32 m0, s19
	s_nop 0
	global_load_lds_dwordx4 v154, s[62:63]
	s_add_u32 s80, s62, 0x2b0000
	s_mov_b32 m0, s21
	s_nop 0
	global_load_lds_dwordx4 v156, s[62:63]
	s_addc_u32 s81, s63, 0
	s_mov_b32 m0, s23
	s_nop 0
	global_load_lds_dwordx4 v154, s[80:81]
	s_mov_b32 m0, s26
	s_nop 0
	global_load_lds_dwordx4 v156, s[80:81]
	s_mov_b32 m0, s17
	s_nop 0
	global_load_lds_dwordx4 v1, s[64:65]
	s_mov_b32 m0, s27
	s_nop 0
	global_load_lds_dwordx4 v155, s[64:65]
	s_waitcnt vmcnt(8) lgkmcnt(0)
	s_barrier
	v_mfma_f32_16x16x32_bf16 v[62:65], v[130:133], v[178:181], v[62:65]
	v_mfma_f32_16x16x32_bf16 v[58:61], v[142:145], v[178:181], v[58:61]
	v_mfma_f32_16x16x32_bf16 v[46:49], v[130:133], v[186:189], v[46:49]
	v_mfma_f32_16x16x32_bf16 v[42:45], v[142:145], v[186:189], v[42:45]
	v_mfma_f32_16x16x32_bf16 v[30:33], v[130:133], v[194:197], v[30:33]
	v_mfma_f32_16x16x32_bf16 v[26:29], v[142:145], v[194:197], v[26:29]
	v_mfma_f32_16x16x32_bf16 v[14:17], v[130:133], v[202:205], v[14:17]
	v_mfma_f32_16x16x32_bf16 v[10:13], v[142:145], v[202:205], v[10:13]
	v_mfma_f32_16x16x32_bf16 v[62:65], v[134:137], v[182:185], v[62:65]
	v_mfma_f32_16x16x32_bf16 v[58:61], v[146:149], v[182:185], v[58:61]
	v_mfma_f32_16x16x32_bf16 v[46:49], v[134:137], v[190:193], v[46:49]
	v_mfma_f32_16x16x32_bf16 v[42:45], v[146:149], v[190:193], v[42:45]
	v_mfma_f32_16x16x32_bf16 v[30:33], v[134:137], v[198:201], v[30:33]
	v_mfma_f32_16x16x32_bf16 v[26:29], v[146:149], v[198:201], v[26:29]
	v_mfma_f32_16x16x32_bf16 v[14:17], v[134:137], v[206:209], v[14:17]
	v_mfma_f32_16x16x32_bf16 v[10:13], v[146:149], v[206:209], v[10:13]
	v_mfma_f32_16x16x32_bf16 v[54:57], v[150:153], v[178:181], v[54:57]
	v_mfma_f32_16x16x32_bf16 v[50:53], v[170:173], v[178:181], v[50:53]
	v_mfma_f32_16x16x32_bf16 v[38:41], v[150:153], v[186:189], v[38:41]
	v_mfma_f32_16x16x32_bf16 v[34:37], v[170:173], v[186:189], v[34:37]
	v_mfma_f32_16x16x32_bf16 v[22:25], v[150:153], v[194:197], v[22:25]
	v_mfma_f32_16x16x32_bf16 v[18:21], v[170:173], v[194:197], v[18:21]
	v_mfma_f32_16x16x32_bf16 v[6:9], v[150:153], v[202:205], v[6:9]
	v_mfma_f32_16x16x32_bf16 v[2:5], v[170:173], v[202:205], v[2:5]
	v_mfma_f32_16x16x32_bf16 v[54:57], v[166:169], v[182:185], v[54:57]
	v_mfma_f32_16x16x32_bf16 v[50:53], v[174:177], v[182:185], v[50:53]
	v_mfma_f32_16x16x32_bf16 v[38:41], v[166:169], v[190:193], v[38:41]
	v_mfma_f32_16x16x32_bf16 v[34:37], v[174:177], v[190:193], v[34:37]
	v_mfma_f32_16x16x32_bf16 v[22:25], v[166:169], v[198:201], v[22:25]
	v_mfma_f32_16x16x32_bf16 v[18:21], v[174:177], v[198:201], v[18:21]
	v_mfma_f32_16x16x32_bf16 v[6:9], v[166:169], v[206:209], v[6:9]
	v_mfma_f32_16x16x32_bf16 v[2:5], v[174:177], v[206:209], v[2:5]
	s_barrier
; #define PG8_STAGE(bufoff, gbase, voff) do { if constexpr (VAR != 1 && VAR != 3) { _Pragma("unroll") for (int _i = 0; _i < 2; ++_i) \
;         asm volatile("s_mov_b32 m0, %2\n\ts_nop 0\n\tglobal_load_lds_dwordx4 %0, %1" :: "v"((voff)[_i]), "s"((const char*)(gbase)), "s"(ldsbase + (unsigned)((bufoff) + _i * 8192)) : "memory", "m0"); } } while (0)
; #define PG8_LDA(dst, b, h) do { if constexpr (VAR < 2) _Pragma("unroll") for (int m = 0; m < 4; ++m) _Pragma("unroll") for (int k = 0; k < 2; ++k) dst[m][k] = *(const LAS bf16x8*)(lds + PG8_SA(b, h) + aoff + m * 2048 + k * 1024); } while (0)
; #define PG8_LDB(dst, b, h) do { if constexpr (VAR < 2) _Pragma("unroll") for (int n = 0; n < 2; ++n) _Pragma("unroll") for (int k = 0; k < 2; ++k) dst[n][k] = *(const LAS bf16x8*)(lds + PG8_SB(b, h) + boff + n * 2048 + k * 1024); } while (0)
; #define PG8_WAIT_V(n) asm volatile("s_waitcnt vmcnt(" #n ")" ::: "memory")
; #define PG8_WAIT_L(n) asm volatile("s_waitcnt lgkmcnt(" #n ")" ::: "memory")
; #define PG8_BAR do { if constexpr (VAR != 3) __builtin_amdgcn_s_barrier(); } while (0)
; #define PG8_SCHED __builtin_amdgcn_sched_barrier(0)
;     ...
;             PG8_LDB(B0, 1, 0); PG8_LDB(B1, 1, 1); PG8_SCHED; PG8_LDA(At, 1, 0); PG8_STAGE(PG8_SA(0, 1), a2 + hstepA, voffA);
;             PG8_WAIT_V(8); PG8_WAIT_L(0); PG8_BAR; PG8_MMA(0, 0, At, B0); PG8_MMA(0, 1, At, B1); PG8_BAR; PG8_SCHED;
;             PG8_LDA(At, 1, 1); PG8_STAGE(PG8_SB(1, 0), b3, voffB); PG8_STAGE(PG8_SB(1, 1), b3 + hstepB, voffB); PG8_STAGE(PG8_SA(1, 0), a3, voffA);
;             PG8_WAIT_V(8); PG8_WAIT_L(0); PG8_BAR; PG8_MMA(1, 0, At, B0); PG8_MMA(1, 1, At, B1); PG8_BAR; PG8_SCHED;
;         }
	ds_read_b128 v[130:133], v163
	ds_read_b128 v[134:137], v163 offset:1024
	ds_read_b128 v[142:145], v163 offset:2048
	ds_read_b128 v[146:149], v163 offset:3072
	ds_read_b128 v[150:153], v164
	ds_read_b128 v[166:169], v164 offset:1024
	ds_read_b128 v[170:173], v164 offset:2048
	ds_read_b128 v[174:177], v164 offset:3072
	ds_read_b128 v[178:181], v162 offset:32768
	ds_read_b128 v[182:185], v162 offset:33792
	ds_read_b128 v[186:189], v162 offset:34816
	ds_read_b128 v[190:193], v162 offset:35840
	ds_read_b128 v[194:197], v162 offset:36864
	ds_read_b128 v[198:201], v162 offset:37888
	ds_read_b128 v[202:205], v162 offset:38912
	ds_read_b128 v[206:209], v162 offset:39936
	s_add_u32 s64, s64, 0x2b0000
	s_addc_u32 s65, s65, 0
	s_mov_b32 m0, s28
	s_nop 0
	global_load_lds_dwordx4 v1, s[64:65]
	s_mov_b32 m0, s29
	s_nop 0
	global_load_lds_dwordx4 v155, s[64:65]
	s_waitcnt vmcnt(8) lgkmcnt(0)
	s_barrier
	v_mfma_f32_16x16x32_bf16 v[126:129], v[130:133], v[178:181], v[126:129]
	v_mfma_f32_16x16x32_bf16 v[122:125], v[142:145], v[178:181], v[122:125]
	v_mfma_f32_16x16x32_bf16 v[110:113], v[130:133], v[186:189], v[110:113]
	v_mfma_f32_16x16x32_bf16 v[106:109], v[142:145], v[186:189], v[106:109]
	v_mfma_f32_16x16x32_bf16 v[94:97], v[130:133], v[194:197], v[94:97]
	v_mfma_f32_16x16x32_bf16 v[90:93], v[142:145], v[194:197], v[90:93]
	v_mfma_f32_16x16x32_bf16 v[78:81], v[130:133], v[202:205], v[78:81]
	v_mfma_f32_16x16x32_bf16 v[74:77], v[142:145], v[202:205], v[74:77]
	v_mfma_f32_16x16x32_bf16 v[126:129], v[134:137], v[182:185], v[126:129]
	v_mfma_f32_16x16x32_bf16 v[122:125], v[146:149], v[182:185], v[122:125]
	v_mfma_f32_16x16x32_bf16 v[110:113], v[134:137], v[190:193], v[110:113]
	v_mfma_f32_16x16x32_bf16 v[106:109], v[146:149], v[190:193], v[106:109]
	v_mfma_f32_16x16x32_bf16 v[94:97], v[134:137], v[198:201], v[94:97]
	v_mfma_f32_16x16x32_bf16 v[90:93], v[146:149], v[198:201], v[90:93]
	v_mfma_f32_16x16x32_bf16 v[78:81], v[134:137], v[206:209], v[78:81]
	v_mfma_f32_16x16x32_bf16 v[74:77], v[146:149], v[206:209], v[74:77]
	v_mfma_f32_16x16x32_bf16 v[118:121], v[150:153], v[178:181], v[118:121]
	v_mfma_f32_16x16x32_bf16 v[114:117], v[170:173], v[178:181], v[114:117]
	v_mfma_f32_16x16x32_bf16 v[102:105], v[150:153], v[186:189], v[102:105]
	v_mfma_f32_16x16x32_bf16 v[98:101], v[170:173], v[186:189], v[98:101]
	v_mfma_f32_16x16x32_bf16 v[86:89], v[150:153], v[194:197], v[86:89]
	v_mfma_f32_16x16x32_bf16 v[82:85], v[170:173], v[194:197], v[82:85]
	v_mfma_f32_16x16x32_bf16 v[70:73], v[150:153], v[202:205], v[70:73]
	v_mfma_f32_16x16x32_bf16 v[66:69], v[170:173], v[202:205], v[66:69]
	v_mfma_f32_16x16x32_bf16 v[118:121], v[166:169], v[182:185], v[118:121]
	v_mfma_f32_16x16x32_bf16 v[114:117], v[174:177], v[182:185], v[114:117]
	v_mfma_f32_16x16x32_bf16 v[102:105], v[166:169], v[190:193], v[102:105]
	v_mfma_f32_16x16x32_bf16 v[98:101], v[174:177], v[190:193], v[98:101]
	v_mfma_f32_16x16x32_bf16 v[86:89], v[166:169], v[198:201], v[86:89]
	v_mfma_f32_16x16x32_bf16 v[82:85], v[174:177], v[198:201], v[82:85]
	v_mfma_f32_16x16x32_bf16 v[70:73], v[166:169], v[206:209], v[70:73]
	v_mfma_f32_16x16x32_bf16 v[66:69], v[174:177], v[206:209], v[66:69]
	s_barrier
	ds_read_b128 v[178:181], v162 offset:49152
	ds_read_b128 v[182:185], v162 offset:50176
	ds_read_b128 v[186:189], v162 offset:51200
	ds_read_b128 v[190:193], v162 offset:52224
	ds_read_b128 v[194:197], v162 offset:53248
	ds_read_b128 v[198:201], v162 offset:54272
	ds_read_b128 v[202:205], v162 offset:55296
	ds_read_b128 v[206:209], v162 offset:56320
	s_add_u32 s64, s62, 0x80
	s_addc_u32 s65, s63, 0
	s_mov_b32 m0, s30
	s_nop 0
	global_load_lds_dwordx4 v154, s[64:65]
	s_add_u32 s62, s62, 0x2b0080
	s_mov_b32 m0, s31
	s_nop 0
	global_load_lds_dwordx4 v156, s[64:65]
	s_addc_u32 s63, s63, 0
	s_mov_b32 m0, s67
	s_nop 0
	global_load_lds_dwordx4 v154, s[62:63]
	s_mov_b32 m0, s68
	s_nop 0
	global_load_lds_dwordx4 v156, s[62:63]
	s_mov_b32 m0, s33
	s_nop 0
	global_load_lds_dwordx4 v1, s[60:61]
	s_mov_b32 m0, s66
	s_nop 0
	global_load_lds_dwordx4 v155, s[60:61]
	s_waitcnt vmcnt(8) lgkmcnt(0)
	s_barrier
	v_mfma_f32_16x16x32_bf16 v[62:65], v[130:133], v[178:181], v[62:65]
	v_mfma_f32_16x16x32_bf16 v[58:61], v[142:145], v[178:181], v[58:61]
	v_mfma_f32_16x16x32_bf16 v[46:49], v[130:133], v[186:189], v[46:49]
	v_mfma_f32_16x16x32_bf16 v[42:45], v[142:145], v[186:189], v[42:45]
	v_mfma_f32_16x16x32_bf16 v[30:33], v[130:133], v[194:197], v[30:33]
	v_mfma_f32_16x16x32_bf16 v[26:29], v[142:145], v[194:197], v[26:29]
	v_mfma_f32_16x16x32_bf16 v[14:17], v[130:133], v[202:205], v[14:17]
	v_mfma_f32_16x16x32_bf16 v[10:13], v[142:145], v[202:205], v[10:13]
	v_mfma_f32_16x16x32_bf16 v[62:65], v[134:137], v[182:185], v[62:65]
	v_mfma_f32_16x16x32_bf16 v[58:61], v[146:149], v[182:185], v[58:61]
	v_mfma_f32_16x16x32_bf16 v[46:49], v[134:137], v[190:193], v[46:49]
	v_mfma_f32_16x16x32_bf16 v[42:45], v[146:149], v[190:193], v[42:45]
	v_mfma_f32_16x16x32_bf16 v[30:33], v[134:137], v[198:201], v[30:33]
	v_mfma_f32_16x16x32_bf16 v[26:29], v[146:149], v[198:201], v[26:29]
	v_mfma_f32_16x16x32_bf16 v[14:17], v[134:137], v[206:209], v[14:17]
	v_mfma_f32_16x16x32_bf16 v[10:13], v[146:149], v[206:209], v[10:13]
	v_mfma_f32_16x16x32_bf16 v[54:57], v[150:153], v[178:181], v[54:57]
	v_mfma_f32_16x16x32_bf16 v[50:53], v[170:173], v[178:181], v[50:53]
	v_mfma_f32_16x16x32_bf16 v[38:41], v[150:153], v[186:189], v[38:41]
	v_mfma_f32_16x16x32_bf16 v[34:37], v[170:173], v[186:189], v[34:37]
	v_mfma_f32_16x16x32_bf16 v[22:25], v[150:153], v[194:197], v[22:25]
	v_mfma_f32_16x16x32_bf16 v[18:21], v[170:173], v[194:197], v[18:21]
	v_mfma_f32_16x16x32_bf16 v[6:9], v[150:153], v[202:205], v[6:9]
	v_mfma_f32_16x16x32_bf16 v[2:5], v[170:173], v[202:205], v[2:5]
	v_mfma_f32_16x16x32_bf16 v[54:57], v[166:169], v[182:185], v[54:57]
	v_mfma_f32_16x16x32_bf16 v[50:53], v[174:177], v[182:185], v[50:53]
	v_mfma_f32_16x16x32_bf16 v[38:41], v[166:169], v[190:193], v[38:41]
	v_mfma_f32_16x16x32_bf16 v[34:37], v[174:177], v[190:193], v[34:37]
	v_mfma_f32_16x16x32_bf16 v[22:25], v[166:169], v[198:201], v[22:25]
	v_mfma_f32_16x16x32_bf16 v[18:21], v[174:177], v[198:201], v[18:21]
	v_mfma_f32_16x16x32_bf16 v[6:9], v[166:169], v[206:209], v[6:9]
	v_mfma_f32_16x16x32_bf16 v[2:5], v[174:177], v[206:209], v[2:5]
	s_barrier
	s_add_i32 s78, s78, 2
	s_add_u32 s74, s74, 0x100
	s_addc_u32 s75, s75, 0
	s_add_u32 s76, s76, 0x100
	s_addc_u32 s77, s77, 0
	s_add_u32 s58, s58, 0x100
	s_addc_u32 s59, s59, 0
	s_cmpk_gt_u32 s78, 0xa9
	s_cbranch_scc0 .LBB0_1361
